# v33 + cross-row ds_bpermute gathers in LRU scans replaced by v_permlane16/32_swap VALU network
# baseline (speedup 1.0000x reference)
; #define LAS __attribute__((address_space(3)))
; __device__ __forceinline__ u32x4 pack8(const float (&f)[8]) { u32x4 o; o.x = pk2(f[0], f[1]); o.y = pk2(f[2], f[3]); o.z = pk2(f[4], f[5]); o.w = pk2(f[6], f[7]); return o; }
; __device__ __forceinline__ void lru_conv_tile(const Args& a, LAS bf16_t* cxb, int l, const Tile& T) {
;     ...
;     for (int i = 0; i < 11; ++i) {
;         const int tg = T.t0 + grp * 8 + i - 2;
;         u32x4 rv = raw[i]; if (!(tg >= 0 && tg < T.seqlen)) rv = (u32x4){0u, 0u, 0u, 0u};
; #pragma unroll
;         for (int e = 0; e < 8; ++e) { win[0][e] = win[1][e]; win[1][e] = win[2][e]; win[2][e] = win[3][e]; }
;         unpack8(rv, win[3]);
;         if (i >= 3) {
;             float o[8];
; #pragma unroll
;             for (int e = 0; e < 8; ++e) o[e] = bias[e] + w[0][e] * win[0][e] + w[1][e] * win[1][e] + w[2][e] * win[2][e] + w[3][e] * win[3][e];
;             *(LAS u32x4*)(cxb + (grp * 8 + i - 3) * CXS + c0) = pack8(o);
;         }
;     }
.LBB0_545:
	s_or_b64 exec, exec, s[4:5]
	s_waitcnt vmcnt(0)
	v_lshlrev_b32_e32 v162, 16, v146
	v_and_b32_e32 v164, 0xffff0000, v146
	v_add_u32_e32 v146, 1, v158
	v_cmp_lt_i32_e32 vcc, 1, v146
	v_add_u32_e32 v146, -1, v158
	v_cmp_gt_u32_e64 s[0:1], s34, v146
	s_and_b64 vcc, vcc, s[0:1]
	v_cndmask_b32_e32 v182, 0, v144, vcc
	v_add_u32_e32 v144, 2, v158
	v_cndmask_b32_e32 v180, 0, v145, vcc
	v_cndmask_b32_e32 v143, 0, v143, vcc
	v_cndmask_b32_e32 v142, 0, v142, vcc
	v_cmp_lt_i32_e32 vcc, 1, v144
	v_cmp_ge_i32_e64 s[0:1], s34, v144
	s_and_b64 vcc, vcc, s[0:1]
	v_or_b32_e32 v190, 3, v160
	v_cndmask_b32_e32 v186, 0, v136, vcc
	v_add_u32_e32 v136, s72, v190
	v_cndmask_b32_e32 v184, 0, v137, vcc
	v_cndmask_b32_e32 v135, 0, v135, vcc
	v_cndmask_b32_e32 v134, 0, v134, vcc
	v_cmp_lt_i32_e32 vcc, 1, v136
	v_add_u32_e32 v136, -2, v136
	v_cmp_gt_u32_e64 s[0:1], s34, v136
	s_and_b64 vcc, vcc, s[0:1]
	v_cndmask_b32_e32 v136, 0, v139, vcc
	v_cndmask_b32_e32 v137, 0, v138, vcc
	v_lshlrev_b32_e32 v163, 16, v147
	v_and_b32_e32 v165, 0xffff0000, v147
	v_lshlrev_b32_e32 v177, 16, v135
	v_lshlrev_b32_e32 v176, 16, v134
	v_and_b32_e32 v179, 0xffff0000, v135
	v_and_b32_e32 v178, 0xffff0000, v134
	v_lshlrev_b32_e32 v147, 16, v136
	v_lshlrev_b32_e32 v146, 16, v137
	v_and_b32_e32 v145, 0xffff0000, v136
	v_and_b32_e32 v144, 0xffff0000, v137
	v_mov_b32_e32 v134, v86
	v_mov_b32_e32 v135, v88
	v_mov_b32_e32 v136, v102
	v_mov_b32_e32 v137, v104
	v_mov_b32_e32 v88, v87
	v_mov_b32_e32 v104, v103
	v_cndmask_b32_e32 v188, 0, v141, vcc
	v_cndmask_b32_e32 v191, 0, v140, vcc
	v_lshlrev_b32_e32 v173, 16, v143
	v_lshlrev_b32_e32 v172, 16, v142
	v_and_b32_e32 v175, 0xffff0000, v143
	v_and_b32_e32 v174, 0xffff0000, v142
	v_pk_fma_f32 v[140:141], v[134:135], v[162:163], v[136:137]
	v_mov_b32_e32 v138, v90
	v_mov_b32_e32 v139, v92
	v_pk_fma_f32 v[86:87], v[88:89], v[164:165], v[104:105]
	v_mov_b32_e32 v92, v91
	v_pk_fma_f32 v[142:143], v[138:139], v[172:173], v[140:141]
	v_mov_b32_e32 v140, v94
	v_mov_b32_e32 v141, v96
	v_pk_fma_f32 v[86:87], v[92:93], v[174:175], v[86:87]
	v_mov_b32_e32 v96, v95
	v_pk_fma_f32 v[160:161], v[140:141], v[176:177], v[142:143]
	v_mov_b32_e32 v143, v100
	v_pk_fma_f32 v[86:87], v[96:97], v[178:179], v[86:87]
	v_mov_b32_e32 v100, v99
	v_lshlrev_b32_e32 v166, 16, v148
	v_lshlrev_b32_e32 v167, 16, v149
	v_pk_fma_f32 v[162:163], v[100:101], v[144:145], v[86:87]
	v_mov_b32_e32 v86, v66
	v_mov_b32_e32 v87, v68
	v_mov_b32_e32 v90, v82
	v_mov_b32_e32 v91, v84
	v_and_b32_e32 v148, 0xffff0000, v148
	v_and_b32_e32 v149, 0xffff0000, v149
	v_mov_b32_e32 v142, v98
	v_lshlrev_b32_e32 v165, 16, v180
	v_lshlrev_b32_e32 v164, 16, v182
	v_pk_fma_f32 v[98:99], v[86:87], v[166:167], v[90:91]
	v_mov_b32_e32 v94, v70
	v_mov_b32_e32 v95, v72
	v_mov_b32_e32 v68, v67
	v_mov_b32_e32 v84, v83
	v_and_b32_e32 v181, 0xffff0000, v180
	v_and_b32_e32 v180, 0xffff0000, v182
	v_lshlrev_b32_e32 v183, 16, v184
	v_lshlrev_b32_e32 v182, 16, v186
	v_pk_fma_f32 v[102:103], v[94:95], v[164:165], v[98:99]
	v_mov_b32_e32 v98, v74
	v_mov_b32_e32 v99, v76
	v_pk_fma_f32 v[66:67], v[68:69], v[148:149], v[84:85]
	v_mov_b32_e32 v72, v71
	v_and_b32_e32 v185, 0xffff0000, v184
	v_and_b32_e32 v184, 0xffff0000, v186
	v_lshlrev_b32_e32 v187, 16, v188
	v_lshlrev_b32_e32 v186, 16, v191
	v_pk_fma_f32 v[166:167], v[98:99], v[182:183], v[102:103]
	v_mov_b32_e32 v102, v78
	v_mov_b32_e32 v103, v80
	v_pk_fma_f32 v[66:67], v[72:73], v[180:181], v[66:67]
	v_mov_b32_e32 v76, v75
	v_and_b32_e32 v189, 0xffff0000, v188
	v_and_b32_e32 v188, 0xffff0000, v191
	v_pk_fma_f32 v[166:167], v[102:103], v[186:187], v[166:167]
	v_pk_fma_f32 v[66:67], v[76:77], v[184:185], v[66:67]
	v_mov_b32_e32 v80, v79
	v_pk_fma_f32 v[66:67], v[80:81], v[188:189], v[66:67]
	v_bfe_u32 v78, v166, 16, 1
	v_pk_fma_f32 v[160:161], v[142:143], v[146:147], v[160:161]
	v_bfe_u32 v70, v67, 16, 1
	v_bfe_u32 v71, v66, 16, 1
	v_add3_u32 v78, v166, v78, s27
	v_bfe_u32 v75, v162, 16, 1
	v_add3_u32 v66, v66, v71, s27
	v_add3_u32 v67, v67, v70, s27
	v_bfe_u32 v70, v160, 16, 1
	v_bfe_u32 v71, v161, 16, 1
	v_bfe_u32 v79, v167, 16, 1
	v_lshrrev_b32_e32 v78, 16, v78
	v_bfe_u32 v74, v163, 16, 1
	v_add3_u32 v75, v162, v75, s27
	v_add3_u32 v79, v167, v79, s27
	v_add3_u32 v71, v161, v71, s27
	v_add3_u32 v70, v160, v70, s27
	v_and_or_b32 v162, v66, s6, v78
	v_mul_lo_u32 v66, v190, s29
	v_add3_u32 v74, v163, v74, s27
	v_lshrrev_b32_e32 v70, 16, v70
	v_lshrrev_b32_e32 v71, 16, v71
	v_lshrrev_b32_e32 v79, 16, v79
	v_add3_u32 v166, 0, v66, v206
	v_and_or_b32 v163, v67, s6, v79
	v_and_or_b32 v161, v74, s6, v71
	v_and_or_b32 v160, v75, s6, v70
	v_add_u32_e32 v66, 0xfffff9d0, v166
	ds_write_b128 v66, v[160:163]
	v_add_u32_e32 v66, 4, v158
	v_cmp_lt_i32_e32 vcc, 1, v66
	v_cmp_ge_i32_e64 s[0:1], s34, v66
	s_and_b64 vcc, vcc, s[0:1]
	v_cndmask_b32_e32 v133, 0, v133, vcc
	v_cndmask_b32_e32 v132, 0, v132, vcc
	v_cndmask_b32_e32 v70, 0, v131, vcc
	v_cndmask_b32_e32 v74, 0, v130, vcc
	v_pk_fma_f32 v[78:79], v[88:89], v[174:175], v[104:105]
	v_lshlrev_b32_e32 v83, 16, v133
	v_lshlrev_b32_e32 v82, 16, v132
	v_and_b32_e32 v149, 0xffff0000, v133
	v_and_b32_e32 v148, 0xffff0000, v132
	v_pk_fma_f32 v[132:133], v[68:69], v[180:181], v[84:85]
	v_lshlrev_b32_e32 v67, 16, v70
	v_lshlrev_b32_e32 v66, 16, v74
	v_and_b32_e32 v71, 0xffff0000, v70
	v_and_b32_e32 v70, 0xffff0000, v74
	v_pk_fma_f32 v[74:75], v[134:135], v[172:173], v[136:137]
	v_pk_fma_f32 v[78:79], v[92:93], v[178:179], v[78:79]
	v_pk_fma_f32 v[130:131], v[86:87], v[164:165], v[90:91]
	v_pk_fma_f32 v[132:133], v[72:73], v[184:185], v[132:133]
	v_pk_fma_f32 v[74:75], v[138:139], v[176:177], v[74:75]
	v_pk_fma_f32 v[78:79], v[96:97], v[144:145], v[78:79]
; #define LAS __attribute__((address_space(3)))
; __device__ __forceinline__ u32x4 pack8(const float (&f)[8]) { u32x4 o; o.x = pk2(f[0], f[1]); o.y = pk2(f[2], f[3]); o.z = pk2(f[4], f[5]); o.w = pk2(f[6], f[7]); return o; }
; __device__ __forceinline__ void lru_conv_tile(const Args& a, LAS bf16_t* cxb, int l, const Tile& T) {
;     ...
;     for (int i = 0; i < 11; ++i) {
;         const int tg = T.t0 + grp * 8 + i - 2;
;         u32x4 rv = raw[i]; if (!(tg >= 0 && tg < T.seqlen)) rv = (u32x4){0u, 0u, 0u, 0u};
; #pragma unroll
;         for (int e = 0; e < 8; ++e) { win[0][e] = win[1][e]; win[1][e] = win[2][e]; win[2][e] = win[3][e]; }
;         unpack8(rv, win[3]);
;         if (i >= 3) {
;             float o[8];
; #pragma unroll
;             for (int e = 0; e < 8; ++e) o[e] = bias[e] + w[0][e] * win[0][e] + w[1][e] * win[1][e] + w[2][e] * win[2][e] + w[3][e] * win[3][e];
;             *(LAS u32x4*)(cxb + (grp * 8 + i - 3) * CXS + c0) = pack8(o);
;         }
;     }
	v_pk_fma_f32 v[130:131], v[94:95], v[182:183], v[130:131]
	v_pk_fma_f32 v[132:133], v[76:77], v[188:189], v[132:133]
	v_pk_fma_f32 v[74:75], v[140:141], v[146:147], v[74:75]
	v_pk_fma_f32 v[78:79], v[100:101], v[70:71], v[78:79]
	v_pk_fma_f32 v[130:131], v[98:99], v[186:187], v[130:131]
	v_pk_fma_f32 v[132:133], v[80:81], v[148:149], v[132:133]
	v_pk_fma_f32 v[74:75], v[142:143], v[66:67], v[74:75]
	v_pk_fma_f32 v[130:131], v[102:103], v[82:83], v[130:131]
	v_bfe_u32 v160, v133, 16, 1
	v_bfe_u32 v161, v132, 16, 1
	v_bfe_u32 v162, v79, 16, 1
	v_bfe_u32 v163, v78, 16, 1
	v_add3_u32 v78, v78, v163, s27
	v_add3_u32 v79, v79, v162, s27
	v_add3_u32 v132, v132, v161, s27
	v_add3_u32 v133, v133, v160, s27
	v_bfe_u32 v160, v74, 16, 1
	v_bfe_u32 v161, v75, 16, 1
	v_bfe_u32 v162, v130, 16, 1
	v_bfe_u32 v163, v131, 16, 1
	v_add3_u32 v131, v131, v163, s27
	v_add3_u32 v130, v130, v162, s27
	v_add3_u32 v75, v75, v161, s27
	v_add3_u32 v74, v74, v160, s27
	v_lshrrev_b32_e32 v74, 16, v74
	v_lshrrev_b32_e32 v75, 16, v75
	v_lshrrev_b32_e32 v130, 16, v130
	v_lshrrev_b32_e32 v131, 16, v131
	v_and_or_b32 v133, v133, s6, v131
	v_and_or_b32 v132, v132, s6, v130
	v_and_or_b32 v131, v79, s6, v75
	v_and_or_b32 v130, v78, s6, v74
	v_add_u32_e32 v74, 0xfffffbe0, v166
	ds_write_b128 v74, v[130:133]
	v_add_u32_e32 v74, 5, v158
	v_cmp_lt_i32_e32 vcc, 1, v74
	v_add_u32_e32 v74, 3, v158
	v_cmp_gt_u32_e64 s[0:1], s34, v74
	s_and_b64 vcc, vcc, s[0:1]
	v_cndmask_b32_e32 v132, 0, v129, vcc
	v_cndmask_b32_e32 v160, 0, v128, vcc
	v_cndmask_b32_e32 v78, 0, v127, vcc
	v_cndmask_b32_e32 v126, 0, v126, vcc
	v_pk_fma_f32 v[128:129], v[88:89], v[178:179], v[104:105]
	v_pk_fma_f32 v[162:163], v[68:69], v[184:185], v[84:85]
	v_lshlrev_b32_e32 v75, 16, v78
	v_lshlrev_b32_e32 v74, 16, v126
	v_and_b32_e32 v79, 0xffff0000, v78
	v_and_b32_e32 v78, 0xffff0000, v126
	v_pk_fma_f32 v[126:127], v[134:135], v[176:177], v[136:137]
	v_pk_fma_f32 v[128:129], v[92:93], v[144:145], v[128:129]
	v_lshlrev_b32_e32 v131, 16, v132
	v_lshlrev_b32_e32 v130, 16, v160
	v_and_b32_e32 v133, 0xffff0000, v132
	v_and_b32_e32 v132, 0xffff0000, v160
	v_pk_fma_f32 v[160:161], v[86:87], v[182:183], v[90:91]
	v_pk_fma_f32 v[162:163], v[72:73], v[188:189], v[162:163]
	v_pk_fma_f32 v[126:127], v[138:139], v[146:147], v[126:127]
	v_pk_fma_f32 v[128:129], v[96:97], v[70:71], v[128:129]
	v_pk_fma_f32 v[160:161], v[94:95], v[186:187], v[160:161]
	v_pk_fma_f32 v[162:163], v[76:77], v[148:149], v[162:163]
	v_pk_fma_f32 v[126:127], v[140:141], v[66:67], v[126:127]
	v_pk_fma_f32 v[128:129], v[100:101], v[78:79], v[128:129]
	v_pk_fma_f32 v[160:161], v[98:99], v[82:83], v[160:161]
	v_pk_fma_f32 v[162:163], v[80:81], v[132:133], v[162:163]
	v_pk_fma_f32 v[126:127], v[142:143], v[74:75], v[126:127]
	v_pk_fma_f32 v[160:161], v[102:103], v[130:131], v[160:161]
	v_bfe_u32 v164, v163, 16, 1
	v_bfe_u32 v165, v162, 16, 1
	v_bfe_u32 v167, v129, 16, 1
	v_bfe_u32 v172, v128, 16, 1
	v_add3_u32 v172, v128, v172, s27
	v_add3_u32 v167, v129, v167, s27
	v_add3_u32 v128, v162, v165, s27
	v_add3_u32 v129, v163, v164, s27
	v_bfe_u32 v162, v126, 16, 1
	v_bfe_u32 v163, v127, 16, 1
	v_bfe_u32 v164, v160, 16, 1
	v_bfe_u32 v165, v161, 16, 1
	v_add3_u32 v161, v161, v165, s27
	v_add3_u32 v160, v160, v164, s27
	v_add3_u32 v127, v127, v163, s27
	v_add3_u32 v126, v126, v162, s27
	v_lshrrev_b32_e32 v126, 16, v126
	v_lshrrev_b32_e32 v127, 16, v127
	v_lshrrev_b32_e32 v160, 16, v160
	v_lshrrev_b32_e32 v161, 16, v161
	v_and_or_b32 v129, v129, s6, v161
	v_and_or_b32 v128, v128, s6, v160
	v_and_or_b32 v127, v167, s6, v127
	v_and_or_b32 v126, v172, s6, v126
	v_add_u32_e32 v160, 0xfffffdf0, v166
	ds_write_b128 v160, v[126:129]
	v_add_u32_e32 v126, 6, v158
	v_cmp_lt_i32_e32 vcc, 1, v126
	v_cmp_ge_i32_e64 s[0:1], s34, v126
	s_and_b64 vcc, vcc, s[0:1]
	v_cndmask_b32_e32 v160, 0, v125, vcc
	v_cndmask_b32_e32 v161, 0, v124, vcc
	v_cndmask_b32_e32 v123, 0, v123, vcc
	v_cndmask_b32_e32 v122, 0, v122, vcc
	v_pk_fma_f32 v[124:125], v[88:89], v[144:145], v[104:105]
	v_pk_fma_f32 v[162:163], v[68:69], v[188:189], v[84:85]
	v_lshlrev_b32_e32 v127, 16, v123
	v_lshlrev_b32_e32 v126, 16, v122
	v_and_b32_e32 v129, 0xffff0000, v123
	v_and_b32_e32 v128, 0xffff0000, v122
	v_pk_fma_f32 v[122:123], v[134:135], v[146:147], v[136:137]
	v_pk_fma_f32 v[124:125], v[92:93], v[70:71], v[124:125]
	v_lshlrev_b32_e32 v145, 16, v160
	v_lshlrev_b32_e32 v144, 16, v161
	v_and_b32_e32 v147, 0xffff0000, v160
	v_and_b32_e32 v146, 0xffff0000, v161
	v_pk_fma_f32 v[160:161], v[86:87], v[186:187], v[90:91]
	v_pk_fma_f32 v[162:163], v[72:73], v[148:149], v[162:163]
	v_pk_fma_f32 v[122:123], v[138:139], v[66:67], v[122:123]
	v_pk_fma_f32 v[124:125], v[96:97], v[78:79], v[124:125]
	v_pk_fma_f32 v[160:161], v[94:95], v[82:83], v[160:161]
	v_pk_fma_f32 v[162:163], v[76:77], v[132:133], v[162:163]
	v_pk_fma_f32 v[122:123], v[140:141], v[74:75], v[122:123]
	v_pk_fma_f32 v[124:125], v[100:101], v[128:129], v[124:125]
	v_pk_fma_f32 v[160:161], v[98:99], v[130:131], v[160:161]
	v_pk_fma_f32 v[162:163], v[80:81], v[146:147], v[162:163]
	v_pk_fma_f32 v[122:123], v[142:143], v[126:127], v[122:123]
	v_pk_fma_f32 v[160:161], v[102:103], v[144:145], v[160:161]
	v_bfe_u32 v164, v163, 16, 1
	v_bfe_u32 v165, v162, 16, 1
	v_bfe_u32 v167, v125, 16, 1
	v_bfe_u32 v172, v124, 16, 1
	v_add3_u32 v172, v124, v172, s27
	v_add3_u32 v167, v125, v167, s27
	v_add3_u32 v124, v162, v165, s27
	v_add3_u32 v125, v163, v164, s27
	v_bfe_u32 v162, v122, 16, 1
	v_bfe_u32 v163, v123, 16, 1
	v_bfe_u32 v164, v160, 16, 1
	v_bfe_u32 v165, v161, 16, 1
	v_add3_u32 v161, v161, v165, s27
	v_add3_u32 v160, v160, v164, s27
	v_add3_u32 v123, v123, v163, s27
; #define LAS __attribute__((address_space(3)))
; __device__ __forceinline__ u32x4 pack8(const float (&f)[8]) { u32x4 o; o.x = pk2(f[0], f[1]); o.y = pk2(f[2], f[3]); o.z = pk2(f[4], f[5]); o.w = pk2(f[6], f[7]); return o; }
; __device__ __forceinline__ void lru_conv_tile(const Args& a, LAS bf16_t* cxb, int l, const Tile& T) {
;     ...
;     for (int i = 0; i < 11; ++i) {
;         const int tg = T.t0 + grp * 8 + i - 2;
;         u32x4 rv = raw[i]; if (!(tg >= 0 && tg < T.seqlen)) rv = (u32x4){0u, 0u, 0u, 0u};
; #pragma unroll
;         for (int e = 0; e < 8; ++e) { win[0][e] = win[1][e]; win[1][e] = win[2][e]; win[2][e] = win[3][e]; }
;         unpack8(rv, win[3]);
;         if (i >= 3) {
;             float o[8];
; #pragma unroll
;             for (int e = 0; e < 8; ++e) o[e] = bias[e] + w[0][e] * win[0][e] + w[1][e] * win[1][e] + w[2][e] * win[2][e] + w[3][e] * win[3][e];
;             *(LAS u32x4*)(cxb + (grp * 8 + i - 3) * CXS + c0) = pack8(o);
;         }
;     }
	v_add3_u32 v122, v122, v162, s27
	v_lshrrev_b32_e32 v122, 16, v122
	v_lshrrev_b32_e32 v123, 16, v123
	v_lshrrev_b32_e32 v160, 16, v160
	v_lshrrev_b32_e32 v161, 16, v161
	v_and_or_b32 v125, v125, s6, v161
	v_and_or_b32 v124, v124, s6, v160
	v_and_or_b32 v123, v167, s6, v123
	v_and_or_b32 v122, v172, s6, v122
	v_or_b32_e32 v159, 7, v159
	ds_write_b128 v166, v[122:125]
	v_add_u32_e32 v122, s72, v159
	v_cmp_lt_i32_e32 vcc, 1, v122
	v_add_u32_e32 v122, -2, v122
	v_cmp_gt_u32_e64 s[0:1], s34, v122
	s_and_b64 vcc, vcc, s[0:1]
	v_cndmask_b32_e32 v119, 0, v119, vcc
	v_cndmask_b32_e32 v118, 0, v118, vcc
	v_lshlrev_b32_e32 v123, 16, v119
	v_lshlrev_b32_e32 v122, 16, v118
	v_and_b32_e32 v125, 0xffff0000, v119
	v_and_b32_e32 v124, 0xffff0000, v118
	v_pk_fma_f32 v[70:71], v[88:89], v[70:71], v[104:105]
	v_pk_fma_f32 v[118:119], v[68:69], v[148:149], v[84:85]
	v_cndmask_b32_e32 v121, 0, v121, vcc
	v_cndmask_b32_e32 v120, 0, v120, vcc
	v_pk_fma_f32 v[66:67], v[134:135], v[66:67], v[136:137]
	v_pk_fma_f32 v[70:71], v[92:93], v[78:79], v[70:71]
	v_pk_fma_f32 v[82:83], v[86:87], v[82:83], v[90:91]
	v_pk_fma_f32 v[118:119], v[72:73], v[132:133], v[118:119]
	v_pk_fma_f32 v[66:67], v[138:139], v[74:75], v[66:67]
	v_pk_fma_f32 v[70:71], v[96:97], v[128:129], v[70:71]
	v_and_b32_e32 v163, 0xffff0000, v121
	v_and_b32_e32 v162, 0xffff0000, v120
	v_pk_fma_f32 v[82:83], v[94:95], v[130:131], v[82:83]
	v_pk_fma_f32 v[118:119], v[76:77], v[146:147], v[118:119]
	v_pk_fma_f32 v[66:67], v[140:141], v[126:127], v[66:67]
	v_pk_fma_f32 v[70:71], v[100:101], v[124:125], v[70:71]
	v_lshlrev_b32_e32 v161, 16, v121
	v_lshlrev_b32_e32 v160, 16, v120
	v_pk_fma_f32 v[82:83], v[98:99], v[144:145], v[82:83]
	v_pk_fma_f32 v[118:119], v[80:81], v[162:163], v[118:119]
	v_pk_fma_f32 v[66:67], v[142:143], v[122:123], v[66:67]
	v_pk_fma_f32 v[82:83], v[102:103], v[160:161], v[82:83]
	v_bfe_u32 v120, v119, 16, 1
	v_bfe_u32 v148, v71, 16, 1
	v_add3_u32 v71, v71, v148, s27
	v_add3_u32 v119, v119, v120, s27
	v_bfe_u32 v120, v66, 16, 1
	v_bfe_u32 v148, v82, 16, 1
	v_bfe_u32 v121, v118, 16, 1
	v_bfe_u32 v149, v70, 16, 1
	v_add3_u32 v82, v82, v148, s27
	v_add3_u32 v66, v66, v120, s27
	v_add3_u32 v70, v70, v149, s27
	v_add3_u32 v118, v118, v121, s27
	v_bfe_u32 v121, v67, 16, 1
	v_bfe_u32 v149, v83, 16, 1
	v_lshrrev_b32_e32 v66, 16, v66
	v_lshrrev_b32_e32 v82, 16, v82
	v_add3_u32 v83, v83, v149, s27
	v_add3_u32 v67, v67, v121, s27
	v_and_or_b32 v120, v118, s6, v82
	v_and_or_b32 v118, v70, s6, v66
	v_mul_lo_u32 v66, v159, s29
	v_lshrrev_b32_e32 v67, 16, v67
	v_lshrrev_b32_e32 v83, 16, v83
	v_add_u32_e32 v66, 0, v66
	s_movk_i32 s0, 0xf9d0
	v_and_or_b32 v121, v119, s6, v83
	v_and_or_b32 v119, v71, s6, v67
	v_add3_u32 v66, v66, v206, s0
	ds_write_b128 v66, v[118:121]
	v_add_u32_e32 v66, 8, v158
	v_cmp_lt_i32_e32 vcc, 1, v66
	v_cmp_ge_i32_e64 s[0:1], s34, v66
	s_and_b64 vcc, vcc, s[0:1]
	v_cndmask_b32_e32 v117, 0, v117, vcc
	v_cndmask_b32_e32 v116, 0, v116, vcc
	v_cndmask_b32_e32 v70, 0, v115, vcc
	v_cndmask_b32_e32 v82, 0, v114, vcc
	v_lshlrev_b32_e32 v67, 16, v70
	v_lshlrev_b32_e32 v66, 16, v82
	v_and_b32_e32 v71, 0xffff0000, v70
	v_and_b32_e32 v70, 0xffff0000, v82
	v_pk_fma_f32 v[78:79], v[88:89], v[78:79], v[104:105]
	v_lshlrev_b32_e32 v83, 16, v117
	v_lshlrev_b32_e32 v82, 16, v116
	v_and_b32_e32 v119, 0xffff0000, v117
	v_and_b32_e32 v118, 0xffff0000, v116
	v_pk_fma_f32 v[116:117], v[68:69], v[132:133], v[84:85]
	v_pk_fma_f32 v[74:75], v[134:135], v[74:75], v[136:137]
	v_pk_fma_f32 v[78:79], v[92:93], v[128:129], v[78:79]
	v_pk_fma_f32 v[114:115], v[86:87], v[130:131], v[90:91]
	v_pk_fma_f32 v[116:117], v[72:73], v[146:147], v[116:117]
	v_pk_fma_f32 v[74:75], v[138:139], v[126:127], v[74:75]
	v_pk_fma_f32 v[78:79], v[96:97], v[124:125], v[78:79]
	v_pk_fma_f32 v[114:115], v[94:95], v[144:145], v[114:115]
	v_pk_fma_f32 v[116:117], v[76:77], v[162:163], v[116:117]
	v_pk_fma_f32 v[74:75], v[140:141], v[122:123], v[74:75]
	v_pk_fma_f32 v[78:79], v[100:101], v[70:71], v[78:79]
	v_pk_fma_f32 v[114:115], v[98:99], v[160:161], v[114:115]
	v_pk_fma_f32 v[116:117], v[80:81], v[118:119], v[116:117]
	v_pk_fma_f32 v[74:75], v[142:143], v[66:67], v[74:75]
	v_pk_fma_f32 v[114:115], v[102:103], v[82:83], v[114:115]
	v_bfe_u32 v120, v117, 16, 1
	v_bfe_u32 v130, v79, 16, 1
	v_add3_u32 v79, v79, v130, s27
	v_add3_u32 v117, v117, v120, s27
	v_bfe_u32 v120, v74, 16, 1
	v_bfe_u32 v130, v114, 16, 1
	v_bfe_u32 v121, v116, 16, 1
	v_bfe_u32 v131, v78, 16, 1
	v_add3_u32 v114, v114, v130, s27
	v_add3_u32 v74, v74, v120, s27
	v_add3_u32 v78, v78, v131, s27
	v_add3_u32 v116, v116, v121, s27
	v_lshrrev_b32_e32 v74, 16, v74
	v_lshrrev_b32_e32 v114, 16, v114
	v_and_or_b32 v116, v116, s6, v114
	v_and_or_b32 v114, v78, s6, v74
	v_add_u32_e32 v74, 9, v158
	v_bfe_u32 v121, v75, 16, 1
	v_bfe_u32 v131, v115, 16, 1
	v_cmp_lt_i32_e32 vcc, 1, v74
	v_add_u32_e32 v74, 7, v158
	v_add3_u32 v115, v115, v131, s27
	v_add3_u32 v75, v75, v121, s27
	v_cmp_gt_u32_e64 s[0:1], s34, v74
	v_lshrrev_b32_e32 v75, 16, v75
	v_lshrrev_b32_e32 v115, 16, v115
	s_and_b64 vcc, vcc, s[0:1]
	v_and_or_b32 v117, v117, s6, v115
	v_and_or_b32 v115, v79, s6, v75
	v_cndmask_b32_e32 v78, 0, v111, vcc
	v_cndmask_b32_e32 v110, 0, v110, vcc
	ds_write_b128 v166, v[114:117] offset:1056
	v_cndmask_b32_e32 v116, 0, v113, vcc
	v_cndmask_b32_e32 v120, 0, v112, vcc
	v_lshlrev_b32_e32 v75, 16, v78
	v_lshlrev_b32_e32 v74, 16, v110
	v_and_b32_e32 v79, 0xffff0000, v78
	v_and_b32_e32 v78, 0xffff0000, v110
	v_pk_fma_f32 v[110:111], v[134:135], v[126:127], v[136:137]
	v_pk_fma_f32 v[112:113], v[88:89], v[128:129], v[104:105]
	v_pk_fma_f32 v[126:127], v[68:69], v[146:147], v[84:85]
; #define LAS __attribute__((address_space(3)))
; __device__ __forceinline__ u32x4 pack8(const float (&f)[8]) { u32x4 o; o.x = pk2(f[0], f[1]); o.y = pk2(f[2], f[3]); o.z = pk2(f[4], f[5]); o.w = pk2(f[6], f[7]); return o; }
; __device__ __forceinline__ void lru_conv_tile(const Args& a, LAS bf16_t* cxb, int l, const Tile& T) {
;     ...
;     for (int i = 0; i < 11; ++i) {
;         const int tg = T.t0 + grp * 8 + i - 2;
;         u32x4 rv = raw[i]; if (!(tg >= 0 && tg < T.seqlen)) rv = (u32x4){0u, 0u, 0u, 0u};
; #pragma unroll
;         for (int e = 0; e < 8; ++e) { win[0][e] = win[1][e]; win[1][e] = win[2][e]; win[2][e] = win[3][e]; }
;         unpack8(rv, win[3]);
;         if (i >= 3) {
;             float o[8];
; #pragma unroll
;             for (int e = 0; e < 8; ++e) o[e] = bias[e] + w[0][e] * win[0][e] + w[1][e] * win[1][e] + w[2][e] * win[2][e] + w[3][e] * win[3][e];
;             *(LAS u32x4*)(cxb + (grp * 8 + i - 3) * CXS + c0) = pack8(o);
;         }
;     }
; template <int MODE>
; __device__ __forceinline__ void lru_unit(const Args& a, LAS unsigned char* lds, int l, int tt) {
;     ...
;     for (int nt = 0; nt < 2; ++nt) { prm0[nt][2] = -8.0f * log1pf(__expf(-prm0[nt][2])); prm1[nt][2] = -8.0f * log1pf(__expf(-prm1[nt][2])); }
	v_pk_fma_f32 v[112:113], v[92:93], v[124:125], v[112:113]
	v_lshlrev_b32_e32 v115, 16, v116
	v_lshlrev_b32_e32 v114, 16, v120
	v_and_b32_e32 v117, 0xffff0000, v116
	v_and_b32_e32 v116, 0xffff0000, v120
	v_pk_fma_f32 v[120:121], v[86:87], v[144:145], v[90:91]
	v_pk_fma_f32 v[126:127], v[72:73], v[162:163], v[126:127]
	v_pk_fma_f32 v[110:111], v[138:139], v[122:123], v[110:111]
	v_pk_fma_f32 v[112:113], v[96:97], v[70:71], v[112:113]
	v_pk_fma_f32 v[120:121], v[94:95], v[160:161], v[120:121]
	v_pk_fma_f32 v[126:127], v[76:77], v[118:119], v[126:127]
	v_pk_fma_f32 v[110:111], v[140:141], v[66:67], v[110:111]
	v_pk_fma_f32 v[112:113], v[100:101], v[78:79], v[112:113]
	v_pk_fma_f32 v[120:121], v[98:99], v[82:83], v[120:121]
	v_pk_fma_f32 v[126:127], v[80:81], v[116:117], v[126:127]
	v_pk_fma_f32 v[110:111], v[142:143], v[74:75], v[110:111]
	v_pk_fma_f32 v[120:121], v[102:103], v[114:115], v[120:121]
	v_bfe_u32 v128, v127, 16, 1
	v_bfe_u32 v129, v126, 16, 1
	v_bfe_u32 v130, v113, 16, 1
	v_bfe_u32 v131, v112, 16, 1
	v_add3_u32 v131, v112, v131, s27
	v_add3_u32 v130, v113, v130, s27
	v_add3_u32 v112, v126, v129, s27
	v_add3_u32 v113, v127, v128, s27
	v_bfe_u32 v126, v110, 16, 1
	v_bfe_u32 v127, v111, 16, 1
	v_bfe_u32 v128, v120, 16, 1
	v_bfe_u32 v129, v121, 16, 1
	v_add3_u32 v121, v121, v129, s27
	v_add3_u32 v120, v120, v128, s27
	v_add3_u32 v111, v111, v127, s27
	v_add3_u32 v110, v110, v126, s27
	v_lshrrev_b32_e32 v110, 16, v110
	v_lshrrev_b32_e32 v111, 16, v111
	v_lshrrev_b32_e32 v120, 16, v120
	v_lshrrev_b32_e32 v121, 16, v121
	v_and_or_b32 v113, v113, s6, v121
	v_and_or_b32 v112, v112, s6, v120
	v_and_or_b32 v111, v130, s6, v111
	v_and_or_b32 v110, v131, s6, v110
	ds_write_b128 v166, v[110:113] offset:1584
	v_add_u32_e32 v110, 10, v158
	v_cmp_lt_i32_e32 vcc, 1, v110
	v_cmp_ge_i32_e64 s[0:1], s34, v110
	s_and_b64 vcc, vcc, s[0:1]
	v_cndmask_b32_e32 v113, 0, v108, vcc
	v_cndmask_b32_e32 v108, 0, v107, vcc
	v_cndmask_b32_e32 v110, 0, v106, vcc
	v_cndmask_b32_e32 v112, 0, v109, vcc
	v_and_b32_e32 v107, 0xffff0000, v108
	v_and_b32_e32 v106, 0xffff0000, v110
	v_lshlrev_b32_e32 v109, 16, v108
	v_lshlrev_b32_e32 v108, 16, v110
	v_pk_fma_f32 v[110:111], v[134:135], v[122:123], v[136:137]
	v_pk_fma_f32 v[86:87], v[86:87], v[160:161], v[90:91]
	v_pk_fma_f32 v[66:67], v[138:139], v[66:67], v[110:111]
	v_pk_fma_f32 v[68:69], v[68:69], v[162:163], v[84:85]
	v_pk_fma_f32 v[66:67], v[140:141], v[74:75], v[66:67]
	v_pk_fma_f32 v[74:75], v[88:89], v[124:125], v[104:105]
	v_pk_fma_f32 v[82:83], v[94:95], v[82:83], v[86:87]
	v_pk_fma_f32 v[70:71], v[92:93], v[70:71], v[74:75]
	v_pk_fma_f32 v[68:69], v[72:73], v[118:119], v[68:69]
	v_pk_fma_f32 v[70:71], v[96:97], v[78:79], v[70:71]
	v_and_b32_e32 v75, 0xffff0000, v112
	v_pk_fma_f32 v[70:71], v[100:101], v[106:107], v[70:71]
	v_and_b32_e32 v74, 0xffff0000, v113
	v_lshlrev_b32_e32 v79, 16, v112
	v_lshlrev_b32_e32 v78, 16, v113
	v_pk_fma_f32 v[82:83], v[98:99], v[114:115], v[82:83]
	v_pk_fma_f32 v[68:69], v[76:77], v[116:117], v[68:69]
	v_pk_fma_f32 v[78:79], v[102:103], v[78:79], v[82:83]
	v_pk_fma_f32 v[68:69], v[80:81], v[74:75], v[68:69]
	v_bfe_u32 v74, v71, 16, 1
	v_pk_fma_f32 v[66:67], v[142:143], v[108:109], v[66:67]
	v_bfe_u32 v72, v69, 16, 1
	v_add3_u32 v71, v71, v74, s27
	v_bfe_u32 v74, v78, 16, 1
	v_bfe_u32 v73, v68, 16, 1
	v_add3_u32 v69, v69, v72, s27
	v_bfe_u32 v72, v66, 16, 1
	v_add3_u32 v74, v78, v74, s27
	v_add3_u32 v68, v68, v73, s27
	v_add3_u32 v66, v66, v72, s27
	v_lshrrev_b32_e32 v72, 16, v74
	v_bfe_u32 v75, v70, 16, 1
	v_and_or_b32 v68, v68, s6, v72
	v_mul_f32_e32 v72, 0xbfb8aa3b, v157
	v_add3_u32 v70, v70, v75, s27
	v_bfe_u32 v73, v67, 16, 1
	v_bfe_u32 v75, v79, 16, 1
	v_exp_f32_e32 v72, v72
	v_add3_u32 v75, v79, v75, s27
	v_add3_u32 v67, v67, v73, s27
	v_lshrrev_b32_e32 v66, 16, v66
	v_lshrrev_b32_e32 v67, 16, v67
	v_lshrrev_b32_e32 v73, 16, v75
	v_and_or_b32 v69, v69, s6, v73
	v_and_or_b32 v67, v71, s6, v67
	v_and_or_b32 v66, v70, s6, v66
	ds_write_b128 v166, v[66:69] offset:2112
	v_add_f32_e32 v68, 1.0, v72
	v_add_f32_e32 v66, -1.0, v68
	v_sub_f32_e32 v67, v66, v68
	v_add_f32_e32 v67, 1.0, v67
	v_sub_f32_e32 v66, v72, v66
	v_add_f32_e32 v69, v66, v67
	v_frexp_mant_f32_e32 v70, v68
	v_cvt_f64_f32_e32 v[66:67], v68
	s_mov_b32 s0, 0x3f2aaaab
	v_frexp_exp_i32_f64_e32 v66, v[66:67]
	v_cmp_gt_f32_e32 vcc, s0, v70
	s_mov_b32 s5, 0x3f317218
	v_mov_b32_e32 v85, 0x3ecc95a3
	v_subbrev_co_u32_e32 v66, vcc, 0, v66, vcc
	v_sub_u32_e32 v67, 0, v66
	v_ldexp_f32 v68, v68, v67
	v_ldexp_f32 v67, v69, v67
	v_add_f32_e32 v69, -1.0, v68
	v_add_f32_e32 v73, 1.0, v68
	v_add_f32_e32 v70, 1.0, v69
	v_add_f32_e32 v74, -1.0, v73
	v_sub_f32_e32 v70, v68, v70
	v_sub_f32_e32 v68, v68, v74
	v_add_f32_e32 v70, v67, v70
	v_add_f32_e32 v67, v67, v68
	v_add_f32_e32 v68, v73, v67
	v_rcp_f32_e32 v74, v68
	v_add_f32_e32 v71, v69, v70
	v_sub_f32_e32 v69, v71, v69
	v_sub_f32_e32 v69, v70, v69
	v_sub_f32_e32 v70, v68, v73
	v_sub_f32_e32 v67, v67, v70
	v_mul_f32_e32 v70, v71, v74
	v_mul_f32_e32 v73, v68, v70
	v_fma_f32 v75, v70, v68, -v73
	v_fmac_f32_e32 v75, v70, v67
	v_add_f32_e32 v76, v73, v75
	v_sub_f32_e32 v77, v71, v76
	v_sub_f32_e32 v71, v71, v77
	v_sub_f32_e32 v73, v76, v73
	v_sub_f32_e32 v71, v71, v76
	v_add_f32_e32 v69, v69, v71
	v_sub_f32_e32 v71, v73, v75
	v_add_f32_e32 v69, v71, v69
	v_add_f32_e32 v71, v77, v69
	v_mul_f32_e32 v73, v74, v71
	v_mul_f32_e32 v75, v68, v73
	v_fma_f32 v68, v73, v68, -v75
	v_fmac_f32_e32 v68, v73, v67
	v_sub_f32_e32 v67, v77, v71
	v_add_f32_e32 v67, v69, v67
	v_add_f32_e32 v69, v75, v68
	v_sub_f32_e32 v76, v71, v69
	v_sub_f32_e32 v71, v71, v76
	v_sub_f32_e32 v75, v69, v75
	v_sub_f32_e32 v69, v71, v69
; template <int MODE>
; __device__ __forceinline__ void lru_unit(const Args& a, LAS unsigned char* lds, int l, int tt) {
;     ...
;     for (int nt = 0; nt < 2; ++nt) { prm0[nt][2] = -8.0f * log1pf(__expf(-prm0[nt][2])); prm1[nt][2] = -8.0f * log1pf(__expf(-prm1[nt][2])); }
;     __syncthreads();
	v_add_f32_e32 v67, v67, v69
	v_sub_f32_e32 v68, v75, v68
	v_cvt_f32_i32_e32 v66, v66
	v_add_f32_e32 v67, v68, v67
	v_add_f32_e32 v68, v70, v73
	v_add_f32_e32 v67, v76, v67
	v_sub_f32_e32 v69, v68, v70
	v_mul_f32_e32 v67, v74, v67
	v_sub_f32_e32 v69, v73, v69
	v_add_f32_e32 v67, v69, v67
	v_mul_f32_e32 v73, 0x3f317218, v66
	v_add_f32_e32 v69, v68, v67
	v_fma_f32 v74, v66, s5, -v73
	v_mul_f32_e32 v70, v69, v69
	v_fmac_f32_e32 v74, 0xb102e308, v66
	v_sub_f32_e32 v66, v69, v68
	v_fmamk_f32 v71, v70, 0x3e9b6dac, v85
	v_sub_f32_e32 v66, v67, v66
	v_add_f32_e32 v67, v73, v74
	v_fmaak_f32 v71, v70, v71, 0x3f2aaada
	v_sub_f32_e32 v68, v67, v73
	v_ldexp_f32 v73, v69, 1
	v_mul_f32_e32 v69, v69, v70
	v_mul_f32_e32 v69, v69, v71
	v_add_f32_e32 v70, v73, v69
	v_sub_f32_e32 v71, v70, v73
	v_ldexp_f32 v66, v66, 1
	v_sub_f32_e32 v69, v69, v71
	v_add_f32_e32 v66, v66, v69
	v_add_f32_e32 v69, v70, v66
	v_sub_f32_e32 v70, v69, v70
	v_sub_f32_e32 v66, v66, v70
	v_add_f32_e32 v70, v67, v69
	v_sub_f32_e32 v71, v70, v67
	v_sub_f32_e32 v73, v70, v71
	v_sub_f32_e32 v68, v74, v68
	v_sub_f32_e32 v67, v67, v73
	v_sub_f32_e32 v69, v69, v71
	v_add_f32_e32 v67, v69, v67
	v_add_f32_e32 v69, v68, v66
	v_sub_f32_e32 v71, v69, v68
	v_sub_f32_e32 v73, v69, v71
	v_sub_f32_e32 v68, v68, v73
	v_sub_f32_e32 v66, v66, v71
	v_add_f32_e32 v67, v69, v67
	v_add_f32_e32 v66, v66, v68
	v_add_f32_e32 v68, v70, v67
	v_sub_f32_e32 v69, v68, v70
	v_sub_f32_e32 v67, v67, v69
	v_add_f32_e32 v66, v66, v67
	s_mov_b32 s1, 0x7f800000
	v_add_f32_e32 v66, v68, v66
	v_cmp_neq_f32_e32 vcc, s1, v72
	v_mov_b32_e32 v67, 0x7f800000
	s_mov_b32 s1, 0x33800000
	v_cndmask_b32_e32 v66, v67, v66, vcc
	v_cmp_ngt_f32_e32 vcc, -1.0, v72
	v_mov_b32_e32 v67, 0x7fc00000
	s_waitcnt lgkmcnt(0)
	v_cndmask_b32_e32 v66, v67, v66, vcc
	v_cmp_neq_f32_e32 vcc, -1.0, v72
	v_mov_b32_e32 v67, 0xff800000
	s_barrier
	v_cndmask_b32_e32 v66, v67, v66, vcc
	v_mul_f32_e32 v67, 0xbfb8aa3b, v156
	v_exp_f32_e32 v183, v67
	v_cmp_lt_f32_e64 vcc, |v72|, s1
	s_movk_i32 s28, 0x210
	s_nop 0
	v_cndmask_b32_e32 v66, v66, v72, vcc
	v_add_f32_e32 v68, 1.0, v183
	v_mul_f32_e32 v214, 0xc1000000, v66
	v_add_f32_e32 v66, -1.0, v68
	v_sub_f32_e32 v67, v66, v68
	v_add_f32_e32 v67, 1.0, v67
	v_sub_f32_e32 v66, v183, v66
	v_add_f32_e32 v69, v66, v67
	v_frexp_mant_f32_e32 v70, v68
	v_cvt_f64_f32_e32 v[66:67], v68
	v_frexp_exp_i32_f64_e32 v66, v[66:67]
	v_cmp_gt_f32_e32 vcc, s0, v70
	s_nop 1
	v_subbrev_co_u32_e32 v66, vcc, 0, v66, vcc
	v_sub_u32_e32 v67, 0, v66
	v_ldexp_f32 v68, v68, v67
	v_ldexp_f32 v67, v69, v67
	v_add_f32_e32 v69, -1.0, v68
	v_add_f32_e32 v72, 1.0, v68
	v_add_f32_e32 v70, 1.0, v69
	v_add_f32_e32 v73, -1.0, v72
	v_sub_f32_e32 v70, v68, v70
	v_sub_f32_e32 v68, v68, v73
	v_add_f32_e32 v70, v67, v70
	v_add_f32_e32 v67, v67, v68
	v_add_f32_e32 v68, v72, v67
	v_rcp_f32_e32 v73, v68
	v_add_f32_e32 v71, v69, v70
	v_sub_f32_e32 v69, v71, v69
	v_sub_f32_e32 v69, v70, v69
	v_sub_f32_e32 v70, v68, v72
	v_sub_f32_e32 v67, v67, v70
	v_mul_f32_e32 v70, v71, v73
	v_mul_f32_e32 v72, v68, v70
	v_fma_f32 v74, v70, v68, -v72
	v_fmac_f32_e32 v74, v70, v67
	v_add_f32_e32 v75, v72, v74
	v_sub_f32_e32 v76, v71, v75
	v_sub_f32_e32 v71, v71, v76
	v_sub_f32_e32 v72, v75, v72
	v_sub_f32_e32 v71, v71, v75
	v_add_f32_e32 v69, v69, v71
	v_sub_f32_e32 v71, v72, v74
	v_add_f32_e32 v69, v71, v69
	v_add_f32_e32 v71, v76, v69
	v_mul_f32_e32 v72, v73, v71
	v_mul_f32_e32 v74, v68, v72
	v_fma_f32 v68, v72, v68, -v74
	v_fmac_f32_e32 v68, v72, v67
	v_sub_f32_e32 v67, v76, v71
	v_add_f32_e32 v67, v69, v67
	v_add_f32_e32 v69, v74, v68
	v_sub_f32_e32 v75, v71, v69
	v_sub_f32_e32 v71, v71, v75
	v_sub_f32_e32 v74, v69, v74
	v_sub_f32_e32 v69, v71, v69
	v_add_f32_e32 v67, v67, v69
	v_sub_f32_e32 v68, v74, v68
	v_cvt_f32_i32_e32 v66, v66
	v_add_f32_e32 v67, v68, v67
	v_add_f32_e32 v68, v70, v72
	v_add_f32_e32 v67, v75, v67
	v_sub_f32_e32 v69, v68, v70
	v_mul_f32_e32 v67, v73, v67
	v_sub_f32_e32 v69, v72, v69
	v_add_f32_e32 v67, v69, v67
	v_mul_f32_e32 v194, 0x3f317218, v66
	v_add_f32_e32 v191, v68, v67
	v_fma_f32 v195, v66, s5, -v194
	v_fmac_f32_e32 v195, 0xb102e308, v66
	v_sub_f32_e32 v66, v191, v68
	v_sub_f32_e32 v66, v67, v66
	v_mul_f32_e32 v67, 0xbfb8aa3b, v155
	v_exp_f32_e32 v76, v67
	v_ldexp_f32 v196, v66, 1
	v_mul_f32_e32 v192, v191, v191
	v_fmamk_f32 v69, v192, 0x3e9b6dac, v85
	v_add_f32_e32 v68, 1.0, v76
	v_add_f32_e32 v66, -1.0, v68
	v_sub_f32_e32 v67, v66, v68
	v_add_f32_e32 v67, 1.0, v67
	v_sub_f32_e32 v66, v76, v66
	v_fmaak_f32 v193, v192, v69, 0x3f2aaada
	v_add_f32_e32 v69, v66, v67
	v_frexp_mant_f32_e32 v70, v68
	v_cvt_f64_f32_e32 v[66:67], v68
	v_frexp_exp_i32_f64_e32 v66, v[66:67]
	v_cmp_gt_f32_e32 vcc, s0, v70
	v_ldexp_f32 v197, v191, 1
	s_nop 0
	v_subbrev_co_u32_e32 v66, vcc, 0, v66, vcc
	v_sub_u32_e32 v67, 0, v66
	v_ldexp_f32 v68, v68, v67
	v_ldexp_f32 v67, v69, v67
	v_add_f32_e32 v69, -1.0, v68
	v_add_f32_e32 v72, 1.0, v68
	v_add_f32_e32 v70, 1.0, v69
	v_add_f32_e32 v73, -1.0, v72
	v_sub_f32_e32 v70, v68, v70
	v_sub_f32_e32 v68, v68, v73
	v_add_f32_e32 v70, v67, v70
	v_add_f32_e32 v67, v67, v68
	v_add_f32_e32 v68, v72, v67
	v_rcp_f32_e32 v73, v68
	v_add_f32_e32 v71, v69, v70
	v_sub_f32_e32 v69, v71, v69
	v_sub_f32_e32 v69, v70, v69
	v_sub_f32_e32 v70, v68, v72
	v_sub_f32_e32 v67, v67, v70
	v_mul_f32_e32 v70, v71, v73
	v_mul_f32_e32 v72, v68, v70
	v_fma_f32 v74, v70, v68, -v72
	v_fmac_f32_e32 v74, v70, v67
	v_add_f32_e32 v75, v72, v74
	v_sub_f32_e32 v77, v71, v75
	v_sub_f32_e32 v71, v71, v77
	v_sub_f32_e32 v72, v75, v72
	v_sub_f32_e32 v71, v71, v75
	v_add_f32_e32 v69, v69, v71
	v_sub_f32_e32 v71, v72, v74
	v_add_f32_e32 v69, v71, v69
	v_add_f32_e32 v71, v77, v69
; #define LAS __attribute__((address_space(3)))
; __device__ __forceinline__ float fsig(float x) { return frcp(1.0f + __expf(-x)); }
; template <int DIR, int MODE>
; __device__ __forceinline__ void lru_pass(const Args& a, const LAS bf16_t* cxb, LAS bf16_t* gyb, const LAS float* carry, const bf16x8 (&Bw)[2][2][2], const float (&prm)[2][3], int l, int tt, float (&hf)[8][2][4]) {
;     ...
;     for (int mi = 0; mi < 8; ++mi) {
;         const int m = DIR ? 7 - mi : mi;
;         bf16x8 Af[2];
; #pragma unroll
;         for (int ks = 0; ks < 2; ++ks) Af[ks] = *(const LAS bf16x8*)(cxb + (m * 16 + fr) * CXS + 64 * h + 32 * ks + 8 * fq);
; #pragma unroll
;         for (int nt = 0; nt < 2; ++nt) {
;             f32x4 pr = (f32x4){0.f, 0.f, 0.f, 0.f}, pi = (f32x4){0.f, 0.f, 0.f, 0.f};
; #pragma unroll
;             for (int ks = 0; ks < 2; ++ks) { pr = __builtin_amdgcn_mfma_f32_16x16x32_bf16(Af[ks], Bw[0][nt][ks], pr, 0, 0, 0); pi = __builtin_amdgcn_mfma_f32_16x16x32_bf16(Af[ks], Bw[1][nt][ks], pi, 0, 0, 0); }
;             float av[4], bv[4];
; #pragma unroll
;             for (int reg = 0; reg < 4; ++reg) {
;                 const int tok = m * 16 + 4 * fq + reg;
;                 const float x = bf2f(cxb[tok * CXS + cc[nt]]);
;                 const float r = fsig(pr[reg] + ba[nt]), ig = fsig(pi[reg] + bxv[nt]);
;                 const float aa = __expf(k8[nt] * r);
;                 av[reg] = aa; bv[reg] = __builtin_amdgcn_sqrtf(fmaxf(1.0f - aa * aa, 0.f)) * ig * x;
;             }
;             float cum[4], hl[4];
;             if (DIR == 0) { cum[0] = av[0]; hl[0] = bv[0];
; #pragma unroll
;                 for (int reg = 1; reg < 4; ++reg) { cum[reg] = cum[reg - 1] * av[reg]; hl[reg] = av[reg] * hl[reg - 1] + bv[reg]; } }
; template <int MODE>
; __device__ __forceinline__ void lru_unit(const Args& a, LAS unsigned char* lds, int l, int tt) {
;     ...
;     for (int nt = 0; nt < 2; ++nt) { prm0[nt][2] = -8.0f * log1pf(__expf(-prm0[nt][2])); prm1[nt][2] = -8.0f * log1pf(__expf(-prm1[nt][2])); }
	v_mul_f32_e32 v72, v73, v71
	v_mul_f32_e32 v74, v68, v72
	v_fma_f32 v68, v72, v68, -v74
	v_fmac_f32_e32 v68, v72, v67
	v_sub_f32_e32 v67, v77, v71
	v_add_f32_e32 v67, v69, v67
	v_add_f32_e32 v69, v74, v68
	v_sub_f32_e32 v75, v71, v69
	v_sub_f32_e32 v71, v71, v75
	v_sub_f32_e32 v74, v69, v74
	v_sub_f32_e32 v69, v71, v69
	v_add_f32_e32 v67, v67, v69
	v_sub_f32_e32 v68, v74, v68
	v_cvt_f32_i32_e32 v66, v66
	v_add_f32_e32 v67, v68, v67
	v_add_f32_e32 v68, v70, v72
	v_add_f32_e32 v67, v75, v67
	v_sub_f32_e32 v69, v68, v70
	v_mul_f32_e32 v67, v73, v67
	v_sub_f32_e32 v69, v72, v69
	v_add_f32_e32 v67, v69, v67
	v_mul_f32_e32 v81, 0x3f317218, v66
	v_add_f32_e32 v78, v68, v67
	v_fma_f32 v82, v66, s5, -v81
	v_fmac_f32_e32 v82, 0xb102e308, v66
	v_sub_f32_e32 v66, v78, v68
	v_sub_f32_e32 v66, v67, v66
	v_mul_f32_e32 v67, 0xbfb8aa3b, v154
	v_exp_f32_e32 v181, v67
	v_ldexp_f32 v83, v66, 1
	v_mul_f32_e32 v79, v78, v78
	v_fmamk_f32 v69, v79, 0x3e9b6dac, v85
	v_add_f32_e32 v68, 1.0, v181
	v_add_f32_e32 v66, -1.0, v68
	v_sub_f32_e32 v67, v66, v68
	v_add_f32_e32 v67, 1.0, v67
	v_sub_f32_e32 v66, v181, v66
	v_fmaak_f32 v80, v79, v69, 0x3f2aaada
	v_add_f32_e32 v69, v66, v67
	v_frexp_mant_f32_e32 v70, v68
	v_cvt_f64_f32_e32 v[66:67], v68
	v_frexp_exp_i32_f64_e32 v66, v[66:67]
	v_cmp_gt_f32_e32 vcc, s0, v70
	v_ldexp_f32 v92, v78, 1
	v_and_b32_e32 v77, 0x7fffffff, v76
	v_subbrev_co_u32_e32 v66, vcc, 0, v66, vcc
	v_sub_u32_e32 v67, 0, v66
	v_ldexp_f32 v68, v68, v67
	v_ldexp_f32 v67, v69, v67
	v_add_f32_e32 v69, -1.0, v68
	v_add_f32_e32 v72, 1.0, v68
	v_add_f32_e32 v70, 1.0, v69
	v_add_f32_e32 v73, -1.0, v72
	v_sub_f32_e32 v70, v68, v70
	v_sub_f32_e32 v68, v68, v73
	v_add_f32_e32 v70, v67, v70
	v_add_f32_e32 v67, v67, v68
	v_add_f32_e32 v68, v72, v67
	v_rcp_f32_e32 v73, v68
	v_add_f32_e32 v71, v69, v70
	v_sub_f32_e32 v69, v71, v69
	v_sub_f32_e32 v69, v70, v69
	v_sub_f32_e32 v70, v68, v72
	v_sub_f32_e32 v67, v67, v70
	v_mul_f32_e32 v70, v71, v73
	v_mul_f32_e32 v72, v68, v70
	v_fma_f32 v74, v70, v68, -v72
	v_fmac_f32_e32 v74, v70, v67
	v_add_f32_e32 v75, v72, v74
	v_sub_f32_e32 v84, v71, v75
	v_sub_f32_e32 v71, v71, v84
	v_sub_f32_e32 v72, v75, v72
	v_sub_f32_e32 v71, v71, v75
	v_add_f32_e32 v69, v69, v71
	v_sub_f32_e32 v71, v72, v74
	v_add_f32_e32 v69, v71, v69
	v_add_f32_e32 v71, v84, v69
	v_mul_f32_e32 v72, v73, v71
	v_mul_f32_e32 v74, v68, v72
	v_fma_f32 v68, v72, v68, -v74
	v_fmac_f32_e32 v68, v72, v67
	v_sub_f32_e32 v67, v84, v71
	v_add_f32_e32 v67, v69, v67
	v_add_f32_e32 v69, v74, v68
	v_sub_f32_e32 v75, v71, v69
	v_sub_f32_e32 v71, v71, v75
	v_sub_f32_e32 v74, v69, v74
	v_sub_f32_e32 v69, v71, v69
	v_add_f32_e32 v67, v67, v69
	v_sub_f32_e32 v68, v74, v68
	v_add_f32_e32 v67, v68, v67
	v_add_f32_e32 v68, v70, v72
	v_add_f32_e32 v67, v75, v67
	v_sub_f32_e32 v69, v68, v70
	v_mul_f32_e32 v67, v73, v67
	v_sub_f32_e32 v69, v72, v69
	v_add_f32_e32 v67, v69, v67
	v_mov_b32_e32 v69, v0
	v_cvt_f32_i32_e32 v66, v66
	v_readfirstlane_b32 s0, v69
	s_bfe_u32 s1, s0, 0x20006
	s_lshl_b32 s4, s1, 7
	v_bfe_u32 v200, v69, 4, 2
	s_add_i32 s4, s4, 0
	v_and_b32_e32 v75, 15, v69
	v_lshl_add_u32 v93, v200, 4, s4
	v_mad_u32_u24 v69, v75, s29, v93
	ds_read_b128 v[70:73], v69
	v_add_f32_e32 v184, v68, v67
	v_mul_f32_e32 v187, 0x3f317218, v66
	v_mul_f32_e32 v185, v184, v184
	v_fma_f32 v188, v66, s5, -v187
	v_fmamk_f32 v74, v185, 0x3e9b6dac, v85
	v_fmac_f32_e32 v188, 0xb102e308, v66
	v_sub_f32_e32 v66, v184, v68
	v_fmaak_f32 v186, v185, v74, 0x3f2aaada
	v_sub_f32_e32 v74, v67, v66
	ds_read_b128 v[66:69], v69 offset:64
	s_waitcnt lgkmcnt(1)
	v_mfma_f32_16x16x32_bf16 v[84:87], v[70:73], v[50:53], 0
	s_ashr_i32 s0, s0, 3
	s_lshl_b32 s1, s1, 6
	s_andn2_b32 s0, s0, 31
	s_waitcnt lgkmcnt(0)
	v_mfma_f32_16x16x32_bf16 v[94:97], v[66:69], v[54:57], v[84:87]
	s_nop 2
	v_and_b32_e32 v84, 64, v227
	v_or_b32_e32 v98, v84, v75
	s_add_i32 s1, s1, s0
	s_nop 1
	v_add_f32_e32 v84, v171, v94
	v_mul_f32_e32 v84, 0xbfb8aa3b, v84
	v_exp_f32_e32 v84, v84
	v_mfma_f32_16x16x32_bf16 v[88:91], v[70:73], v[58:61], 0
	v_ldexp_f32 v189, v74, 1
	v_or_b32_e32 v74, s1, v75
	v_add_f32_e32 v84, 1.0, v84
	v_rcp_f32_e32 v84, v84
	v_mfma_f32_16x16x32_bf16 v[88:91], v[66:69], v[62:65], v[88:91]
	v_lshlrev_b32_e32 v85, 1, v74
	v_mul_u32_u24_e32 v86, 0x840, v200
	v_mul_f32_e32 v84, v214, v84
	v_add3_u32 v213, 0, v85, v86
	v_mul_f32_e32 v84, 0x3fb8aa3b, v84
	s_nop 2
	v_add_f32_e32 v85, v170, v88
	v_mul_f32_e32 v85, 0xbfb8aa3b, v85
	v_exp_f32_e32 v87, v84
	v_exp_f32_e32 v85, v85
	ds_read_u16 v84, v213
	v_add_f32_e32 v88, v170, v89
	v_fma_f32 v86, -v87, v87, 1.0
	v_add_f32_e32 v85, 1.0, v85
	v_max_f32_e32 v86, 0, v86
	v_rcp_f32_e32 v85, v85
	v_sqrt_f32_e32 v86, v86
	s_waitcnt lgkmcnt(0)
	v_lshlrev_b32_e32 v84, 16, v84
	v_mul_f32_e32 v88, 0xbfb8aa3b, v88
	v_exp_f32_e32 v89, v88
	v_mul_f32_e32 v85, v85, v86
	v_add_f32_e32 v86, v171, v95
	v_mul_f32_e32 v86, 0xbfb8aa3b, v86
	v_exp_f32_e32 v86, v86
	v_mul_f32_e32 v88, v85, v84
	v_add_f32_e32 v84, 1.0, v89
	v_add_f32_e32 v90, v170, v90
	v_add_f32_e32 v86, 1.0, v86
	v_rcp_f32_e32 v86, v86
	v_mul_f32_e32 v90, 0xbfb8aa3b, v90
	v_rcp_f32_e32 v84, v84
	v_exp_f32_e32 v90, v90
	v_mul_f32_e32 v85, v214, v86
	v_add_f32_e32 v86, v171, v96
	v_mul_f32_e32 v86, 0xbfb8aa3b, v86
	v_exp_f32_e32 v86, v86
	v_mul_f32_e32 v85, 0x3fb8aa3b, v85
	v_exp_f32_e32 v85, v85
	v_add_f32_e32 v91, v170, v91
	v_add_f32_e32 v86, 1.0, v86
	v_rcp_f32_e32 v86, v86
	v_fma_f32 v89, -v85, v85, 1.0
	v_max_f32_e32 v89, 0, v89
	v_sqrt_f32_e32 v89, v89
	v_mul_f32_e32 v86, v214, v86
	v_mul_f32_e32 v86, 0x3fb8aa3b, v86
	v_exp_f32_e32 v95, v86
	v_add_f32_e32 v86, v171, v97
	v_mul_f32_e32 v86, 0xbfb8aa3b, v86
	v_exp_f32_e32 v86, v86
	v_mul_f32_e32 v91, 0xbfb8aa3b, v91
	v_mul_f32_e32 v84, v84, v89
	v_add_f32_e32 v89, 1.0, v90
	v_add_f32_e32 v86, 1.0, v86
	v_rcp_f32_e32 v86, v86
	v_fma_f32 v90, -v95, v95, 1.0
	v_exp_f32_e32 v91, v91
	v_max_f32_e32 v90, 0, v90
	v_mul_f32_e32 v86, v214, v86
	v_mul_f32_e32 v86, 0x3fb8aa3b, v86
	v_exp_f32_e32 v96, v86
	ds_read_u16 v94, v213 offset:528
	ds_read_u16 v99, v213 offset:1056
	ds_read_u16 v100, v213 offset:1584
	v_rcp_f32_e32 v89, v89
	v_sqrt_f32_e32 v86, v90
	v_add_f32_e32 v90, 1.0, v91
	v_fma_f32 v91, -v96, v96, 1.0
	v_max_f32_e32 v91, 0, v91
	s_waitcnt lgkmcnt(2)
; #define LAS __attribute__((address_space(3)))
; __device__ __forceinline__ float fsig(float x) { return frcp(1.0f + __expf(-x)); }
; template <int DIR, int MODE>
; __device__ __forceinline__ void lru_pass(const Args& a, const LAS bf16_t* cxb, LAS bf16_t* gyb, const LAS float* carry, const bf16x8 (&Bw)[2][2][2], const float (&prm)[2][3], int l, int tt, float (&hf)[8][2][4]) {
;     ...
;         C[nt] = MODE == 1 ? carry[DIR * 256 + c] : 0.f; At[nt] = 1.f;
;     }
; #pragma unroll
;     for (int mi = 0; mi < 8; ++mi) {
;         const int m = DIR ? 7 - mi : mi;
;         bf16x8 Af[2];
; #pragma unroll
;         for (int ks = 0; ks < 2; ++ks) Af[ks] = *(const LAS bf16x8*)(cxb + (m * 16 + fr) * CXS + 64 * h + 32 * ks + 8 * fq);
; #pragma unroll
;         for (int nt = 0; nt < 2; ++nt) {
;             f32x4 pr = (f32x4){0.f, 0.f, 0.f, 0.f}, pi = (f32x4){0.f, 0.f, 0.f, 0.f};
; #pragma unroll
;             for (int ks = 0; ks < 2; ++ks) { pr = __builtin_amdgcn_mfma_f32_16x16x32_bf16(Af[ks], Bw[0][nt][ks], pr, 0, 0, 0); pi = __builtin_amdgcn_mfma_f32_16x16x32_bf16(Af[ks], Bw[1][nt][ks], pi, 0, 0, 0); }
;             float av[4], bv[4];
; #pragma unroll
;             for (int reg = 0; reg < 4; ++reg) {
;                 const int tok = m * 16 + 4 * fq + reg;
;                 const float x = bf2f(cxb[tok * CXS + cc[nt]]);
;                 const float r = fsig(pr[reg] + ba[nt]), ig = fsig(pi[reg] + bxv[nt]);
;                 const float aa = __expf(k8[nt] * r);
;                 av[reg] = aa; bv[reg] = __builtin_amdgcn_sqrtf(fmaxf(1.0f - aa * aa, 0.f)) * ig * x;
;             }
;             float cum[4], hl[4];
;             if (DIR == 0) { cum[0] = av[0]; hl[0] = bv[0];
; #pragma unroll
;                 for (int reg = 1; reg < 4; ++reg) { cum[reg] = cum[reg - 1] * av[reg]; hl[reg] = av[reg] * hl[reg - 1] + bv[reg]; } }
;             else { cum[3] = av[3]; hl[3] = bv[3];
; #pragma unroll
;     ...
;             const float A4 = DIR ? cum[0] : cum[3], H4 = DIR ? hl[0] : hl[3];
;             float Aq[4], Hq[4];
; #pragma unroll
;             for (int q = 0; q < 4; ++q) { Aq[q] = __shfl(A4, fr + 16 * q); Hq[q] = __shfl(H4, fr + 16 * q); }
;             float hin;
;             if (DIR == 0) { const float s0 = C[nt], s1 = Aq[0] * s0 + Hq[0], s2 = Aq[1] * s1 + Hq[1], s3 = Aq[2] * s2 + Hq[2]; C[nt] = Aq[3] * s3 + Hq[3]; hin = fq == 0 ? s0 : (fq == 1 ? s1 : (fq == 2 ? s2 : s3)); }
	v_lshlrev_b32_e32 v94, 16, v94
	v_rcp_f32_e32 v90, v90
	v_sqrt_f32_e32 v91, v91
	s_waitcnt lgkmcnt(1)
	v_lshlrev_b32_e32 v97, 16, v99
	v_mul_f32_e32 v99, v89, v86
	v_mul_f32_e32 v86, v85, v88
	v_fmac_f32_e32 v86, v84, v94
	v_mul_f32_e32 v89, v85, v87
	v_mul_f32_e32 v85, v95, v86
	v_fmac_f32_e32 v85, v99, v97
	s_waitcnt lgkmcnt(0)
	v_lshlrev_b32_e32 v100, 16, v100
	v_mul_f32_e32 v101, v90, v91
	v_mul_f32_e32 v90, v95, v89
	v_mul_f32_e32 v84, v96, v85
	v_lshl_add_u32 v74, v74, 2, 0
	v_mul_f32_e32 v91, v96, v90
	v_fmac_f32_e32 v84, v101, v100
	v_lshlrev_b32_e32 v210, 2, v98
	v_add_u32_e32 v74, 0x21000, v74
	s_nop 0
	s_nop 0
	v_mul_u32_u24_e32 v96, 0x210, v75
	ds_read2_b32 v[74:75], v74 offset1:16
	s_nop 0
	s_nop 0
	s_nop 0
	s_nop 0
	v_mov_b32_e32 v99, v91
	v_mov_b32_e32 v100, v91
	s_nop 1
	v_permlane16_swap_b32_e32 v99, v100
	s_nop 1
	v_mov_b32_e32 v102, v99
	v_mov_b32_e32 v95, v100
	s_nop 1
	v_permlane32_swap_b32_e32 v99, v102
	v_permlane32_swap_b32_e32 v100, v95
	s_nop 1
	v_mov_b32_e32 v97, v84
	v_mov_b32_e32 v98, v84
	s_nop 1
	v_permlane16_swap_b32_e32 v97, v98
	s_nop 1
	v_mov_b32_e32 v94, v97
	v_mov_b32_e32 v101, v98
	s_nop 1
	v_permlane32_swap_b32_e32 v97, v94
	v_permlane32_swap_b32_e32 v98, v101
	s_nop 1
	s_waitcnt lgkmcnt(0)
	v_fmac_f32_e32 v97, v74, v99
	s_waitcnt lgkmcnt(0)
	v_fmac_f32_e32 v98, v97, v100
	v_ldexp_f32 v190, v184, 1
	v_or_b32_e32 v212, 64, v210
	v_or_b32_e32 v211, 0x80, v210
	v_or_b32_e32 v218, 0xc0, v210
	v_cmp_eq_u32_e32 vcc, 2, v200
	s_waitcnt lgkmcnt(0)
	v_fmac_f32_e32 v94, v98, v102
	v_cmp_lt_i32_e64 s[0:1], 0, v200
	s_and_saveexec_b64 s[4:5], s[0:1]
	s_cbranch_execz .LBB0_551
	v_cmp_ne_u32_e64 s[0:1], 1, v200
	s_and_saveexec_b64 s[34:35], s[0:1]
	s_xor_b64 s[0:1], exec, s[34:35]
	v_cndmask_b32_e32 v74, v94, v98, vcc
	s_andn2_saveexec_b64 s[0:1], s[0:1]
	v_mov_b32_e32 v74, v97
	s_or_b64 exec, exec, s[0:1]
.LBB0_551:
	s_or_b64 exec, exec, s[4:5]
	v_mul_f32_e32 v78, v78, v79
	v_mul_f32_e32 v78, v78, v80
	v_add_f32_e32 v79, v92, v78
	v_sub_f32_e32 v80, v79, v92
	v_sub_f32_e32 v78, v78, v80
	v_add_f32_e32 v78, v83, v78
	v_add_f32_e32 v80, v79, v78
	v_add_f32_e32 v97, v81, v82
	v_sub_f32_e32 v79, v80, v79
	v_sub_f32_e32 v81, v97, v81
	v_sub_f32_e32 v78, v78, v79
	v_add_f32_e32 v79, v97, v80
	v_sub_f32_e32 v81, v82, v81
	v_sub_f32_e32 v82, v79, v97
	v_sub_f32_e32 v83, v79, v82
	v_sub_f32_e32 v83, v97, v83
	v_sub_f32_e32 v80, v80, v82
	v_add_f32_e32 v82, v81, v78
	v_add_f32_e32 v80, v80, v83
	v_sub_f32_e32 v83, v82, v81
	v_sub_f32_e32 v92, v82, v83
	v_sub_f32_e32 v81, v81, v92
	v_sub_f32_e32 v78, v78, v83
	v_add_f32_e32 v80, v82, v80
	v_add_f32_e32 v78, v78, v81
	v_add_f32_e32 v81, v79, v80
	v_sub_f32_e32 v79, v81, v79
	v_sub_f32_e32 v79, v80, v79
	v_add_f32_e32 v78, v78, v79
	s_mov_b32 s0, 0x7f800000
	v_add_f32_e32 v82, v81, v78
	v_cmp_neq_f32_e64 s[0:1], s0, v76
	v_mov_b32_e32 v83, 0x7f800000
	v_mfma_f32_16x16x32_bf16 v[78:81], v[70:73], v[34:37], 0
	v_cndmask_b32_e64 v82, v83, v82, s[0:1]
	v_cmp_ngt_f32_e64 s[0:1], -1.0, v76
	v_mov_b32_e32 v83, 0x7fc00000
	v_mfma_f32_16x16x32_bf16 v[70:73], v[70:73], v[42:45], 0
	v_cndmask_b32_e64 v82, v83, v82, s[0:1]
	v_cmp_neq_f32_e64 s[0:1], -1.0, v76
	v_mov_b32_e32 v83, 0xff800000
	s_nop 0
	v_cndmask_b32_e64 v82, v83, v82, s[0:1]
	s_mov_b32 s0, 0x33800000
	v_cmp_gt_f32_e64 s[0:1], s0, v77
	s_nop 1
	v_cndmask_b32_e64 v76, v82, v76, s[0:1]
	v_mfma_f32_16x16x32_bf16 v[80:83], v[66:69], v[38:41], v[78:81]
	v_mul_f32_e32 v215, 0xc1000000, v76
	v_cmp_lt_i32_e64 s[0:1], 0, v200
	v_mfma_f32_16x16x32_bf16 v[66:69], v[66:69], v[46:49], v[70:73]
	s_nop 4
	v_add_f32_e32 v77, v169, v80
	v_mul_f32_e32 v77, 0xbfb8aa3b, v77
	v_exp_f32_e32 v77, v77
	v_add_f32_e32 v66, v168, v66
	v_mul_f32_e32 v66, 0xbfb8aa3b, v66
	v_exp_f32_e32 v66, v66
	v_add_f32_e32 v70, 1.0, v77
	v_rcp_f32_e32 v70, v70
	v_add_f32_e32 v67, v168, v67
	v_add_f32_e32 v66, 1.0, v66
	v_rcp_f32_e32 v66, v66
	v_mul_f32_e32 v70, v215, v70
	v_mul_f32_e32 v70, 0x3fb8aa3b, v70
	v_exp_f32_e32 v79, v70
	ds_read_u16 v70, v213 offset:32
	v_mul_f32_e32 v67, 0xbfb8aa3b, v67
	v_exp_f32_e32 v67, v67
	v_fma_f32 v71, -v79, v79, 1.0
	v_max_f32_e32 v71, 0, v71
	v_sqrt_f32_e32 v71, v71
	s_waitcnt lgkmcnt(0)
	v_lshlrev_b32_e32 v70, 16, v70
	v_add_f32_e32 v69, v168, v69
	v_mul_f32_e32 v69, 0xbfb8aa3b, v69
	v_mul_f32_e32 v66, v66, v71
	v_add_f32_e32 v71, v169, v81
	v_mul_f32_e32 v71, 0xbfb8aa3b, v71
	v_exp_f32_e32 v71, v71
	v_mul_f32_e32 v226, v66, v70
	v_add_f32_e32 v66, 1.0, v67
	v_rcp_f32_e32 v66, v66
	v_add_f32_e32 v71, 1.0, v71
	v_rcp_f32_e32 v71, v71
	v_add_f32_e32 v70, v169, v82
	v_mul_f32_e32 v70, 0xbfb8aa3b, v70
	v_exp_f32_e32 v70, v70
	v_mul_f32_e32 v67, v215, v71
	v_mul_f32_e32 v67, 0x3fb8aa3b, v67
	v_exp_f32_e32 v67, v67
	v_add_f32_e32 v70, 1.0, v70
	v_rcp_f32_e32 v70, v70
	v_add_f32_e32 v68, v168, v68
	v_fma_f32 v71, -v67, v67, 1.0
	v_max_f32_e32 v71, 0, v71
	v_sqrt_f32_e32 v71, v71
	v_mul_f32_e32 v70, v215, v70
	v_mul_f32_e32 v70, 0x3fb8aa3b, v70
	v_exp_f32_e32 v69, v69
	v_mul_f32_e32 v66, v66, v71
	v_add_f32_e32 v71, v169, v83
	v_mul_f32_e32 v71, 0xbfb8aa3b, v71
	v_exp_f32_e32 v71, v71
	v_mul_f32_e32 v68, 0xbfb8aa3b, v68
	v_exp_f32_e32 v70, v70
	v_exp_f32_e32 v68, v68
	v_add_f32_e32 v71, 1.0, v71
	v_rcp_f32_e32 v71, v71
	v_add_f32_e32 v69, 1.0, v69
	v_fma_f32 v77, -v70, v70, 1.0
	v_rcp_f32_e32 v69, v69
	v_mul_f32_e32 v71, v215, v71
	v_mul_f32_e32 v71, 0x3fb8aa3b, v71
	v_exp_f32_e32 v71, v71
	ds_read_u16 v72, v213 offset:560
	ds_read_u16 v73, v213 offset:1088
	ds_read_u16 v76, v213 offset:1616
	v_add_f32_e32 v68, 1.0, v68
	v_max_f32_e32 v77, 0, v77
	v_fma_f32 v78, -v71, v71, 1.0
	v_max_f32_e32 v78, 0, v78
	v_sqrt_f32_e32 v78, v78
	v_rcp_f32_e32 v68, v68
	v_sqrt_f32_e32 v77, v77
	s_waitcnt lgkmcnt(2)
	v_lshlrev_b32_e32 v72, 16, v72
	v_mul_f32_e32 v69, v69, v78
	v_mul_f32_e32 v78, v67, v226
	v_fmac_f32_e32 v78, v66, v72
	s_waitcnt lgkmcnt(1)
	v_lshlrev_b32_e32 v73, 16, v73
	v_mul_f32_e32 v68, v68, v77
	v_mul_f32_e32 v77, v70, v78
	v_mul_f32_e32 v244, v67, v79
	v_fmac_f32_e32 v77, v68, v73
	s_waitcnt lgkmcnt(0)
	v_lshlrev_b32_e32 v80, 16, v76
	v_mul_f32_e32 v245, v70, v244
	v_mul_f32_e32 v76, v71, v77
	v_mul_f32_e32 v237, v71, v245
	v_fmac_f32_e32 v76, v69, v80
	s_nop 0
	s_nop 0
	s_nop 0
	s_nop 0
	s_nop 0
	s_nop 0
	v_mov_b32_e32 v68, v237
	v_mov_b32_e32 v69, v237
	s_nop 1
	v_permlane16_swap_b32_e32 v68, v69
	s_nop 1
	v_mov_b32_e32 v70, v68
	v_mov_b32_e32 v114, v69
	s_nop 1
	v_permlane32_swap_b32_e32 v68, v70
	v_permlane32_swap_b32_e32 v69, v114
	s_nop 1
	v_mov_b32_e32 v66, v76
	v_mov_b32_e32 v67, v76
	s_nop 1
	v_permlane16_swap_b32_e32 v66, v67
	s_nop 1
	v_mov_b32_e32 v112, v66
	v_mov_b32_e32 v92, v67
	s_nop 1
	v_permlane32_swap_b32_e32 v66, v112
	v_permlane32_swap_b32_e32 v67, v92
	s_nop 1
	s_waitcnt lgkmcnt(0)
	v_fmac_f32_e32 v66, v75, v68
	s_waitcnt lgkmcnt(0)
	v_fmac_f32_e32 v67, v66, v69
	s_waitcnt lgkmcnt(0)
	v_fmac_f32_e32 v112, v67, v70
	s_and_saveexec_b64 s[4:5], s[0:1]
	s_cbranch_execz .LBB0_557
; template <int DIR, int MODE>
; __device__ __forceinline__ void lru_pass(const Args& a, const LAS bf16_t* cxb, LAS bf16_t* gyb, const LAS float* carry, const bf16x8 (&Bw)[2][2][2], const float (&prm)[2][3], int l, int tt, float (&hf)[8][2][4]) {
;     ...
;     for (int mi = 0; mi < 8; ++mi) {
;         const int m = DIR ? 7 - mi : mi;
;         bf16x8 Af[2];
; #pragma unroll
;         for (int ks = 0; ks < 2; ++ks) Af[ks] = *(const LAS bf16x8*)(cxb + (m * 16 + fr) * CXS + 64 * h + 32 * ks + 8 * fq);
; #pragma unroll
;         for (int nt = 0; nt < 2; ++nt) {
;             f32x4 pr = (f32x4){0.f, 0.f, 0.f, 0.f}, pi = (f32x4){0.f, 0.f, 0.f, 0.f};
; #pragma unroll
;             for (int ks = 0; ks < 2; ++ks) { pr = __builtin_amdgcn_mfma_f32_16x16x32_bf16(Af[ks], Bw[0][nt][ks], pr, 0, 0, 0); pi = __builtin_amdgcn_mfma_f32_16x16x32_bf16(Af[ks], Bw[1][nt][ks], pi, 0, 0, 0); }
;             float av[4], bv[4];
; #pragma unroll
;             for (int reg = 0; reg < 4; ++reg) {
;                 const int tok = m * 16 + 4 * fq + reg;
;                 const float x = bf2f(cxb[tok * CXS + cc[nt]]);
;                 const float r = fsig(pr[reg] + ba[nt]), ig = fsig(pi[reg] + bxv[nt]);
;                 const float aa = __expf(k8[nt] * r);
;                 av[reg] = aa; bv[reg] = __builtin_amdgcn_sqrtf(fmaxf(1.0f - aa * aa, 0.f)) * ig * x;
;             }
;             float cum[4], hl[4];
;             if (DIR == 0) { cum[0] = av[0]; hl[0] = bv[0];
; #pragma unroll
;                 for (int reg = 1; reg < 4; ++reg) { cum[reg] = cum[reg - 1] * av[reg]; hl[reg] = av[reg] * hl[reg - 1] + bv[reg]; } }
;             else { cum[3] = av[3]; hl[3] = bv[3];
; #pragma unroll
;     ...
;             const float A4 = DIR ? cum[0] : cum[3], H4 = DIR ? hl[0] : hl[3];
;             float Aq[4], Hq[4];
; #pragma unroll
;             for (int q = 0; q < 4; ++q) { Aq[q] = __shfl(A4, fr + 16 * q); Hq[q] = __shfl(H4, fr + 16 * q); }
;             float hin;
;             if (DIR == 0) { const float s0 = C[nt], s1 = Aq[0] * s0 + Hq[0], s2 = Aq[1] * s1 + Hq[1], s3 = Aq[2] * s2 + Hq[2]; C[nt] = Aq[3] * s3 + Hq[3]; hin = fq == 0 ? s0 : (fq == 1 ? s1 : (fq == 2 ? s2 : s3)); }
;             else { const float s3 = C[nt], s2 = Aq[3] * s3 + Hq[3], s1 = Aq[2] * s2 + Hq[2], s0 = Aq[1] * s1 + Hq[1]; C[nt] = Aq[0] * s0 + Hq[0]; hin = fq == 3 ? s3 : (fq == 2 ? s2 : (fq == 1 ? s1 : s0)); }
	v_cmp_ne_u32_e64 s[0:1], 1, v200
	s_and_saveexec_b64 s[34:35], s[0:1]
	s_xor_b64 s[0:1], exec, s[34:35]
	v_cndmask_b32_e32 v75, v112, v67, vcc
	s_andn2_saveexec_b64 s[0:1], s[0:1]
	v_mov_b32_e32 v75, v66
	s_or_b64 exec, exec, s[0:1]
.LBB0_557:
	s_or_b64 exec, exec, s[4:5]
	v_add_u32_e32 v220, v93, v96
	ds_read_b128 v[70:73], v220 offset:8448
	ds_read_b128 v[66:69], v220 offset:8512
	ds_read_u16 v80, v213 offset:8448
	ds_read_u16 v81, v213 offset:8976
	ds_read_u16 v82, v213 offset:9504
	ds_read_u16 v83, v213 offset:10032
	v_fmac_f32_e32 v101, v94, v95
	s_waitcnt lgkmcnt(5)
	v_mfma_f32_16x16x32_bf16 v[96:99], v[70:73], v[50:53], 0
	s_waitcnt lgkmcnt(2)
	v_lshlrev_b32_e32 v81, 16, v81
	v_lshlrev_b32_e32 v80, 16, v80
	s_waitcnt lgkmcnt(1)
	v_lshlrev_b32_e32 v82, 16, v82
	v_mfma_f32_16x16x32_bf16 v[96:99], v[66:69], v[54:57], v[96:99]
	s_waitcnt lgkmcnt(0)
	v_lshlrev_b32_e32 v83, 16, v83
	v_cmp_lt_i32_e64 s[0:1], 0, v200
	v_mfma_f32_16x16x32_bf16 v[102:105], v[70:73], v[58:61], 0
	v_mfma_f32_16x16x32_bf16 v[106:109], v[66:69], v[62:65], v[102:105]
	s_nop 2
	v_add_f32_e32 v93, v171, v96
	v_mul_f32_e32 v93, 0xbfb8aa3b, v93
	v_exp_f32_e32 v93, v93
	v_add_f32_e32 v97, v171, v97
	v_mul_f32_e32 v97, 0xbfb8aa3b, v97
	v_add_f32_e32 v96, v170, v106
	v_add_f32_e32 v93, 1.0, v93
	v_rcp_f32_e32 v93, v93
	v_mul_f32_e32 v96, 0xbfb8aa3b, v96
	v_exp_f32_e32 v96, v96
	v_exp_f32_e32 v97, v97
	v_add_f32_e32 v100, v170, v107
	v_mul_f32_e32 v100, 0xbfb8aa3b, v100
	v_mul_f32_e32 v93, v214, v93
	v_exp_f32_e32 v100, v100
	v_mul_f32_e32 v93, 0x3fb8aa3b, v93
	v_add_f32_e32 v96, 1.0, v96
	v_add_f32_e32 v97, 1.0, v97
	v_exp_f32_e32 v106, v93
	v_rcp_f32_e32 v93, v96
	v_rcp_f32_e32 v96, v97
	v_add_f32_e32 v100, 1.0, v100
	v_rcp_f32_e32 v97, v100
	v_fma_f32 v100, -v106, v106, 1.0
	v_max_f32_e32 v100, 0, v100
	v_mul_f32_e32 v96, v214, v96
	v_sqrt_f32_e32 v100, v100
	v_mul_f32_e32 v96, 0x3fb8aa3b, v96
	v_exp_f32_e32 v96, v96
	v_mul_f32_e32 v93, v93, v100
	v_mul_f32_e32 v105, v93, v80
	v_add_f32_e32 v80, v171, v98
	v_fma_f32 v93, -v96, v96, 1.0
	v_add_f32_e32 v98, v170, v108
	v_max_f32_e32 v93, 0, v93
	v_mul_f32_e32 v98, 0xbfb8aa3b, v98
	v_sqrt_f32_e32 v93, v93
	v_exp_f32_e32 v98, v98
	v_mul_f32_e32 v80, 0xbfb8aa3b, v80
	v_exp_f32_e32 v80, v80
	v_mul_f32_e32 v93, v97, v93
	v_add_f32_e32 v97, 1.0, v98
	v_add_f32_e32 v98, v171, v99
	v_mul_f32_e32 v98, 0xbfb8aa3b, v98
	v_exp_f32_e32 v98, v98
	v_add_f32_e32 v80, 1.0, v80
	v_rcp_f32_e32 v80, v80
	v_add_f32_e32 v100, v170, v109
	v_add_f32_e32 v98, 1.0, v98
	v_rcp_f32_e32 v98, v98
	v_mul_f32_e32 v80, v214, v80
	v_mul_f32_e32 v80, 0x3fb8aa3b, v80
	v_exp_f32_e32 v80, v80
	v_mul_f32_e32 v98, v214, v98
	v_mul_f32_e32 v98, 0x3fb8aa3b, v98
	v_mul_f32_e32 v100, 0xbfb8aa3b, v100
	v_exp_f32_e32 v98, v98
	v_exp_f32_e32 v100, v100
	v_fma_f32 v99, -v80, v80, 1.0
	v_max_f32_e32 v99, 0, v99
	v_rcp_f32_e32 v97, v97
	v_sqrt_f32_e32 v99, v99
	v_fma_f32 v102, -v98, v98, 1.0
	v_add_f32_e32 v100, 1.0, v100
	v_max_f32_e32 v102, 0, v102
	v_rcp_f32_e32 v100, v100
	v_sqrt_f32_e32 v102, v102
	v_mul_f32_e32 v104, v96, v105
	v_fmac_f32_e32 v104, v93, v81
	v_mul_f32_e32 v97, v97, v99
	v_mul_f32_e32 v103, v80, v104
	v_mul_f32_e32 v107, v96, v106
	v_fmac_f32_e32 v103, v97, v82
	v_mul_f32_e32 v99, v100, v102
	v_mul_f32_e32 v108, v80, v107
	v_mul_f32_e32 v102, v98, v103
	v_mul_f32_e32 v109, v98, v108
	v_fmac_f32_e32 v102, v99, v83
	s_nop 0
	s_nop 0
	s_nop 0
	s_nop 0
	s_nop 0
	s_nop 0
	v_mov_b32_e32 v97, v109
	v_mov_b32_e32 v98, v109
	s_nop 1
	v_permlane16_swap_b32_e32 v97, v98
	s_nop 1
	v_mov_b32_e32 v99, v97
	v_mov_b32_e32 v113, v98
	s_nop 1
	v_permlane32_swap_b32_e32 v97, v99
	v_permlane32_swap_b32_e32 v98, v113
	s_nop 1
	v_mov_b32_e32 v93, v102
	v_mov_b32_e32 v96, v102
	s_nop 1
	v_permlane16_swap_b32_e32 v93, v96
	s_nop 1
	v_mov_b32_e32 v111, v93
	v_mov_b32_e32 v119, v96
	s_nop 1
	v_permlane32_swap_b32_e32 v93, v111
	v_permlane32_swap_b32_e32 v96, v119
	s_nop 1
	s_waitcnt lgkmcnt(0)
	v_fmac_f32_e32 v93, v101, v97
	s_waitcnt lgkmcnt(0)
	v_fmac_f32_e32 v96, v93, v98
	s_waitcnt lgkmcnt(0)
	v_fmac_f32_e32 v111, v96, v99
	s_and_saveexec_b64 s[4:5], s[0:1]
	s_cbranch_execz .LBB0_563
	v_cmp_ne_u32_e64 s[0:1], 1, v200
	s_and_saveexec_b64 s[34:35], s[0:1]
	s_xor_b64 s[0:1], exec, s[34:35]
	v_cndmask_b32_e32 v101, v111, v96, vcc
	s_andn2_saveexec_b64 s[0:1], s[0:1]
	v_mov_b32_e32 v101, v93
	s_or_b64 exec, exec, s[0:1]
; template <int DIR, int MODE>
; __device__ __forceinline__ void lru_pass(const Args& a, const LAS bf16_t* cxb, LAS bf16_t* gyb, const LAS float* carry, const bf16x8 (&Bw)[2][2][2], const float (&prm)[2][3], int l, int tt, float (&hf)[8][2][4]) {
;     ...
;     for (int mi = 0; mi < 8; ++mi) {
;         const int m = DIR ? 7 - mi : mi;
;         bf16x8 Af[2];
; #pragma unroll
;         for (int ks = 0; ks < 2; ++ks) Af[ks] = *(const LAS bf16x8*)(cxb + (m * 16 + fr) * CXS + 64 * h + 32 * ks + 8 * fq);
; #pragma unroll
;         for (int nt = 0; nt < 2; ++nt) {
;             f32x4 pr = (f32x4){0.f, 0.f, 0.f, 0.f}, pi = (f32x4){0.f, 0.f, 0.f, 0.f};
; #pragma unroll
;             for (int ks = 0; ks < 2; ++ks) { pr = __builtin_amdgcn_mfma_f32_16x16x32_bf16(Af[ks], Bw[0][nt][ks], pr, 0, 0, 0); pi = __builtin_amdgcn_mfma_f32_16x16x32_bf16(Af[ks], Bw[1][nt][ks], pi, 0, 0, 0); }
;             float av[4], bv[4];
; #pragma unroll
;             for (int reg = 0; reg < 4; ++reg) {
;                 const int tok = m * 16 + 4 * fq + reg;
;                 const float x = bf2f(cxb[tok * CXS + cc[nt]]);
;                 const float r = fsig(pr[reg] + ba[nt]), ig = fsig(pi[reg] + bxv[nt]);
;                 const float aa = __expf(k8[nt] * r);
;                 av[reg] = aa; bv[reg] = __builtin_amdgcn_sqrtf(fmaxf(1.0f - aa * aa, 0.f)) * ig * x;
;             }
;             float cum[4], hl[4];
;             if (DIR == 0) { cum[0] = av[0]; hl[0] = bv[0];
; #pragma unroll
;                 for (int reg = 1; reg < 4; ++reg) { cum[reg] = cum[reg - 1] * av[reg]; hl[reg] = av[reg] * hl[reg - 1] + bv[reg]; } }
;             else { cum[3] = av[3]; hl[3] = bv[3];
; #pragma unroll
;     ...
;             const float A4 = DIR ? cum[0] : cum[3], H4 = DIR ? hl[0] : hl[3];
;             float Aq[4], Hq[4];
; #pragma unroll
;             for (int q = 0; q < 4; ++q) { Aq[q] = __shfl(A4, fr + 16 * q); Hq[q] = __shfl(H4, fr + 16 * q); }
;             float hin;
;             if (DIR == 0) { const float s0 = C[nt], s1 = Aq[0] * s0 + Hq[0], s2 = Aq[1] * s1 + Hq[1], s3 = Aq[2] * s2 + Hq[2]; C[nt] = Aq[3] * s3 + Hq[3]; hin = fq == 0 ? s0 : (fq == 1 ? s1 : (fq == 2 ? s2 : s3)); }
;             else { const float s3 = C[nt], s2 = Aq[3] * s3 + Hq[3], s1 = Aq[2] * s2 + Hq[2], s0 = Aq[1] * s1 + Hq[1]; C[nt] = Aq[0] * s0 + Hq[0]; hin = fq == 3 ? s3 : (fq == 2 ? s2 : (fq == 1 ? s1 : s0)); }
.LBB0_563:
	s_or_b64 exec, exec, s[4:5]
	v_mfma_f32_16x16x32_bf16 v[94:97], v[70:73], v[34:37], 0
	ds_read_u16 v80, v213 offset:8480
	v_fmac_f32_e32 v92, v112, v114
	v_cmp_lt_i32_e64 s[0:1], 0, v200
	v_mfma_f32_16x16x32_bf16 v[120:123], v[70:73], v[42:45], 0
	v_mfma_f32_16x16x32_bf16 v[70:73], v[66:69], v[38:41], v[94:97]
	v_mfma_f32_16x16x32_bf16 v[66:69], v[66:69], v[46:49], v[120:123]
	s_nop 6
	v_add_f32_e32 v70, v169, v70
	v_mul_f32_e32 v70, 0xbfb8aa3b, v70
	v_exp_f32_e32 v70, v70
	v_add_f32_e32 v66, v168, v66
	v_mul_f32_e32 v66, 0xbfb8aa3b, v66
	v_exp_f32_e32 v66, v66
	v_add_f32_e32 v70, 1.0, v70
	v_rcp_f32_e32 v70, v70
	v_add_f32_e32 v72, v169, v72
	v_add_f32_e32 v66, 1.0, v66
	v_rcp_f32_e32 v66, v66
	v_mul_f32_e32 v70, v215, v70
	v_mul_f32_e32 v70, 0x3fb8aa3b, v70
	v_exp_f32_e32 v94, v70
	v_mul_f32_e32 v72, 0xbfb8aa3b, v72
	v_exp_f32_e32 v72, v72
	v_add_f32_e32 v67, v168, v67
	v_fma_f32 v70, -v94, v94, 1.0
	v_max_f32_e32 v70, 0, v70
	v_sqrt_f32_e32 v70, v70
	v_add_f32_e32 v73, v169, v73
	v_mul_f32_e32 v67, 0xbfb8aa3b, v67
	v_add_f32_e32 v72, 1.0, v72
	v_mul_f32_e32 v66, v66, v70
	v_add_f32_e32 v70, v169, v71
	v_mul_f32_e32 v70, 0xbfb8aa3b, v70
	v_exp_f32_e32 v70, v70
	v_mul_f32_e32 v73, 0xbfb8aa3b, v73
	v_exp_f32_e32 v67, v67
	v_rcp_f32_e32 v72, v72
	v_add_f32_e32 v70, 1.0, v70
	v_rcp_f32_e32 v70, v70
	v_exp_f32_e32 v73, v73
	v_add_f32_e32 v67, 1.0, v67
	v_mul_f32_e32 v72, v215, v72
	v_mul_f32_e32 v70, v215, v70
	v_mul_f32_e32 v70, 0x3fb8aa3b, v70
	v_exp_f32_e32 v70, v70
	v_add_f32_e32 v73, 1.0, v73
	v_rcp_f32_e32 v67, v67
	v_add_f32_e32 v68, v168, v68
	v_fma_f32 v71, -v70, v70, 1.0
	v_max_f32_e32 v71, 0, v71
	v_sqrt_f32_e32 v71, v71
	v_mul_f32_e32 v72, 0x3fb8aa3b, v72
	v_rcp_f32_e32 v73, v73
	v_mul_f32_e32 v68, 0xbfb8aa3b, v68
	v_exp_f32_e32 v72, v72
	v_exp_f32_e32 v68, v68
	v_mul_f32_e32 v67, v67, v71
	ds_read_u16 v71, v213 offset:9536
	s_waitcnt lgkmcnt(1)
	v_lshlrev_b32_e32 v80, 16, v80
	v_mul_f32_e32 v73, v215, v73
	v_mul_f32_e32 v93, v66, v80
	v_fma_f32 v80, -v72, v72, 1.0
	v_add_f32_e32 v69, v168, v69
	v_mul_f32_e32 v73, 0x3fb8aa3b, v73
	v_add_f32_e32 v68, 1.0, v68
	v_max_f32_e32 v80, 0, v80
	v_mul_f32_e32 v69, 0xbfb8aa3b, v69
	v_exp_f32_e32 v73, v73
	ds_read_u16 v66, v213 offset:9008
	v_rcp_f32_e32 v68, v68
	v_sqrt_f32_e32 v80, v80
	v_exp_f32_e32 v69, v69
	v_fma_f32 v81, -v73, v73, 1.0
	v_max_f32_e32 v81, 0, v81
	v_mul_f32_e32 v68, v68, v80
	ds_read_u16 v80, v213 offset:10064
	v_add_f32_e32 v69, 1.0, v69
	s_waitcnt lgkmcnt(1)
	v_lshlrev_b32_e32 v66, 16, v66
	v_rcp_f32_e32 v69, v69
	v_sqrt_f32_e32 v81, v81
	v_mul_f32_e32 v97, v70, v93
	v_fmac_f32_e32 v97, v67, v66
	v_lshlrev_b32_e32 v71, 16, v71
	v_mul_f32_e32 v96, v72, v97
	v_mul_f32_e32 v98, v70, v94
	v_fmac_f32_e32 v96, v68, v71
	s_waitcnt lgkmcnt(0)
	v_lshlrev_b32_e32 v80, 16, v80
	v_mul_f32_e32 v69, v69, v81
	v_mul_f32_e32 v99, v72, v98
	v_mul_f32_e32 v95, v73, v96
	v_mul_f32_e32 v100, v73, v99
	v_fmac_f32_e32 v95, v69, v80
	s_nop 0
	s_nop 0
	s_nop 0
	s_nop 0
	s_nop 0
	s_nop 0
	v_mov_b32_e32 v68, v100
	v_mov_b32_e32 v69, v100
	s_nop 1
	v_permlane16_swap_b32_e32 v68, v69
	s_nop 1
	v_mov_b32_e32 v70, v68
	v_mov_b32_e32 v131, v69
	s_nop 1
	v_permlane32_swap_b32_e32 v68, v70
	v_permlane32_swap_b32_e32 v69, v131
	s_nop 1
	v_mov_b32_e32 v66, v95
	v_mov_b32_e32 v67, v95
	s_nop 1
	v_permlane16_swap_b32_e32 v66, v67
	s_nop 1
	v_mov_b32_e32 v129, v66
	v_mov_b32_e32 v110, v67
	s_nop 1
	v_permlane32_swap_b32_e32 v66, v129
	v_permlane32_swap_b32_e32 v67, v110
	s_nop 1
	s_waitcnt lgkmcnt(0)
	v_fmac_f32_e32 v66, v92, v68
	s_waitcnt lgkmcnt(0)
	v_fmac_f32_e32 v67, v66, v69
	s_waitcnt lgkmcnt(0)
	v_fmac_f32_e32 v129, v67, v70
	s_and_saveexec_b64 s[4:5], s[0:1]
	s_cbranch_execz .LBB0_569
	v_cmp_ne_u32_e64 s[0:1], 1, v200
	s_and_saveexec_b64 s[34:35], s[0:1]
	s_xor_b64 s[0:1], exec, s[34:35]
	v_cndmask_b32_e32 v92, v129, v67, vcc
	s_andn2_saveexec_b64 s[0:1], s[0:1]
	v_mov_b32_e32 v92, v66
	s_or_b64 exec, exec, s[0:1]
.LBB0_569:
	s_or_b64 exec, exec, s[4:5]
	ds_read_b128 v[70:73], v220 offset:16896
	ds_read_b128 v[66:69], v220 offset:16960
	ds_read_u16 v80, v213 offset:16896
	ds_read_u16 v81, v213 offset:17424
	ds_read_u16 v82, v213 offset:17952
	ds_read_u16 v83, v213 offset:18480
	v_fmac_f32_e32 v119, v111, v113
	s_waitcnt lgkmcnt(5)
	v_mfma_f32_16x16x32_bf16 v[114:117], v[70:73], v[50:53], 0
	s_waitcnt lgkmcnt(2)
	v_lshlrev_b32_e32 v81, 16, v81
	v_lshlrev_b32_e32 v80, 16, v80
	s_waitcnt lgkmcnt(1)
	v_lshlrev_b32_e32 v82, 16, v82
	v_mfma_f32_16x16x32_bf16 v[114:117], v[66:69], v[54:57], v[114:117]
	s_waitcnt lgkmcnt(0)
; template <int DIR, int MODE>
; __device__ __forceinline__ void lru_pass(const Args& a, const LAS bf16_t* cxb, LAS bf16_t* gyb, const LAS float* carry, const bf16x8 (&Bw)[2][2][2], const float (&prm)[2][3], int l, int tt, float (&hf)[8][2][4]) {
;     ...
;     for (int mi = 0; mi < 8; ++mi) {
;         const int m = DIR ? 7 - mi : mi;
;         bf16x8 Af[2];
; #pragma unroll
;         for (int ks = 0; ks < 2; ++ks) Af[ks] = *(const LAS bf16x8*)(cxb + (m * 16 + fr) * CXS + 64 * h + 32 * ks + 8 * fq);
; #pragma unroll
;         for (int nt = 0; nt < 2; ++nt) {
;             f32x4 pr = (f32x4){0.f, 0.f, 0.f, 0.f}, pi = (f32x4){0.f, 0.f, 0.f, 0.f};
; #pragma unroll
;             for (int ks = 0; ks < 2; ++ks) { pr = __builtin_amdgcn_mfma_f32_16x16x32_bf16(Af[ks], Bw[0][nt][ks], pr, 0, 0, 0); pi = __builtin_amdgcn_mfma_f32_16x16x32_bf16(Af[ks], Bw[1][nt][ks], pi, 0, 0, 0); }
;             float av[4], bv[4];
; #pragma unroll
;             for (int reg = 0; reg < 4; ++reg) {
;                 const int tok = m * 16 + 4 * fq + reg;
;                 const float x = bf2f(cxb[tok * CXS + cc[nt]]);
;                 const float r = fsig(pr[reg] + ba[nt]), ig = fsig(pi[reg] + bxv[nt]);
;                 const float aa = __expf(k8[nt] * r);
;                 av[reg] = aa; bv[reg] = __builtin_amdgcn_sqrtf(fmaxf(1.0f - aa * aa, 0.f)) * ig * x;
;             }
;             float cum[4], hl[4];
;             if (DIR == 0) { cum[0] = av[0]; hl[0] = bv[0];
; #pragma unroll
;                 for (int reg = 1; reg < 4; ++reg) { cum[reg] = cum[reg - 1] * av[reg]; hl[reg] = av[reg] * hl[reg - 1] + bv[reg]; } }
;             else { cum[3] = av[3]; hl[3] = bv[3];
; #pragma unroll
;     ...
;             const float A4 = DIR ? cum[0] : cum[3], H4 = DIR ? hl[0] : hl[3];
;             float Aq[4], Hq[4];
; #pragma unroll
;             for (int q = 0; q < 4; ++q) { Aq[q] = __shfl(A4, fr + 16 * q); Hq[q] = __shfl(H4, fr + 16 * q); }
;             float hin;
;             if (DIR == 0) { const float s0 = C[nt], s1 = Aq[0] * s0 + Hq[0], s2 = Aq[1] * s1 + Hq[1], s3 = Aq[2] * s2 + Hq[2]; C[nt] = Aq[3] * s3 + Hq[3]; hin = fq == 0 ? s0 : (fq == 1 ? s1 : (fq == 2 ? s2 : s3)); }
;             else { const float s3 = C[nt], s2 = Aq[3] * s3 + Hq[3], s1 = Aq[2] * s2 + Hq[2], s0 = Aq[1] * s1 + Hq[1]; C[nt] = Aq[0] * s0 + Hq[0]; hin = fq == 3 ? s3 : (fq == 2 ? s2 : (fq == 1 ? s1 : s0)); }
	v_lshlrev_b32_e32 v83, 16, v83
	v_cmp_lt_i32_e64 s[0:1], 0, v200
	v_mfma_f32_16x16x32_bf16 v[120:123], v[70:73], v[58:61], 0
	v_mfma_f32_16x16x32_bf16 v[124:127], v[66:69], v[62:65], v[120:123]
	s_nop 2
	v_add_f32_e32 v112, v171, v114
	v_mul_f32_e32 v112, 0xbfb8aa3b, v112
	v_exp_f32_e32 v112, v112
	v_add_f32_e32 v115, v171, v115
	v_mul_f32_e32 v115, 0xbfb8aa3b, v115
	v_add_f32_e32 v114, v170, v124
	v_add_f32_e32 v112, 1.0, v112
	v_rcp_f32_e32 v112, v112
	v_mul_f32_e32 v114, 0xbfb8aa3b, v114
	v_exp_f32_e32 v114, v114
	v_exp_f32_e32 v115, v115
	v_add_f32_e32 v118, v170, v125
	v_mul_f32_e32 v118, 0xbfb8aa3b, v118
	v_mul_f32_e32 v112, v214, v112
	v_exp_f32_e32 v118, v118
	v_mul_f32_e32 v112, 0x3fb8aa3b, v112
	v_add_f32_e32 v114, 1.0, v114
	v_add_f32_e32 v115, 1.0, v115
	v_exp_f32_e32 v124, v112
	v_rcp_f32_e32 v112, v114
	v_rcp_f32_e32 v114, v115
	v_add_f32_e32 v118, 1.0, v118
	v_rcp_f32_e32 v115, v118
	v_fma_f32 v118, -v124, v124, 1.0
	v_max_f32_e32 v118, 0, v118
	v_mul_f32_e32 v114, v214, v114
	v_sqrt_f32_e32 v118, v118
	v_mul_f32_e32 v114, 0x3fb8aa3b, v114
	v_exp_f32_e32 v114, v114
	v_mul_f32_e32 v112, v112, v118
	v_mul_f32_e32 v123, v112, v80
	v_add_f32_e32 v80, v171, v116
	v_fma_f32 v112, -v114, v114, 1.0
	v_add_f32_e32 v116, v170, v126
	v_max_f32_e32 v112, 0, v112
	v_mul_f32_e32 v116, 0xbfb8aa3b, v116
	v_sqrt_f32_e32 v112, v112
	v_exp_f32_e32 v116, v116
	v_mul_f32_e32 v80, 0xbfb8aa3b, v80
	v_exp_f32_e32 v80, v80
	v_mul_f32_e32 v112, v115, v112
	v_add_f32_e32 v115, 1.0, v116
	v_add_f32_e32 v116, v171, v117
	v_mul_f32_e32 v116, 0xbfb8aa3b, v116
	v_exp_f32_e32 v116, v116
	v_add_f32_e32 v80, 1.0, v80
	v_rcp_f32_e32 v80, v80
	v_add_f32_e32 v118, v170, v127
	v_add_f32_e32 v116, 1.0, v116
	v_rcp_f32_e32 v116, v116
	v_mul_f32_e32 v80, v214, v80
	v_mul_f32_e32 v80, 0x3fb8aa3b, v80
	v_exp_f32_e32 v80, v80
	v_mul_f32_e32 v116, v214, v116
	v_mul_f32_e32 v116, 0x3fb8aa3b, v116
	v_mul_f32_e32 v118, 0xbfb8aa3b, v118
	v_exp_f32_e32 v116, v116
	v_exp_f32_e32 v118, v118
	v_fma_f32 v117, -v80, v80, 1.0
	v_max_f32_e32 v117, 0, v117
	v_rcp_f32_e32 v115, v115
	v_sqrt_f32_e32 v117, v117
	v_fma_f32 v120, -v116, v116, 1.0
	v_add_f32_e32 v118, 1.0, v118
	v_max_f32_e32 v120, 0, v120
	v_rcp_f32_e32 v118, v118
	v_sqrt_f32_e32 v120, v120
	v_mul_f32_e32 v122, v114, v123
	v_fmac_f32_e32 v122, v112, v81
	v_mul_f32_e32 v115, v115, v117
	v_mul_f32_e32 v121, v80, v122
	v_mul_f32_e32 v125, v114, v124
	v_fmac_f32_e32 v121, v115, v82
	v_mul_f32_e32 v117, v118, v120
	v_mul_f32_e32 v126, v80, v125
	v_mul_f32_e32 v120, v116, v121
	v_mul_f32_e32 v127, v116, v126
	v_fmac_f32_e32 v120, v117, v83
	s_nop 0
	s_nop 0
	s_nop 0
	s_nop 0
	s_nop 0
	s_nop 0
	v_mov_b32_e32 v115, v127
	v_mov_b32_e32 v116, v127
	s_nop 1
	v_permlane16_swap_b32_e32 v115, v116
	s_nop 1
	v_mov_b32_e32 v117, v115
	v_mov_b32_e32 v132, v116
	s_nop 1
	v_permlane32_swap_b32_e32 v115, v117
	v_permlane32_swap_b32_e32 v116, v132
	s_nop 1
	v_mov_b32_e32 v112, v120
	v_mov_b32_e32 v114, v120
	s_nop 1
	v_permlane16_swap_b32_e32 v112, v114
	s_nop 1
	v_mov_b32_e32 v130, v112
	v_mov_b32_e32 v137, v114
	s_nop 1
	v_permlane32_swap_b32_e32 v112, v130
	v_permlane32_swap_b32_e32 v114, v137
	s_nop 1
	s_waitcnt lgkmcnt(0)
	v_fmac_f32_e32 v112, v119, v115
	s_waitcnt lgkmcnt(0)
	v_fmac_f32_e32 v114, v112, v116
	s_waitcnt lgkmcnt(0)
	v_fmac_f32_e32 v130, v114, v117
	s_and_saveexec_b64 s[4:5], s[0:1]
	s_cbranch_execz .LBB0_575
	v_cmp_ne_u32_e64 s[0:1], 1, v200
	s_and_saveexec_b64 s[34:35], s[0:1]
	s_xor_b64 s[0:1], exec, s[34:35]
	v_cndmask_b32_e32 v119, v130, v114, vcc
	s_andn2_saveexec_b64 s[0:1], s[0:1]
	v_mov_b32_e32 v119, v112
	s_or_b64 exec, exec, s[0:1]
.LBB0_575:
	s_or_b64 exec, exec, s[4:5]
	v_mfma_f32_16x16x32_bf16 v[112:115], v[70:73], v[34:37], 0
	ds_read_u16 v80, v213 offset:16928
	v_fmac_f32_e32 v110, v129, v131
	v_cmp_lt_i32_e64 s[0:1], 0, v200
	v_mfma_f32_16x16x32_bf16 v[138:141], v[70:73], v[42:45], 0
	v_mfma_f32_16x16x32_bf16 v[70:73], v[66:69], v[38:41], v[112:115]
	v_mfma_f32_16x16x32_bf16 v[66:69], v[66:69], v[46:49], v[138:141]
	s_nop 6
	v_add_f32_e32 v70, v169, v70
	v_mul_f32_e32 v70, 0xbfb8aa3b, v70
	v_exp_f32_e32 v70, v70
	v_add_f32_e32 v66, v168, v66
	v_mul_f32_e32 v66, 0xbfb8aa3b, v66
	v_exp_f32_e32 v66, v66
	v_add_f32_e32 v70, 1.0, v70
	v_rcp_f32_e32 v70, v70
	v_add_f32_e32 v72, v169, v72
	v_add_f32_e32 v66, 1.0, v66
	v_rcp_f32_e32 v66, v66
	v_mul_f32_e32 v70, v215, v70
	v_mul_f32_e32 v70, 0x3fb8aa3b, v70
	v_exp_f32_e32 v112, v70
	v_mul_f32_e32 v72, 0xbfb8aa3b, v72
	v_exp_f32_e32 v72, v72
	v_add_f32_e32 v67, v168, v67
	v_fma_f32 v70, -v112, v112, 1.0
	v_max_f32_e32 v70, 0, v70
	v_sqrt_f32_e32 v70, v70
	v_add_f32_e32 v73, v169, v73
	v_mul_f32_e32 v67, 0xbfb8aa3b, v67
	v_add_f32_e32 v72, 1.0, v72
	v_mul_f32_e32 v66, v66, v70
	v_add_f32_e32 v70, v169, v71
	v_mul_f32_e32 v70, 0xbfb8aa3b, v70
	v_exp_f32_e32 v70, v70
	v_mul_f32_e32 v73, 0xbfb8aa3b, v73
	v_exp_f32_e32 v67, v67
	v_rcp_f32_e32 v72, v72
	v_add_f32_e32 v70, 1.0, v70
	v_rcp_f32_e32 v70, v70
	v_exp_f32_e32 v73, v73
	v_add_f32_e32 v67, 1.0, v67
	v_mul_f32_e32 v72, v215, v72
	v_mul_f32_e32 v70, v215, v70
	v_mul_f32_e32 v70, 0x3fb8aa3b, v70
	v_exp_f32_e32 v70, v70
	v_add_f32_e32 v73, 1.0, v73
	v_rcp_f32_e32 v67, v67
	v_add_f32_e32 v68, v168, v68
	v_fma_f32 v71, -v70, v70, 1.0
	v_max_f32_e32 v71, 0, v71
	v_sqrt_f32_e32 v71, v71
	v_mul_f32_e32 v72, 0x3fb8aa3b, v72
	v_rcp_f32_e32 v73, v73
	v_mul_f32_e32 v68, 0xbfb8aa3b, v68
	v_exp_f32_e32 v72, v72
	v_exp_f32_e32 v68, v68
	v_mul_f32_e32 v67, v67, v71
	ds_read_u16 v71, v213 offset:17984
	s_waitcnt lgkmcnt(1)
; template <int DIR, int MODE>
; __device__ __forceinline__ void lru_pass(const Args& a, const LAS bf16_t* cxb, LAS bf16_t* gyb, const LAS float* carry, const bf16x8 (&Bw)[2][2][2], const float (&prm)[2][3], int l, int tt, float (&hf)[8][2][4]) {
;     ...
;     for (int mi = 0; mi < 8; ++mi) {
;         const int m = DIR ? 7 - mi : mi;
;         bf16x8 Af[2];
; #pragma unroll
;         for (int ks = 0; ks < 2; ++ks) Af[ks] = *(const LAS bf16x8*)(cxb + (m * 16 + fr) * CXS + 64 * h + 32 * ks + 8 * fq);
; #pragma unroll
;         for (int nt = 0; nt < 2; ++nt) {
;             f32x4 pr = (f32x4){0.f, 0.f, 0.f, 0.f}, pi = (f32x4){0.f, 0.f, 0.f, 0.f};
; #pragma unroll
;             for (int ks = 0; ks < 2; ++ks) { pr = __builtin_amdgcn_mfma_f32_16x16x32_bf16(Af[ks], Bw[0][nt][ks], pr, 0, 0, 0); pi = __builtin_amdgcn_mfma_f32_16x16x32_bf16(Af[ks], Bw[1][nt][ks], pi, 0, 0, 0); }
;             float av[4], bv[4];
; #pragma unroll
;             for (int reg = 0; reg < 4; ++reg) {
;                 const int tok = m * 16 + 4 * fq + reg;
;                 const float x = bf2f(cxb[tok * CXS + cc[nt]]);
;                 const float r = fsig(pr[reg] + ba[nt]), ig = fsig(pi[reg] + bxv[nt]);
;                 const float aa = __expf(k8[nt] * r);
;                 av[reg] = aa; bv[reg] = __builtin_amdgcn_sqrtf(fmaxf(1.0f - aa * aa, 0.f)) * ig * x;
;             }
;             float cum[4], hl[4];
;             if (DIR == 0) { cum[0] = av[0]; hl[0] = bv[0];
; #pragma unroll
;                 for (int reg = 1; reg < 4; ++reg) { cum[reg] = cum[reg - 1] * av[reg]; hl[reg] = av[reg] * hl[reg - 1] + bv[reg]; } }
;             else { cum[3] = av[3]; hl[3] = bv[3];
; #pragma unroll
;     ...
;             const float A4 = DIR ? cum[0] : cum[3], H4 = DIR ? hl[0] : hl[3];
;             float Aq[4], Hq[4];
; #pragma unroll
;             for (int q = 0; q < 4; ++q) { Aq[q] = __shfl(A4, fr + 16 * q); Hq[q] = __shfl(H4, fr + 16 * q); }
;             float hin;
;             if (DIR == 0) { const float s0 = C[nt], s1 = Aq[0] * s0 + Hq[0], s2 = Aq[1] * s1 + Hq[1], s3 = Aq[2] * s2 + Hq[2]; C[nt] = Aq[3] * s3 + Hq[3]; hin = fq == 0 ? s0 : (fq == 1 ? s1 : (fq == 2 ? s2 : s3)); }
;             else { const float s3 = C[nt], s2 = Aq[3] * s3 + Hq[3], s1 = Aq[2] * s2 + Hq[2], s0 = Aq[1] * s1 + Hq[1]; C[nt] = Aq[0] * s0 + Hq[0]; hin = fq == 3 ? s3 : (fq == 2 ? s2 : (fq == 1 ? s1 : s0)); }
	v_lshlrev_b32_e32 v80, 16, v80
	v_mul_f32_e32 v73, v215, v73
	v_mul_f32_e32 v111, v66, v80
	v_fma_f32 v80, -v72, v72, 1.0
	v_add_f32_e32 v69, v168, v69
	v_mul_f32_e32 v73, 0x3fb8aa3b, v73
	v_add_f32_e32 v68, 1.0, v68
	v_max_f32_e32 v80, 0, v80
	v_mul_f32_e32 v69, 0xbfb8aa3b, v69
	v_exp_f32_e32 v73, v73
	ds_read_u16 v66, v213 offset:17456
	v_rcp_f32_e32 v68, v68
	v_sqrt_f32_e32 v80, v80
	v_exp_f32_e32 v69, v69
	v_fma_f32 v81, -v73, v73, 1.0
	v_max_f32_e32 v81, 0, v81
	v_mul_f32_e32 v68, v68, v80
	ds_read_u16 v80, v213 offset:18512
	v_add_f32_e32 v69, 1.0, v69
	s_waitcnt lgkmcnt(1)
	v_lshlrev_b32_e32 v66, 16, v66
	v_rcp_f32_e32 v69, v69
	v_sqrt_f32_e32 v81, v81
	v_mul_f32_e32 v115, v70, v111
	v_fmac_f32_e32 v115, v67, v66
	v_lshlrev_b32_e32 v71, 16, v71
	v_mul_f32_e32 v114, v72, v115
	v_mul_f32_e32 v116, v70, v112
	v_fmac_f32_e32 v114, v68, v71
	s_waitcnt lgkmcnt(0)
	v_lshlrev_b32_e32 v80, 16, v80
	v_mul_f32_e32 v69, v69, v81
	v_mul_f32_e32 v117, v72, v116
	v_mul_f32_e32 v113, v73, v114
	v_mul_f32_e32 v118, v73, v117
	v_fmac_f32_e32 v113, v69, v80
	s_nop 0
	s_nop 0
	s_nop 0
	s_nop 0
	s_nop 0
	s_nop 0
	v_mov_b32_e32 v68, v118
	v_mov_b32_e32 v69, v118
	s_nop 1
	v_permlane16_swap_b32_e32 v68, v69
	s_nop 1
	v_mov_b32_e32 v70, v68
	v_mov_b32_e32 v149, v69
	s_nop 1
	v_permlane32_swap_b32_e32 v68, v70
	v_permlane32_swap_b32_e32 v69, v149
	s_nop 1
	v_mov_b32_e32 v66, v113
	v_mov_b32_e32 v67, v113
	s_nop 1
	v_permlane16_swap_b32_e32 v66, v67
	s_nop 1
	v_mov_b32_e32 v147, v66
	v_mov_b32_e32 v128, v67
	s_nop 1
	v_permlane32_swap_b32_e32 v66, v147
	v_permlane32_swap_b32_e32 v67, v128
	s_nop 1
	s_waitcnt lgkmcnt(0)
	v_fmac_f32_e32 v66, v110, v68
	s_waitcnt lgkmcnt(0)
	v_fmac_f32_e32 v67, v66, v69
	s_waitcnt lgkmcnt(0)
	v_fmac_f32_e32 v147, v67, v70
	s_and_saveexec_b64 s[4:5], s[0:1]
	s_cbranch_execz .LBB0_581
	v_cmp_ne_u32_e64 s[0:1], 1, v200
	s_and_saveexec_b64 s[34:35], s[0:1]
	s_xor_b64 s[0:1], exec, s[34:35]
	v_cndmask_b32_e32 v110, v147, v67, vcc
	s_andn2_saveexec_b64 s[0:1], s[0:1]
	v_mov_b32_e32 v110, v66
	s_or_b64 exec, exec, s[0:1]
.LBB0_581:
	s_or_b64 exec, exec, s[4:5]
	ds_read_b128 v[70:73], v220 offset:25344
	ds_read_b128 v[66:69], v220 offset:25408
	ds_read_u16 v80, v213 offset:25344
	ds_read_u16 v81, v213 offset:25872
	ds_read_u16 v82, v213 offset:26400
	ds_read_u16 v83, v213 offset:26928
	v_fmac_f32_e32 v137, v130, v132
	s_waitcnt lgkmcnt(5)
	v_mfma_f32_16x16x32_bf16 v[138:141], v[70:73], v[50:53], 0
	s_waitcnt lgkmcnt(2)
	v_lshlrev_b32_e32 v81, 16, v81
	v_lshlrev_b32_e32 v80, 16, v80
	s_waitcnt lgkmcnt(1)
	v_lshlrev_b32_e32 v82, 16, v82
	v_mfma_f32_16x16x32_bf16 v[154:157], v[66:69], v[54:57], v[138:141]
	s_waitcnt lgkmcnt(0)
	v_lshlrev_b32_e32 v83, 16, v83
	v_cmp_lt_i32_e64 s[0:1], 0, v200
	v_mfma_f32_16x16x32_bf16 v[142:145], v[70:73], v[58:61], 0
	v_mfma_f32_16x16x32_bf16 v[142:145], v[66:69], v[62:65], v[142:145]
	s_nop 2
	v_add_f32_e32 v129, v171, v154
	v_mul_f32_e32 v129, 0xbfb8aa3b, v129
	v_exp_f32_e32 v129, v129
	v_add_f32_e32 v133, v171, v155
	v_mul_f32_e32 v133, 0xbfb8aa3b, v133
	v_add_f32_e32 v131, v170, v142
	v_add_f32_e32 v129, 1.0, v129
	v_rcp_f32_e32 v129, v129
	v_mul_f32_e32 v131, 0xbfb8aa3b, v131
	v_exp_f32_e32 v131, v131
	v_exp_f32_e32 v133, v133
	v_add_f32_e32 v134, v170, v143
	v_mul_f32_e32 v134, 0xbfb8aa3b, v134
	v_mul_f32_e32 v129, v214, v129
	v_exp_f32_e32 v134, v134
	v_mul_f32_e32 v129, 0x3fb8aa3b, v129
	v_add_f32_e32 v131, 1.0, v131
	v_add_f32_e32 v133, 1.0, v133
	v_exp_f32_e32 v142, v129
	v_rcp_f32_e32 v129, v131
	v_rcp_f32_e32 v131, v133
	v_add_f32_e32 v134, 1.0, v134
	v_rcp_f32_e32 v133, v134
	v_fma_f32 v134, -v142, v142, 1.0
	v_max_f32_e32 v134, 0, v134
	v_mul_f32_e32 v131, v214, v131
	v_sqrt_f32_e32 v134, v134
	v_mul_f32_e32 v131, 0x3fb8aa3b, v131
	v_exp_f32_e32 v131, v131
	v_add_f32_e32 v136, v170, v145
	v_mul_f32_e32 v129, v129, v134
	v_mul_f32_e32 v141, v129, v80
	v_fma_f32 v129, -v131, v131, 1.0
	v_add_f32_e32 v134, v170, v144
	v_max_f32_e32 v129, 0, v129
	v_mul_f32_e32 v134, 0xbfb8aa3b, v134
	v_sqrt_f32_e32 v129, v129
	v_exp_f32_e32 v134, v134
	v_add_f32_e32 v80, v171, v156
	v_mul_f32_e32 v80, 0xbfb8aa3b, v80
	v_exp_f32_e32 v80, v80
	v_mul_f32_e32 v129, v133, v129
	v_add_f32_e32 v133, 1.0, v134
	v_add_f32_e32 v134, v171, v157
	v_mul_f32_e32 v134, 0xbfb8aa3b, v134
	v_exp_f32_e32 v134, v134
	v_add_f32_e32 v80, 1.0, v80
	v_rcp_f32_e32 v80, v80
	v_mul_f32_e32 v136, 0xbfb8aa3b, v136
	v_add_f32_e32 v134, 1.0, v134
	v_rcp_f32_e32 v134, v134
	v_mul_f32_e32 v80, v214, v80
	v_mul_f32_e32 v80, 0x3fb8aa3b, v80
	v_exp_f32_e32 v80, v80
	v_mul_f32_e32 v134, v214, v134
	v_mul_f32_e32 v134, 0x3fb8aa3b, v134
	v_exp_f32_e32 v134, v134
	v_exp_f32_e32 v136, v136
	v_fma_f32 v135, -v80, v80, 1.0
	v_max_f32_e32 v135, 0, v135
	v_rcp_f32_e32 v133, v133
	v_sqrt_f32_e32 v135, v135
	v_fma_f32 v138, -v134, v134, 1.0
	v_add_f32_e32 v136, 1.0, v136
	v_max_f32_e32 v138, 0, v138
	v_rcp_f32_e32 v136, v136
	v_sqrt_f32_e32 v138, v138
	v_mul_f32_e32 v140, v131, v141
	v_fmac_f32_e32 v140, v129, v81
	v_mul_f32_e32 v133, v133, v135
	v_mul_f32_e32 v139, v80, v140
	v_mul_f32_e32 v143, v131, v142
	v_fmac_f32_e32 v139, v133, v82
	v_mul_f32_e32 v135, v136, v138
	v_mul_f32_e32 v144, v80, v143
	v_mul_f32_e32 v138, v134, v139
	v_mul_f32_e32 v145, v134, v144
	v_fmac_f32_e32 v138, v135, v83
	s_nop 0
	s_nop 0
	s_nop 0
	s_nop 0
	s_nop 0
	s_nop 0
	v_mov_b32_e32 v133, v145
	v_mov_b32_e32 v134, v145
	s_nop 1
	v_permlane16_swap_b32_e32 v133, v134
	s_nop 1
	v_mov_b32_e32 v135, v133
	v_mov_b32_e32 v154, v134
	s_nop 1
	v_permlane32_swap_b32_e32 v133, v135
	v_permlane32_swap_b32_e32 v134, v154
	s_nop 1
	v_mov_b32_e32 v129, v138
	v_mov_b32_e32 v131, v138
	s_nop 1
	v_permlane16_swap_b32_e32 v129, v131
	s_nop 1
	v_mov_b32_e32 v148, v129
	v_mov_b32_e32 v159, v131
	s_nop 1
	v_permlane32_swap_b32_e32 v129, v148
	v_permlane32_swap_b32_e32 v131, v159
	s_nop 1
	s_waitcnt lgkmcnt(0)
	v_fmac_f32_e32 v129, v137, v133
	s_waitcnt lgkmcnt(0)
	v_fmac_f32_e32 v131, v129, v134
	s_waitcnt lgkmcnt(0)
	v_fmac_f32_e32 v148, v131, v135
	s_and_saveexec_b64 s[4:5], s[0:1]
	s_cbranch_execz .LBB0_587
	v_cmp_ne_u32_e64 s[0:1], 1, v200
	s_and_saveexec_b64 s[34:35], s[0:1]
	s_xor_b64 s[0:1], exec, s[34:35]
	v_cndmask_b32_e32 v137, v148, v131, vcc
	s_andn2_saveexec_b64 s[0:1], s[0:1]
	v_mov_b32_e32 v137, v129
	s_or_b64 exec, exec, s[0:1]
; template <int DIR, int MODE>
; __device__ __forceinline__ void lru_pass(const Args& a, const LAS bf16_t* cxb, LAS bf16_t* gyb, const LAS float* carry, const bf16x8 (&Bw)[2][2][2], const float (&prm)[2][3], int l, int tt, float (&hf)[8][2][4]) {
;     ...
;     for (int mi = 0; mi < 8; ++mi) {
;         const int m = DIR ? 7 - mi : mi;
;         bf16x8 Af[2];
; #pragma unroll
;         for (int ks = 0; ks < 2; ++ks) Af[ks] = *(const LAS bf16x8*)(cxb + (m * 16 + fr) * CXS + 64 * h + 32 * ks + 8 * fq);
; #pragma unroll
;         for (int nt = 0; nt < 2; ++nt) {
;             f32x4 pr = (f32x4){0.f, 0.f, 0.f, 0.f}, pi = (f32x4){0.f, 0.f, 0.f, 0.f};
; #pragma unroll
;             for (int ks = 0; ks < 2; ++ks) { pr = __builtin_amdgcn_mfma_f32_16x16x32_bf16(Af[ks], Bw[0][nt][ks], pr, 0, 0, 0); pi = __builtin_amdgcn_mfma_f32_16x16x32_bf16(Af[ks], Bw[1][nt][ks], pi, 0, 0, 0); }
;             float av[4], bv[4];
; #pragma unroll
;             for (int reg = 0; reg < 4; ++reg) {
;                 const int tok = m * 16 + 4 * fq + reg;
;                 const float x = bf2f(cxb[tok * CXS + cc[nt]]);
;                 const float r = fsig(pr[reg] + ba[nt]), ig = fsig(pi[reg] + bxv[nt]);
;                 const float aa = __expf(k8[nt] * r);
;                 av[reg] = aa; bv[reg] = __builtin_amdgcn_sqrtf(fmaxf(1.0f - aa * aa, 0.f)) * ig * x;
;             }
;             float cum[4], hl[4];
;             if (DIR == 0) { cum[0] = av[0]; hl[0] = bv[0];
; #pragma unroll
;                 for (int reg = 1; reg < 4; ++reg) { cum[reg] = cum[reg - 1] * av[reg]; hl[reg] = av[reg] * hl[reg - 1] + bv[reg]; } }
;             else { cum[3] = av[3]; hl[3] = bv[3];
; #pragma unroll
;     ...
;             const float A4 = DIR ? cum[0] : cum[3], H4 = DIR ? hl[0] : hl[3];
;             float Aq[4], Hq[4];
; #pragma unroll
;             for (int q = 0; q < 4; ++q) { Aq[q] = __shfl(A4, fr + 16 * q); Hq[q] = __shfl(H4, fr + 16 * q); }
;             float hin;
;             if (DIR == 0) { const float s0 = C[nt], s1 = Aq[0] * s0 + Hq[0], s2 = Aq[1] * s1 + Hq[1], s3 = Aq[2] * s2 + Hq[2]; C[nt] = Aq[3] * s3 + Hq[3]; hin = fq == 0 ? s0 : (fq == 1 ? s1 : (fq == 2 ? s2 : s3)); }
;             else { const float s3 = C[nt], s2 = Aq[3] * s3 + Hq[3], s1 = Aq[2] * s2 + Hq[2], s0 = Aq[1] * s1 + Hq[1]; C[nt] = Aq[0] * s0 + Hq[0]; hin = fq == 3 ? s3 : (fq == 2 ? s2 : (fq == 1 ? s1 : s0)); }
.LBB0_587:
	s_or_b64 exec, exec, s[4:5]
	v_mfma_f32_16x16x32_bf16 v[130:133], v[70:73], v[34:37], 0
	ds_read_u16 v80, v213 offset:25376
	v_fmac_f32_e32 v128, v147, v149
	v_cmp_lt_i32_e64 s[0:1], 0, v200
	v_mfma_f32_16x16x32_bf16 v[160:163], v[70:73], v[42:45], 0
	v_mfma_f32_16x16x32_bf16 v[70:73], v[66:69], v[38:41], v[130:133]
	v_mfma_f32_16x16x32_bf16 v[66:69], v[66:69], v[46:49], v[160:163]
	s_nop 6
	v_add_f32_e32 v70, v169, v70
	v_mul_f32_e32 v70, 0xbfb8aa3b, v70
	v_exp_f32_e32 v70, v70
	v_add_f32_e32 v66, v168, v66
	v_mul_f32_e32 v66, 0xbfb8aa3b, v66
	v_exp_f32_e32 v66, v66
	v_add_f32_e32 v70, 1.0, v70
	v_rcp_f32_e32 v70, v70
	v_add_f32_e32 v72, v169, v72
	v_add_f32_e32 v66, 1.0, v66
	v_rcp_f32_e32 v66, v66
	v_mul_f32_e32 v70, v215, v70
	v_mul_f32_e32 v70, 0x3fb8aa3b, v70
	v_exp_f32_e32 v130, v70
	v_mul_f32_e32 v72, 0xbfb8aa3b, v72
	v_exp_f32_e32 v72, v72
	v_add_f32_e32 v67, v168, v67
	v_fma_f32 v70, -v130, v130, 1.0
	v_max_f32_e32 v70, 0, v70
	v_sqrt_f32_e32 v70, v70
	v_add_f32_e32 v73, v169, v73
	v_mul_f32_e32 v67, 0xbfb8aa3b, v67
	v_add_f32_e32 v72, 1.0, v72
	v_mul_f32_e32 v66, v66, v70
	v_add_f32_e32 v70, v169, v71
	v_mul_f32_e32 v70, 0xbfb8aa3b, v70
	v_exp_f32_e32 v70, v70
	v_mul_f32_e32 v73, 0xbfb8aa3b, v73
	v_exp_f32_e32 v67, v67
	v_rcp_f32_e32 v72, v72
	v_add_f32_e32 v70, 1.0, v70
	v_rcp_f32_e32 v70, v70
	v_exp_f32_e32 v73, v73
	v_add_f32_e32 v67, 1.0, v67
	v_mul_f32_e32 v72, v215, v72
	v_mul_f32_e32 v70, v215, v70
	v_mul_f32_e32 v70, 0x3fb8aa3b, v70
	v_exp_f32_e32 v70, v70
	v_add_f32_e32 v73, 1.0, v73
	v_rcp_f32_e32 v67, v67
	v_add_f32_e32 v68, v168, v68
	v_fma_f32 v71, -v70, v70, 1.0
	v_max_f32_e32 v71, 0, v71
	v_sqrt_f32_e32 v71, v71
	v_mul_f32_e32 v72, 0x3fb8aa3b, v72
	v_rcp_f32_e32 v73, v73
	v_mul_f32_e32 v68, 0xbfb8aa3b, v68
	v_exp_f32_e32 v72, v72
	v_exp_f32_e32 v68, v68
	v_mul_f32_e32 v67, v67, v71
	ds_read_u16 v71, v213 offset:26432
	s_waitcnt lgkmcnt(1)
	v_lshlrev_b32_e32 v80, 16, v80
	v_mul_f32_e32 v73, v215, v73
	v_mul_f32_e32 v129, v66, v80
	v_fma_f32 v80, -v72, v72, 1.0
	v_add_f32_e32 v69, v168, v69
	v_mul_f32_e32 v73, 0x3fb8aa3b, v73
	v_add_f32_e32 v68, 1.0, v68
	v_max_f32_e32 v80, 0, v80
	v_mul_f32_e32 v69, 0xbfb8aa3b, v69
	v_exp_f32_e32 v73, v73
	ds_read_u16 v66, v213 offset:25904
	v_rcp_f32_e32 v68, v68
	v_sqrt_f32_e32 v80, v80
	v_exp_f32_e32 v69, v69
	v_fma_f32 v81, -v73, v73, 1.0
	v_max_f32_e32 v81, 0, v81
	v_mul_f32_e32 v68, v68, v80
	ds_read_u16 v80, v213 offset:26960
	v_add_f32_e32 v69, 1.0, v69
	s_waitcnt lgkmcnt(1)
	v_lshlrev_b32_e32 v66, 16, v66
	v_rcp_f32_e32 v69, v69
	v_sqrt_f32_e32 v81, v81
	v_mul_f32_e32 v133, v70, v129
	v_fmac_f32_e32 v133, v67, v66
	v_lshlrev_b32_e32 v71, 16, v71
	v_mul_f32_e32 v132, v72, v133
	v_mul_f32_e32 v134, v70, v130
	v_fmac_f32_e32 v132, v68, v71
	s_waitcnt lgkmcnt(0)
	v_lshlrev_b32_e32 v80, 16, v80
	v_mul_f32_e32 v69, v69, v81
	v_mul_f32_e32 v135, v72, v134
	v_mul_f32_e32 v131, v73, v132
	v_mul_f32_e32 v136, v73, v135
	v_fmac_f32_e32 v131, v69, v80
	s_nop 0
	s_nop 0
	s_nop 0
	s_nop 0
	s_nop 0
	s_nop 0
	v_mov_b32_e32 v68, v136
	v_mov_b32_e32 v69, v136
	s_nop 1
	v_permlane16_swap_b32_e32 v68, v69
	s_nop 1
	v_mov_b32_e32 v70, v68
	v_mov_b32_e32 v175, v69
	s_nop 1
	v_permlane32_swap_b32_e32 v68, v70
	v_permlane32_swap_b32_e32 v69, v175
	s_nop 1
	v_mov_b32_e32 v66, v131
	v_mov_b32_e32 v67, v131
	s_nop 1
	v_permlane16_swap_b32_e32 v66, v67
	s_nop 1
	v_mov_b32_e32 v173, v66
	v_mov_b32_e32 v146, v67
	s_nop 1
	v_permlane32_swap_b32_e32 v66, v173
	v_permlane32_swap_b32_e32 v67, v146
	s_nop 1
	s_waitcnt lgkmcnt(0)
	v_fmac_f32_e32 v66, v128, v68
	s_waitcnt lgkmcnt(0)
	v_fmac_f32_e32 v67, v66, v69
	s_waitcnt lgkmcnt(0)
	v_fmac_f32_e32 v173, v67, v70
	s_and_saveexec_b64 s[4:5], s[0:1]
	s_cbranch_execz .LBB0_593
	v_cmp_ne_u32_e64 s[0:1], 1, v200
	s_and_saveexec_b64 s[34:35], s[0:1]
	s_xor_b64 s[0:1], exec, s[34:35]
	v_cndmask_b32_e32 v128, v173, v67, vcc
	s_andn2_saveexec_b64 s[0:1], s[0:1]
	v_mov_b32_e32 v128, v66
	s_or_b64 exec, exec, s[0:1]
.LBB0_593:
	s_or_b64 exec, exec, s[4:5]
	ds_read_b128 v[70:73], v220 offset:33792
	ds_read_b128 v[66:69], v220 offset:33856
	ds_read_u16 v80, v213 offset:33792
	ds_read_u16 v81, v213 offset:34320
	ds_read_u16 v82, v213 offset:34848
	ds_read_u16 v83, v213 offset:35376
	v_fmac_f32_e32 v159, v148, v154
	s_waitcnt lgkmcnt(5)
	v_mfma_f32_16x16x32_bf16 v[160:163], v[70:73], v[50:53], 0
	s_waitcnt lgkmcnt(2)
	v_lshlrev_b32_e32 v81, 16, v81
	v_lshlrev_b32_e32 v80, 16, v80
	s_waitcnt lgkmcnt(1)
	v_lshlrev_b32_e32 v82, 16, v82
	v_mfma_f32_16x16x32_bf16 v[176:179], v[66:69], v[54:57], v[160:163]
	s_waitcnt lgkmcnt(0)
; template <int DIR, int MODE>
; __device__ __forceinline__ void lru_pass(const Args& a, const LAS bf16_t* cxb, LAS bf16_t* gyb, const LAS float* carry, const bf16x8 (&Bw)[2][2][2], const float (&prm)[2][3], int l, int tt, float (&hf)[8][2][4]) {
;     ...
;     for (int mi = 0; mi < 8; ++mi) {
;         const int m = DIR ? 7 - mi : mi;
;         bf16x8 Af[2];
; #pragma unroll
;         for (int ks = 0; ks < 2; ++ks) Af[ks] = *(const LAS bf16x8*)(cxb + (m * 16 + fr) * CXS + 64 * h + 32 * ks + 8 * fq);
; #pragma unroll
;         for (int nt = 0; nt < 2; ++nt) {
;             f32x4 pr = (f32x4){0.f, 0.f, 0.f, 0.f}, pi = (f32x4){0.f, 0.f, 0.f, 0.f};
; #pragma unroll
;             for (int ks = 0; ks < 2; ++ks) { pr = __builtin_amdgcn_mfma_f32_16x16x32_bf16(Af[ks], Bw[0][nt][ks], pr, 0, 0, 0); pi = __builtin_amdgcn_mfma_f32_16x16x32_bf16(Af[ks], Bw[1][nt][ks], pi, 0, 0, 0); }
;             float av[4], bv[4];
; #pragma unroll
;             for (int reg = 0; reg < 4; ++reg) {
;                 const int tok = m * 16 + 4 * fq + reg;
;                 const float x = bf2f(cxb[tok * CXS + cc[nt]]);
;                 const float r = fsig(pr[reg] + ba[nt]), ig = fsig(pi[reg] + bxv[nt]);
;                 const float aa = __expf(k8[nt] * r);
;                 av[reg] = aa; bv[reg] = __builtin_amdgcn_sqrtf(fmaxf(1.0f - aa * aa, 0.f)) * ig * x;
;             }
;             float cum[4], hl[4];
;             if (DIR == 0) { cum[0] = av[0]; hl[0] = bv[0];
; #pragma unroll
;                 for (int reg = 1; reg < 4; ++reg) { cum[reg] = cum[reg - 1] * av[reg]; hl[reg] = av[reg] * hl[reg - 1] + bv[reg]; } }
;             else { cum[3] = av[3]; hl[3] = bv[3];
; #pragma unroll
;     ...
;             const float A4 = DIR ? cum[0] : cum[3], H4 = DIR ? hl[0] : hl[3];
;             float Aq[4], Hq[4];
; #pragma unroll
;             for (int q = 0; q < 4; ++q) { Aq[q] = __shfl(A4, fr + 16 * q); Hq[q] = __shfl(H4, fr + 16 * q); }
;             float hin;
;             if (DIR == 0) { const float s0 = C[nt], s1 = Aq[0] * s0 + Hq[0], s2 = Aq[1] * s1 + Hq[1], s3 = Aq[2] * s2 + Hq[2]; C[nt] = Aq[3] * s3 + Hq[3]; hin = fq == 0 ? s0 : (fq == 1 ? s1 : (fq == 2 ? s2 : s3)); }
;             else { const float s3 = C[nt], s2 = Aq[3] * s3 + Hq[3], s1 = Aq[2] * s2 + Hq[2], s0 = Aq[1] * s1 + Hq[1]; C[nt] = Aq[0] * s0 + Hq[0]; hin = fq == 3 ? s3 : (fq == 2 ? s2 : (fq == 1 ? s1 : s0)); }
	v_lshlrev_b32_e32 v83, 16, v83
	v_cmp_lt_i32_e64 s[0:1], 0, v200
	v_mfma_f32_16x16x32_bf16 v[164:167], v[70:73], v[58:61], 0
	v_mfma_f32_16x16x32_bf16 v[164:167], v[66:69], v[62:65], v[164:167]
	s_nop 2
	v_add_f32_e32 v147, v171, v176
	v_mul_f32_e32 v147, 0xbfb8aa3b, v147
	v_exp_f32_e32 v147, v147
	v_add_f32_e32 v155, v171, v177
	v_mul_f32_e32 v155, 0xbfb8aa3b, v155
	v_add_f32_e32 v149, v170, v164
	v_add_f32_e32 v147, 1.0, v147
	v_rcp_f32_e32 v147, v147
	v_mul_f32_e32 v149, 0xbfb8aa3b, v149
	v_exp_f32_e32 v149, v149
	v_exp_f32_e32 v155, v155
	v_add_f32_e32 v156, v170, v165
	v_mul_f32_e32 v156, 0xbfb8aa3b, v156
	v_mul_f32_e32 v147, v214, v147
	v_exp_f32_e32 v156, v156
	v_mul_f32_e32 v147, 0x3fb8aa3b, v147
	v_add_f32_e32 v149, 1.0, v149
	v_add_f32_e32 v155, 1.0, v155
	v_exp_f32_e32 v164, v147
	v_rcp_f32_e32 v147, v149
	v_rcp_f32_e32 v149, v155
	v_add_f32_e32 v156, 1.0, v156
	v_rcp_f32_e32 v155, v156
	v_fma_f32 v156, -v164, v164, 1.0
	v_max_f32_e32 v156, 0, v156
	v_mul_f32_e32 v149, v214, v149
	v_sqrt_f32_e32 v156, v156
	v_mul_f32_e32 v149, 0x3fb8aa3b, v149
	v_exp_f32_e32 v149, v149
	v_add_f32_e32 v158, v170, v167
	v_mul_f32_e32 v147, v147, v156
	v_mul_f32_e32 v163, v147, v80
	v_fma_f32 v147, -v149, v149, 1.0
	v_add_f32_e32 v156, v170, v166
	v_max_f32_e32 v147, 0, v147
	v_mul_f32_e32 v156, 0xbfb8aa3b, v156
	v_sqrt_f32_e32 v147, v147
	v_exp_f32_e32 v156, v156
	v_add_f32_e32 v80, v171, v178
	v_mul_f32_e32 v80, 0xbfb8aa3b, v80
	v_exp_f32_e32 v80, v80
	v_mul_f32_e32 v147, v155, v147
	v_add_f32_e32 v155, 1.0, v156
	v_add_f32_e32 v156, v171, v179
	v_mul_f32_e32 v156, 0xbfb8aa3b, v156
	v_exp_f32_e32 v156, v156
	v_add_f32_e32 v80, 1.0, v80
	v_rcp_f32_e32 v80, v80
	v_mul_f32_e32 v158, 0xbfb8aa3b, v158
	v_add_f32_e32 v156, 1.0, v156
	v_rcp_f32_e32 v156, v156
	v_mul_f32_e32 v80, v214, v80
	v_mul_f32_e32 v80, 0x3fb8aa3b, v80
	v_exp_f32_e32 v80, v80
	v_mul_f32_e32 v156, v214, v156
	v_mul_f32_e32 v156, 0x3fb8aa3b, v156
	v_exp_f32_e32 v156, v156
	v_exp_f32_e32 v158, v158
	v_fma_f32 v157, -v80, v80, 1.0
	v_max_f32_e32 v157, 0, v157
	v_rcp_f32_e32 v155, v155
	v_sqrt_f32_e32 v157, v157
	v_fma_f32 v160, -v156, v156, 1.0
	v_add_f32_e32 v158, 1.0, v158
	v_max_f32_e32 v160, 0, v160
	v_rcp_f32_e32 v158, v158
	v_sqrt_f32_e32 v160, v160
	v_mul_f32_e32 v162, v149, v163
	v_fmac_f32_e32 v162, v147, v81
	v_mul_f32_e32 v155, v155, v157
	v_mul_f32_e32 v161, v80, v162
	v_mul_f32_e32 v165, v149, v164
	v_fmac_f32_e32 v161, v155, v82
	v_mul_f32_e32 v157, v158, v160
	v_mul_f32_e32 v166, v80, v165
	v_mul_f32_e32 v160, v156, v161
	v_mul_f32_e32 v167, v156, v166
	v_fmac_f32_e32 v160, v157, v83
	s_nop 0
	s_nop 0
	s_nop 0
	s_nop 0
	s_nop 0
	s_nop 0
	v_mov_b32_e32 v155, v167
	v_mov_b32_e32 v156, v167
	s_nop 1
	v_permlane16_swap_b32_e32 v155, v156
	s_nop 1
	v_mov_b32_e32 v157, v155
	v_mov_b32_e32 v176, v156
	s_nop 1
	v_permlane32_swap_b32_e32 v155, v157
	v_permlane32_swap_b32_e32 v156, v176
	s_nop 1
	v_mov_b32_e32 v147, v160
	v_mov_b32_e32 v149, v160
	s_nop 1
	v_permlane16_swap_b32_e32 v147, v149
	s_nop 1
	v_mov_b32_e32 v174, v147
	v_mov_b32_e32 v182, v149
	s_nop 1
	v_permlane32_swap_b32_e32 v147, v174
	v_permlane32_swap_b32_e32 v149, v182
	s_nop 1
	s_waitcnt lgkmcnt(0)
	v_fmac_f32_e32 v147, v159, v155
	s_waitcnt lgkmcnt(0)
	v_fmac_f32_e32 v149, v147, v156
	s_waitcnt lgkmcnt(0)
	v_fmac_f32_e32 v174, v149, v157
	s_and_saveexec_b64 s[4:5], s[0:1]
	s_cbranch_execz .LBB0_599
	v_cmp_ne_u32_e64 s[0:1], 1, v200
	s_and_saveexec_b64 s[34:35], s[0:1]
	s_xor_b64 s[0:1], exec, s[34:35]
	v_cndmask_b32_e32 v159, v174, v149, vcc
	s_andn2_saveexec_b64 s[0:1], s[0:1]
	v_mov_b32_e32 v159, v147
	s_or_b64 exec, exec, s[0:1]
.LBB0_599:
	s_or_b64 exec, exec, s[4:5]
	v_mfma_f32_16x16x32_bf16 v[154:157], v[70:73], v[34:37], 0
	ds_read_u16 v80, v213 offset:33824
	v_fmac_f32_e32 v146, v173, v175
	v_cmp_lt_i32_e64 s[0:1], 0, v200
	v_mfma_f32_16x16x32_bf16 v[202:205], v[70:73], v[42:45], 0
	v_mfma_f32_16x16x32_bf16 v[70:73], v[66:69], v[38:41], v[154:157]
	v_mfma_f32_16x16x32_bf16 v[66:69], v[66:69], v[46:49], v[202:205]
	s_nop 6
	v_add_f32_e32 v70, v169, v70
	v_mul_f32_e32 v70, 0xbfb8aa3b, v70
	v_exp_f32_e32 v70, v70
	v_add_f32_e32 v66, v168, v66
	v_mul_f32_e32 v66, 0xbfb8aa3b, v66
	v_exp_f32_e32 v66, v66
	v_add_f32_e32 v70, 1.0, v70
	v_rcp_f32_e32 v70, v70
	v_add_f32_e32 v72, v169, v72
	v_add_f32_e32 v66, 1.0, v66
	v_rcp_f32_e32 v66, v66
	v_mul_f32_e32 v70, v215, v70
	v_mul_f32_e32 v70, 0x3fb8aa3b, v70
	v_exp_f32_e32 v148, v70
	v_mul_f32_e32 v72, 0xbfb8aa3b, v72
	v_exp_f32_e32 v72, v72
	v_add_f32_e32 v67, v168, v67
	v_fma_f32 v70, -v148, v148, 1.0
	v_max_f32_e32 v70, 0, v70
	v_sqrt_f32_e32 v70, v70
	v_add_f32_e32 v73, v169, v73
	v_mul_f32_e32 v67, 0xbfb8aa3b, v67
	v_add_f32_e32 v72, 1.0, v72
	v_mul_f32_e32 v66, v66, v70
	v_add_f32_e32 v70, v169, v71
	v_mul_f32_e32 v70, 0xbfb8aa3b, v70
	v_exp_f32_e32 v70, v70
	v_mul_f32_e32 v73, 0xbfb8aa3b, v73
	v_exp_f32_e32 v67, v67
	v_rcp_f32_e32 v72, v72
	v_add_f32_e32 v70, 1.0, v70
	v_rcp_f32_e32 v70, v70
	v_exp_f32_e32 v73, v73
	v_add_f32_e32 v67, 1.0, v67
	v_mul_f32_e32 v72, v215, v72
	v_mul_f32_e32 v70, v215, v70
	v_mul_f32_e32 v70, 0x3fb8aa3b, v70
	v_exp_f32_e32 v70, v70
	v_add_f32_e32 v73, 1.0, v73
	v_rcp_f32_e32 v67, v67
	v_add_f32_e32 v68, v168, v68
	v_fma_f32 v71, -v70, v70, 1.0
	v_max_f32_e32 v71, 0, v71
	v_sqrt_f32_e32 v71, v71
	v_mul_f32_e32 v72, 0x3fb8aa3b, v72
	v_rcp_f32_e32 v73, v73
	v_mul_f32_e32 v68, 0xbfb8aa3b, v68
	v_exp_f32_e32 v72, v72
	v_exp_f32_e32 v68, v68
	v_mul_f32_e32 v67, v67, v71
	ds_read_u16 v71, v213 offset:34880
	s_waitcnt lgkmcnt(1)
; template <int DIR, int MODE>
; __device__ __forceinline__ void lru_pass(const Args& a, const LAS bf16_t* cxb, LAS bf16_t* gyb, const LAS float* carry, const bf16x8 (&Bw)[2][2][2], const float (&prm)[2][3], int l, int tt, float (&hf)[8][2][4]) {
;     ...
;     for (int mi = 0; mi < 8; ++mi) {
;         const int m = DIR ? 7 - mi : mi;
;         bf16x8 Af[2];
; #pragma unroll
;         for (int ks = 0; ks < 2; ++ks) Af[ks] = *(const LAS bf16x8*)(cxb + (m * 16 + fr) * CXS + 64 * h + 32 * ks + 8 * fq);
; #pragma unroll
;         for (int nt = 0; nt < 2; ++nt) {
;             f32x4 pr = (f32x4){0.f, 0.f, 0.f, 0.f}, pi = (f32x4){0.f, 0.f, 0.f, 0.f};
; #pragma unroll
;             for (int ks = 0; ks < 2; ++ks) { pr = __builtin_amdgcn_mfma_f32_16x16x32_bf16(Af[ks], Bw[0][nt][ks], pr, 0, 0, 0); pi = __builtin_amdgcn_mfma_f32_16x16x32_bf16(Af[ks], Bw[1][nt][ks], pi, 0, 0, 0); }
;             float av[4], bv[4];
; #pragma unroll
;             for (int reg = 0; reg < 4; ++reg) {
;                 const int tok = m * 16 + 4 * fq + reg;
;                 const float x = bf2f(cxb[tok * CXS + cc[nt]]);
;                 const float r = fsig(pr[reg] + ba[nt]), ig = fsig(pi[reg] + bxv[nt]);
;                 const float aa = __expf(k8[nt] * r);
;                 av[reg] = aa; bv[reg] = __builtin_amdgcn_sqrtf(fmaxf(1.0f - aa * aa, 0.f)) * ig * x;
;             }
;             float cum[4], hl[4];
;             if (DIR == 0) { cum[0] = av[0]; hl[0] = bv[0];
; #pragma unroll
;                 for (int reg = 1; reg < 4; ++reg) { cum[reg] = cum[reg - 1] * av[reg]; hl[reg] = av[reg] * hl[reg - 1] + bv[reg]; } }
;             else { cum[3] = av[3]; hl[3] = bv[3];
; #pragma unroll
;     ...
;             const float A4 = DIR ? cum[0] : cum[3], H4 = DIR ? hl[0] : hl[3];
;             float Aq[4], Hq[4];
; #pragma unroll
;             for (int q = 0; q < 4; ++q) { Aq[q] = __shfl(A4, fr + 16 * q); Hq[q] = __shfl(H4, fr + 16 * q); }
;             float hin;
;             if (DIR == 0) { const float s0 = C[nt], s1 = Aq[0] * s0 + Hq[0], s2 = Aq[1] * s1 + Hq[1], s3 = Aq[2] * s2 + Hq[2]; C[nt] = Aq[3] * s3 + Hq[3]; hin = fq == 0 ? s0 : (fq == 1 ? s1 : (fq == 2 ? s2 : s3)); }
;             else { const float s3 = C[nt], s2 = Aq[3] * s3 + Hq[3], s1 = Aq[2] * s2 + Hq[2], s0 = Aq[1] * s1 + Hq[1]; C[nt] = Aq[0] * s0 + Hq[0]; hin = fq == 3 ? s3 : (fq == 2 ? s2 : (fq == 1 ? s1 : s0)); }
	v_lshlrev_b32_e32 v80, 16, v80
	v_mul_f32_e32 v73, v215, v73
	v_mul_f32_e32 v147, v66, v80
	v_fma_f32 v80, -v72, v72, 1.0
	v_add_f32_e32 v69, v168, v69
	v_mul_f32_e32 v73, 0x3fb8aa3b, v73
	v_add_f32_e32 v68, 1.0, v68
	v_max_f32_e32 v80, 0, v80
	v_mul_f32_e32 v69, 0xbfb8aa3b, v69
	v_exp_f32_e32 v73, v73
	ds_read_u16 v66, v213 offset:34352
	v_rcp_f32_e32 v68, v68
	v_sqrt_f32_e32 v80, v80
	v_exp_f32_e32 v69, v69
	v_fma_f32 v81, -v73, v73, 1.0
	v_max_f32_e32 v81, 0, v81
	v_mul_f32_e32 v68, v68, v80
	ds_read_u16 v80, v213 offset:35408
	v_add_f32_e32 v69, 1.0, v69
	s_waitcnt lgkmcnt(1)
	v_lshlrev_b32_e32 v66, 16, v66
	v_rcp_f32_e32 v69, v69
	v_sqrt_f32_e32 v81, v81
	v_mul_f32_e32 v155, v70, v147
	v_fmac_f32_e32 v155, v67, v66
	v_lshlrev_b32_e32 v71, 16, v71
	v_mul_f32_e32 v154, v72, v155
	v_mul_f32_e32 v156, v70, v148
	v_fmac_f32_e32 v154, v68, v71
	s_waitcnt lgkmcnt(0)
	v_lshlrev_b32_e32 v80, 16, v80
	v_mul_f32_e32 v69, v69, v81
	v_mul_f32_e32 v157, v72, v156
	v_mul_f32_e32 v149, v73, v154
	v_mul_f32_e32 v158, v73, v157
	v_fmac_f32_e32 v149, v69, v80
	s_nop 0
	s_nop 0
	s_nop 0
	s_nop 0
	s_nop 0
	s_nop 0
	v_mov_b32_e32 v68, v158
	v_mov_b32_e32 v69, v158
	s_nop 1
	v_permlane16_swap_b32_e32 v68, v69
	s_nop 1
	v_mov_b32_e32 v70, v68
	v_mov_b32_e32 v209, v69
	s_nop 1
	v_permlane32_swap_b32_e32 v68, v70
	v_permlane32_swap_b32_e32 v69, v209
	s_nop 1
	v_mov_b32_e32 v66, v149
	v_mov_b32_e32 v67, v149
	s_nop 1
	v_permlane16_swap_b32_e32 v66, v67
	s_nop 1
	v_mov_b32_e32 v208, v66
	v_mov_b32_e32 v172, v67
	s_nop 1
	v_permlane32_swap_b32_e32 v66, v208
	v_permlane32_swap_b32_e32 v67, v172
	s_nop 1
	s_waitcnt lgkmcnt(0)
	v_fmac_f32_e32 v66, v146, v68
	s_waitcnt lgkmcnt(0)
	v_fmac_f32_e32 v67, v66, v69
	s_waitcnt lgkmcnt(0)
	v_fmac_f32_e32 v208, v67, v70
	s_and_saveexec_b64 s[4:5], s[0:1]
	s_cbranch_execz .LBB0_605
	v_cmp_ne_u32_e64 s[0:1], 1, v200
	s_and_saveexec_b64 s[34:35], s[0:1]
	s_xor_b64 s[0:1], exec, s[34:35]
	v_cndmask_b32_e32 v146, v208, v67, vcc
	s_andn2_saveexec_b64 s[0:1], s[0:1]
	v_mov_b32_e32 v146, v66
	s_or_b64 exec, exec, s[0:1]
.LBB0_605:
	s_or_b64 exec, exec, s[4:5]
	ds_read_b128 v[70:73], v220 offset:42240
	ds_read_b128 v[66:69], v220 offset:42304
	ds_read_u16 v80, v213 offset:42240
	ds_read_u16 v81, v213 offset:42768
	ds_read_u16 v82, v213 offset:43296
	ds_read_u16 v83, v213 offset:43824
	v_fmac_f32_e32 v182, v174, v176
	s_waitcnt lgkmcnt(5)
	v_mfma_f32_16x16x32_bf16 v[202:205], v[70:73], v[50:53], 0
	s_waitcnt lgkmcnt(2)
	v_lshlrev_b32_e32 v81, 16, v81
	v_lshlrev_b32_e32 v80, 16, v80
	s_waitcnt lgkmcnt(1)
	v_lshlrev_b32_e32 v82, 16, v82
	v_mfma_f32_16x16x32_bf16 v[202:205], v[66:69], v[54:57], v[202:205]
	s_waitcnt lgkmcnt(0)
	v_lshlrev_b32_e32 v83, 16, v83
	v_cmp_lt_i32_e64 s[0:1], 0, v200
	v_mfma_f32_16x16x32_bf16 v[230:233], v[70:73], v[58:61], 0
	v_mfma_f32_16x16x32_bf16 v[230:233], v[66:69], v[62:65], v[230:233]
	s_nop 2
	v_add_f32_e32 v173, v171, v202
	v_mul_f32_e32 v173, 0xbfb8aa3b, v173
	v_exp_f32_e32 v173, v173
	v_add_f32_e32 v177, v171, v203
	v_mul_f32_e32 v177, 0xbfb8aa3b, v177
	v_add_f32_e32 v175, v170, v230
	v_add_f32_e32 v173, 1.0, v173
	v_rcp_f32_e32 v173, v173
	v_mul_f32_e32 v175, 0xbfb8aa3b, v175
	v_exp_f32_e32 v175, v175
	v_exp_f32_e32 v177, v177
	v_add_f32_e32 v178, v170, v231
	v_mul_f32_e32 v178, 0xbfb8aa3b, v178
	v_mul_f32_e32 v173, v214, v173
	v_exp_f32_e32 v178, v178
	v_mul_f32_e32 v173, 0x3fb8aa3b, v173
	v_add_f32_e32 v175, 1.0, v175
	v_add_f32_e32 v177, 1.0, v177
	v_exp_f32_e32 v203, v173
	v_rcp_f32_e32 v173, v175
	v_rcp_f32_e32 v175, v177
	v_add_f32_e32 v178, 1.0, v178
	v_rcp_f32_e32 v177, v178
	v_fma_f32 v178, -v203, v203, 1.0
	v_max_f32_e32 v178, 0, v178
	v_mul_f32_e32 v175, v214, v175
	v_sqrt_f32_e32 v178, v178
	v_mul_f32_e32 v175, 0x3fb8aa3b, v175
	v_exp_f32_e32 v175, v175
	v_add_f32_e32 v180, v170, v233
	v_mul_f32_e32 v173, v173, v178
	v_mul_f32_e32 v202, v173, v80
	v_fma_f32 v173, -v175, v175, 1.0
	v_add_f32_e32 v178, v170, v232
	v_max_f32_e32 v173, 0, v173
	v_mul_f32_e32 v178, 0xbfb8aa3b, v178
	v_sqrt_f32_e32 v173, v173
	v_exp_f32_e32 v178, v178
	v_add_f32_e32 v80, v171, v204
	v_mul_f32_e32 v80, 0xbfb8aa3b, v80
	v_exp_f32_e32 v80, v80
	v_mul_f32_e32 v173, v177, v173
	v_add_f32_e32 v177, 1.0, v178
	v_add_f32_e32 v178, v171, v205
	v_mul_f32_e32 v178, 0xbfb8aa3b, v178
	v_exp_f32_e32 v178, v178
	v_add_f32_e32 v80, 1.0, v80
	v_rcp_f32_e32 v80, v80
	v_mul_f32_e32 v180, 0xbfb8aa3b, v180
	v_add_f32_e32 v178, 1.0, v178
	v_rcp_f32_e32 v178, v178
	v_mul_f32_e32 v80, v214, v80
	v_mul_f32_e32 v80, 0x3fb8aa3b, v80
	v_exp_f32_e32 v80, v80
	v_mul_f32_e32 v178, v214, v178
	v_mul_f32_e32 v178, 0x3fb8aa3b, v178
	v_exp_f32_e32 v178, v178
	v_exp_f32_e32 v180, v180
	v_fma_f32 v179, -v80, v80, 1.0
	v_max_f32_e32 v179, 0, v179
	v_rcp_f32_e32 v177, v177
	v_sqrt_f32_e32 v179, v179
	v_fma_f32 v198, -v178, v178, 1.0
	v_add_f32_e32 v180, 1.0, v180
	v_max_f32_e32 v198, 0, v198
	v_rcp_f32_e32 v180, v180
	v_sqrt_f32_e32 v198, v198
	v_mul_f32_e32 v201, v175, v202
	v_fmac_f32_e32 v201, v173, v81
	v_mul_f32_e32 v177, v177, v179
	v_mul_f32_e32 v199, v80, v201
	v_mul_f32_e32 v204, v175, v203
	v_fmac_f32_e32 v199, v177, v82
	v_mul_f32_e32 v179, v180, v198
	v_mul_f32_e32 v205, v80, v204
	v_mul_f32_e32 v198, v178, v199
	v_mul_f32_e32 v206, v178, v205
	v_fmac_f32_e32 v198, v179, v83
	s_nop 0
	s_nop 0
	s_nop 0
	s_nop 0
	s_nop 0
	s_nop 0
	v_mov_b32_e32 v177, v206
	v_mov_b32_e32 v178, v206
	s_nop 1
	v_permlane16_swap_b32_e32 v177, v178
	s_nop 1
	v_mov_b32_e32 v179, v177
	v_mov_b32_e32 v219, v178
	s_nop 1
	v_permlane32_swap_b32_e32 v177, v179
	v_permlane32_swap_b32_e32 v178, v219
	s_nop 1
	v_mov_b32_e32 v173, v198
	v_mov_b32_e32 v175, v198
	s_nop 1
	v_permlane16_swap_b32_e32 v173, v175
	s_nop 1
	v_mov_b32_e32 v217, v173
	v_mov_b32_e32 v224, v175
	s_nop 1
	v_permlane32_swap_b32_e32 v173, v217
	v_permlane32_swap_b32_e32 v175, v224
	s_nop 1
	s_waitcnt lgkmcnt(0)
	v_fmac_f32_e32 v173, v182, v177
	s_waitcnt lgkmcnt(0)
	v_fmac_f32_e32 v175, v173, v178
	s_waitcnt lgkmcnt(0)
	v_fmac_f32_e32 v217, v175, v179
	s_and_saveexec_b64 s[4:5], s[0:1]
	s_cbranch_execz .LBB0_611
	v_cmp_ne_u32_e64 s[0:1], 1, v200
	s_and_saveexec_b64 s[34:35], s[0:1]
	s_xor_b64 s[0:1], exec, s[34:35]
	v_cndmask_b32_e32 v182, v217, v175, vcc
	s_andn2_saveexec_b64 s[0:1], s[0:1]
	v_mov_b32_e32 v182, v173
	s_or_b64 exec, exec, s[0:1]
; template <int DIR, int MODE>
; __device__ __forceinline__ void lru_pass(const Args& a, const LAS bf16_t* cxb, LAS bf16_t* gyb, const LAS float* carry, const bf16x8 (&Bw)[2][2][2], const float (&prm)[2][3], int l, int tt, float (&hf)[8][2][4]) {
;     ...
;     for (int mi = 0; mi < 8; ++mi) {
;         const int m = DIR ? 7 - mi : mi;
;         bf16x8 Af[2];
; #pragma unroll
;         for (int ks = 0; ks < 2; ++ks) Af[ks] = *(const LAS bf16x8*)(cxb + (m * 16 + fr) * CXS + 64 * h + 32 * ks + 8 * fq);
; #pragma unroll
;         for (int nt = 0; nt < 2; ++nt) {
;             f32x4 pr = (f32x4){0.f, 0.f, 0.f, 0.f}, pi = (f32x4){0.f, 0.f, 0.f, 0.f};
; #pragma unroll
;             for (int ks = 0; ks < 2; ++ks) { pr = __builtin_amdgcn_mfma_f32_16x16x32_bf16(Af[ks], Bw[0][nt][ks], pr, 0, 0, 0); pi = __builtin_amdgcn_mfma_f32_16x16x32_bf16(Af[ks], Bw[1][nt][ks], pi, 0, 0, 0); }
;             float av[4], bv[4];
; #pragma unroll
;             for (int reg = 0; reg < 4; ++reg) {
;                 const int tok = m * 16 + 4 * fq + reg;
;                 const float x = bf2f(cxb[tok * CXS + cc[nt]]);
;                 const float r = fsig(pr[reg] + ba[nt]), ig = fsig(pi[reg] + bxv[nt]);
;                 const float aa = __expf(k8[nt] * r);
;                 av[reg] = aa; bv[reg] = __builtin_amdgcn_sqrtf(fmaxf(1.0f - aa * aa, 0.f)) * ig * x;
;             }
;             float cum[4], hl[4];
;             if (DIR == 0) { cum[0] = av[0]; hl[0] = bv[0];
; #pragma unroll
;                 for (int reg = 1; reg < 4; ++reg) { cum[reg] = cum[reg - 1] * av[reg]; hl[reg] = av[reg] * hl[reg - 1] + bv[reg]; } }
;             else { cum[3] = av[3]; hl[3] = bv[3];
; #pragma unroll
;     ...
;             const float A4 = DIR ? cum[0] : cum[3], H4 = DIR ? hl[0] : hl[3];
;             float Aq[4], Hq[4];
; #pragma unroll
;             for (int q = 0; q < 4; ++q) { Aq[q] = __shfl(A4, fr + 16 * q); Hq[q] = __shfl(H4, fr + 16 * q); }
;             float hin;
;             if (DIR == 0) { const float s0 = C[nt], s1 = Aq[0] * s0 + Hq[0], s2 = Aq[1] * s1 + Hq[1], s3 = Aq[2] * s2 + Hq[2]; C[nt] = Aq[3] * s3 + Hq[3]; hin = fq == 0 ? s0 : (fq == 1 ? s1 : (fq == 2 ? s2 : s3)); }
;             else { const float s3 = C[nt], s2 = Aq[3] * s3 + Hq[3], s1 = Aq[2] * s2 + Hq[2], s0 = Aq[1] * s1 + Hq[1]; C[nt] = Aq[0] * s0 + Hq[0]; hin = fq == 3 ? s3 : (fq == 2 ? s2 : (fq == 1 ? s1 : s0)); }
.LBB0_611:
	s_or_b64 exec, exec, s[4:5]
	v_mfma_f32_16x16x32_bf16 v[174:177], v[70:73], v[34:37], 0
	ds_read_u16 v80, v213 offset:42272
	v_fmac_f32_e32 v172, v208, v209
	v_cmp_lt_i32_e64 s[0:1], 0, v200
	v_mfma_f32_16x16x32_bf16 v[230:233], v[70:73], v[42:45], 0
	v_mfma_f32_16x16x32_bf16 v[70:73], v[66:69], v[38:41], v[174:177]
	v_mfma_f32_16x16x32_bf16 v[66:69], v[66:69], v[46:49], v[230:233]
	s_nop 6
	v_add_f32_e32 v70, v169, v70
	v_mul_f32_e32 v70, 0xbfb8aa3b, v70
	v_exp_f32_e32 v70, v70
	v_add_f32_e32 v66, v168, v66
	v_mul_f32_e32 v66, 0xbfb8aa3b, v66
	v_exp_f32_e32 v66, v66
	v_add_f32_e32 v70, 1.0, v70
	v_rcp_f32_e32 v70, v70
	v_add_f32_e32 v72, v169, v72
	v_add_f32_e32 v66, 1.0, v66
	v_rcp_f32_e32 v66, v66
	v_mul_f32_e32 v70, v215, v70
	v_mul_f32_e32 v70, 0x3fb8aa3b, v70
	v_exp_f32_e32 v174, v70
	v_mul_f32_e32 v72, 0xbfb8aa3b, v72
	v_exp_f32_e32 v72, v72
	v_add_f32_e32 v67, v168, v67
	v_fma_f32 v70, -v174, v174, 1.0
	v_max_f32_e32 v70, 0, v70
	v_sqrt_f32_e32 v70, v70
	v_add_f32_e32 v73, v169, v73
	v_mul_f32_e32 v67, 0xbfb8aa3b, v67
	v_add_f32_e32 v72, 1.0, v72
	v_mul_f32_e32 v66, v66, v70
	v_add_f32_e32 v70, v169, v71
	v_mul_f32_e32 v70, 0xbfb8aa3b, v70
	v_exp_f32_e32 v70, v70
	v_mul_f32_e32 v73, 0xbfb8aa3b, v73
	v_exp_f32_e32 v67, v67
	v_rcp_f32_e32 v72, v72
	v_add_f32_e32 v70, 1.0, v70
	v_rcp_f32_e32 v70, v70
	v_exp_f32_e32 v73, v73
	v_add_f32_e32 v67, 1.0, v67
	v_mul_f32_e32 v72, v215, v72
	v_mul_f32_e32 v70, v215, v70
	v_mul_f32_e32 v70, 0x3fb8aa3b, v70
	v_exp_f32_e32 v70, v70
	v_add_f32_e32 v73, 1.0, v73
	v_rcp_f32_e32 v67, v67
	v_add_f32_e32 v68, v168, v68
	v_fma_f32 v71, -v70, v70, 1.0
	v_max_f32_e32 v71, 0, v71
	v_sqrt_f32_e32 v71, v71
	v_mul_f32_e32 v72, 0x3fb8aa3b, v72
	v_rcp_f32_e32 v73, v73
	v_mul_f32_e32 v68, 0xbfb8aa3b, v68
	v_exp_f32_e32 v72, v72
	v_exp_f32_e32 v68, v68
	v_mul_f32_e32 v67, v67, v71
	ds_read_u16 v71, v213 offset:43328
	s_waitcnt lgkmcnt(1)
	v_lshlrev_b32_e32 v80, 16, v80
	v_mul_f32_e32 v73, v215, v73
	v_mul_f32_e32 v173, v66, v80
	v_fma_f32 v80, -v72, v72, 1.0
	v_add_f32_e32 v69, v168, v69
	v_mul_f32_e32 v73, 0x3fb8aa3b, v73
	v_add_f32_e32 v68, 1.0, v68
	v_max_f32_e32 v80, 0, v80
	v_mul_f32_e32 v69, 0xbfb8aa3b, v69
	v_exp_f32_e32 v73, v73
	ds_read_u16 v66, v213 offset:42800
	v_rcp_f32_e32 v68, v68
	v_sqrt_f32_e32 v80, v80
	v_exp_f32_e32 v69, v69
	v_fma_f32 v81, -v73, v73, 1.0
	v_max_f32_e32 v81, 0, v81
	v_mul_f32_e32 v68, v68, v80
	ds_read_u16 v80, v213 offset:43856
	v_add_f32_e32 v69, 1.0, v69
	s_waitcnt lgkmcnt(1)
	v_lshlrev_b32_e32 v66, 16, v66
	v_rcp_f32_e32 v69, v69
	v_sqrt_f32_e32 v81, v81
	v_mul_f32_e32 v177, v70, v173
	v_fmac_f32_e32 v177, v67, v66
	v_lshlrev_b32_e32 v71, 16, v71
	v_mul_f32_e32 v176, v72, v177
	v_mul_f32_e32 v178, v70, v174
	v_fmac_f32_e32 v176, v68, v71
	s_waitcnt lgkmcnt(0)
	v_lshlrev_b32_e32 v80, 16, v80
	v_mul_f32_e32 v69, v69, v81
	v_mul_f32_e32 v179, v72, v178
	v_mul_f32_e32 v175, v73, v176
	v_mul_f32_e32 v180, v73, v179
	v_fmac_f32_e32 v175, v69, v80
	s_nop 0
	s_nop 0
	s_nop 0
	s_nop 0
	s_nop 0
	s_nop 0
	v_mov_b32_e32 v68, v180
	v_mov_b32_e32 v69, v180
	s_nop 1
	v_permlane16_swap_b32_e32 v68, v69
	s_nop 1
	v_mov_b32_e32 v70, v68
	v_mov_b32_e32 v236, v69
	s_nop 1
	v_permlane32_swap_b32_e32 v68, v70
	v_permlane32_swap_b32_e32 v69, v236
	s_nop 1
	v_mov_b32_e32 v66, v175
	v_mov_b32_e32 v67, v175
	s_nop 1
	v_permlane16_swap_b32_e32 v66, v67
	s_nop 1
	v_mov_b32_e32 v243, v66
	v_mov_b32_e32 v216, v67
	s_nop 1
	v_permlane32_swap_b32_e32 v66, v243
	v_permlane32_swap_b32_e32 v67, v216
	s_nop 1
	s_waitcnt lgkmcnt(0)
	v_fmac_f32_e32 v66, v172, v68
	s_waitcnt lgkmcnt(0)
	v_fmac_f32_e32 v67, v66, v69
	s_waitcnt lgkmcnt(0)
	v_fmac_f32_e32 v243, v67, v70
	s_and_saveexec_b64 s[4:5], s[0:1]
	s_cbranch_execz .LBB0_617
	v_cmp_ne_u32_e64 s[0:1], 1, v200
	s_and_saveexec_b64 s[34:35], s[0:1]
	s_xor_b64 s[0:1], exec, s[34:35]
	v_cndmask_b32_e32 v172, v243, v67, vcc
	s_andn2_saveexec_b64 s[0:1], s[0:1]
	v_mov_b32_e32 v172, v66
	s_or_b64 exec, exec, s[0:1]
.LBB0_617:
	s_or_b64 exec, exec, s[4:5]
	ds_read_b128 v[70:73], v220 offset:50688
	ds_read_b128 v[66:69], v220 offset:50752
	ds_read_u16 v80, v213 offset:50688
	ds_read_u16 v81, v213 offset:51216
	ds_read_u16 v82, v213 offset:51744
	ds_read_u16 v83, v213 offset:52272
	v_fmac_f32_e32 v224, v217, v219
	s_waitcnt lgkmcnt(5)
	v_mfma_f32_16x16x32_bf16 v[230:233], v[70:73], v[50:53], 0
	s_waitcnt lgkmcnt(2)
	v_lshlrev_b32_e32 v81, 16, v81
	v_lshlrev_b32_e32 v80, 16, v80
	s_waitcnt lgkmcnt(1)
	v_lshlrev_b32_e32 v82, 16, v82
	v_mfma_f32_16x16x32_bf16 v[238:241], v[66:69], v[54:57], v[230:233]
	s_waitcnt lgkmcnt(0)
; template <int DIR, int MODE>
; __device__ __forceinline__ void lru_pass(const Args& a, const LAS bf16_t* cxb, LAS bf16_t* gyb, const LAS float* carry, const bf16x8 (&Bw)[2][2][2], const float (&prm)[2][3], int l, int tt, float (&hf)[8][2][4]) {
;     ...
;     for (int mi = 0; mi < 8; ++mi) {
;         const int m = DIR ? 7 - mi : mi;
;         bf16x8 Af[2];
; #pragma unroll
;         for (int ks = 0; ks < 2; ++ks) Af[ks] = *(const LAS bf16x8*)(cxb + (m * 16 + fr) * CXS + 64 * h + 32 * ks + 8 * fq);
; #pragma unroll
;         for (int nt = 0; nt < 2; ++nt) {
;             f32x4 pr = (f32x4){0.f, 0.f, 0.f, 0.f}, pi = (f32x4){0.f, 0.f, 0.f, 0.f};
; #pragma unroll
;             for (int ks = 0; ks < 2; ++ks) { pr = __builtin_amdgcn_mfma_f32_16x16x32_bf16(Af[ks], Bw[0][nt][ks], pr, 0, 0, 0); pi = __builtin_amdgcn_mfma_f32_16x16x32_bf16(Af[ks], Bw[1][nt][ks], pi, 0, 0, 0); }
;             float av[4], bv[4];
; #pragma unroll
;             for (int reg = 0; reg < 4; ++reg) {
;                 const int tok = m * 16 + 4 * fq + reg;
;                 const float x = bf2f(cxb[tok * CXS + cc[nt]]);
;                 const float r = fsig(pr[reg] + ba[nt]), ig = fsig(pi[reg] + bxv[nt]);
;                 const float aa = __expf(k8[nt] * r);
;                 av[reg] = aa; bv[reg] = __builtin_amdgcn_sqrtf(fmaxf(1.0f - aa * aa, 0.f)) * ig * x;
;             }
;             float cum[4], hl[4];
;             if (DIR == 0) { cum[0] = av[0]; hl[0] = bv[0];
; #pragma unroll
;                 for (int reg = 1; reg < 4; ++reg) { cum[reg] = cum[reg - 1] * av[reg]; hl[reg] = av[reg] * hl[reg - 1] + bv[reg]; } }
;             else { cum[3] = av[3]; hl[3] = bv[3];
; #pragma unroll
;     ...
;             const float A4 = DIR ? cum[0] : cum[3], H4 = DIR ? hl[0] : hl[3];
;             float Aq[4], Hq[4];
; #pragma unroll
;             for (int q = 0; q < 4; ++q) { Aq[q] = __shfl(A4, fr + 16 * q); Hq[q] = __shfl(H4, fr + 16 * q); }
;             float hin;
;             if (DIR == 0) { const float s0 = C[nt], s1 = Aq[0] * s0 + Hq[0], s2 = Aq[1] * s1 + Hq[1], s3 = Aq[2] * s2 + Hq[2]; C[nt] = Aq[3] * s3 + Hq[3]; hin = fq == 0 ? s0 : (fq == 1 ? s1 : (fq == 2 ? s2 : s3)); }
;             else { const float s3 = C[nt], s2 = Aq[3] * s3 + Hq[3], s1 = Aq[2] * s2 + Hq[2], s0 = Aq[1] * s1 + Hq[1]; C[nt] = Aq[0] * s0 + Hq[0]; hin = fq == 3 ? s3 : (fq == 2 ? s2 : (fq == 1 ? s1 : s0)); }
	v_lshlrev_b32_e32 v83, 16, v83
	v_cmp_lt_i32_e64 s[0:1], 0, v200
	v_mfma_f32_16x16x32_bf16 v[246:249], v[70:73], v[58:61], 0
	v_mfma_f32_16x16x32_bf16 v[246:249], v[66:69], v[62:65], v[246:249]
	s_nop 2
	v_add_f32_e32 v208, v171, v238
	v_mul_f32_e32 v208, 0xbfb8aa3b, v208
	v_exp_f32_e32 v208, v208
	v_add_f32_e32 v221, v171, v239
	v_mul_f32_e32 v221, 0xbfb8aa3b, v221
	v_add_f32_e32 v209, v170, v246
	v_add_f32_e32 v208, 1.0, v208
	v_rcp_f32_e32 v208, v208
	v_mul_f32_e32 v209, 0xbfb8aa3b, v209
	v_exp_f32_e32 v209, v209
	v_exp_f32_e32 v221, v221
	v_add_f32_e32 v223, v170, v247
	v_mul_f32_e32 v223, 0xbfb8aa3b, v223
	v_mul_f32_e32 v208, v214, v208
	v_exp_f32_e32 v223, v223
	v_mul_f32_e32 v208, 0x3fb8aa3b, v208
	v_add_f32_e32 v209, 1.0, v209
	v_add_f32_e32 v221, 1.0, v221
	v_exp_f32_e32 v233, v208
	v_rcp_f32_e32 v208, v209
	v_rcp_f32_e32 v209, v221
	v_add_f32_e32 v223, 1.0, v223
	v_rcp_f32_e32 v221, v223
	v_fma_f32 v223, -v233, v233, 1.0
	v_max_f32_e32 v223, 0, v223
	v_mul_f32_e32 v209, v214, v209
	v_sqrt_f32_e32 v223, v223
	v_mul_f32_e32 v209, 0x3fb8aa3b, v209
	v_exp_f32_e32 v209, v209
	v_add_f32_e32 v228, v170, v249
	v_mul_f32_e32 v208, v208, v223
	v_mul_f32_e32 v232, v208, v80
	v_fma_f32 v208, -v209, v209, 1.0
	v_add_f32_e32 v223, v170, v248
	v_max_f32_e32 v208, 0, v208
	v_mul_f32_e32 v223, 0xbfb8aa3b, v223
	v_sqrt_f32_e32 v208, v208
	v_exp_f32_e32 v223, v223
	v_add_f32_e32 v80, v171, v240
	v_mul_f32_e32 v80, 0xbfb8aa3b, v80
	v_exp_f32_e32 v80, v80
	v_mul_f32_e32 v221, v221, v208
	v_add_f32_e32 v208, 1.0, v223
	v_add_f32_e32 v223, v171, v241
	v_mul_f32_e32 v223, 0xbfb8aa3b, v223
	v_exp_f32_e32 v223, v223
	v_add_f32_e32 v80, 1.0, v80
	v_rcp_f32_e32 v80, v80
	v_mul_f32_e32 v228, 0xbfb8aa3b, v228
	v_add_f32_e32 v223, 1.0, v223
	v_rcp_f32_e32 v223, v223
	v_mul_f32_e32 v80, v214, v80
	v_mul_f32_e32 v80, 0x3fb8aa3b, v80
	v_exp_f32_e32 v80, v80
	v_mul_f32_e32 v223, v214, v223
	v_mul_f32_e32 v223, 0x3fb8aa3b, v223
	v_exp_f32_e32 v223, v223
	v_exp_f32_e32 v228, v228
	v_fma_f32 v225, -v80, v80, 1.0
	v_max_f32_e32 v225, 0, v225
	v_rcp_f32_e32 v208, v208
	v_sqrt_f32_e32 v225, v225
	v_fma_f32 v230, -v223, v223, 1.0
	v_add_f32_e32 v228, 1.0, v228
	v_max_f32_e32 v230, 0, v230
	v_rcp_f32_e32 v228, v228
	v_sqrt_f32_e32 v230, v230
	v_mul_f32_e32 v239, v209, v232
	v_fmac_f32_e32 v239, v221, v81
	v_mul_f32_e32 v225, v208, v225
	v_mul_f32_e32 v238, v80, v239
	v_mul_f32_e32 v208, v209, v233
	v_fmac_f32_e32 v238, v225, v82
	v_mul_f32_e32 v230, v228, v230
	v_mul_f32_e32 v209, v80, v208
	v_mul_f32_e32 v225, v223, v238
	v_mul_f32_e32 v228, v223, v209
	v_fmac_f32_e32 v225, v230, v83
	s_nop 0
	s_nop 0
	s_nop 0
	s_nop 0
	s_nop 0
	s_nop 0
	v_mov_b32_e32 v242, v228
	v_mov_b32_e32 v246, v228
	s_nop 1
	v_permlane16_swap_b32_e32 v242, v246
	s_nop 1
	v_mov_b32_e32 v247, v242
	v_mov_b32_e32 v223, v246
	s_nop 1
	v_permlane32_swap_b32_e32 v242, v247
	v_permlane32_swap_b32_e32 v246, v223
	s_nop 1
	v_mov_b32_e32 v221, v225
	v_mov_b32_e32 v241, v225
	s_nop 1
	v_permlane16_swap_b32_e32 v221, v241
	s_nop 1
	v_mov_b32_e32 v231, v221
	v_mov_b32_e32 v230, v241
	s_nop 1
	v_permlane32_swap_b32_e32 v221, v231
	v_permlane32_swap_b32_e32 v241, v230
	s_nop 1
	s_waitcnt lgkmcnt(0)
	v_fmac_f32_e32 v221, v224, v242
	s_waitcnt lgkmcnt(0)
	v_fmac_f32_e32 v241, v221, v246
	s_waitcnt lgkmcnt(0)
	v_fmac_f32_e32 v231, v241, v247
	s_and_saveexec_b64 s[4:5], s[0:1]
	s_cbranch_execz .LBB0_623
	v_cmp_ne_u32_e64 s[0:1], 1, v200
	s_and_saveexec_b64 s[34:35], s[0:1]
	s_xor_b64 s[0:1], exec, s[34:35]
	v_cndmask_b32_e32 v224, v231, v241, vcc
	s_andn2_saveexec_b64 s[0:1], s[0:1]
	v_mov_b32_e32 v224, v221
	s_or_b64 exec, exec, s[0:1]
; template <int DIR, int MODE>
; __device__ __forceinline__ void lru_pass(const Args& a, const LAS bf16_t* cxb, LAS bf16_t* gyb, const LAS float* carry, const bf16x8 (&Bw)[2][2][2], const float (&prm)[2][3], int l, int tt, float (&hf)[8][2][4]) {
;     ...
;     for (int mi = 0; mi < 8; ++mi) {
;         const int m = DIR ? 7 - mi : mi;
;         bf16x8 Af[2];
; #pragma unroll
;         for (int ks = 0; ks < 2; ++ks) Af[ks] = *(const LAS bf16x8*)(cxb + (m * 16 + fr) * CXS + 64 * h + 32 * ks + 8 * fq);
; #pragma unroll
;         for (int nt = 0; nt < 2; ++nt) {
;             f32x4 pr = (f32x4){0.f, 0.f, 0.f, 0.f}, pi = (f32x4){0.f, 0.f, 0.f, 0.f};
; #pragma unroll
;             for (int ks = 0; ks < 2; ++ks) { pr = __builtin_amdgcn_mfma_f32_16x16x32_bf16(Af[ks], Bw[0][nt][ks], pr, 0, 0, 0); pi = __builtin_amdgcn_mfma_f32_16x16x32_bf16(Af[ks], Bw[1][nt][ks], pi, 0, 0, 0); }
;             float av[4], bv[4];
; #pragma unroll
;             for (int reg = 0; reg < 4; ++reg) {
;                 const int tok = m * 16 + 4 * fq + reg;
;                 const float x = bf2f(cxb[tok * CXS + cc[nt]]);
;                 const float r = fsig(pr[reg] + ba[nt]), ig = fsig(pi[reg] + bxv[nt]);
;                 const float aa = __expf(k8[nt] * r);
;                 av[reg] = aa; bv[reg] = __builtin_amdgcn_sqrtf(fmaxf(1.0f - aa * aa, 0.f)) * ig * x;
;             }
;             float cum[4], hl[4];
;             if (DIR == 0) { cum[0] = av[0]; hl[0] = bv[0];
; #pragma unroll
;                 for (int reg = 1; reg < 4; ++reg) { cum[reg] = cum[reg - 1] * av[reg]; hl[reg] = av[reg] * hl[reg - 1] + bv[reg]; } }
;             else { cum[3] = av[3]; hl[3] = bv[3];
; #pragma unroll
;     ...
;             const float A4 = DIR ? cum[0] : cum[3], H4 = DIR ? hl[0] : hl[3];
;             float Aq[4], Hq[4];
; #pragma unroll
;             for (int q = 0; q < 4; ++q) { Aq[q] = __shfl(A4, fr + 16 * q); Hq[q] = __shfl(H4, fr + 16 * q); }
;             float hin;
;             if (DIR == 0) { const float s0 = C[nt], s1 = Aq[0] * s0 + Hq[0], s2 = Aq[1] * s1 + Hq[1], s3 = Aq[2] * s2 + Hq[2]; C[nt] = Aq[3] * s3 + Hq[3]; hin = fq == 0 ? s0 : (fq == 1 ? s1 : (fq == 2 ? s2 : s3)); }
;             else { const float s3 = C[nt], s2 = Aq[3] * s3 + Hq[3], s1 = Aq[2] * s2 + Hq[2], s0 = Aq[1] * s1 + Hq[1]; C[nt] = Aq[0] * s0 + Hq[0]; hin = fq == 3 ? s3 : (fq == 2 ? s2 : (fq == 1 ? s1 : s0)); }
.LBB0_623:
	s_or_b64 exec, exec, s[4:5]
	v_mfma_f32_16x16x32_bf16 v[246:249], v[70:73], v[34:37], 0
	v_fmac_f32_e32 v216, v243, v236
	v_cmp_lt_i32_e64 s[0:1], 0, v200
	v_mfma_f32_16x16x32_bf16 v[80:83], v[70:73], v[42:45], 0
	v_mfma_f32_16x16x32_bf16 v[70:73], v[66:69], v[38:41], v[246:249]
	v_mfma_f32_16x16x32_bf16 v[66:69], v[66:69], v[46:49], v[80:83]
	s_nop 5
	ds_read_u16 v80, v213 offset:50720
	v_add_f32_e32 v70, v169, v70
	v_mul_f32_e32 v70, 0xbfb8aa3b, v70
	v_exp_f32_e32 v70, v70
	v_add_f32_e32 v66, v168, v66
	v_mul_f32_e32 v66, 0xbfb8aa3b, v66
	v_exp_f32_e32 v66, v66
	v_add_f32_e32 v70, 1.0, v70
	v_rcp_f32_e32 v70, v70
	v_add_f32_e32 v72, v169, v72
	v_add_f32_e32 v66, 1.0, v66
	v_rcp_f32_e32 v66, v66
	v_mul_f32_e32 v70, v215, v70
	v_mul_f32_e32 v70, 0x3fb8aa3b, v70
	v_exp_f32_e32 v219, v70
	v_mul_f32_e32 v72, 0xbfb8aa3b, v72
	v_exp_f32_e32 v72, v72
	v_add_f32_e32 v67, v168, v67
	v_fma_f32 v70, -v219, v219, 1.0
	v_max_f32_e32 v70, 0, v70
	v_sqrt_f32_e32 v70, v70
	v_add_f32_e32 v73, v169, v73
	v_mul_f32_e32 v67, 0xbfb8aa3b, v67
	v_add_f32_e32 v72, 1.0, v72
	v_mul_f32_e32 v66, v66, v70
	v_add_f32_e32 v70, v169, v71
	v_mul_f32_e32 v70, 0xbfb8aa3b, v70
	v_exp_f32_e32 v70, v70
	v_mul_f32_e32 v73, 0xbfb8aa3b, v73
	v_exp_f32_e32 v67, v67
	v_rcp_f32_e32 v72, v72
	v_add_f32_e32 v70, 1.0, v70
	v_rcp_f32_e32 v70, v70
	v_exp_f32_e32 v73, v73
	v_add_f32_e32 v67, 1.0, v67
	v_mul_f32_e32 v72, v215, v72
	v_mul_f32_e32 v70, v215, v70
	v_mul_f32_e32 v70, 0x3fb8aa3b, v70
	v_exp_f32_e32 v70, v70
	v_add_f32_e32 v73, 1.0, v73
	v_rcp_f32_e32 v67, v67
	v_add_f32_e32 v68, v168, v68
	v_fma_f32 v71, -v70, v70, 1.0
	v_max_f32_e32 v71, 0, v71
	v_sqrt_f32_e32 v71, v71
	v_mul_f32_e32 v72, 0x3fb8aa3b, v72
	v_rcp_f32_e32 v73, v73
	v_mul_f32_e32 v68, 0xbfb8aa3b, v68
	v_exp_f32_e32 v72, v72
	v_exp_f32_e32 v68, v68
	v_mul_f32_e32 v67, v67, v71
	ds_read_u16 v71, v213 offset:51776
	s_waitcnt lgkmcnt(1)
	v_lshlrev_b32_e32 v80, 16, v80
	v_mul_f32_e32 v73, v215, v73
	v_mul_f32_e32 v217, v66, v80
	v_fma_f32 v80, -v72, v72, 1.0
	v_add_f32_e32 v69, v168, v69
	v_mul_f32_e32 v73, 0x3fb8aa3b, v73
	v_add_f32_e32 v68, 1.0, v68
	v_max_f32_e32 v80, 0, v80
	v_mul_f32_e32 v69, 0xbfb8aa3b, v69
	v_exp_f32_e32 v73, v73
	ds_read_u16 v66, v213 offset:51248
	v_rcp_f32_e32 v68, v68
	v_sqrt_f32_e32 v80, v80
	v_exp_f32_e32 v69, v69
	v_fma_f32 v81, -v73, v73, 1.0
	v_max_f32_e32 v81, 0, v81
	v_mul_f32_e32 v68, v68, v80
	ds_read_u16 v80, v213 offset:52304
	v_add_f32_e32 v69, 1.0, v69
	s_waitcnt lgkmcnt(1)
	v_lshlrev_b32_e32 v66, 16, v66
	v_rcp_f32_e32 v69, v69
	v_sqrt_f32_e32 v81, v81
	v_mul_f32_e32 v247, v70, v217
	v_fmac_f32_e32 v247, v67, v66
	v_lshlrev_b32_e32 v71, 16, v71
	v_mul_f32_e32 v246, v72, v247
	v_mul_f32_e32 v248, v70, v219
	v_fmac_f32_e32 v246, v68, v71
	s_waitcnt lgkmcnt(0)
	v_lshlrev_b32_e32 v80, 16, v80
	v_mul_f32_e32 v69, v69, v81
	v_mul_f32_e32 v249, v72, v248
	v_mul_f32_e32 v221, v73, v246
	v_mul_f32_e32 v250, v73, v249
	v_fmac_f32_e32 v221, v69, v80
	s_nop 0
	s_nop 0
	s_nop 0
	s_nop 0
	s_nop 0
	s_nop 0
	v_mov_b32_e32 v68, v250
	v_mov_b32_e32 v69, v250
	s_nop 1
	v_permlane16_swap_b32_e32 v68, v69
	s_nop 1
	v_mov_b32_e32 v70, v68
	v_mov_b32_e32 v242, v69
	s_nop 1
	v_permlane32_swap_b32_e32 v68, v70
	v_permlane32_swap_b32_e32 v69, v242
	s_nop 1
	v_mov_b32_e32 v66, v221
	v_mov_b32_e32 v67, v221
	s_nop 1
	v_permlane16_swap_b32_e32 v66, v67
	s_nop 1
	v_mov_b32_e32 v241, v66
	v_mov_b32_e32 v218, v67
	s_nop 1
	v_permlane32_swap_b32_e32 v66, v241
	v_permlane32_swap_b32_e32 v67, v218
	s_nop 1
	s_waitcnt lgkmcnt(0)
	v_fmac_f32_e32 v66, v216, v68
	s_waitcnt lgkmcnt(0)
	v_fmac_f32_e32 v67, v66, v69
	s_waitcnt lgkmcnt(0)
	v_fmac_f32_e32 v241, v67, v70
	s_and_saveexec_b64 s[4:5], s[0:1]
	s_cbranch_execz .LBB0_629
	v_cmp_ne_u32_e64 s[0:1], 1, v200
	s_and_saveexec_b64 s[34:35], s[0:1]
	s_xor_b64 s[0:1], exec, s[34:35]
	v_cndmask_b32_e32 v216, v241, v67, vcc
	s_andn2_saveexec_b64 s[0:1], s[0:1]
	v_mov_b32_e32 v216, v66
	s_or_b64 exec, exec, s[0:1]

; __device__ __forceinline__ float fsig(float x) { return frcp(1.0f + __expf(-x)); }
; template <int DIR, int MODE>
; __device__ __forceinline__ void lru_pass(const Args& a, const LAS bf16_t* cxb, LAS bf16_t* gyb, const LAS float* carry, const bf16x8 (&Bw)[2][2][2], const float (&prm)[2][3], int l, int tt, float (&hf)[8][2][4]) {
;     ...
;         for (int nt = 0; nt < 2; ++nt) {
;             f32x4 pr = (f32x4){0.f, 0.f, 0.f, 0.f}, pi = (f32x4){0.f, 0.f, 0.f, 0.f};
; #pragma unroll
;             for (int ks = 0; ks < 2; ++ks) { pr = __builtin_amdgcn_mfma_f32_16x16x32_bf16(Af[ks], Bw[0][nt][ks], pr, 0, 0, 0); pi = __builtin_amdgcn_mfma_f32_16x16x32_bf16(Af[ks], Bw[1][nt][ks], pi, 0, 0, 0); }
;             float av[4], bv[4];
; #pragma unroll
;             for (int reg = 0; reg < 4; ++reg) {
;                 const int tok = m * 16 + 4 * fq + reg;
;                 const float x = bf2f(cxb[tok * CXS + cc[nt]]);
;                 const float r = fsig(pr[reg] + ba[nt]), ig = fsig(pi[reg] + bxv[nt]);
;                 const float aa = __expf(k8[nt] * r);
;                 av[reg] = aa; bv[reg] = __builtin_amdgcn_sqrtf(fmaxf(1.0f - aa * aa, 0.f)) * ig * x;
;             }
;             float cum[4], hl[4];
;             if (DIR == 0) { cum[0] = av[0]; hl[0] = bv[0];
; #pragma unroll
;                 for (int reg = 1; reg < 4; ++reg) { cum[reg] = cum[reg - 1] * av[reg]; hl[reg] = av[reg] * hl[reg - 1] + bv[reg]; } }
;             else { cum[3] = av[3]; hl[3] = bv[3];
; #pragma unroll
;     ...
;             const float A4 = DIR ? cum[0] : cum[3], H4 = DIR ? hl[0] : hl[3];
;             float Aq[4], Hq[4];
; #pragma unroll
;             for (int q = 0; q < 4; ++q) { Aq[q] = __shfl(A4, fr + 16 * q); Hq[q] = __shfl(H4, fr + 16 * q); }
;             float hin;
;             if (DIR == 0) { const float s0 = C[nt], s1 = Aq[0] * s0 + Hq[0], s2 = Aq[1] * s1 + Hq[1], s3 = Aq[2] * s2 + Hq[2]; C[nt] = Aq[3] * s3 + Hq[3]; hin = fq == 0 ? s0 : (fq == 1 ? s1 : (fq == 2 ? s2 : s3)); }
;             else { const float s3 = C[nt], s2 = Aq[3] * s3 + Hq[3], s1 = Aq[2] * s2 + Hq[2], s0 = Aq[1] * s1 + Hq[1]; C[nt] = Aq[0] * s0 + Hq[0]; hin = fq == 3 ? s3 : (fq == 2 ? s2 : (fq == 1 ? s1 : s0)); }
;             if (MODE == 0) At[nt] *= (Aq[0] * Aq[1]) * (Aq[2] * Aq[3]);
.LBB0_641:
	s_or_b64 exec, exec, s[4:5]
	s_waitcnt lgkmcnt(0)
	v_mul_f32_e32 v36, v191, v192
	v_mul_f32_e32 v36, v36, v193
	s_waitcnt lgkmcnt(0)
	v_add_f32_e32 v37, v197, v36
	s_waitcnt lgkmcnt(0)
	v_sub_f32_e32 v38, v37, v197
	v_sub_f32_e32 v36, v36, v38
	v_add_f32_e32 v36, v196, v36
	v_add_f32_e32 v38, v37, v36
	v_add_f32_e32 v34, v194, v195
	v_sub_f32_e32 v37, v38, v37
	v_sub_f32_e32 v36, v36, v37
	v_add_f32_e32 v37, v34, v38
	v_sub_f32_e32 v39, v37, v34
	v_sub_f32_e32 v35, v34, v194
	v_sub_f32_e32 v40, v37, v39
	v_sub_f32_e32 v35, v195, v35
	v_sub_f32_e32 v34, v34, v40
	v_sub_f32_e32 v38, v38, v39
	v_add_f32_e32 v34, v38, v34
	v_add_f32_e32 v38, v35, v36
	v_sub_f32_e32 v39, v38, v35
	v_sub_f32_e32 v40, v38, v39
	v_add_f32_e32 v34, v38, v34
	v_sub_f32_e32 v35, v35, v40
	v_sub_f32_e32 v36, v36, v39
	v_add_f32_e32 v38, v37, v34
	v_add_f32_e32 v35, v36, v35
	v_sub_f32_e32 v36, v38, v37
	v_sub_f32_e32 v34, v34, v36
	v_add_f32_e32 v39, v35, v34
	v_mov_b32_e32 v34, v0
	v_add_f32_e32 v38, v38, v39
	v_readfirstlane_b32 s0, v34
	s_bfe_u32 s1, s0, 0x20006
	s_lshl_b32 s4, s1, 7
	v_bfe_u32 v51, v34, 4, 2
	s_add_i32 s4, s4, 0
	v_and_b32_e32 v48, 15, v34
	v_lshl_add_u32 v46, v51, 4, s4
	v_mad_u32_u24 v40, v48, s28, v46
	ds_read_b128 v[34:37], v40 offset:59136
	s_mov_b32 s4, 0x7f800000
	v_cmp_neq_f32_e32 vcc, s4, v183
	v_mov_b32_e32 v39, 0x7f800000
	s_waitcnt lgkmcnt(0)
	v_mfma_f32_16x16x32_bf16 v[80:83], v[34:37], v[22:25], 0
	v_cndmask_b32_e32 v38, v39, v38, vcc
	v_cmp_ngt_f32_e32 vcc, -1.0, v183
	v_mov_b32_e32 v39, 0x7fc00000
	v_and_b32_e32 v53, 0x7fffffff, v183
	v_cndmask_b32_e32 v38, v39, v38, vcc
	v_cmp_neq_f32_e32 vcc, -1.0, v183
	v_mov_b32_e32 v39, 0xff800000
	s_mov_b32 s4, 0x33800000
	v_cndmask_b32_e32 v50, v39, v38, vcc
	ds_read_b128 v[38:41], v40 offset:59200
	s_waitcnt lgkmcnt(0)
	v_mfma_f32_16x16x32_bf16 v[80:83], v[38:41], v[18:21], v[80:83]
	v_cmp_gt_f32_e32 vcc, s4, v53
	s_ashr_i32 s0, s0, 3
	s_lshl_b32 s1, s1, 6
	v_cndmask_b32_e32 v50, v50, v183, vcc
	v_mul_f32_e32 v60, 0xc1000000, v50
	v_and_b32_e32 v50, 64, v227
	v_or_b32_e32 v53, v48, v50
	s_nop 0
	v_add_f32_e32 v50, v153, v80
	v_mul_f32_e32 v50, 0xbfb8aa3b, v50
	v_exp_f32_e32 v55, v50
	v_mfma_f32_16x16x32_bf16 v[210:213], v[34:37], v[30:33], 0
	v_add_f32_e32 v71, v153, v81
	v_mul_f32_e32 v71, 0xbfb8aa3b, v71
	v_add_f32_e32 v55, 1.0, v55
	v_rcp_f32_e32 v55, v55
	v_mfma_f32_16x16x32_bf16 v[210:213], v[38:41], v[26:29], v[210:213]
	v_exp_f32_e32 v71, v71
	s_andn2_b32 s0, s0, 31
	v_mul_f32_e32 v55, v60, v55
	v_mul_f32_e32 v55, 0x3fb8aa3b, v55
	v_exp_f32_e32 v55, v55
	s_nop 2
	v_add_f32_e32 v56, v152, v210
	v_mul_f32_e32 v56, 0xbfb8aa3b, v56
	v_exp_f32_e32 v56, v56
	v_fma_f32 v68, -v55, v55, 1.0
	v_add_f32_e32 v72, v152, v211
	v_max_f32_e32 v68, 0, v68
	v_add_f32_e32 v56, 1.0, v56
	v_mul_f32_e32 v72, 0xbfb8aa3b, v72
	v_rcp_f32_e32 v56, v56
	v_sqrt_f32_e32 v68, v68
	v_exp_f32_e32 v72, v72
	v_add_f32_e32 v71, 1.0, v71
	v_rcp_f32_e32 v71, v71
	v_mul_f32_e32 v56, v56, v68
	v_add_f32_e32 v68, 1.0, v72
	v_add_f32_e32 v72, v153, v82
	v_mul_f32_e32 v71, v60, v71
	v_mul_f32_e32 v72, 0xbfb8aa3b, v72
	v_mul_f32_e32 v71, 0x3fb8aa3b, v71
	v_exp_f32_e32 v72, v72
	v_exp_f32_e32 v71, v71
	v_add_f32_e32 v80, v152, v212
	v_mul_f32_e32 v80, 0xbfb8aa3b, v80
	v_add_f32_e32 v72, 1.0, v72
	v_fma_f32 v73, -v71, v71, 1.0
	v_rcp_f32_e32 v72, v72
	v_max_f32_e32 v73, 0, v73
	v_rcp_f32_e32 v68, v68
	v_sqrt_f32_e32 v73, v73
	v_exp_f32_e32 v80, v80
	v_mul_f32_e32 v72, v60, v72
	v_mul_f32_e32 v72, 0x3fb8aa3b, v72
	v_mul_f32_e32 v68, v68, v73
	v_add_f32_e32 v73, 1.0, v80
	v_exp_f32_e32 v80, v72
	v_add_f32_e32 v72, v153, v83
	v_mul_f32_e32 v72, 0xbfb8aa3b, v72
	v_exp_f32_e32 v72, v72
	v_add_f32_e32 v82, v152, v213
	v_mul_f32_e32 v82, 0xbfb8aa3b, v82
	s_add_i32 s1, s1, s0
	v_add_f32_e32 v72, 1.0, v72
	v_rcp_f32_e32 v72, v72
	v_exp_f32_e32 v82, v82
	v_or_b32_e32 v194, s1, v48
	v_lshlrev_b32_e32 v54, 1, v194
	v_mul_f32_e32 v72, v60, v72
	v_mul_f32_e32 v72, 0x3fb8aa3b, v72
	v_exp_f32_e32 v72, v72
	v_mul_u32_u24_e32 v50, 0x840, v51
	v_add3_u32 v58, 0, v54, v50
	v_fma_f32 v81, -v80, v80, 1.0
	v_fma_f32 v83, -v72, v72, 1.0
	ds_read_u16 v54, v58 offset:59136
	ds_read_u16 v61, v58 offset:59664
	ds_read_u16 v66, v58 offset:60192
	ds_read_u16 v67, v58 offset:60720
	v_max_f32_e32 v81, 0, v81
	v_add_f32_e32 v82, 1.0, v82
	v_max_f32_e32 v83, 0, v83
	v_rcp_f32_e32 v73, v73
	v_sqrt_f32_e32 v81, v81
	v_rcp_f32_e32 v82, v82
	v_sqrt_f32_e32 v83, v83
	s_waitcnt lgkmcnt(0)
	v_lshlrev_b32_e32 v67, 16, v67
	v_mul_f32_e32 v81, v73, v81
	v_lshlrev_b32_e32 v66, 16, v66
	v_mul_f32_e32 v73, v82, v83
	v_mul_f32_e32 v73, v73, v67
	v_mul_f32_e32 v169, v80, v73
	v_fmac_f32_e32 v169, v81, v66
	v_lshlrev_b32_e32 v61, 16, v61
	v_mul_f32_e32 v191, v71, v169
	v_mul_f32_e32 v168, v80, v72
	v_fmac_f32_e32 v191, v68, v61
	v_lshlrev_b32_e32 v54, 16, v54
	v_mul_f32_e32 v183, v71, v168
	v_mul_f32_e32 v193, v55, v191
	s_add_i32 s0, 0, 0x21000
	v_mul_f32_e32 v192, v55, v183
	v_fmac_f32_e32 v193, v56, v54
	v_lshlrev_b32_e32 v61, 2, v53
	v_lshl_add_u32 v53, v194, 2, s0
	s_nop 0
	s_nop 0
	ds_read_b32 v171, v53 offset:1024
	s_nop 0
	s_nop 0
	v_or_b32_e32 v53, 16, v194
	s_nop 0
	s_nop 0
	v_lshl_add_u32 v71, v53, 2, s0
	v_mov_b32_e32 v67, v192
	v_mov_b32_e32 v197, v192
	s_nop 1
	v_permlane16_swap_b32_e32 v67, v197
	s_nop 1
	v_mov_b32_e32 v200, v67
	v_mov_b32_e32 v210, v197
	s_nop 1
	v_permlane32_swap_b32_e32 v67, v200
	v_permlane32_swap_b32_e32 v197, v210
	s_nop 1
	v_mov_b32_e32 v66, v193
	v_mov_b32_e32 v68, v193
	s_nop 1
	v_permlane16_swap_b32_e32 v66, v68
	s_nop 1
	v_mov_b32_e32 v196, v66
	v_mov_b32_e32 v195, v68
	s_nop 1
	v_permlane32_swap_b32_e32 v66, v196
	v_permlane32_swap_b32_e32 v68, v195
	s_nop 1
	ds_read_b32 v71, v71 offset:1024
	s_waitcnt lgkmcnt(1)
	v_fmac_f32_e32 v195, v171, v210
	s_waitcnt lgkmcnt(1)
	v_fmac_f32_e32 v196, v195, v200
	v_mul_u32_u24_e32 v48, 0x210, v48
	v_or_b32_e32 v56, 64, v61
	v_or_b32_e32 v55, 0x80, v61
	v_or_b32_e32 v54, 0xc0, v61
	v_cmp_eq_u32_e32 vcc, 1, v51
	s_waitcnt lgkmcnt(1)
	v_fmac_f32_e32 v68, v196, v197
	v_cmp_gt_i32_e64 s[0:1], 3, v51
	s_and_saveexec_b64 s[4:5], s[0:1]
	s_cbranch_execz .LBB0_647
	v_cmp_ne_u32_e64 s[0:1], 2, v51
	s_and_saveexec_b64 s[34:35], s[0:1]
	s_xor_b64 s[0:1], exec, s[34:35]
	v_cndmask_b32_e32 v171, v68, v196, vcc
	s_andn2_saveexec_b64 s[0:1], s[0:1]
	v_mov_b32_e32 v171, v195
	s_or_b64 exec, exec, s[0:1]
; #define LAS __attribute__((address_space(3)))
; __device__ __forceinline__ unsigned f2bf(float f) { unsigned u = __builtin_bit_cast(unsigned, f); return (u + 0x7fffu + ((u >> 16) & 1u)) >> 16; }
; __device__ __forceinline__ float fsig(float x) { return frcp(1.0f + __expf(-x)); }
; template <int DIR, int MODE>
; __device__ __forceinline__ void lru_pass(const Args& a, const LAS bf16_t* cxb, LAS bf16_t* gyb, const LAS float* carry, const bf16x8 (&Bw)[2][2][2], const float (&prm)[2][3], int l, int tt, float (&hf)[8][2][4]) {
;     ...
;         for (int nt = 0; nt < 2; ++nt) {
;             f32x4 pr = (f32x4){0.f, 0.f, 0.f, 0.f}, pi = (f32x4){0.f, 0.f, 0.f, 0.f};
; #pragma unroll
;             for (int ks = 0; ks < 2; ++ks) { pr = __builtin_amdgcn_mfma_f32_16x16x32_bf16(Af[ks], Bw[0][nt][ks], pr, 0, 0, 0); pi = __builtin_amdgcn_mfma_f32_16x16x32_bf16(Af[ks], Bw[1][nt][ks], pi, 0, 0, 0); }
;             float av[4], bv[4];
; #pragma unroll
;             for (int reg = 0; reg < 4; ++reg) {
;                 const int tok = m * 16 + 4 * fq + reg;
;                 const float x = bf2f(cxb[tok * CXS + cc[nt]]);
;                 const float r = fsig(pr[reg] + ba[nt]), ig = fsig(pi[reg] + bxv[nt]);
;                 const float aa = __expf(k8[nt] * r);
;                 av[reg] = aa; bv[reg] = __builtin_amdgcn_sqrtf(fmaxf(1.0f - aa * aa, 0.f)) * ig * x;
;     ...
;             if (DIR == 0) { const float s0 = C[nt], s1 = Aq[0] * s0 + Hq[0], s2 = Aq[1] * s1 + Hq[1], s3 = Aq[2] * s2 + Hq[2]; C[nt] = Aq[3] * s3 + Hq[3]; hin = fq == 0 ? s0 : (fq == 1 ? s1 : (fq == 2 ? s2 : s3)); }
;             else { const float s3 = C[nt], s2 = Aq[3] * s3 + Hq[3], s1 = Aq[2] * s2 + Hq[2], s0 = Aq[1] * s1 + Hq[1]; C[nt] = Aq[0] * s0 + Hq[0]; hin = fq == 3 ? s3 : (fq == 2 ? s2 : (fq == 1 ? s1 : s0)); }
;             if (MODE == 0) At[nt] *= (Aq[0] * Aq[1]) * (Aq[2] * Aq[3]);
;             else {
; #pragma unroll
;                 for (int reg = 0; reg < 4; ++reg) {
;                     const float hv = hl[reg] + cum[reg] * hin;
;                     if (DIR == 0) hf[m][nt][reg] = hv;
;                     else { LAS bf16_t* gp = gyb + (m * 16 + 4 * fq + reg) * CXS + cc[nt];
;                         const float g = bf2f(*gp);
;                         *gp = (bf16_t)f2bf((hf[m][nt][reg] + hv) * fgelu(g)); }
.LBB0_647:
	s_or_b64 exec, exec, s[4:5]
	v_fmac_f32_e32 v63, v65, v230
	v_mul_f32_e32 v65, v184, v185
	v_mul_f32_e32 v65, v65, v186
	v_add_f32_e32 v80, v190, v65
	v_sub_f32_e32 v81, v80, v190
	v_sub_f32_e32 v65, v65, v81
	v_add_f32_e32 v65, v189, v65
	v_add_f32_e32 v81, v80, v65
	v_fmac_f32_e32 v64, v57, v230
	v_add_f32_e32 v57, v187, v188
	v_sub_f32_e32 v80, v81, v80
	v_sub_f32_e32 v65, v65, v80
	v_add_f32_e32 v80, v57, v81
	v_sub_f32_e32 v82, v80, v57
	v_fmac_f32_e32 v62, v59, v230
	v_sub_f32_e32 v59, v57, v187
	v_sub_f32_e32 v83, v80, v82
	v_sub_f32_e32 v59, v188, v59
	v_sub_f32_e32 v57, v57, v83
	v_sub_f32_e32 v81, v81, v82
	v_add_f32_e32 v57, v81, v57
	v_add_f32_e32 v81, v59, v65
	v_sub_f32_e32 v82, v81, v59
	v_sub_f32_e32 v83, v81, v82
	v_sub_f32_e32 v59, v59, v83
	v_sub_f32_e32 v65, v65, v82
	v_add_f32_e32 v57, v81, v57
	v_add_f32_e32 v59, v65, v59
	v_add_f32_e32 v65, v80, v57
	v_sub_f32_e32 v80, v65, v80
	v_sub_f32_e32 v57, v57, v80
	v_add_f32_e32 v57, v59, v57
	s_mov_b32 s0, 0x7f800000
	v_add_f32_e32 v57, v65, v57
	v_cmp_neq_f32_e64 s[0:1], s0, v181
	v_mov_b32_e32 v59, 0x7f800000
	v_fmac_f32_e32 v52, v170, v230
	v_cndmask_b32_e64 v57, v59, v57, s[0:1]
	v_cmp_ngt_f32_e64 s[0:1], -1.0, v181
	v_mov_b32_e32 v59, 0x7fc00000
	v_and_b32_e32 v187, 0x7fffffff, v181
	v_cndmask_b32_e64 v57, v59, v57, s[0:1]
	v_cmp_neq_f32_e64 s[0:1], -1.0, v181
	v_mov_b32_e32 v59, 0xff800000
	v_fmac_f32_e32 v193, v192, v171
	v_cndmask_b32_e64 v57, v59, v57, s[0:1]
	v_lshl_add_u32 v59, v194, 1, s38
	v_add_u32_e32 v59, v59, v50
	ds_read_u16 v65, v59 offset:59136
	ds_read_u16 v80, v59 offset:59664
	ds_read_u16 v81, v59 offset:60192
	ds_read_u16 v82, v59 offset:60720
	ds_read_u16 v83, v58 offset:59168
	ds_read_u16 v170, v58 offset:59696
	ds_read_u16 v184, v58 offset:60224
	ds_read_u16 v185, v58 offset:60752
	s_waitcnt lgkmcnt(7)
	v_lshlrev_b32_e32 v65, 16, v65
	v_mul_f32_e32 v186, 0x3d372713, v65
	v_mul_f32_e32 v186, v186, v65
	v_fma_f32 v186, v186, v65, v65
	v_mul_f32_e32 v186, 0x3f4c422a, v186
	v_add_f32_e32 v186, v186, v186
	v_mul_f32_e32 v186, 0x3fb8aa3b, v186
	v_exp_f32_e32 v186, v186
	s_mov_b32 s0, 0x33800000
	v_cmp_gt_f32_e64 s[0:1], s0, v187
	v_mul_f32_e32 v65, 0.5, v65
	v_add_f32_e32 v62, v62, v193
	v_cndmask_b32_e64 v57, v57, v181, s[0:1]
	v_add_f32_e32 v181, 1.0, v186
	v_rcp_f32_e32 v181, v181
	v_fmac_f32_e32 v191, v183, v171
	v_add_f32_e32 v64, v64, v191
	v_fmac_f32_e32 v169, v168, v171
	v_fma_f32 v181, v181, -2.0, 2.0
	v_mul_f32_e32 v65, v65, v181
	v_mul_f32_e32 v62, v62, v65
	s_waitcnt lgkmcnt(6)
	v_lshlrev_b32_e32 v65, 16, v80
	v_mul_f32_e32 v80, 0x3d372713, v65
	v_mul_f32_e32 v80, v80, v65
	v_fma_f32 v80, v80, v65, v65
	v_mul_f32_e32 v80, 0x3f4c422a, v80
	v_add_f32_e32 v80, v80, v80
	v_mul_f32_e32 v80, 0x3fb8aa3b, v80
	v_exp_f32_e32 v80, v80
	v_bfe_u32 v181, v62, 16, 1
	v_add3_u32 v62, v62, v181, s27
	ds_write_b16_d16_hi v59, v62 offset:59136
	v_add_f32_e32 v62, 1.0, v80
	v_rcp_f32_e32 v62, v62
	v_mul_f32_e32 v65, 0.5, v65
	v_add_f32_e32 v63, v63, v169
	v_mul_f32_e32 v57, 0xc1000000, v57
	v_fma_f32 v62, v62, -2.0, 2.0
	v_mul_f32_e32 v62, v65, v62
	v_mul_f32_e32 v62, v64, v62
	s_waitcnt lgkmcnt(6)
	v_lshlrev_b32_e32 v64, 16, v81
	v_mul_f32_e32 v65, 0x3d372713, v64
	v_mul_f32_e32 v65, v65, v64
	v_fma_f32 v65, v65, v64, v64
	v_mul_f32_e32 v65, 0x3f4c422a, v65
	v_add_f32_e32 v65, v65, v65
	v_mul_f32_e32 v65, 0x3fb8aa3b, v65
	v_exp_f32_e32 v65, v65
	v_bfe_u32 v80, v62, 16, 1
	v_add3_u32 v62, v62, v80, s27
	ds_write_b16_d16_hi v59, v62 offset:59664
	v_add_f32_e32 v62, 1.0, v65
	v_rcp_f32_e32 v62, v62
	v_mul_f32_e32 v64, 0.5, v64
	s_waitcnt lgkmcnt(6)
	v_lshlrev_b32_e32 v80, 16, v82
	v_fmac_f32_e32 v73, v72, v171
	v_fma_f32 v62, v62, -2.0, 2.0
	v_mul_f32_e32 v62, v64, v62
	v_mul_f32_e32 v62, v63, v62
	v_bfe_u32 v63, v62, 16, 1
	v_add3_u32 v62, v62, v63, s27
	v_mul_f32_e32 v63, 0x3d372713, v80
	v_mul_f32_e32 v63, v63, v80
	v_fma_f32 v63, v63, v80, v80
	v_mul_f32_e32 v63, 0x3f4c422a, v63
	v_add_f32_e32 v63, v63, v63
	v_mul_f32_e32 v63, 0x3fb8aa3b, v63
	v_exp_f32_e32 v81, v63
	ds_write_b16_d16_hi v59, v62 offset:60192
	v_mfma_f32_16x16x32_bf16 v[62:65], v[34:37], v[6:9], 0
	v_cmp_gt_i32_e64 s[0:1], 3, v51
	v_add_f32_e32 v72, 1.0, v81
	v_rcp_f32_e32 v72, v72
	v_mfma_f32_16x16x32_bf16 v[62:65], v[38:41], v[2:5], v[62:65]
	v_add_f32_e32 v81, v52, v73
	v_mul_f32_e32 v52, 0.5, v80
	v_fma_f32 v72, v72, -2.0, 2.0
	v_mfma_f32_16x16x32_bf16 v[34:37], v[34:37], v[14:17], 0
	v_mul_f32_e32 v80, v52, v72
	s_nop 2
	v_add_f32_e32 v62, v151, v62
	v_mul_f32_e32 v62, 0xbfb8aa3b, v62
	v_exp_f32_e32 v62, v62
	v_mfma_f32_16x16x32_bf16 v[34:37], v[38:41], v[10:13], v[34:37]
	v_add_f32_e32 v39, v151, v63
	v_mul_f32_e32 v39, 0xbfb8aa3b, v39
	v_add_f32_e32 v38, 1.0, v62
	v_rcp_f32_e32 v38, v38
	v_exp_f32_e32 v39, v39
	s_nop 2
	v_add_f32_e32 v34, v150, v34
	v_mul_f32_e32 v34, 0xbfb8aa3b, v34
	v_mul_f32_e32 v38, v57, v38
	v_mul_f32_e32 v38, 0x3fb8aa3b, v38
	v_exp_f32_e32 v40, v38
	v_exp_f32_e32 v34, v34
	v_add_f32_e32 v35, v150, v35
	v_mul_f32_e32 v35, 0xbfb8aa3b, v35
	v_fma_f32 v38, -v40, v40, 1.0
	v_add_f32_e32 v34, 1.0, v34
	v_max_f32_e32 v38, 0, v38
	v_add_f32_e32 v39, 1.0, v39
	v_rcp_f32_e32 v34, v34
	v_sqrt_f32_e32 v38, v38
	v_exp_f32_e32 v35, v35
	v_rcp_f32_e32 v39, v39
	v_add_f32_e32 v36, v150, v36
	v_mul_f32_e32 v62, v34, v38
	v_add_f32_e32 v34, 1.0, v35
	v_mul_f32_e32 v35, v57, v39
	v_mul_f32_e32 v35, 0x3fb8aa3b, v35
	v_exp_f32_e32 v38, v35
	v_add_f32_e32 v35, v151, v64
	v_mul_f32_e32 v35, 0xbfb8aa3b, v35
	v_exp_f32_e32 v35, v35
	v_fma_f32 v39, -v38, v38, 1.0
	v_max_f32_e32 v39, 0, v39
	v_mul_f32_e32 v36, 0xbfb8aa3b, v36
	v_add_f32_e32 v35, 1.0, v35
	v_rcp_f32_e32 v35, v35
	v_rcp_f32_e32 v34, v34
	v_sqrt_f32_e32 v39, v39
	v_exp_f32_e32 v36, v36
	v_mul_f32_e32 v35, v57, v35
	v_mul_f32_e32 v35, 0x3fb8aa3b, v35
	v_mul_f32_e32 v63, v34, v39
	v_add_f32_e32 v34, 1.0, v36
	v_exp_f32_e32 v36, v35
	v_add_f32_e32 v35, v151, v65
	v_mul_f32_e32 v35, 0xbfb8aa3b, v35
	v_exp_f32_e32 v35, v35
	v_add_f32_e32 v37, v150, v37
	v_mul_f32_e32 v37, 0xbfb8aa3b, v37
	v_exp_f32_e32 v37, v37
	v_add_f32_e32 v35, 1.0, v35
	v_rcp_f32_e32 v35, v35
	v_fma_f32 v39, -v36, v36, 1.0
	v_max_f32_e32 v39, 0, v39
	v_add_f32_e32 v37, 1.0, v37
	v_mul_f32_e32 v35, v57, v35
	v_mul_f32_e32 v35, 0x3fb8aa3b, v35
	v_exp_f32_e32 v35, v35
	v_rcp_f32_e32 v34, v34
	v_sqrt_f32_e32 v39, v39
	v_rcp_f32_e32 v37, v37
	v_fma_f32 v64, -v35, v35, 1.0
	v_max_f32_e32 v64, 0, v64
	v_sqrt_f32_e32 v64, v64
	v_mul_f32_e32 v39, v34, v39
	s_waitcnt lgkmcnt(3)
; #define LAS __attribute__((address_space(3)))
; __device__ __forceinline__ unsigned f2bf(float f) { unsigned u = __builtin_bit_cast(unsigned, f); return (u + 0x7fffu + ((u >> 16) & 1u)) >> 16; }
; template <int DIR, int MODE>
; __device__ __forceinline__ void lru_pass(const Args& a, const LAS bf16_t* cxb, LAS bf16_t* gyb, const LAS float* carry, const bf16x8 (&Bw)[2][2][2], const float (&prm)[2][3], int l, int tt, float (&hf)[8][2][4]) {
;     ...
;     for (int mi = 0; mi < 8; ++mi) {
;         const int m = DIR ? 7 - mi : mi;
;         bf16x8 Af[2];
; #pragma unroll
;         for (int ks = 0; ks < 2; ++ks) Af[ks] = *(const LAS bf16x8*)(cxb + (m * 16 + fr) * CXS + 64 * h + 32 * ks + 8 * fq);
; #pragma unroll
;         for (int nt = 0; nt < 2; ++nt) {
;             f32x4 pr = (f32x4){0.f, 0.f, 0.f, 0.f}, pi = (f32x4){0.f, 0.f, 0.f, 0.f};
; #pragma unroll
;             for (int ks = 0; ks < 2; ++ks) { pr = __builtin_amdgcn_mfma_f32_16x16x32_bf16(Af[ks], Bw[0][nt][ks], pr, 0, 0, 0); pi = __builtin_amdgcn_mfma_f32_16x16x32_bf16(Af[ks], Bw[1][nt][ks], pi, 0, 0, 0); }
;     ...
;             const float A4 = DIR ? cum[0] : cum[3], H4 = DIR ? hl[0] : hl[3];
;             float Aq[4], Hq[4];
; #pragma unroll
;             for (int q = 0; q < 4; ++q) { Aq[q] = __shfl(A4, fr + 16 * q); Hq[q] = __shfl(H4, fr + 16 * q); }
;             float hin;
;             if (DIR == 0) { const float s0 = C[nt], s1 = Aq[0] * s0 + Hq[0], s2 = Aq[1] * s1 + Hq[1], s3 = Aq[2] * s2 + Hq[2]; C[nt] = Aq[3] * s3 + Hq[3]; hin = fq == 0 ? s0 : (fq == 1 ? s1 : (fq == 2 ? s2 : s3)); }
;             else { const float s3 = C[nt], s2 = Aq[3] * s3 + Hq[3], s1 = Aq[2] * s2 + Hq[2], s0 = Aq[1] * s1 + Hq[1]; C[nt] = Aq[0] * s0 + Hq[0]; hin = fq == 3 ? s3 : (fq == 2 ? s2 : (fq == 1 ? s1 : s0)); }
;             if (MODE == 0) At[nt] *= (Aq[0] * Aq[1]) * (Aq[2] * Aq[3]);
;             else {
; #pragma unroll
;                 for (int reg = 0; reg < 4; ++reg) {
;                     const float hv = hl[reg] + cum[reg] * hin;
;                     if (DIR == 0) hf[m][nt][reg] = hv;
;                     else { LAS bf16_t* gp = gyb + (m * 16 + 4 * fq + reg) * CXS + cc[nt];
;                         const float g = bf2f(*gp);
;                         *gp = (bf16_t)f2bf((hf[m][nt][reg] + hv) * fgelu(g)); }
	v_lshlrev_b32_e32 v34, 16, v185
	v_lshlrev_b32_e32 v65, 16, v184
	v_mul_f32_e32 v37, v37, v64
	v_mul_f32_e32 v34, v37, v34
	v_mul_f32_e32 v37, v36, v35
	v_mul_f32_e32 v36, v36, v34
	v_fmac_f32_e32 v36, v39, v65
	v_lshlrev_b32_e32 v41, 16, v170
	v_mul_f32_e32 v39, v38, v37
	v_mul_f32_e32 v38, v38, v36
	v_fmac_f32_e32 v38, v63, v41
	v_lshlrev_b32_e32 v52, 16, v83
	v_mul_f32_e32 v41, v40, v39
	v_mul_f32_e32 v40, v40, v38
	v_fmac_f32_e32 v40, v62, v52
	s_nop 0
	s_nop 0
	s_nop 0
	s_nop 0
	s_nop 0
	s_nop 0
	v_mov_b32_e32 v64, v41
	v_mov_b32_e32 v72, v41
	s_nop 1
	v_permlane16_swap_b32_e32 v64, v72
	s_nop 1
	v_mov_b32_e32 v73, v64
	v_mov_b32_e32 v168, v72
	s_nop 1
	v_permlane32_swap_b32_e32 v64, v73
	v_permlane32_swap_b32_e32 v72, v168
	s_nop 1
	v_mov_b32_e32 v63, v40
	v_mov_b32_e32 v65, v40
	s_nop 1
	v_permlane16_swap_b32_e32 v63, v65
	s_nop 1
	v_mov_b32_e32 v62, v63
	v_mov_b32_e32 v52, v65
	s_nop 1
	v_permlane32_swap_b32_e32 v63, v62
	v_permlane32_swap_b32_e32 v65, v52
	s_nop 1
	v_mul_f32_e32 v80, v81, v80
	s_waitcnt lgkmcnt(0)
	v_fmac_f32_e32 v52, v71, v168
	v_bfe_u32 v81, v80, 16, 1
	s_waitcnt lgkmcnt(0)
	v_fmac_f32_e32 v62, v52, v73
	v_add3_u32 v80, v80, v81, s27
	s_waitcnt lgkmcnt(0)
	v_fmac_f32_e32 v65, v62, v72
	ds_write_b16_d16_hi v59, v80 offset:60720
	s_and_saveexec_b64 s[4:5], s[0:1]
	s_cbranch_execz .LBB0_653
	v_cmp_ne_u32_e64 s[0:1], 2, v51
	s_and_saveexec_b64 s[34:35], s[0:1]
	s_xor_b64 s[0:1], exec, s[34:35]
	v_cndmask_b32_e32 v71, v65, v62, vcc
	s_andn2_saveexec_b64 s[0:1], s[0:1]
	v_mov_b32_e32 v71, v52
	s_or_b64 exec, exec, s[0:1]
.LBB0_653:
	s_or_b64 exec, exec, s[4:5]
	v_fmac_f32_e32 v42, v43, v218
	v_lshl_add_u32 v43, v53, 1, s38
	v_add_u32_e32 v52, v43, v50
	v_fmac_f32_e32 v40, v41, v71
	ds_read_u16 v41, v52 offset:59136
	v_fmac_f32_e32 v38, v39, v71
	ds_read_u16 v39, v52 offset:59664
	v_fmac_f32_e32 v36, v37, v71
	ds_read_u16 v37, v52 offset:60192
	v_fmac_f32_e32 v34, v35, v71
	ds_read_u16 v35, v52 offset:60720
	s_waitcnt lgkmcnt(3)
	v_lshlrev_b32_e32 v41, 16, v41
	v_add_f32_e32 v40, v42, v40
	v_mul_f32_e32 v42, 0x3d372713, v41
	v_mul_f32_e32 v42, v42, v41
	v_fma_f32 v42, v42, v41, v41
	v_mul_f32_e32 v42, 0x3f4c422a, v42
	v_add_f32_e32 v42, v42, v42
	v_mul_f32_e32 v42, 0x3fb8aa3b, v42
	v_exp_f32_e32 v42, v42
	v_mul_f32_e32 v41, 0.5, v41
	s_waitcnt lgkmcnt(2)
	v_lshlrev_b32_e32 v39, 16, v39
	v_fmac_f32_e32 v47, v49, v218
	v_add_f32_e32 v42, 1.0, v42
	v_rcp_f32_e32 v42, v42
	v_add_f32_e32 v38, v47, v38
	s_waitcnt lgkmcnt(1)
	v_lshlrev_b32_e32 v37, 16, v37
	v_fmac_f32_e32 v45, v69, v218
	v_fma_f32 v42, v42, -2.0, 2.0
	v_mul_f32_e32 v41, v41, v42
	v_mul_f32_e32 v40, v40, v41
	v_bfe_u32 v41, v40, 16, 1
	v_add3_u32 v40, v40, v41, s27
	ds_write_b16_d16_hi v52, v40 offset:59136
	v_mul_f32_e32 v40, 0x3d372713, v39
	v_mul_f32_e32 v40, v40, v39
	v_fma_f32 v40, v40, v39, v39
	v_mul_f32_e32 v40, 0x3f4c422a, v40
	v_add_f32_e32 v40, v40, v40
	v_mul_f32_e32 v40, 0x3fb8aa3b, v40
	v_exp_f32_e32 v40, v40
	v_mul_f32_e32 v39, 0.5, v39
	v_add_f32_e32 v36, v45, v36
	s_waitcnt lgkmcnt(1)
	v_lshlrev_b32_e32 v35, 16, v35
	v_add_f32_e32 v40, 1.0, v40
	v_rcp_f32_e32 v40, v40
	v_fmac_f32_e32 v44, v70, v218
	v_add_f32_e32 v34, v44, v34
	v_add_u32_e32 v62, v46, v48
	v_fma_f32 v40, v40, -2.0, 2.0
	v_mul_f32_e32 v39, v39, v40
	v_mul_f32_e32 v38, v38, v39
	v_bfe_u32 v39, v38, 16, 1
	v_add3_u32 v38, v38, v39, s27
	ds_write_b16_d16_hi v52, v38 offset:59664
	v_mul_f32_e32 v38, 0x3d372713, v37
	v_mul_f32_e32 v38, v38, v37
	v_fma_f32 v38, v38, v37, v37
	v_mul_f32_e32 v38, 0x3f4c422a, v38
	v_add_f32_e32 v38, v38, v38
	v_mul_f32_e32 v38, 0x3fb8aa3b, v38
	v_exp_f32_e32 v38, v38
	v_mul_f32_e32 v37, 0.5, v37
	v_fmac_f32_e32 v66, v68, v67
	v_cmp_gt_i32_e64 s[0:1], 3, v51
	v_add_f32_e32 v38, 1.0, v38
	v_rcp_f32_e32 v38, v38
	s_nop 0
	v_fma_f32 v38, v38, -2.0, 2.0
	v_mul_f32_e32 v37, v37, v38
	v_mul_f32_e32 v36, v36, v37
	v_bfe_u32 v37, v36, 16, 1
	v_add3_u32 v36, v36, v37, s27
	ds_write_b16_d16_hi v52, v36 offset:60192
	v_mul_f32_e32 v36, 0x3d372713, v35
	v_mul_f32_e32 v36, v36, v35
	v_fma_f32 v36, v36, v35, v35
	v_mul_f32_e32 v36, 0x3f4c422a, v36
	v_add_f32_e32 v36, v36, v36
	v_mul_f32_e32 v36, 0x3fb8aa3b, v36
	v_exp_f32_e32 v36, v36
	v_mul_f32_e32 v35, 0.5, v35
	v_add_f32_e32 v36, 1.0, v36
	v_rcp_f32_e32 v36, v36
	s_nop 0
	v_fma_f32 v36, v36, -2.0, 2.0
	v_mul_f32_e32 v35, v35, v36
	v_mul_f32_e32 v34, v34, v35
	v_bfe_u32 v35, v34, 16, 1
	v_add3_u32 v34, v34, v35, s27
	ds_write_b16_d16_hi v52, v34 offset:60720
	ds_read_b128 v[38:41], v62 offset:50688
	ds_read_b128 v[34:37], v62 offset:50752
	s_waitcnt lgkmcnt(1)
	v_mfma_f32_16x16x32_bf16 v[42:45], v[38:41], v[22:25], 0
	ds_read_u16 v69, v58 offset:50688
	v_mfma_f32_16x16x32_bf16 v[70:73], v[38:41], v[30:33], 0
	s_waitcnt lgkmcnt(1)
; template <int DIR, int MODE>
; __device__ __forceinline__ void lru_pass(const Args& a, const LAS bf16_t* cxb, LAS bf16_t* gyb, const LAS float* carry, const bf16x8 (&Bw)[2][2][2], const float (&prm)[2][3], int l, int tt, float (&hf)[8][2][4]) {
;     ...
;             for (int ks = 0; ks < 2; ++ks) { pr = __builtin_amdgcn_mfma_f32_16x16x32_bf16(Af[ks], Bw[0][nt][ks], pr, 0, 0, 0); pi = __builtin_amdgcn_mfma_f32_16x16x32_bf16(Af[ks], Bw[1][nt][ks], pi, 0, 0, 0); }
;             float av[4], bv[4];
; #pragma unroll
;             for (int reg = 0; reg < 4; ++reg) {
;                 const int tok = m * 16 + 4 * fq + reg;
;                 const float x = bf2f(cxb[tok * CXS + cc[nt]]);
;                 const float r = fsig(pr[reg] + ba[nt]), ig = fsig(pi[reg] + bxv[nt]);
;                 const float aa = __expf(k8[nt] * r);
;                 av[reg] = aa; bv[reg] = __builtin_amdgcn_sqrtf(fmaxf(1.0f - aa * aa, 0.f)) * ig * x;
;             }
;             float cum[4], hl[4];
;             if (DIR == 0) { cum[0] = av[0]; hl[0] = bv[0];
; #pragma unroll
;                 for (int reg = 1; reg < 4; ++reg) { cum[reg] = cum[reg - 1] * av[reg]; hl[reg] = av[reg] * hl[reg - 1] + bv[reg]; } }
;             else { cum[3] = av[3]; hl[3] = bv[3];
; #pragma unroll
;     ...
;             const float A4 = DIR ? cum[0] : cum[3], H4 = DIR ? hl[0] : hl[3];
;             float Aq[4], Hq[4];
; #pragma unroll
;             for (int q = 0; q < 4; ++q) { Aq[q] = __shfl(A4, fr + 16 * q); Hq[q] = __shfl(H4, fr + 16 * q); }
;             float hin;
;             if (DIR == 0) { const float s0 = C[nt], s1 = Aq[0] * s0 + Hq[0], s2 = Aq[1] * s1 + Hq[1], s3 = Aq[2] * s2 + Hq[2]; C[nt] = Aq[3] * s3 + Hq[3]; hin = fq == 0 ? s0 : (fq == 1 ? s1 : (fq == 2 ? s2 : s3)); }
;             else { const float s3 = C[nt], s2 = Aq[3] * s3 + Hq[3], s1 = Aq[2] * s2 + Hq[2], s0 = Aq[1] * s1 + Hq[1]; C[nt] = Aq[0] * s0 + Hq[0]; hin = fq == 3 ? s3 : (fq == 2 ? s2 : (fq == 1 ? s1 : s0)); }
;             if (MODE == 0) At[nt] *= (Aq[0] * Aq[1]) * (Aq[2] * Aq[3]);
;             else {
; #pragma unroll
;                 for (int reg = 0; reg < 4; ++reg) {
;                     const float hv = hl[reg] + cum[reg] * hin;
;                     if (DIR == 0) hf[m][nt][reg] = hv;
;                     else { LAS bf16_t* gp = gyb + (m * 16 + 4 * fq + reg) * CXS + cc[nt];
;                         const float g = bf2f(*gp);
	v_mfma_f32_16x16x32_bf16 v[46:49], v[34:37], v[18:21], v[42:45]
	v_mfma_f32_16x16x32_bf16 v[42:45], v[34:37], v[26:29], v[70:73]
	s_nop 6
	v_add_f32_e32 v46, v153, v46
	v_add_f32_e32 v47, v153, v47
	v_add_f32_e32 v48, v153, v48
	v_mul_f32_e32 v46, 0xbfb8aa3b, v46
	v_mul_f32_e32 v47, 0xbfb8aa3b, v47
	v_mul_f32_e32 v48, 0xbfb8aa3b, v48
	v_exp_f32_e32 v46, v46
	v_exp_f32_e32 v47, v47
	v_exp_f32_e32 v48, v48
	v_add_f32_e32 v42, v152, v42
	v_add_f32_e32 v43, v152, v43
	v_add_f32_e32 v44, v152, v44
	v_mul_f32_e32 v42, 0xbfb8aa3b, v42
	v_mul_f32_e32 v43, 0xbfb8aa3b, v43
	v_mul_f32_e32 v44, 0xbfb8aa3b, v44
	v_add_f32_e32 v49, v153, v49
	v_add_f32_e32 v46, 1.0, v46
	v_exp_f32_e32 v42, v42
	v_add_f32_e32 v47, 1.0, v47
	v_exp_f32_e32 v43, v43
	v_add_f32_e32 v48, 1.0, v48
	v_exp_f32_e32 v44, v44
	v_mul_f32_e32 v49, 0xbfb8aa3b, v49
	v_rcp_f32_e32 v46, v46
	v_rcp_f32_e32 v47, v47
	v_rcp_f32_e32 v48, v48
	v_exp_f32_e32 v49, v49
	v_add_f32_e32 v42, 1.0, v42
	v_add_f32_e32 v43, 1.0, v43
	v_add_f32_e32 v44, 1.0, v44
	v_rcp_f32_e32 v70, v42
	v_mul_f32_e32 v42, v60, v46
	v_rcp_f32_e32 v71, v43
	v_mul_f32_e32 v43, v60, v47
	v_rcp_f32_e32 v72, v44
	v_mul_f32_e32 v44, v60, v48
	v_add_f32_e32 v49, 1.0, v49
	v_mul_f32_e32 v42, 0x3fb8aa3b, v42
	v_mul_f32_e32 v43, 0x3fb8aa3b, v43
	v_mul_f32_e32 v44, 0x3fb8aa3b, v44
	v_rcp_f32_e32 v49, v49
	v_exp_f32_e32 v42, v42
	v_exp_f32_e32 v43, v43
	v_exp_f32_e32 v44, v44
	v_mul_f32_e32 v49, v60, v49
	v_fma_f32 v46, -v42, v42, 1.0
	v_fma_f32 v47, -v43, v43, 1.0
	v_fma_f32 v48, -v44, v44, 1.0
	v_add_f32_e32 v45, v152, v45
	v_mul_f32_e32 v49, 0x3fb8aa3b, v49
	v_max_f32_e32 v46, 0, v46
	v_max_f32_e32 v47, 0, v47
	v_max_f32_e32 v48, 0, v48
	v_mul_f32_e32 v45, 0xbfb8aa3b, v45
	v_exp_f32_e32 v49, v49
	v_sqrt_f32_e32 v46, v46
	v_sqrt_f32_e32 v47, v47
	v_sqrt_f32_e32 v48, v48
	v_exp_f32_e32 v45, v45
	v_fma_f32 v73, -v49, v49, 1.0
	v_mul_f32_e32 v46, v70, v46
	ds_read_u16 v70, v58 offset:51216
	v_mul_f32_e32 v47, v71, v47
	ds_read_u16 v71, v58 offset:51744
	v_mul_f32_e32 v48, v72, v48
	ds_read_u16 v72, v58 offset:52272
	v_add_f32_e32 v45, 1.0, v45
	v_max_f32_e32 v73, 0, v73
	v_rcp_f32_e32 v45, v45
	v_sqrt_f32_e32 v73, v73
	s_waitcnt lgkmcnt(0)
	v_lshlrev_b32_e32 v72, 16, v72
	v_lshlrev_b32_e32 v71, 16, v71
	v_lshlrev_b32_e32 v70, 16, v70
	v_mul_f32_e32 v45, v45, v73
	v_mul_f32_e32 v45, v45, v72
	v_mul_f32_e32 v72, v44, v49
	v_mul_f32_e32 v44, v44, v45
	v_fmac_f32_e32 v44, v48, v71
	v_mul_f32_e32 v71, v43, v44
	v_mul_f32_e32 v73, v43, v72
	v_fmac_f32_e32 v71, v47, v70
	v_lshlrev_b32_e32 v69, 16, v69
	v_mul_f32_e32 v47, v42, v73
	v_mul_f32_e32 v42, v42, v71
	v_fmac_f32_e32 v42, v46, v69
	s_nop 0
	s_nop 0
	s_nop 0
	s_nop 0
	s_nop 0
	s_nop 0
	v_mov_b32_e32 v46, v47
	v_mov_b32_e32 v168, v47
	s_nop 1
	v_permlane16_swap_b32_e32 v46, v168
	s_nop 1
	v_mov_b32_e32 v169, v46
	v_mov_b32_e32 v170, v168
	s_nop 1
	v_permlane32_swap_b32_e32 v46, v169
	v_permlane32_swap_b32_e32 v168, v170
	s_nop 1
	v_mov_b32_e32 v43, v42
	v_mov_b32_e32 v48, v42
	s_nop 1
	v_permlane16_swap_b32_e32 v43, v48
	s_nop 1
	v_mov_b32_e32 v70, v43
	v_mov_b32_e32 v69, v48
	s_nop 1
	v_permlane32_swap_b32_e32 v43, v70
	v_permlane32_swap_b32_e32 v48, v69
	s_nop 1
	s_waitcnt lgkmcnt(0)
	v_fmac_f32_e32 v69, v66, v170
	s_waitcnt lgkmcnt(0)
	v_fmac_f32_e32 v70, v69, v169
	s_waitcnt lgkmcnt(0)
	v_fmac_f32_e32 v48, v70, v168
	s_and_saveexec_b64 s[4:5], s[0:1]
	s_cbranch_execz .LBB0_659
	v_cmp_ne_u32_e64 s[0:1], 2, v51
	s_and_saveexec_b64 s[34:35], s[0:1]
	s_xor_b64 s[0:1], exec, s[34:35]
	v_cndmask_b32_e32 v66, v48, v70, vcc
	s_andn2_saveexec_b64 s[0:1], s[0:1]
	v_mov_b32_e32 v66, v69
	s_or_b64 exec, exec, s[0:1]
.LBB0_659:
	s_or_b64 exec, exec, s[4:5]
	v_fmac_f32_e32 v42, v47, v66
	ds_read_u16 v47, v59 offset:50688
	v_fmac_f32_e32 v232, v233, v224
	v_add_f32_e32 v42, v232, v42
	v_fmac_f32_e32 v239, v208, v224
	v_fmac_f32_e32 v71, v73, v66
	s_waitcnt lgkmcnt(0)
	v_lshlrev_b32_e32 v47, 16, v47
	v_mul_f32_e32 v67, 0x3d372713, v47
	v_mul_f32_e32 v67, v67, v47
	v_fma_f32 v67, v67, v47, v47
	v_mul_f32_e32 v67, 0x3f4c422a, v67
	v_add_f32_e32 v67, v67, v67
	v_mul_f32_e32 v67, 0x3fb8aa3b, v67
	v_exp_f32_e32 v67, v67
	v_mul_f32_e32 v47, 0.5, v47
	v_fmac_f32_e32 v238, v209, v224
	v_fmac_f32_e32 v44, v72, v66
	v_add_f32_e32 v67, 1.0, v67
	v_rcp_f32_e32 v67, v67
	v_add_f32_e32 v44, v238, v44
	v_fmac_f32_e32 v225, v228, v224
	v_fmac_f32_e32 v45, v49, v66
	v_fma_f32 v67, v67, -2.0, 2.0
	v_mul_f32_e32 v47, v47, v67
	v_mul_f32_e32 v42, v42, v47
	v_bfe_u32 v47, v42, 16, 1
	v_add3_u32 v42, v42, v47, s27
	ds_write_b16_d16_hi v59, v42 offset:50688
	ds_read_u16 v42, v59 offset:51216
	v_add_f32_e32 v47, v239, v71
	v_mfma_f32_16x16x32_bf16 v[70:73], v[38:41], v[14:17], 0
	v_fmac_f32_e32 v63, v65, v64
	v_cmp_gt_i32_e64 s[0:1], 3, v51
	s_waitcnt lgkmcnt(0)
	v_lshlrev_b32_e32 v42, 16, v42
	v_mul_f32_e32 v67, 0x3d372713, v42
	v_mul_f32_e32 v67, v67, v42
	v_fma_f32 v67, v67, v42, v42
	v_mul_f32_e32 v67, 0x3f4c422a, v67
	v_add_f32_e32 v67, v67, v67
	v_mul_f32_e32 v67, 0x3fb8aa3b, v67
	v_exp_f32_e32 v67, v67
	v_mul_f32_e32 v42, 0.5, v42
	v_add_f32_e32 v67, 1.0, v67
	v_rcp_f32_e32 v67, v67
	s_nop 0
	v_fma_f32 v67, v67, -2.0, 2.0
	v_mul_f32_e32 v42, v42, v67
	v_mul_f32_e32 v42, v47, v42
	v_bfe_u32 v47, v42, 16, 1
	v_add3_u32 v42, v42, v47, s27
	ds_write_b16_d16_hi v59, v42 offset:51216
	ds_read_u16 v42, v59 offset:51744
	v_mfma_f32_16x16x32_bf16 v[66:69], v[38:41], v[6:9], 0
	s_waitcnt lgkmcnt(0)
; template <int DIR, int MODE>
; __device__ __forceinline__ void lru_pass(const Args& a, const LAS bf16_t* cxb, LAS bf16_t* gyb, const LAS float* carry, const bf16x8 (&Bw)[2][2][2], const float (&prm)[2][3], int l, int tt, float (&hf)[8][2][4]) {
;     ...
;             for (int ks = 0; ks < 2; ++ks) { pr = __builtin_amdgcn_mfma_f32_16x16x32_bf16(Af[ks], Bw[0][nt][ks], pr, 0, 0, 0); pi = __builtin_amdgcn_mfma_f32_16x16x32_bf16(Af[ks], Bw[1][nt][ks], pi, 0, 0, 0); }
;             float av[4], bv[4];
; #pragma unroll
;             for (int reg = 0; reg < 4; ++reg) {
;                 const int tok = m * 16 + 4 * fq + reg;
;                 const float x = bf2f(cxb[tok * CXS + cc[nt]]);
;                 const float r = fsig(pr[reg] + ba[nt]), ig = fsig(pi[reg] + bxv[nt]);
;                 const float aa = __expf(k8[nt] * r);
;                 av[reg] = aa; bv[reg] = __builtin_amdgcn_sqrtf(fmaxf(1.0f - aa * aa, 0.f)) * ig * x;
;             }
;             float cum[4], hl[4];
;             if (DIR == 0) { cum[0] = av[0]; hl[0] = bv[0];
; #pragma unroll
;                 for (int reg = 1; reg < 4; ++reg) { cum[reg] = cum[reg - 1] * av[reg]; hl[reg] = av[reg] * hl[reg - 1] + bv[reg]; } }
;             else { cum[3] = av[3]; hl[3] = bv[3];
; #pragma unroll
;     ...
;             const float A4 = DIR ? cum[0] : cum[3], H4 = DIR ? hl[0] : hl[3];
;             float Aq[4], Hq[4];
; #pragma unroll
;             for (int q = 0; q < 4; ++q) { Aq[q] = __shfl(A4, fr + 16 * q); Hq[q] = __shfl(H4, fr + 16 * q); }
;             float hin;
;             if (DIR == 0) { const float s0 = C[nt], s1 = Aq[0] * s0 + Hq[0], s2 = Aq[1] * s1 + Hq[1], s3 = Aq[2] * s2 + Hq[2]; C[nt] = Aq[3] * s3 + Hq[3]; hin = fq == 0 ? s0 : (fq == 1 ? s1 : (fq == 2 ? s2 : s3)); }
;             else { const float s3 = C[nt], s2 = Aq[3] * s3 + Hq[3], s1 = Aq[2] * s2 + Hq[2], s0 = Aq[1] * s1 + Hq[1]; C[nt] = Aq[0] * s0 + Hq[0]; hin = fq == 3 ? s3 : (fq == 2 ? s2 : (fq == 1 ? s1 : s0)); }
;             if (MODE == 0) At[nt] *= (Aq[0] * Aq[1]) * (Aq[2] * Aq[3]);
;             else {
; #pragma unroll
;                 for (int reg = 0; reg < 4; ++reg) {
;                     const float hv = hl[reg] + cum[reg] * hin;
;                     if (DIR == 0) hf[m][nt][reg] = hv;
;                     else { LAS bf16_t* gp = gyb + (m * 16 + 4 * fq + reg) * CXS + cc[nt];
;                         const float g = bf2f(*gp);
	v_lshlrev_b32_e32 v42, 16, v42
	v_mul_f32_e32 v47, 0x3d372713, v42
	v_mul_f32_e32 v47, v47, v42
	v_fma_f32 v47, v47, v42, v42
	v_mul_f32_e32 v47, 0x3f4c422a, v47
	v_add_f32_e32 v47, v47, v47
	v_mul_f32_e32 v47, 0x3fb8aa3b, v47
	v_exp_f32_e32 v47, v47
	v_mul_f32_e32 v42, 0.5, v42
	v_mfma_f32_16x16x32_bf16 v[38:41], v[34:37], v[2:5], v[66:69]
	v_add_f32_e32 v47, 1.0, v47
	v_rcp_f32_e32 v47, v47
	v_mfma_f32_16x16x32_bf16 v[34:37], v[34:37], v[10:13], v[70:73]
	v_fma_f32 v47, v47, -2.0, 2.0
	v_mul_f32_e32 v42, v42, v47
	v_mul_f32_e32 v42, v44, v42
	v_bfe_u32 v44, v42, 16, 1
	v_add3_u32 v42, v42, v44, s27
	ds_write_b16_d16_hi v59, v42 offset:51744
	ds_read_u16 v42, v59 offset:52272
	v_add_f32_e32 v44, v225, v45
	v_add_f32_e32 v38, v151, v38
	v_add_f32_e32 v39, v151, v39
	v_add_f32_e32 v40, v151, v40
	s_waitcnt lgkmcnt(0)
	v_lshlrev_b32_e32 v42, 16, v42
	v_mul_f32_e32 v45, 0x3d372713, v42
	v_mul_f32_e32 v45, v45, v42
	v_fma_f32 v45, v45, v42, v42
	v_mul_f32_e32 v45, 0x3f4c422a, v45
	v_add_f32_e32 v45, v45, v45
	v_mul_f32_e32 v45, 0x3fb8aa3b, v45
	v_exp_f32_e32 v45, v45
	v_mul_f32_e32 v38, 0xbfb8aa3b, v38
	v_mul_f32_e32 v39, 0xbfb8aa3b, v39
	v_mul_f32_e32 v40, 0xbfb8aa3b, v40
	v_add_f32_e32 v45, 1.0, v45
	v_exp_f32_e32 v38, v38
	v_exp_f32_e32 v39, v39
	v_exp_f32_e32 v40, v40
	v_rcp_f32_e32 v45, v45
	v_add_f32_e32 v34, v150, v34
	v_add_f32_e32 v35, v150, v35
	v_add_f32_e32 v36, v150, v36
	v_mul_f32_e32 v34, 0xbfb8aa3b, v34
	v_mul_f32_e32 v35, 0xbfb8aa3b, v35
	v_mul_f32_e32 v36, 0xbfb8aa3b, v36
	v_add_f32_e32 v41, v151, v41
	v_add_f32_e32 v38, 1.0, v38
	v_exp_f32_e32 v34, v34
	v_add_f32_e32 v39, 1.0, v39
	v_exp_f32_e32 v35, v35
	v_add_f32_e32 v40, 1.0, v40
	v_exp_f32_e32 v36, v36
	v_mul_f32_e32 v41, 0xbfb8aa3b, v41
	v_mul_f32_e32 v42, 0.5, v42
	v_fma_f32 v45, v45, -2.0, 2.0
	v_rcp_f32_e32 v38, v38
	v_rcp_f32_e32 v39, v39
	v_rcp_f32_e32 v40, v40
	v_exp_f32_e32 v41, v41
	v_mul_f32_e32 v42, v42, v45
	v_mul_f32_e32 v42, v44, v42
	v_add_f32_e32 v37, v150, v37
	v_bfe_u32 v44, v42, 16, 1
	v_add_f32_e32 v34, 1.0, v34
	v_add_f32_e32 v35, 1.0, v35
	v_add_f32_e32 v36, 1.0, v36
	v_mul_f32_e32 v37, 0xbfb8aa3b, v37
	v_add3_u32 v42, v42, v44, s27
	v_rcp_f32_e32 v44, v34
	v_mul_f32_e32 v34, v57, v38
	v_rcp_f32_e32 v45, v35
	v_mul_f32_e32 v35, v57, v39
	v_rcp_f32_e32 v47, v36
	v_mul_f32_e32 v36, v57, v40
	v_add_f32_e32 v41, 1.0, v41
	v_exp_f32_e32 v37, v37
	v_mul_f32_e32 v34, 0x3fb8aa3b, v34
	v_mul_f32_e32 v35, 0x3fb8aa3b, v35
	v_mul_f32_e32 v36, 0x3fb8aa3b, v36
	v_rcp_f32_e32 v41, v41
	v_exp_f32_e32 v34, v34
	v_exp_f32_e32 v35, v35
	v_exp_f32_e32 v36, v36
	v_add_f32_e32 v37, 1.0, v37
	v_rcp_f32_e32 v49, v37
	v_mul_f32_e32 v37, v57, v41
	v_fma_f32 v38, -v34, v34, 1.0
	v_fma_f32 v39, -v35, v35, 1.0
	v_fma_f32 v40, -v36, v36, 1.0
	v_mul_f32_e32 v37, 0x3fb8aa3b, v37
	v_max_f32_e32 v38, 0, v38
	v_max_f32_e32 v39, 0, v39
	v_max_f32_e32 v40, 0, v40
	v_exp_f32_e32 v37, v37
	v_sqrt_f32_e32 v38, v38
	v_sqrt_f32_e32 v39, v39
	v_sqrt_f32_e32 v40, v40
	v_fma_f32 v41, -v37, v37, 1.0
	ds_write_b16_d16_hi v59, v42 offset:52272
	ds_read_u16 v42, v58 offset:50720
	v_mul_f32_e32 v38, v44, v38
	ds_read_u16 v44, v58 offset:51248
	v_mul_f32_e32 v39, v45, v39
	ds_read_u16 v45, v58 offset:51776
	v_mul_f32_e32 v40, v47, v40
	ds_read_u16 v47, v58 offset:52304
	v_max_f32_e32 v41, 0, v41
	v_sqrt_f32_e32 v41, v41
	s_waitcnt lgkmcnt(1)
	v_lshlrev_b32_e32 v45, 16, v45
	v_lshlrev_b32_e32 v44, 16, v44
	s_waitcnt lgkmcnt(0)
	v_lshlrev_b32_e32 v47, 16, v47
	v_mul_f32_e32 v41, v49, v41
	v_mul_f32_e32 v41, v41, v47
	v_mul_f32_e32 v49, v36, v37
	v_mul_f32_e32 v36, v36, v41
	v_fmac_f32_e32 v36, v40, v45
	v_mul_f32_e32 v40, v35, v49
	v_mul_f32_e32 v35, v35, v36
	v_fmac_f32_e32 v35, v39, v44
	v_lshlrev_b32_e32 v42, 16, v42
	v_mul_f32_e32 v39, v34, v40
	v_mul_f32_e32 v34, v34, v35
	v_fmac_f32_e32 v34, v38, v42
	s_nop 0
	s_nop 0
	s_nop 0
	s_nop 0
	s_nop 0
	s_nop 0
	v_mov_b32_e32 v45, v39
	v_mov_b32_e32 v66, v39
	s_nop 1
	v_permlane16_swap_b32_e32 v45, v66
	s_nop 1
	v_mov_b32_e32 v67, v45
	v_mov_b32_e32 v68, v66
	s_nop 1
	v_permlane32_swap_b32_e32 v45, v67
	v_permlane32_swap_b32_e32 v66, v68
	s_nop 1
	v_mov_b32_e32 v42, v34
	v_mov_b32_e32 v47, v34
	s_nop 1
	v_permlane16_swap_b32_e32 v42, v47
	s_nop 1
	v_mov_b32_e32 v44, v42
	v_mov_b32_e32 v38, v47
	s_nop 1
	v_permlane32_swap_b32_e32 v42, v44
	v_permlane32_swap_b32_e32 v47, v38
	s_nop 1
	s_waitcnt lgkmcnt(0)
	v_fmac_f32_e32 v38, v63, v68
	s_waitcnt lgkmcnt(0)
	v_fmac_f32_e32 v44, v38, v67
	s_waitcnt lgkmcnt(0)
	v_fmac_f32_e32 v47, v44, v66
	s_and_saveexec_b64 s[4:5], s[0:1]
	s_cbranch_execz .LBB0_665
	v_cmp_ne_u32_e64 s[0:1], 2, v51
	s_and_saveexec_b64 s[34:35], s[0:1]
	s_xor_b64 s[0:1], exec, s[34:35]
	v_cndmask_b32_e32 v63, v47, v44, vcc
	s_andn2_saveexec_b64 s[0:1], s[0:1]
	v_mov_b32_e32 v63, v38
	s_or_b64 exec, exec, s[0:1]
; template <int DIR, int MODE>
; __device__ __forceinline__ void lru_pass(const Args& a, const LAS bf16_t* cxb, LAS bf16_t* gyb, const LAS float* carry, const bf16x8 (&Bw)[2][2][2], const float (&prm)[2][3], int l, int tt, float (&hf)[8][2][4]) {
;     ...
;             for (int ks = 0; ks < 2; ++ks) { pr = __builtin_amdgcn_mfma_f32_16x16x32_bf16(Af[ks], Bw[0][nt][ks], pr, 0, 0, 0); pi = __builtin_amdgcn_mfma_f32_16x16x32_bf16(Af[ks], Bw[1][nt][ks], pi, 0, 0, 0); }
;             float av[4], bv[4];
; #pragma unroll
;             for (int reg = 0; reg < 4; ++reg) {
;                 const int tok = m * 16 + 4 * fq + reg;
;                 const float x = bf2f(cxb[tok * CXS + cc[nt]]);
;                 const float r = fsig(pr[reg] + ba[nt]), ig = fsig(pi[reg] + bxv[nt]);
;                 const float aa = __expf(k8[nt] * r);
;                 av[reg] = aa; bv[reg] = __builtin_amdgcn_sqrtf(fmaxf(1.0f - aa * aa, 0.f)) * ig * x;
;             }
;             float cum[4], hl[4];
;             if (DIR == 0) { cum[0] = av[0]; hl[0] = bv[0];
; #pragma unroll
;                 for (int reg = 1; reg < 4; ++reg) { cum[reg] = cum[reg - 1] * av[reg]; hl[reg] = av[reg] * hl[reg - 1] + bv[reg]; } }
;             else { cum[3] = av[3]; hl[3] = bv[3];
; #pragma unroll
;     ...
;             const float A4 = DIR ? cum[0] : cum[3], H4 = DIR ? hl[0] : hl[3];
;             float Aq[4], Hq[4];
; #pragma unroll
;             for (int q = 0; q < 4; ++q) { Aq[q] = __shfl(A4, fr + 16 * q); Hq[q] = __shfl(H4, fr + 16 * q); }
;             float hin;
;             if (DIR == 0) { const float s0 = C[nt], s1 = Aq[0] * s0 + Hq[0], s2 = Aq[1] * s1 + Hq[1], s3 = Aq[2] * s2 + Hq[2]; C[nt] = Aq[3] * s3 + Hq[3]; hin = fq == 0 ? s0 : (fq == 1 ? s1 : (fq == 2 ? s2 : s3)); }
;             else { const float s3 = C[nt], s2 = Aq[3] * s3 + Hq[3], s1 = Aq[2] * s2 + Hq[2], s0 = Aq[1] * s1 + Hq[1]; C[nt] = Aq[0] * s0 + Hq[0]; hin = fq == 3 ? s3 : (fq == 2 ? s2 : (fq == 1 ? s1 : s0)); }
;             if (MODE == 0) At[nt] *= (Aq[0] * Aq[1]) * (Aq[2] * Aq[3]);
;             else {
; #pragma unroll
;                 for (int reg = 0; reg < 4; ++reg) {
;                     const float hv = hl[reg] + cum[reg] * hin;
;                     if (DIR == 0) hf[m][nt][reg] = hv;
;                     else { LAS bf16_t* gp = gyb + (m * 16 + 4 * fq + reg) * CXS + cc[nt];
;                         const float g = bf2f(*gp);
.LBB0_665:
	s_or_b64 exec, exec, s[4:5]
	ds_read_u16 v38, v52 offset:50688
	ds_read_u16 v44, v52 offset:51216
	ds_read_u16 v64, v52 offset:51744
	ds_read_u16 v65, v52 offset:52272
	ds_read_u16 v72, v58 offset:43824
	s_waitcnt lgkmcnt(4)
	v_lshlrev_b32_e32 v38, 16, v38
	v_mul_f32_e32 v66, 0x3d372713, v38
	v_mul_f32_e32 v66, v66, v38
	v_fma_f32 v66, v66, v38, v38
	v_mul_f32_e32 v66, 0x3f4c422a, v66
	v_add_f32_e32 v66, v66, v66
	v_mul_f32_e32 v66, 0x3fb8aa3b, v66
	v_exp_f32_e32 v66, v66
	v_fmac_f32_e32 v217, v219, v216
	v_fmac_f32_e32 v34, v39, v63
	v_mul_f32_e32 v38, 0.5, v38
	v_add_f32_e32 v66, 1.0, v66
	v_rcp_f32_e32 v66, v66
	v_add_f32_e32 v34, v217, v34
	v_fmac_f32_e32 v247, v248, v216
	v_fmac_f32_e32 v35, v40, v63
	v_fma_f32 v39, v66, -2.0, 2.0
	v_mul_f32_e32 v38, v38, v39
	v_mul_f32_e32 v34, v34, v38
	s_waitcnt lgkmcnt(3)
	v_lshlrev_b32_e32 v38, 16, v44
	v_mul_f32_e32 v39, 0x3d372713, v38
	v_mul_f32_e32 v39, v39, v38
	v_fma_f32 v39, v39, v38, v38
	v_mul_f32_e32 v39, 0x3f4c422a, v39
	v_add_f32_e32 v39, v39, v39
	v_mul_f32_e32 v39, 0x3fb8aa3b, v39
	v_exp_f32_e32 v39, v39
	v_bfe_u32 v44, v34, 16, 1
	v_add3_u32 v34, v34, v44, s27
	ds_write_b16_d16_hi v52, v34 offset:50688
	v_add_f32_e32 v34, 1.0, v39
	v_rcp_f32_e32 v34, v34
	v_mul_f32_e32 v38, 0.5, v38
	v_add_f32_e32 v35, v247, v35
	v_fmac_f32_e32 v246, v249, v216
	v_fma_f32 v34, v34, -2.0, 2.0
	v_mul_f32_e32 v34, v38, v34
	v_mul_f32_e32 v34, v35, v34
	s_waitcnt lgkmcnt(3)
	v_lshlrev_b32_e32 v35, 16, v64
	v_mul_f32_e32 v38, 0x3d372713, v35
	v_mul_f32_e32 v38, v38, v35
	v_fma_f32 v38, v38, v35, v35
	v_mul_f32_e32 v38, 0x3f4c422a, v38
	v_add_f32_e32 v38, v38, v38
	v_mul_f32_e32 v38, 0x3fb8aa3b, v38
	v_exp_f32_e32 v38, v38
	v_bfe_u32 v39, v34, 16, 1
	v_add3_u32 v34, v34, v39, s27
	ds_write_b16_d16_hi v52, v34 offset:51216
	v_add_f32_e32 v34, 1.0, v38
	v_rcp_f32_e32 v34, v34
	v_fmac_f32_e32 v36, v49, v63
	v_mul_f32_e32 v35, 0.5, v35
	v_add_f32_e32 v36, v246, v36
	v_fma_f32 v34, v34, -2.0, 2.0
	v_mul_f32_e32 v34, v35, v34
	s_waitcnt lgkmcnt(3)
	v_lshlrev_b32_e32 v35, 16, v65
	v_mul_f32_e32 v34, v36, v34
	v_mul_f32_e32 v36, 0x3d372713, v35
	v_mul_f32_e32 v36, v36, v35
	v_fma_f32 v36, v36, v35, v35
	v_mul_f32_e32 v36, 0x3f4c422a, v36
	v_add_f32_e32 v36, v36, v36
	v_mul_f32_e32 v36, 0x3fb8aa3b, v36
	v_exp_f32_e32 v36, v36
	v_bfe_u32 v38, v34, 16, 1
	v_add3_u32 v34, v34, v38, s27
	ds_write_b16_d16_hi v52, v34 offset:51744
	v_add_f32_e32 v34, 1.0, v36
	v_rcp_f32_e32 v34, v34
	v_fmac_f32_e32 v221, v250, v216
	v_fmac_f32_e32 v41, v37, v63
	v_mul_f32_e32 v35, 0.5, v35
	v_fma_f32 v34, v34, -2.0, 2.0
	v_add_f32_e32 v36, v221, v41
	v_mul_f32_e32 v34, v35, v34
	v_mul_f32_e32 v34, v36, v34
	v_bfe_u32 v35, v34, 16, 1
	v_add3_u32 v34, v34, v35, s27
	ds_write_b16_d16_hi v52, v34 offset:52272
	ds_read_b128 v[38:41], v62 offset:42240
	ds_read_b128 v[34:37], v62 offset:42304
	s_waitcnt lgkmcnt(1)
	v_mfma_f32_16x16x32_bf16 v[64:67], v[38:41], v[22:25], 0
	v_fmac_f32_e32 v43, v48, v46
	v_cmp_gt_i32_e64 s[0:1], 3, v51
	s_waitcnt lgkmcnt(0)
	v_mfma_f32_16x16x32_bf16 v[64:67], v[34:37], v[18:21], v[64:67]
	v_mfma_f32_16x16x32_bf16 v[68:71], v[38:41], v[30:33], 0
	v_mfma_f32_16x16x32_bf16 v[68:71], v[34:37], v[26:29], v[68:71]
	s_nop 5
	v_add_f32_e32 v44, v153, v64
	v_mul_f32_e32 v44, 0xbfb8aa3b, v44
	v_exp_f32_e32 v44, v44
	v_add_f32_e32 v65, v153, v65
	v_mul_f32_e32 v65, 0xbfb8aa3b, v65
	v_exp_f32_e32 v65, v65
	v_add_f32_e32 v44, 1.0, v44
	v_rcp_f32_e32 v44, v44
	v_add_f32_e32 v68, v152, v68
	v_add_f32_e32 v65, 1.0, v65
	v_rcp_f32_e32 v65, v65
	v_mul_f32_e32 v44, v60, v44
	v_mul_f32_e32 v44, 0x3fb8aa3b, v44
	v_mul_f32_e32 v68, 0xbfb8aa3b, v68
	v_exp_f32_e32 v44, v44
	v_mul_f32_e32 v65, v60, v65
	v_exp_f32_e32 v68, v68
	v_mul_f32_e32 v65, 0x3fb8aa3b, v65
	v_exp_f32_e32 v80, v65
	v_add_f32_e32 v65, v153, v66
	v_mul_f32_e32 v65, 0xbfb8aa3b, v65
	v_fma_f32 v73, -v44, v44, 1.0
	v_add_f32_e32 v69, v152, v69
	v_exp_f32_e32 v65, v65
	v_add_f32_e32 v68, 1.0, v68
	v_max_f32_e32 v73, 0, v73
	v_mul_f32_e32 v69, 0xbfb8aa3b, v69
	v_rcp_f32_e32 v68, v68
	v_sqrt_f32_e32 v73, v73
	v_exp_f32_e32 v69, v69
	v_add_f32_e32 v65, 1.0, v65
	v_fma_f32 v66, -v80, v80, 1.0
	v_rcp_f32_e32 v65, v65
	v_mul_f32_e32 v73, v68, v73
	v_add_f32_e32 v68, 1.0, v69
	v_max_f32_e32 v66, 0, v66
	v_rcp_f32_e32 v68, v68
	v_sqrt_f32_e32 v66, v66
	v_mul_f32_e32 v65, v60, v65
	v_mul_f32_e32 v65, 0x3fb8aa3b, v65
	v_add_f32_e32 v69, v152, v70
	v_mul_f32_e32 v81, v68, v66
	v_exp_f32_e32 v66, v65
	v_add_f32_e32 v65, v153, v67
	v_mul_f32_e32 v65, 0xbfb8aa3b, v65
	v_exp_f32_e32 v65, v65
	v_mul_f32_e32 v69, 0xbfb8aa3b, v69
	v_add_f32_e32 v68, v152, v71
	ds_read_u16 v49, v58 offset:42240
	ds_read_u16 v63, v58 offset:42768
	ds_read_u16 v64, v58 offset:43296
	v_add_f32_e32 v65, 1.0, v65
	v_rcp_f32_e32 v65, v65
	v_exp_f32_e32 v69, v69
	v_mul_f32_e32 v68, 0xbfb8aa3b, v68
	v_exp_f32_e32 v68, v68
	v_mul_f32_e32 v65, v60, v65
	v_mul_f32_e32 v65, 0x3fb8aa3b, v65
	v_exp_f32_e32 v65, v65
	s_waitcnt lgkmcnt(1)
	v_lshlrev_b32_e32 v70, 16, v63
	v_add_f32_e32 v63, 1.0, v69
	v_fma_f32 v67, -v66, v66, 1.0
	v_fma_f32 v69, -v65, v65, 1.0
	v_max_f32_e32 v67, 0, v67
	v_add_f32_e32 v68, 1.0, v68
	v_max_f32_e32 v69, 0, v69
	v_rcp_f32_e32 v63, v63
	v_sqrt_f32_e32 v67, v67
	v_rcp_f32_e32 v68, v68
	v_sqrt_f32_e32 v69, v69
	s_waitcnt lgkmcnt(0)
	v_lshlrev_b32_e32 v64, 16, v64
	v_mul_f32_e32 v71, v63, v67
	v_lshlrev_b32_e32 v63, 16, v72
	v_mul_f32_e32 v67, v68, v69
	v_mul_f32_e32 v63, v67, v63
	v_mul_f32_e32 v67, v66, v65
	v_mul_f32_e32 v66, v66, v63
	v_fmac_f32_e32 v66, v71, v64
	v_mul_f32_e32 v68, v80, v66
	v_fmac_f32_e32 v68, v81, v70
	v_lshlrev_b32_e32 v49, 16, v49
	v_mul_f32_e32 v69, v80, v67
	v_mul_f32_e32 v70, v44, v68
	v_mul_f32_e32 v71, v44, v69
	v_fmac_f32_e32 v70, v73, v49
	s_nop 0
	ds_bpermute_b32 v72, v54, v70
	s_nop 0
	ds_bpermute_b32 v73, v55, v70
	s_nop 0
	ds_bpermute_b32 v64, v56, v70
	v_mov_b32_e32 v49, v71
	v_mov_b32_e32 v168, v71
	s_nop 1
	v_permlane16_swap_b32_e32 v49, v168
	s_nop 1
	v_mov_b32_e32 v169, v49
	v_mov_b32_e32 v170, v168
	s_nop 1
	v_permlane32_swap_b32_e32 v49, v169
	v_permlane32_swap_b32_e32 v168, v170
	s_nop 1
	ds_bpermute_b32 v44, v61, v70
	s_waitcnt lgkmcnt(3)
	v_fmac_f32_e32 v72, v43, v170
	s_waitcnt lgkmcnt(2)
	v_fmac_f32_e32 v73, v72, v169
	s_waitcnt lgkmcnt(1)
	v_fmac_f32_e32 v64, v73, v168
	s_and_saveexec_b64 s[4:5], s[0:1]
	s_cbranch_execz .LBB0_671
	v_cmp_ne_u32_e64 s[0:1], 2, v51
	s_and_saveexec_b64 s[34:35], s[0:1]
	s_xor_b64 s[0:1], exec, s[34:35]
	v_cndmask_b32_e32 v43, v64, v73, vcc
	s_andn2_saveexec_b64 s[0:1], s[0:1]
	v_mov_b32_e32 v43, v72
	s_or_b64 exec, exec, s[0:1]
; template <int DIR, int MODE>
; __device__ __forceinline__ void lru_pass(const Args& a, const LAS bf16_t* cxb, LAS bf16_t* gyb, const LAS float* carry, const bf16x8 (&Bw)[2][2][2], const float (&prm)[2][3], int l, int tt, float (&hf)[8][2][4]) {
;     ...
;             for (int ks = 0; ks < 2; ++ks) { pr = __builtin_amdgcn_mfma_f32_16x16x32_bf16(Af[ks], Bw[0][nt][ks], pr, 0, 0, 0); pi = __builtin_amdgcn_mfma_f32_16x16x32_bf16(Af[ks], Bw[1][nt][ks], pi, 0, 0, 0); }
;             float av[4], bv[4];
; #pragma unroll
;             for (int reg = 0; reg < 4; ++reg) {
;                 const int tok = m * 16 + 4 * fq + reg;
;                 const float x = bf2f(cxb[tok * CXS + cc[nt]]);
;                 const float r = fsig(pr[reg] + ba[nt]), ig = fsig(pi[reg] + bxv[nt]);
;                 const float aa = __expf(k8[nt] * r);
;                 av[reg] = aa; bv[reg] = __builtin_amdgcn_sqrtf(fmaxf(1.0f - aa * aa, 0.f)) * ig * x;
;             }
;             float cum[4], hl[4];
;             if (DIR == 0) { cum[0] = av[0]; hl[0] = bv[0];
; #pragma unroll
;                 for (int reg = 1; reg < 4; ++reg) { cum[reg] = cum[reg - 1] * av[reg]; hl[reg] = av[reg] * hl[reg - 1] + bv[reg]; } }
;             else { cum[3] = av[3]; hl[3] = bv[3];
; #pragma unroll
;     ...
;             const float A4 = DIR ? cum[0] : cum[3], H4 = DIR ? hl[0] : hl[3];
;             float Aq[4], Hq[4];
; #pragma unroll
;             for (int q = 0; q < 4; ++q) { Aq[q] = __shfl(A4, fr + 16 * q); Hq[q] = __shfl(H4, fr + 16 * q); }
;             float hin;
;             if (DIR == 0) { const float s0 = C[nt], s1 = Aq[0] * s0 + Hq[0], s2 = Aq[1] * s1 + Hq[1], s3 = Aq[2] * s2 + Hq[2]; C[nt] = Aq[3] * s3 + Hq[3]; hin = fq == 0 ? s0 : (fq == 1 ? s1 : (fq == 2 ? s2 : s3)); }
;             else { const float s3 = C[nt], s2 = Aq[3] * s3 + Hq[3], s1 = Aq[2] * s2 + Hq[2], s0 = Aq[1] * s1 + Hq[1]; C[nt] = Aq[0] * s0 + Hq[0]; hin = fq == 3 ? s3 : (fq == 2 ? s2 : (fq == 1 ? s1 : s0)); }
;             if (MODE == 0) At[nt] *= (Aq[0] * Aq[1]) * (Aq[2] * Aq[3]);
;             else {
; #pragma unroll
;                 for (int reg = 0; reg < 4; ++reg) {
;                     const float hv = hl[reg] + cum[reg] * hin;
;                     if (DIR == 0) hf[m][nt][reg] = hv;
;                     else { LAS bf16_t* gp = gyb + (m * 16 + 4 * fq + reg) * CXS + cc[nt];
;                         const float g = bf2f(*gp);
.LBB0_671:
	s_or_b64 exec, exec, s[4:5]
	ds_read_u16 v46, v59 offset:42240
	v_fmac_f32_e32 v202, v203, v182
	v_fmac_f32_e32 v70, v71, v43
	v_fmac_f32_e32 v68, v69, v43
	v_fmac_f32_e32 v66, v67, v43
	v_fmac_f32_e32 v63, v65, v43
	ds_read_u16 v43, v59 offset:43824
	s_waitcnt lgkmcnt(1)
	v_lshlrev_b32_e32 v46, 16, v46
	v_add_f32_e32 v48, v202, v70
	v_mul_f32_e32 v70, 0x3d372713, v46
	v_mul_f32_e32 v70, v70, v46
	v_fma_f32 v70, v70, v46, v46
	v_mul_f32_e32 v70, 0x3f4c422a, v70
	v_add_f32_e32 v70, v70, v70
	v_mul_f32_e32 v70, 0x3fb8aa3b, v70
	v_exp_f32_e32 v70, v70
	v_mul_f32_e32 v46, 0.5, v46
	v_fmac_f32_e32 v201, v204, v182
	v_fmac_f32_e32 v199, v205, v182
	v_add_f32_e32 v70, 1.0, v70
	v_rcp_f32_e32 v70, v70
	s_waitcnt lgkmcnt(0)
	v_lshlrev_b32_e32 v43, 16, v43
	v_fmac_f32_e32 v198, v206, v182
	v_fmac_f32_e32 v42, v47, v45
	v_fma_f32 v70, v70, -2.0, 2.0
	v_mul_f32_e32 v46, v46, v70
	v_mul_f32_e32 v46, v48, v46
	v_bfe_u32 v48, v46, 16, 1
	v_add3_u32 v46, v46, v48, s27
	ds_write_b16_d16_hi v59, v46 offset:42240
	ds_read_u16 v46, v59 offset:42768
	v_add_f32_e32 v48, v201, v68
	v_mfma_f32_16x16x32_bf16 v[70:73], v[38:41], v[14:17], 0
	v_cmp_gt_i32_e64 s[0:1], 3, v51
	s_waitcnt lgkmcnt(0)
	v_lshlrev_b32_e32 v46, 16, v46
	v_mul_f32_e32 v68, 0x3d372713, v46
	v_mul_f32_e32 v68, v68, v46
	v_fma_f32 v68, v68, v46, v46
	v_mul_f32_e32 v68, 0x3f4c422a, v68
	v_add_f32_e32 v68, v68, v68
	v_mul_f32_e32 v68, 0x3fb8aa3b, v68
	v_exp_f32_e32 v68, v68
	v_mul_f32_e32 v46, 0.5, v46
	v_add_f32_e32 v68, 1.0, v68
	v_rcp_f32_e32 v68, v68
	s_nop 0
	v_fma_f32 v68, v68, -2.0, 2.0
	v_mul_f32_e32 v46, v46, v68
	v_mul_f32_e32 v46, v48, v46
	v_bfe_u32 v48, v46, 16, 1
	v_add3_u32 v46, v46, v48, s27
	ds_write_b16_d16_hi v59, v46 offset:42768
	ds_read_u16 v46, v59 offset:43296
	v_add_f32_e32 v48, v199, v66
	s_waitcnt lgkmcnt(0)
	v_lshlrev_b32_e32 v46, 16, v46
	v_mul_f32_e32 v66, 0x3d372713, v46
	v_mul_f32_e32 v66, v66, v46
	v_fma_f32 v66, v66, v46, v46
	v_mul_f32_e32 v66, 0x3f4c422a, v66
	v_add_f32_e32 v66, v66, v66
	v_mul_f32_e32 v66, 0x3fb8aa3b, v66
	v_exp_f32_e32 v66, v66
	v_mul_f32_e32 v46, 0.5, v46
	v_add_f32_e32 v66, 1.0, v66
	v_rcp_f32_e32 v66, v66
	s_nop 0
	v_fma_f32 v66, v66, -2.0, 2.0
	v_mul_f32_e32 v46, v46, v66
	v_mul_f32_e32 v46, v48, v46
	v_bfe_u32 v48, v46, 16, 1
	v_add3_u32 v46, v46, v48, s27
	v_mul_f32_e32 v48, 0x3d372713, v43
	v_mfma_f32_16x16x32_bf16 v[66:69], v[38:41], v[6:9], 0
	v_mul_f32_e32 v48, v48, v43
	v_fma_f32 v48, v48, v43, v43
	v_mul_f32_e32 v48, 0x3f4c422a, v48
	v_add_f32_e32 v48, v48, v48
	v_mfma_f32_16x16x32_bf16 v[38:41], v[34:37], v[2:5], v[66:69]
	v_mul_f32_e32 v48, 0x3fb8aa3b, v48
	v_exp_f32_e32 v48, v48
	v_mul_f32_e32 v43, 0.5, v43
	v_mfma_f32_16x16x32_bf16 v[34:37], v[34:37], v[10:13], v[70:73]
	ds_write_b16_d16_hi v59, v46 offset:43296
	s_nop 2
	v_add_f32_e32 v38, v151, v38
	v_add_f32_e32 v39, v151, v39
	v_add_f32_e32 v40, v151, v40
	v_mul_f32_e32 v38, 0xbfb8aa3b, v38
	v_mul_f32_e32 v39, 0xbfb8aa3b, v39
	v_mul_f32_e32 v40, 0xbfb8aa3b, v40
	v_add_f32_e32 v48, 1.0, v48
	v_exp_f32_e32 v38, v38
	v_exp_f32_e32 v39, v39
	v_exp_f32_e32 v40, v40
	v_rcp_f32_e32 v48, v48
	v_add_f32_e32 v34, v150, v34
	v_add_f32_e32 v35, v150, v35
	v_add_f32_e32 v36, v150, v36
	v_mul_f32_e32 v34, 0xbfb8aa3b, v34
	v_mul_f32_e32 v35, 0xbfb8aa3b, v35
	v_mul_f32_e32 v36, 0xbfb8aa3b, v36
	v_add_f32_e32 v41, v151, v41
	v_add_f32_e32 v38, 1.0, v38
	v_exp_f32_e32 v34, v34
	v_add_f32_e32 v39, 1.0, v39
	v_exp_f32_e32 v35, v35
	v_add_f32_e32 v40, 1.0, v40
	v_exp_f32_e32 v36, v36
	v_mul_f32_e32 v41, 0xbfb8aa3b, v41
	v_fma_f32 v48, v48, -2.0, 2.0
	v_rcp_f32_e32 v38, v38
	v_rcp_f32_e32 v39, v39
	v_rcp_f32_e32 v40, v40
	v_exp_f32_e32 v41, v41
	v_add_f32_e32 v46, v198, v63
	v_mul_f32_e32 v43, v43, v48
	v_mul_f32_e32 v43, v46, v43
	v_add_f32_e32 v37, v150, v37
	v_bfe_u32 v46, v43, 16, 1
	v_add_f32_e32 v34, 1.0, v34
	v_add_f32_e32 v35, 1.0, v35
	v_add_f32_e32 v36, 1.0, v36
	v_mul_f32_e32 v37, 0xbfb8aa3b, v37
	v_add3_u32 v43, v43, v46, s27
	v_rcp_f32_e32 v46, v34
	v_mul_f32_e32 v34, v57, v38
	v_rcp_f32_e32 v48, v35
	v_mul_f32_e32 v35, v57, v39
	v_rcp_f32_e32 v63, v36
	v_mul_f32_e32 v36, v57, v40
	v_add_f32_e32 v41, 1.0, v41
	v_exp_f32_e32 v37, v37
	v_mul_f32_e32 v34, 0x3fb8aa3b, v34
	v_mul_f32_e32 v35, 0x3fb8aa3b, v35
	v_mul_f32_e32 v36, 0x3fb8aa3b, v36
	v_rcp_f32_e32 v41, v41
	v_exp_f32_e32 v34, v34
	v_exp_f32_e32 v35, v35
	v_exp_f32_e32 v36, v36
	v_add_f32_e32 v37, 1.0, v37
	v_rcp_f32_e32 v65, v37
	v_mul_f32_e32 v37, v57, v41
	v_fma_f32 v38, -v34, v34, 1.0
	v_fma_f32 v39, -v35, v35, 1.0
	v_fma_f32 v40, -v36, v36, 1.0
	v_mul_f32_e32 v37, 0x3fb8aa3b, v37
	v_max_f32_e32 v38, 0, v38
	v_max_f32_e32 v39, 0, v39
	v_max_f32_e32 v40, 0, v40
	v_exp_f32_e32 v37, v37
	v_sqrt_f32_e32 v38, v38
	v_sqrt_f32_e32 v39, v39
	v_sqrt_f32_e32 v40, v40
	v_fma_f32 v41, -v37, v37, 1.0
	ds_write_b16_d16_hi v59, v43 offset:43824
	ds_read_u16 v43, v58 offset:42272
	v_mul_f32_e32 v38, v46, v38
	ds_read_u16 v46, v58 offset:42800
	v_mul_f32_e32 v39, v48, v39
	ds_read_u16 v48, v58 offset:43328
	v_mul_f32_e32 v40, v63, v40
	ds_read_u16 v63, v58 offset:43856
	v_max_f32_e32 v41, 0, v41
	v_sqrt_f32_e32 v41, v41
	s_waitcnt lgkmcnt(1)
	v_lshlrev_b32_e32 v48, 16, v48
	v_lshlrev_b32_e32 v46, 16, v46
	s_waitcnt lgkmcnt(0)
	v_lshlrev_b32_e32 v63, 16, v63
	v_mul_f32_e32 v41, v65, v41
	v_mul_f32_e32 v41, v41, v63
	v_mul_f32_e32 v63, v36, v37
	v_mul_f32_e32 v36, v36, v41
	v_fmac_f32_e32 v36, v40, v48
	v_mul_f32_e32 v40, v35, v63
	v_mul_f32_e32 v35, v35, v36
	v_fmac_f32_e32 v35, v39, v46
	v_lshlrev_b32_e32 v43, 16, v43
	v_mul_f32_e32 v39, v34, v40
	v_mul_f32_e32 v34, v34, v35
	v_fmac_f32_e32 v34, v38, v43
	s_nop 0
	s_nop 0
	s_nop 0
	s_nop 0
	s_nop 0
	s_nop 0
	v_mov_b32_e32 v46, v39
	v_mov_b32_e32 v66, v39
	s_nop 1
	v_permlane16_swap_b32_e32 v46, v66
	s_nop 1
	v_mov_b32_e32 v67, v46
	v_mov_b32_e32 v68, v66
	s_nop 1
	v_permlane32_swap_b32_e32 v46, v67
	v_permlane32_swap_b32_e32 v66, v68
	s_nop 1
	v_mov_b32_e32 v43, v34
	v_mov_b32_e32 v48, v34
	s_nop 1
	v_permlane16_swap_b32_e32 v43, v48
	s_nop 1
	v_mov_b32_e32 v65, v43
	v_mov_b32_e32 v38, v48
	s_nop 1
	v_permlane32_swap_b32_e32 v43, v65
	v_permlane32_swap_b32_e32 v48, v38
	s_nop 1
	s_waitcnt lgkmcnt(0)
	v_fmac_f32_e32 v38, v42, v68
	s_waitcnt lgkmcnt(0)
	v_fmac_f32_e32 v65, v38, v67
	s_waitcnt lgkmcnt(0)
	v_fmac_f32_e32 v48, v65, v66
	s_and_saveexec_b64 s[4:5], s[0:1]
	s_cbranch_execz .LBB0_677
	v_cmp_ne_u32_e64 s[0:1], 2, v51
	s_and_saveexec_b64 s[34:35], s[0:1]
	s_xor_b64 s[0:1], exec, s[34:35]
	v_cndmask_b32_e32 v42, v48, v65, vcc
	s_andn2_saveexec_b64 s[0:1], s[0:1]
	v_mov_b32_e32 v42, v38
	s_or_b64 exec, exec, s[0:1]
; template <int DIR, int MODE>
; __device__ __forceinline__ void lru_pass(const Args& a, const LAS bf16_t* cxb, LAS bf16_t* gyb, const LAS float* carry, const bf16x8 (&Bw)[2][2][2], const float (&prm)[2][3], int l, int tt, float (&hf)[8][2][4]) {
;     ...
;             for (int ks = 0; ks < 2; ++ks) { pr = __builtin_amdgcn_mfma_f32_16x16x32_bf16(Af[ks], Bw[0][nt][ks], pr, 0, 0, 0); pi = __builtin_amdgcn_mfma_f32_16x16x32_bf16(Af[ks], Bw[1][nt][ks], pi, 0, 0, 0); }
;             float av[4], bv[4];
; #pragma unroll
;             for (int reg = 0; reg < 4; ++reg) {
;                 const int tok = m * 16 + 4 * fq + reg;
;                 const float x = bf2f(cxb[tok * CXS + cc[nt]]);
;                 const float r = fsig(pr[reg] + ba[nt]), ig = fsig(pi[reg] + bxv[nt]);
;                 const float aa = __expf(k8[nt] * r);
;                 av[reg] = aa; bv[reg] = __builtin_amdgcn_sqrtf(fmaxf(1.0f - aa * aa, 0.f)) * ig * x;
;             }
;             float cum[4], hl[4];
;             if (DIR == 0) { cum[0] = av[0]; hl[0] = bv[0];
; #pragma unroll
;                 for (int reg = 1; reg < 4; ++reg) { cum[reg] = cum[reg - 1] * av[reg]; hl[reg] = av[reg] * hl[reg - 1] + bv[reg]; } }
;             else { cum[3] = av[3]; hl[3] = bv[3];
; #pragma unroll
;     ...
;             const float A4 = DIR ? cum[0] : cum[3], H4 = DIR ? hl[0] : hl[3];
;             float Aq[4], Hq[4];
; #pragma unroll
;             for (int q = 0; q < 4; ++q) { Aq[q] = __shfl(A4, fr + 16 * q); Hq[q] = __shfl(H4, fr + 16 * q); }
;             float hin;
;             if (DIR == 0) { const float s0 = C[nt], s1 = Aq[0] * s0 + Hq[0], s2 = Aq[1] * s1 + Hq[1], s3 = Aq[2] * s2 + Hq[2]; C[nt] = Aq[3] * s3 + Hq[3]; hin = fq == 0 ? s0 : (fq == 1 ? s1 : (fq == 2 ? s2 : s3)); }
;             else { const float s3 = C[nt], s2 = Aq[3] * s3 + Hq[3], s1 = Aq[2] * s2 + Hq[2], s0 = Aq[1] * s1 + Hq[1]; C[nt] = Aq[0] * s0 + Hq[0]; hin = fq == 3 ? s3 : (fq == 2 ? s2 : (fq == 1 ? s1 : s0)); }
;             if (MODE == 0) At[nt] *= (Aq[0] * Aq[1]) * (Aq[2] * Aq[3]);
;             else {
; #pragma unroll
;                 for (int reg = 0; reg < 4; ++reg) {
;                     const float hv = hl[reg] + cum[reg] * hin;
;                     if (DIR == 0) hf[m][nt][reg] = hv;
;                     else { LAS bf16_t* gp = gyb + (m * 16 + 4 * fq + reg) * CXS + cc[nt];
;                         const float g = bf2f(*gp);
.LBB0_677:
	s_or_b64 exec, exec, s[4:5]
	ds_read_u16 v38, v52 offset:42240
	ds_read_u16 v45, v52 offset:42768
	ds_read_u16 v47, v52 offset:43296
	ds_read_u16 v65, v52 offset:43824
	ds_read_u16 v80, v58 offset:35376
	s_waitcnt lgkmcnt(4)
	v_lshlrev_b32_e32 v38, 16, v38
	v_mul_f32_e32 v66, 0x3d372713, v38
	v_mul_f32_e32 v66, v66, v38
	v_fma_f32 v66, v66, v38, v38
	v_mul_f32_e32 v66, 0x3f4c422a, v66
	v_add_f32_e32 v66, v66, v66
	v_mul_f32_e32 v66, 0x3fb8aa3b, v66
	v_exp_f32_e32 v66, v66
	v_fmac_f32_e32 v173, v174, v172
	v_fmac_f32_e32 v34, v39, v42
	v_mul_f32_e32 v38, 0.5, v38
	v_add_f32_e32 v66, 1.0, v66
	v_rcp_f32_e32 v66, v66
	v_add_f32_e32 v34, v173, v34
	v_fmac_f32_e32 v177, v178, v172
	v_fmac_f32_e32 v35, v40, v42
	v_fma_f32 v39, v66, -2.0, 2.0
	v_mul_f32_e32 v38, v38, v39
	v_mul_f32_e32 v34, v34, v38
	s_waitcnt lgkmcnt(3)
	v_lshlrev_b32_e32 v38, 16, v45
	v_mul_f32_e32 v39, 0x3d372713, v38
	v_mul_f32_e32 v39, v39, v38
	v_fma_f32 v39, v39, v38, v38
	v_mul_f32_e32 v39, 0x3f4c422a, v39
	v_add_f32_e32 v39, v39, v39
	v_mul_f32_e32 v39, 0x3fb8aa3b, v39
	v_exp_f32_e32 v39, v39
	v_bfe_u32 v45, v34, 16, 1
	v_add3_u32 v34, v34, v45, s27
	ds_write_b16_d16_hi v52, v34 offset:42240
	v_add_f32_e32 v34, 1.0, v39
	v_rcp_f32_e32 v34, v34
	v_mul_f32_e32 v38, 0.5, v38
	v_add_f32_e32 v35, v177, v35
	v_fmac_f32_e32 v176, v179, v172
	v_fma_f32 v34, v34, -2.0, 2.0
	v_mul_f32_e32 v34, v38, v34
	v_mul_f32_e32 v34, v35, v34
	s_waitcnt lgkmcnt(3)
	v_lshlrev_b32_e32 v35, 16, v47
	v_mul_f32_e32 v38, 0x3d372713, v35
	v_mul_f32_e32 v38, v38, v35
	v_fma_f32 v38, v38, v35, v35
	v_mul_f32_e32 v38, 0x3f4c422a, v38
	v_add_f32_e32 v38, v38, v38
	v_mul_f32_e32 v38, 0x3fb8aa3b, v38
	v_exp_f32_e32 v38, v38
	v_bfe_u32 v39, v34, 16, 1
	v_add3_u32 v34, v34, v39, s27
	ds_write_b16_d16_hi v52, v34 offset:42768
	v_add_f32_e32 v34, 1.0, v38
	v_rcp_f32_e32 v34, v34
	v_fmac_f32_e32 v36, v63, v42
	v_mul_f32_e32 v35, 0.5, v35
	v_add_f32_e32 v36, v176, v36
	v_fma_f32 v34, v34, -2.0, 2.0
	v_mul_f32_e32 v34, v35, v34
	s_waitcnt lgkmcnt(3)
	v_lshlrev_b32_e32 v35, 16, v65
	v_mul_f32_e32 v34, v36, v34
	v_mul_f32_e32 v36, 0x3d372713, v35
	v_mul_f32_e32 v36, v36, v35
	v_fma_f32 v36, v36, v35, v35
	v_mul_f32_e32 v36, 0x3f4c422a, v36
	v_add_f32_e32 v36, v36, v36
	v_mul_f32_e32 v36, 0x3fb8aa3b, v36
	v_exp_f32_e32 v36, v36
	v_bfe_u32 v38, v34, 16, 1
	v_add3_u32 v34, v34, v38, s27
	ds_write_b16_d16_hi v52, v34 offset:43296
	v_add_f32_e32 v34, 1.0, v36
	v_rcp_f32_e32 v34, v34
	v_fmac_f32_e32 v175, v180, v172
	v_fmac_f32_e32 v41, v37, v42
	v_mul_f32_e32 v35, 0.5, v35
	v_fma_f32 v34, v34, -2.0, 2.0
	v_add_f32_e32 v36, v175, v41
	v_mul_f32_e32 v34, v35, v34
	v_mul_f32_e32 v34, v36, v34
	v_bfe_u32 v35, v34, 16, 1
	v_add3_u32 v34, v34, v35, s27
	ds_write_b16_d16_hi v52, v34 offset:43824
	ds_read_b128 v[38:41], v62 offset:33792
	ds_read_b128 v[34:37], v62 offset:33856
	s_waitcnt lgkmcnt(1)
	v_mfma_f32_16x16x32_bf16 v[66:69], v[38:41], v[22:25], 0
	ds_read_u16 v45, v58 offset:33792
	ds_read_u16 v47, v58 offset:34320
	ds_read_u16 v63, v58 offset:34848
	v_fmac_f32_e32 v44, v64, v49
	v_cmp_gt_i32_e64 s[0:1], 3, v51
	s_waitcnt lgkmcnt(3)
	v_mfma_f32_16x16x32_bf16 v[66:69], v[34:37], v[18:21], v[66:69]
	s_waitcnt lgkmcnt(2)
	v_lshlrev_b32_e32 v45, 16, v45
	s_waitcnt lgkmcnt(0)
	v_lshlrev_b32_e32 v63, 16, v63
	v_mfma_f32_16x16x32_bf16 v[70:73], v[38:41], v[30:33], 0
	v_mfma_f32_16x16x32_bf16 v[70:73], v[34:37], v[26:29], v[70:73]
	s_nop 1
	v_add_f32_e32 v42, v153, v66
	v_add_f32_e32 v66, v153, v67
	v_mul_f32_e32 v66, 0xbfb8aa3b, v66
	v_exp_f32_e32 v66, v66
	v_mul_f32_e32 v42, 0xbfb8aa3b, v42
	v_exp_f32_e32 v42, v42
	v_add_f32_e32 v67, v152, v71
	v_add_f32_e32 v66, 1.0, v66
	v_rcp_f32_e32 v66, v66
	v_add_f32_e32 v42, 1.0, v42
	v_rcp_f32_e32 v42, v42
	v_add_f32_e32 v65, v152, v70
	v_mul_f32_e32 v66, v60, v66
	v_mul_f32_e32 v66, 0x3fb8aa3b, v66
	v_exp_f32_e32 v71, v66
	v_add_f32_e32 v66, v153, v68
	v_mul_f32_e32 v66, 0xbfb8aa3b, v66
	v_exp_f32_e32 v66, v66
	v_mul_f32_e32 v42, v60, v42
	v_mul_f32_e32 v65, 0xbfb8aa3b, v65
	v_mul_f32_e32 v42, 0x3fb8aa3b, v42
	v_add_f32_e32 v66, 1.0, v66
	v_rcp_f32_e32 v66, v66
	v_exp_f32_e32 v65, v65
	v_exp_f32_e32 v70, v42
	v_add_f32_e32 v68, v152, v72
	v_lshlrev_b32_e32 v72, 16, v47
	v_mul_f32_e32 v47, v60, v66
	v_mul_f32_e32 v47, 0x3fb8aa3b, v47
	v_add_f32_e32 v42, 1.0, v65
	v_fma_f32 v65, -v70, v70, 1.0
	v_exp_f32_e32 v66, v47
	v_add_f32_e32 v47, v153, v69
	v_max_f32_e32 v65, 0, v65
	v_mul_f32_e32 v67, 0xbfb8aa3b, v67
	v_mul_f32_e32 v47, 0xbfb8aa3b, v47
	v_rcp_f32_e32 v42, v42
	v_sqrt_f32_e32 v65, v65
	v_exp_f32_e32 v67, v67
	v_exp_f32_e32 v47, v47
	v_mul_f32_e32 v68, 0xbfb8aa3b, v68
	v_mul_f32_e32 v65, v42, v65
	v_add_f32_e32 v42, 1.0, v67
	v_fma_f32 v67, -v71, v71, 1.0
	v_add_f32_e32 v47, 1.0, v47
	v_max_f32_e32 v67, 0, v67
	v_rcp_f32_e32 v47, v47
	v_rcp_f32_e32 v42, v42
	v_sqrt_f32_e32 v67, v67
	v_exp_f32_e32 v68, v68
	v_mul_f32_e32 v47, v60, v47
	v_mul_f32_e32 v47, 0x3fb8aa3b, v47
	v_mul_f32_e32 v81, v42, v67
	v_add_f32_e32 v42, 1.0, v68
	v_add_f32_e32 v68, v152, v73
	v_mul_f32_e32 v68, 0xbfb8aa3b, v68
	v_exp_f32_e32 v47, v47
	v_exp_f32_e32 v68, v68
	v_fma_f32 v67, -v66, v66, 1.0
	v_max_f32_e32 v67, 0, v67
	v_fma_f32 v69, -v47, v47, 1.0
	v_add_f32_e32 v68, 1.0, v68
	v_max_f32_e32 v69, 0, v69
	v_rcp_f32_e32 v42, v42
	v_sqrt_f32_e32 v67, v67
	v_rcp_f32_e32 v68, v68
	v_sqrt_f32_e32 v69, v69
	v_mul_f32_e32 v73, v42, v67
	v_lshlrev_b32_e32 v42, 16, v80
	v_mul_f32_e32 v67, v68, v69
	v_mul_f32_e32 v42, v67, v42
	v_mul_f32_e32 v67, v66, v47
	v_mul_f32_e32 v66, v66, v42
	v_fmac_f32_e32 v66, v73, v63
	v_mul_f32_e32 v68, v71, v66
	v_mul_f32_e32 v69, v71, v67
	v_fmac_f32_e32 v68, v81, v72
	v_mul_f32_e32 v71, v70, v69
	v_mul_f32_e32 v70, v70, v68
	v_fmac_f32_e32 v70, v65, v45
	s_nop 0
	ds_bpermute_b32 v72, v54, v70
	s_nop 0
	ds_bpermute_b32 v73, v55, v70
	s_nop 0
	ds_bpermute_b32 v65, v56, v70
	v_mov_b32_e32 v63, v71
	v_mov_b32_e32 v168, v71
	s_nop 1
	v_permlane16_swap_b32_e32 v63, v168
	s_nop 1
	v_mov_b32_e32 v169, v63
	v_mov_b32_e32 v170, v168
	s_nop 1
	v_permlane32_swap_b32_e32 v63, v169
	v_permlane32_swap_b32_e32 v168, v170
	s_nop 1
	ds_bpermute_b32 v45, v61, v70
	s_waitcnt lgkmcnt(3)
	v_fmac_f32_e32 v72, v44, v170
	s_waitcnt lgkmcnt(2)
	v_fmac_f32_e32 v73, v72, v169
	s_waitcnt lgkmcnt(1)
	v_fmac_f32_e32 v65, v73, v168
	s_and_saveexec_b64 s[4:5], s[0:1]
	s_cbranch_execz .LBB0_683
	v_cmp_ne_u32_e64 s[0:1], 2, v51
	s_and_saveexec_b64 s[34:35], s[0:1]
	s_xor_b64 s[0:1], exec, s[34:35]
	v_cndmask_b32_e32 v44, v65, v73, vcc
	s_andn2_saveexec_b64 s[0:1], s[0:1]
	v_mov_b32_e32 v44, v72
	s_or_b64 exec, exec, s[0:1]
; template <int DIR, int MODE>
; __device__ __forceinline__ void lru_pass(const Args& a, const LAS bf16_t* cxb, LAS bf16_t* gyb, const LAS float* carry, const bf16x8 (&Bw)[2][2][2], const float (&prm)[2][3], int l, int tt, float (&hf)[8][2][4]) {
;     ...
;             for (int ks = 0; ks < 2; ++ks) { pr = __builtin_amdgcn_mfma_f32_16x16x32_bf16(Af[ks], Bw[0][nt][ks], pr, 0, 0, 0); pi = __builtin_amdgcn_mfma_f32_16x16x32_bf16(Af[ks], Bw[1][nt][ks], pi, 0, 0, 0); }
;             float av[4], bv[4];
; #pragma unroll
;             for (int reg = 0; reg < 4; ++reg) {
;                 const int tok = m * 16 + 4 * fq + reg;
;                 const float x = bf2f(cxb[tok * CXS + cc[nt]]);
;                 const float r = fsig(pr[reg] + ba[nt]), ig = fsig(pi[reg] + bxv[nt]);
;                 const float aa = __expf(k8[nt] * r);
;                 av[reg] = aa; bv[reg] = __builtin_amdgcn_sqrtf(fmaxf(1.0f - aa * aa, 0.f)) * ig * x;
;             }
;             float cum[4], hl[4];
;             if (DIR == 0) { cum[0] = av[0]; hl[0] = bv[0];
; #pragma unroll
;                 for (int reg = 1; reg < 4; ++reg) { cum[reg] = cum[reg - 1] * av[reg]; hl[reg] = av[reg] * hl[reg - 1] + bv[reg]; } }
;             else { cum[3] = av[3]; hl[3] = bv[3];
; #pragma unroll
;     ...
;             const float A4 = DIR ? cum[0] : cum[3], H4 = DIR ? hl[0] : hl[3];
;             float Aq[4], Hq[4];
; #pragma unroll
;             for (int q = 0; q < 4; ++q) { Aq[q] = __shfl(A4, fr + 16 * q); Hq[q] = __shfl(H4, fr + 16 * q); }
;             float hin;
;             if (DIR == 0) { const float s0 = C[nt], s1 = Aq[0] * s0 + Hq[0], s2 = Aq[1] * s1 + Hq[1], s3 = Aq[2] * s2 + Hq[2]; C[nt] = Aq[3] * s3 + Hq[3]; hin = fq == 0 ? s0 : (fq == 1 ? s1 : (fq == 2 ? s2 : s3)); }
;             else { const float s3 = C[nt], s2 = Aq[3] * s3 + Hq[3], s1 = Aq[2] * s2 + Hq[2], s0 = Aq[1] * s1 + Hq[1]; C[nt] = Aq[0] * s0 + Hq[0]; hin = fq == 3 ? s3 : (fq == 2 ? s2 : (fq == 1 ? s1 : s0)); }
;             if (MODE == 0) At[nt] *= (Aq[0] * Aq[1]) * (Aq[2] * Aq[3]);
;             else {
; #pragma unroll
;                 for (int reg = 0; reg < 4; ++reg) {
;                     const float hv = hl[reg] + cum[reg] * hin;
;                     if (DIR == 0) hf[m][nt][reg] = hv;
;                     else { LAS bf16_t* gp = gyb + (m * 16 + 4 * fq + reg) * CXS + cc[nt];
;                         const float g = bf2f(*gp);
.LBB0_683:
	s_or_b64 exec, exec, s[4:5]
	ds_read_u16 v49, v59 offset:33792
	v_fmac_f32_e32 v163, v164, v159
	v_fmac_f32_e32 v70, v71, v44
	v_fmac_f32_e32 v68, v69, v44
	v_fmac_f32_e32 v66, v67, v44
	v_fmac_f32_e32 v42, v47, v44
	ds_read_u16 v44, v59 offset:35376
	s_waitcnt lgkmcnt(1)
	v_lshlrev_b32_e32 v49, 16, v49
	v_add_f32_e32 v64, v163, v70
	v_mul_f32_e32 v70, 0x3d372713, v49
	v_mul_f32_e32 v70, v70, v49
	v_fma_f32 v70, v70, v49, v49
	v_mul_f32_e32 v70, 0x3f4c422a, v70
	v_add_f32_e32 v70, v70, v70
	v_mul_f32_e32 v70, 0x3fb8aa3b, v70
	v_exp_f32_e32 v70, v70
	v_mul_f32_e32 v49, 0.5, v49
	v_fmac_f32_e32 v162, v165, v159
	v_fmac_f32_e32 v161, v166, v159
	v_add_f32_e32 v70, 1.0, v70
	v_rcp_f32_e32 v70, v70
	s_waitcnt lgkmcnt(0)
	v_lshlrev_b32_e32 v44, 16, v44
	v_mul_f32_e32 v47, 0x3d372713, v44
	v_mul_f32_e32 v47, v47, v44
	v_fma_f32 v70, v70, -2.0, 2.0
	v_mul_f32_e32 v49, v49, v70
	v_mul_f32_e32 v49, v64, v49
	v_bfe_u32 v64, v49, 16, 1
	v_add3_u32 v49, v49, v64, s27
	ds_write_b16_d16_hi v59, v49 offset:33792
	ds_read_u16 v49, v59 offset:34320
	v_add_f32_e32 v64, v162, v68
	v_fma_f32 v47, v47, v44, v44
	v_mul_f32_e32 v47, 0x3f4c422a, v47
	v_add_f32_e32 v47, v47, v47
	s_waitcnt lgkmcnt(0)
	v_lshlrev_b32_e32 v49, 16, v49
	v_mul_f32_e32 v68, 0x3d372713, v49
	v_mul_f32_e32 v68, v68, v49
	v_fma_f32 v68, v68, v49, v49
	v_mul_f32_e32 v68, 0x3f4c422a, v68
	v_add_f32_e32 v68, v68, v68
	v_mul_f32_e32 v68, 0x3fb8aa3b, v68
	v_exp_f32_e32 v68, v68
	v_mul_f32_e32 v49, 0.5, v49
	v_mfma_f32_16x16x32_bf16 v[70:73], v[38:41], v[14:17], 0
	v_mul_f32_e32 v47, 0x3fb8aa3b, v47
	v_add_f32_e32 v68, 1.0, v68
	v_rcp_f32_e32 v68, v68
	v_exp_f32_e32 v47, v47
	v_fmac_f32_e32 v160, v167, v159
	v_mul_f32_e32 v44, 0.5, v44
	v_fma_f32 v68, v68, -2.0, 2.0
	v_mul_f32_e32 v49, v49, v68
	v_mul_f32_e32 v49, v64, v49
	v_bfe_u32 v64, v49, 16, 1
	v_add3_u32 v49, v49, v64, s27
	ds_write_b16_d16_hi v59, v49 offset:34320
	ds_read_u16 v49, v59 offset:34848
	v_add_f32_e32 v64, v161, v66
	v_add_f32_e32 v47, 1.0, v47
	v_rcp_f32_e32 v47, v47
	v_add_f32_e32 v42, v160, v42
	s_waitcnt lgkmcnt(0)
	v_lshlrev_b32_e32 v49, 16, v49
	v_mul_f32_e32 v66, 0x3d372713, v49
	v_mul_f32_e32 v66, v66, v49
	v_fma_f32 v66, v66, v49, v49
	v_mul_f32_e32 v66, 0x3f4c422a, v66
	v_add_f32_e32 v66, v66, v66
	v_mul_f32_e32 v66, 0x3fb8aa3b, v66
	v_exp_f32_e32 v66, v66
	v_mul_f32_e32 v49, 0.5, v49
	v_fma_f32 v47, v47, -2.0, 2.0
	v_mul_f32_e32 v44, v44, v47
	v_add_f32_e32 v66, 1.0, v66
	v_rcp_f32_e32 v66, v66
	v_mul_f32_e32 v42, v42, v44
	v_bfe_u32 v44, v42, 16, 1
	v_add3_u32 v42, v42, v44, s27
	v_fma_f32 v66, v66, -2.0, 2.0
	v_mul_f32_e32 v49, v49, v66
	v_mfma_f32_16x16x32_bf16 v[66:69], v[38:41], v[6:9], 0
	v_mul_f32_e32 v49, v64, v49
	v_bfe_u32 v64, v49, 16, 1
	v_add3_u32 v49, v49, v64, s27
	v_mfma_f32_16x16x32_bf16 v[38:41], v[34:37], v[2:5], v[66:69]
	ds_write_b16_d16_hi v59, v49 offset:34848
	ds_write_b16_d16_hi v59, v42 offset:35376
	ds_read_u16 v42, v58 offset:33824
	v_mfma_f32_16x16x32_bf16 v[34:37], v[34:37], v[10:13], v[70:73]
	v_fmac_f32_e32 v43, v48, v46
	s_nop 2
	v_add_f32_e32 v38, v151, v38
	v_add_f32_e32 v39, v151, v39
	v_add_f32_e32 v40, v151, v40
	v_mul_f32_e32 v38, 0xbfb8aa3b, v38
	v_mul_f32_e32 v39, 0xbfb8aa3b, v39
	v_mul_f32_e32 v40, 0xbfb8aa3b, v40
	v_exp_f32_e32 v38, v38
	v_exp_f32_e32 v39, v39
	v_exp_f32_e32 v40, v40
	v_add_f32_e32 v34, v150, v34
	v_add_f32_e32 v35, v150, v35
	v_add_f32_e32 v36, v150, v36
	v_mul_f32_e32 v34, 0xbfb8aa3b, v34
	v_mul_f32_e32 v35, 0xbfb8aa3b, v35
	v_mul_f32_e32 v36, 0xbfb8aa3b, v36
	v_add_f32_e32 v41, v151, v41
	v_add_f32_e32 v38, 1.0, v38
	v_exp_f32_e32 v34, v34
	v_add_f32_e32 v39, 1.0, v39
	v_exp_f32_e32 v35, v35
	v_add_f32_e32 v40, 1.0, v40
	v_exp_f32_e32 v36, v36
	v_mul_f32_e32 v41, 0xbfb8aa3b, v41
	v_rcp_f32_e32 v38, v38
	v_rcp_f32_e32 v39, v39
	v_rcp_f32_e32 v40, v40
	v_exp_f32_e32 v41, v41
	v_add_f32_e32 v37, v150, v37
	v_add_f32_e32 v34, 1.0, v34
	v_add_f32_e32 v35, 1.0, v35
	v_add_f32_e32 v36, 1.0, v36
	v_mul_f32_e32 v37, 0xbfb8aa3b, v37
	v_rcp_f32_e32 v44, v34
	v_mul_f32_e32 v34, v57, v38
	v_rcp_f32_e32 v47, v35
	v_mul_f32_e32 v35, v57, v39
	v_rcp_f32_e32 v49, v36
	v_mul_f32_e32 v36, v57, v40
	v_add_f32_e32 v41, 1.0, v41
	v_exp_f32_e32 v37, v37
	v_mul_f32_e32 v34, 0x3fb8aa3b, v34
	v_mul_f32_e32 v35, 0x3fb8aa3b, v35
	v_mul_f32_e32 v36, 0x3fb8aa3b, v36
	v_rcp_f32_e32 v41, v41
	v_exp_f32_e32 v34, v34
	v_exp_f32_e32 v35, v35
	v_exp_f32_e32 v36, v36
	v_add_f32_e32 v37, 1.0, v37
	v_rcp_f32_e32 v64, v37
	v_mul_f32_e32 v37, v57, v41
	v_fma_f32 v38, -v34, v34, 1.0
	v_fma_f32 v39, -v35, v35, 1.0
	v_fma_f32 v40, -v36, v36, 1.0
	v_mul_f32_e32 v37, 0x3fb8aa3b, v37
	v_max_f32_e32 v38, 0, v38
	v_max_f32_e32 v39, 0, v39
	v_max_f32_e32 v40, 0, v40
	v_exp_f32_e32 v37, v37
	v_sqrt_f32_e32 v38, v38
	v_sqrt_f32_e32 v39, v39
	v_sqrt_f32_e32 v40, v40
	v_fma_f32 v41, -v37, v37, 1.0
	v_mul_f32_e32 v38, v44, v38
	ds_read_u16 v44, v58 offset:34352
	v_mul_f32_e32 v39, v47, v39
	ds_read_u16 v47, v58 offset:34880
	v_mul_f32_e32 v40, v49, v40
	ds_read_u16 v49, v58 offset:35408
	v_max_f32_e32 v41, 0, v41
	v_sqrt_f32_e32 v41, v41
	s_waitcnt lgkmcnt(1)
	v_lshlrev_b32_e32 v47, 16, v47
	v_lshlrev_b32_e32 v44, 16, v44
	s_waitcnt lgkmcnt(0)
	v_lshlrev_b32_e32 v49, 16, v49
	v_mul_f32_e32 v41, v64, v41
	v_mul_f32_e32 v41, v41, v49
	v_mul_f32_e32 v64, v36, v37
	v_mul_f32_e32 v36, v36, v41
	v_fmac_f32_e32 v36, v40, v47
	v_mul_f32_e32 v40, v35, v64
	v_mul_f32_e32 v35, v35, v36
	v_fmac_f32_e32 v35, v39, v44
	v_lshlrev_b32_e32 v42, 16, v42
	v_mul_f32_e32 v39, v34, v40
	v_mul_f32_e32 v34, v34, v35
	v_fmac_f32_e32 v34, v38, v42
	s_nop 0
	s_nop 0
	s_nop 0
	s_nop 0
	s_nop 0
	s_nop 0
	v_mov_b32_e32 v47, v39
	v_mov_b32_e32 v66, v39
	s_nop 1
	v_permlane16_swap_b32_e32 v47, v66
	s_nop 1
	v_mov_b32_e32 v67, v47
	v_mov_b32_e32 v68, v66
	s_nop 1
	v_permlane32_swap_b32_e32 v47, v67
	v_permlane32_swap_b32_e32 v66, v68
	s_nop 1
	v_mov_b32_e32 v42, v34
	v_mov_b32_e32 v49, v34
	s_nop 1
	v_permlane16_swap_b32_e32 v42, v49
	s_nop 1
	v_mov_b32_e32 v44, v42
	v_mov_b32_e32 v38, v49
	s_nop 1
	v_permlane32_swap_b32_e32 v42, v44
	v_permlane32_swap_b32_e32 v49, v38
	s_nop 1
	s_waitcnt lgkmcnt(0)
	v_fmac_f32_e32 v38, v43, v68
	s_waitcnt lgkmcnt(0)
	v_fmac_f32_e32 v44, v38, v67
	s_waitcnt lgkmcnt(0)
	v_fmac_f32_e32 v49, v44, v66
	v_cmp_gt_i32_e64 s[0:1], 3, v51
	s_and_saveexec_b64 s[4:5], s[0:1]
	s_cbranch_execz .LBB0_689
	v_cmp_ne_u32_e64 s[0:1], 2, v51
	s_and_saveexec_b64 s[34:35], s[0:1]
	s_xor_b64 s[0:1], exec, s[34:35]
	v_cndmask_b32_e32 v43, v49, v44, vcc
	s_andn2_saveexec_b64 s[0:1], s[0:1]
	v_mov_b32_e32 v43, v38
	s_or_b64 exec, exec, s[0:1]
; template <int DIR, int MODE>
; __device__ __forceinline__ void lru_pass(const Args& a, const LAS bf16_t* cxb, LAS bf16_t* gyb, const LAS float* carry, const bf16x8 (&Bw)[2][2][2], const float (&prm)[2][3], int l, int tt, float (&hf)[8][2][4]) {
;     ...
;             for (int ks = 0; ks < 2; ++ks) { pr = __builtin_amdgcn_mfma_f32_16x16x32_bf16(Af[ks], Bw[0][nt][ks], pr, 0, 0, 0); pi = __builtin_amdgcn_mfma_f32_16x16x32_bf16(Af[ks], Bw[1][nt][ks], pi, 0, 0, 0); }
;             float av[4], bv[4];
; #pragma unroll
;             for (int reg = 0; reg < 4; ++reg) {
;                 const int tok = m * 16 + 4 * fq + reg;
;                 const float x = bf2f(cxb[tok * CXS + cc[nt]]);
;                 const float r = fsig(pr[reg] + ba[nt]), ig = fsig(pi[reg] + bxv[nt]);
;                 const float aa = __expf(k8[nt] * r);
;                 av[reg] = aa; bv[reg] = __builtin_amdgcn_sqrtf(fmaxf(1.0f - aa * aa, 0.f)) * ig * x;
;             }
;             float cum[4], hl[4];
;             if (DIR == 0) { cum[0] = av[0]; hl[0] = bv[0];
; #pragma unroll
;                 for (int reg = 1; reg < 4; ++reg) { cum[reg] = cum[reg - 1] * av[reg]; hl[reg] = av[reg] * hl[reg - 1] + bv[reg]; } }
;             else { cum[3] = av[3]; hl[3] = bv[3];
; #pragma unroll
;     ...
;             const float A4 = DIR ? cum[0] : cum[3], H4 = DIR ? hl[0] : hl[3];
;             float Aq[4], Hq[4];
; #pragma unroll
;             for (int q = 0; q < 4; ++q) { Aq[q] = __shfl(A4, fr + 16 * q); Hq[q] = __shfl(H4, fr + 16 * q); }
;             float hin;
;             if (DIR == 0) { const float s0 = C[nt], s1 = Aq[0] * s0 + Hq[0], s2 = Aq[1] * s1 + Hq[1], s3 = Aq[2] * s2 + Hq[2]; C[nt] = Aq[3] * s3 + Hq[3]; hin = fq == 0 ? s0 : (fq == 1 ? s1 : (fq == 2 ? s2 : s3)); }
;             else { const float s3 = C[nt], s2 = Aq[3] * s3 + Hq[3], s1 = Aq[2] * s2 + Hq[2], s0 = Aq[1] * s1 + Hq[1]; C[nt] = Aq[0] * s0 + Hq[0]; hin = fq == 3 ? s3 : (fq == 2 ? s2 : (fq == 1 ? s1 : s0)); }
;             if (MODE == 0) At[nt] *= (Aq[0] * Aq[1]) * (Aq[2] * Aq[3]);
;             else {
; #pragma unroll
;                 for (int reg = 0; reg < 4; ++reg) {
;                     const float hv = hl[reg] + cum[reg] * hin;
;                     if (DIR == 0) hf[m][nt][reg] = hv;
;                     else { LAS bf16_t* gp = gyb + (m * 16 + 4 * fq + reg) * CXS + cc[nt];
;                         const float g = bf2f(*gp);
.LBB0_689:
	s_or_b64 exec, exec, s[4:5]
	ds_read_u16 v38, v52 offset:33792
	ds_read_u16 v44, v52 offset:34320
	ds_read_u16 v46, v52 offset:34848
	ds_read_u16 v48, v52 offset:35376
	ds_read_u16 v80, v58 offset:26928
	s_waitcnt lgkmcnt(4)
	v_lshlrev_b32_e32 v38, 16, v38
	v_mul_f32_e32 v66, 0x3d372713, v38
	v_mul_f32_e32 v66, v66, v38
	v_fma_f32 v66, v66, v38, v38
	v_mul_f32_e32 v66, 0x3f4c422a, v66
	v_add_f32_e32 v66, v66, v66
	v_mul_f32_e32 v66, 0x3fb8aa3b, v66
	v_exp_f32_e32 v66, v66
	v_fmac_f32_e32 v147, v148, v146
	v_fmac_f32_e32 v34, v39, v43
	v_mul_f32_e32 v38, 0.5, v38
	v_add_f32_e32 v66, 1.0, v66
	v_rcp_f32_e32 v66, v66
	v_add_f32_e32 v34, v147, v34
	v_fmac_f32_e32 v155, v156, v146
	v_fmac_f32_e32 v35, v40, v43
	v_fma_f32 v39, v66, -2.0, 2.0
	v_mul_f32_e32 v38, v38, v39
	v_mul_f32_e32 v34, v34, v38
	s_waitcnt lgkmcnt(3)
	v_lshlrev_b32_e32 v38, 16, v44
	v_mul_f32_e32 v39, 0x3d372713, v38
	v_mul_f32_e32 v39, v39, v38
	v_fma_f32 v39, v39, v38, v38
	v_mul_f32_e32 v39, 0x3f4c422a, v39
	v_add_f32_e32 v39, v39, v39
	v_mul_f32_e32 v39, 0x3fb8aa3b, v39
	v_exp_f32_e32 v39, v39
	v_bfe_u32 v44, v34, 16, 1
	v_add3_u32 v34, v34, v44, s27
	ds_write_b16_d16_hi v52, v34 offset:33792
	v_add_f32_e32 v34, 1.0, v39
	v_rcp_f32_e32 v34, v34
	v_mul_f32_e32 v38, 0.5, v38
	v_add_f32_e32 v35, v155, v35
	v_fmac_f32_e32 v154, v157, v146
	v_fma_f32 v34, v34, -2.0, 2.0
	v_mul_f32_e32 v34, v38, v34
	v_mul_f32_e32 v34, v35, v34
	s_waitcnt lgkmcnt(3)
	v_lshlrev_b32_e32 v35, 16, v46
	v_mul_f32_e32 v38, 0x3d372713, v35
	v_mul_f32_e32 v38, v38, v35
	v_fma_f32 v38, v38, v35, v35
	v_mul_f32_e32 v38, 0x3f4c422a, v38
	v_add_f32_e32 v38, v38, v38
	v_mul_f32_e32 v38, 0x3fb8aa3b, v38
	v_exp_f32_e32 v38, v38
	v_bfe_u32 v39, v34, 16, 1
	v_add3_u32 v34, v34, v39, s27
	ds_write_b16_d16_hi v52, v34 offset:34320
	v_add_f32_e32 v34, 1.0, v38
	v_rcp_f32_e32 v34, v34
	v_fmac_f32_e32 v36, v64, v43
	v_mul_f32_e32 v35, 0.5, v35
	v_add_f32_e32 v36, v154, v36
	v_fma_f32 v34, v34, -2.0, 2.0
	v_mul_f32_e32 v34, v35, v34
	s_waitcnt lgkmcnt(3)
	v_lshlrev_b32_e32 v35, 16, v48
	v_mul_f32_e32 v34, v36, v34
	v_mul_f32_e32 v36, 0x3d372713, v35
	v_mul_f32_e32 v36, v36, v35
	v_fma_f32 v36, v36, v35, v35
	v_mul_f32_e32 v36, 0x3f4c422a, v36
	v_add_f32_e32 v36, v36, v36
	v_mul_f32_e32 v36, 0x3fb8aa3b, v36
	v_exp_f32_e32 v36, v36
	v_bfe_u32 v38, v34, 16, 1
	v_add3_u32 v34, v34, v38, s27
	ds_write_b16_d16_hi v52, v34 offset:34848
	v_add_f32_e32 v34, 1.0, v36
	v_rcp_f32_e32 v34, v34
	v_fmac_f32_e32 v149, v158, v146
	v_fmac_f32_e32 v41, v37, v43
	v_mul_f32_e32 v35, 0.5, v35
	v_fma_f32 v34, v34, -2.0, 2.0
	v_add_f32_e32 v36, v149, v41
	v_mul_f32_e32 v34, v35, v34
	v_mul_f32_e32 v34, v36, v34
	v_bfe_u32 v35, v34, 16, 1
	v_add3_u32 v34, v34, v35, s27
	ds_write_b16_d16_hi v52, v34 offset:35376
	ds_read_b128 v[38:41], v62 offset:25344
	ds_read_b128 v[34:37], v62 offset:25408
	s_waitcnt lgkmcnt(1)
	v_mfma_f32_16x16x32_bf16 v[66:69], v[38:41], v[22:25], 0
	ds_read_u16 v44, v58 offset:25344
	ds_read_u16 v46, v58 offset:25872
	ds_read_u16 v48, v58 offset:26400
	v_fmac_f32_e32 v45, v65, v63
	v_cmp_gt_i32_e64 s[0:1], 3, v51
	s_waitcnt lgkmcnt(3)
	v_mfma_f32_16x16x32_bf16 v[66:69], v[34:37], v[18:21], v[66:69]
	s_waitcnt lgkmcnt(2)
	v_lshlrev_b32_e32 v44, 16, v44
	s_waitcnt lgkmcnt(0)
	v_lshlrev_b32_e32 v48, 16, v48
	v_mfma_f32_16x16x32_bf16 v[70:73], v[38:41], v[30:33], 0
	v_mfma_f32_16x16x32_bf16 v[70:73], v[34:37], v[26:29], v[70:73]
	s_nop 1
	v_add_f32_e32 v43, v153, v66
	v_mul_f32_e32 v43, 0xbfb8aa3b, v43
	v_exp_f32_e32 v43, v43
	v_add_f32_e32 v67, v153, v67
	v_mul_f32_e32 v67, 0xbfb8aa3b, v67
	s_nop 0
	v_add_f32_e32 v64, v152, v70
	v_add_f32_e32 v43, 1.0, v43
	v_rcp_f32_e32 v43, v43
	v_mul_f32_e32 v64, 0xbfb8aa3b, v64
	v_exp_f32_e32 v64, v64
	v_exp_f32_e32 v67, v67
	v_mul_f32_e32 v43, v60, v43
	v_mul_f32_e32 v43, 0x3fb8aa3b, v43
	v_exp_f32_e32 v66, v43
	v_add_f32_e32 v43, 1.0, v64
	v_add_f32_e32 v67, 1.0, v67
	v_rcp_f32_e32 v43, v43
	v_fma_f32 v64, -v66, v66, 1.0
	v_max_f32_e32 v64, 0, v64
	v_sqrt_f32_e32 v64, v64
	v_add_f32_e32 v70, v152, v71
	v_rcp_f32_e32 v67, v67
	v_mul_f32_e32 v70, 0xbfb8aa3b, v70
	v_exp_f32_e32 v70, v70
	v_mul_f32_e32 v81, v43, v64
	v_mul_f32_e32 v64, v60, v67
	v_mul_f32_e32 v64, 0x3fb8aa3b, v64
	v_add_f32_e32 v43, 1.0, v70
	v_exp_f32_e32 v70, v64
	v_add_f32_e32 v64, v153, v68
	v_mul_f32_e32 v64, 0xbfb8aa3b, v64
	v_exp_f32_e32 v64, v64
	v_lshlrev_b32_e32 v71, 16, v46
	v_fma_f32 v67, -v70, v70, 1.0
	v_add_f32_e32 v68, v152, v72
	v_add_f32_e32 v64, 1.0, v64
	v_rcp_f32_e32 v64, v64
	v_max_f32_e32 v67, 0, v67
	v_mul_f32_e32 v68, 0xbfb8aa3b, v68
	v_rcp_f32_e32 v43, v43
	v_mul_f32_e32 v46, v60, v64
	v_mul_f32_e32 v46, 0x3fb8aa3b, v46
	v_exp_f32_e32 v64, v46
	v_add_f32_e32 v46, v153, v69
	v_mul_f32_e32 v46, 0xbfb8aa3b, v46
	v_exp_f32_e32 v46, v46
	v_sqrt_f32_e32 v67, v67
	v_exp_f32_e32 v68, v68
	v_add_f32_e32 v46, 1.0, v46
	v_rcp_f32_e32 v46, v46
	v_mul_f32_e32 v72, v43, v67
	v_add_f32_e32 v43, 1.0, v68
	v_add_f32_e32 v68, v152, v73
	v_mul_f32_e32 v46, v60, v46
	v_mul_f32_e32 v46, 0x3fb8aa3b, v46
	v_mul_f32_e32 v68, 0xbfb8aa3b, v68
	v_exp_f32_e32 v46, v46
	v_exp_f32_e32 v68, v68
	v_fma_f32 v67, -v64, v64, 1.0
	v_max_f32_e32 v67, 0, v67
	v_fma_f32 v69, -v46, v46, 1.0
	v_add_f32_e32 v68, 1.0, v68
	v_max_f32_e32 v69, 0, v69
	v_rcp_f32_e32 v43, v43
	v_sqrt_f32_e32 v67, v67
	v_rcp_f32_e32 v68, v68
	v_sqrt_f32_e32 v69, v69
	v_mul_f32_e32 v73, v43, v67
	v_lshlrev_b32_e32 v43, 16, v80
	v_mul_f32_e32 v67, v68, v69
	v_mul_f32_e32 v43, v67, v43
	v_mul_f32_e32 v67, v64, v46
	v_mul_f32_e32 v64, v64, v43
	v_fmac_f32_e32 v64, v73, v48
	v_mul_f32_e32 v68, v70, v64
	v_fmac_f32_e32 v68, v72, v71
	v_mul_f32_e32 v69, v70, v67
	v_mul_f32_e32 v70, v66, v68
	v_mul_f32_e32 v71, v66, v69
	v_fmac_f32_e32 v70, v81, v44
	s_nop 0
	ds_bpermute_b32 v72, v54, v70
	s_nop 0
	ds_bpermute_b32 v73, v55, v70
	s_nop 0
	ds_bpermute_b32 v66, v56, v70
	v_mov_b32_e32 v48, v71
	v_mov_b32_e32 v146, v71
	s_nop 1
	v_permlane16_swap_b32_e32 v48, v146
	s_nop 1
	v_mov_b32_e32 v147, v48
	v_mov_b32_e32 v148, v146
	s_nop 1
	v_permlane32_swap_b32_e32 v48, v147
	v_permlane32_swap_b32_e32 v146, v148
	s_nop 1
	ds_bpermute_b32 v44, v61, v70
	s_waitcnt lgkmcnt(3)
	v_fmac_f32_e32 v72, v45, v148
	s_waitcnt lgkmcnt(2)
	v_fmac_f32_e32 v73, v72, v147
	s_waitcnt lgkmcnt(1)
	v_fmac_f32_e32 v66, v73, v146
	s_and_saveexec_b64 s[4:5], s[0:1]
	s_cbranch_execz .LBB0_695
	v_cmp_ne_u32_e64 s[0:1], 2, v51
	s_and_saveexec_b64 s[34:35], s[0:1]
	s_xor_b64 s[0:1], exec, s[34:35]
	v_cndmask_b32_e32 v45, v66, v73, vcc
	s_andn2_saveexec_b64 s[0:1], s[0:1]
	v_mov_b32_e32 v45, v72
	s_or_b64 exec, exec, s[0:1]
; template <int DIR, int MODE>
; __device__ __forceinline__ void lru_pass(const Args& a, const LAS bf16_t* cxb, LAS bf16_t* gyb, const LAS float* carry, const bf16x8 (&Bw)[2][2][2], const float (&prm)[2][3], int l, int tt, float (&hf)[8][2][4]) {
;     ...
;             for (int ks = 0; ks < 2; ++ks) { pr = __builtin_amdgcn_mfma_f32_16x16x32_bf16(Af[ks], Bw[0][nt][ks], pr, 0, 0, 0); pi = __builtin_amdgcn_mfma_f32_16x16x32_bf16(Af[ks], Bw[1][nt][ks], pi, 0, 0, 0); }
;             float av[4], bv[4];
; #pragma unroll
;             for (int reg = 0; reg < 4; ++reg) {
;                 const int tok = m * 16 + 4 * fq + reg;
;                 const float x = bf2f(cxb[tok * CXS + cc[nt]]);
;                 const float r = fsig(pr[reg] + ba[nt]), ig = fsig(pi[reg] + bxv[nt]);
;                 const float aa = __expf(k8[nt] * r);
;                 av[reg] = aa; bv[reg] = __builtin_amdgcn_sqrtf(fmaxf(1.0f - aa * aa, 0.f)) * ig * x;
;             }
;             float cum[4], hl[4];
;             if (DIR == 0) { cum[0] = av[0]; hl[0] = bv[0];
; #pragma unroll
;                 for (int reg = 1; reg < 4; ++reg) { cum[reg] = cum[reg - 1] * av[reg]; hl[reg] = av[reg] * hl[reg - 1] + bv[reg]; } }
;             else { cum[3] = av[3]; hl[3] = bv[3];
; #pragma unroll
;     ...
;             const float A4 = DIR ? cum[0] : cum[3], H4 = DIR ? hl[0] : hl[3];
;             float Aq[4], Hq[4];
; #pragma unroll
;             for (int q = 0; q < 4; ++q) { Aq[q] = __shfl(A4, fr + 16 * q); Hq[q] = __shfl(H4, fr + 16 * q); }
;             float hin;
;             if (DIR == 0) { const float s0 = C[nt], s1 = Aq[0] * s0 + Hq[0], s2 = Aq[1] * s1 + Hq[1], s3 = Aq[2] * s2 + Hq[2]; C[nt] = Aq[3] * s3 + Hq[3]; hin = fq == 0 ? s0 : (fq == 1 ? s1 : (fq == 2 ? s2 : s3)); }
;             else { const float s3 = C[nt], s2 = Aq[3] * s3 + Hq[3], s1 = Aq[2] * s2 + Hq[2], s0 = Aq[1] * s1 + Hq[1]; C[nt] = Aq[0] * s0 + Hq[0]; hin = fq == 3 ? s3 : (fq == 2 ? s2 : (fq == 1 ? s1 : s0)); }
;             if (MODE == 0) At[nt] *= (Aq[0] * Aq[1]) * (Aq[2] * Aq[3]);
;             else {
; #pragma unroll
;                 for (int reg = 0; reg < 4; ++reg) {
;                     const float hv = hl[reg] + cum[reg] * hin;
;                     if (DIR == 0) hf[m][nt][reg] = hv;
;                     else { LAS bf16_t* gp = gyb + (m * 16 + 4 * fq + reg) * CXS + cc[nt];
;                         const float g = bf2f(*gp);
.LBB0_695:
	s_or_b64 exec, exec, s[4:5]
	ds_read_u16 v63, v59 offset:25344
	v_fmac_f32_e32 v141, v142, v137
	v_fmac_f32_e32 v70, v71, v45
	v_fmac_f32_e32 v68, v69, v45
	v_fmac_f32_e32 v64, v67, v45
	v_fmac_f32_e32 v43, v46, v45
	ds_read_u16 v45, v59 offset:26928
	s_waitcnt lgkmcnt(1)
	v_lshlrev_b32_e32 v63, 16, v63
	v_add_f32_e32 v65, v141, v70
	v_mul_f32_e32 v70, 0x3d372713, v63
	v_mul_f32_e32 v70, v70, v63
	v_fma_f32 v70, v70, v63, v63
	v_mul_f32_e32 v70, 0x3f4c422a, v70
	v_add_f32_e32 v70, v70, v70
	v_mul_f32_e32 v70, 0x3fb8aa3b, v70
	v_exp_f32_e32 v70, v70
	v_mul_f32_e32 v63, 0.5, v63
	v_fmac_f32_e32 v140, v143, v137
	s_waitcnt lgkmcnt(0)
	v_lshlrev_b32_e32 v45, 16, v45
	v_add_f32_e32 v70, 1.0, v70
	v_rcp_f32_e32 v70, v70
	v_mul_f32_e32 v46, 0x3d372713, v45
	v_mul_f32_e32 v46, v46, v45
	v_fma_f32 v46, v46, v45, v45
	v_fma_f32 v70, v70, -2.0, 2.0
	v_mul_f32_e32 v63, v63, v70
	v_mul_f32_e32 v63, v65, v63
	v_bfe_u32 v65, v63, 16, 1
	v_add3_u32 v63, v63, v65, s27
	ds_write_b16_d16_hi v59, v63 offset:25344
	ds_read_u16 v63, v59 offset:25872
	v_add_f32_e32 v65, v140, v68
	v_mul_f32_e32 v46, 0x3f4c422a, v46
	v_add_f32_e32 v46, v46, v46
	v_mfma_f32_16x16x32_bf16 v[80:83], v[38:41], v[14:17], 0
	s_waitcnt lgkmcnt(0)
	v_lshlrev_b32_e32 v63, 16, v63
	v_mul_f32_e32 v68, 0x3d372713, v63
	v_mul_f32_e32 v68, v68, v63
	v_fma_f32 v68, v68, v63, v63
	v_mul_f32_e32 v68, 0x3f4c422a, v68
	v_add_f32_e32 v68, v68, v68
	v_mul_f32_e32 v68, 0x3fb8aa3b, v68
	v_exp_f32_e32 v68, v68
	v_mul_f32_e32 v63, 0.5, v63
	v_mul_f32_e32 v46, 0x3fb8aa3b, v46
	v_exp_f32_e32 v46, v46
	v_add_f32_e32 v68, 1.0, v68
	v_rcp_f32_e32 v68, v68
	v_fmac_f32_e32 v139, v144, v137
	v_add_f32_e32 v46, 1.0, v46
	v_rcp_f32_e32 v46, v46
	v_fma_f32 v68, v68, -2.0, 2.0
	v_mul_f32_e32 v63, v63, v68
	v_mul_f32_e32 v63, v65, v63
	v_bfe_u32 v65, v63, 16, 1
	v_add3_u32 v63, v63, v65, s27
	ds_write_b16_d16_hi v59, v63 offset:25872
	ds_read_u16 v63, v59 offset:26400
	v_mfma_f32_16x16x32_bf16 v[68:71], v[38:41], v[6:9], 0
	v_fmac_f32_e32 v138, v145, v137
	v_add_f32_e32 v64, v139, v64
	v_mul_f32_e32 v45, 0.5, v45
	s_waitcnt lgkmcnt(0)
	v_lshlrev_b32_e32 v63, 16, v63
	v_mul_f32_e32 v65, 0x3d372713, v63
	v_mul_f32_e32 v65, v65, v63
	v_fma_f32 v65, v65, v63, v63
	v_mul_f32_e32 v65, 0x3f4c422a, v65
	v_add_f32_e32 v65, v65, v65
	v_mul_f32_e32 v65, 0x3fb8aa3b, v65
	v_mfma_f32_16x16x32_bf16 v[38:41], v[34:37], v[2:5], v[68:71]
	v_exp_f32_e32 v65, v65
	v_mul_f32_e32 v63, 0.5, v63
	v_fma_f32 v46, v46, -2.0, 2.0
	v_mfma_f32_16x16x32_bf16 v[34:37], v[34:37], v[10:13], v[80:83]
	v_add_f32_e32 v65, 1.0, v65
	s_nop 2
	v_add_f32_e32 v38, v151, v38
	v_add_f32_e32 v39, v151, v39
	v_add_f32_e32 v40, v151, v40
	v_mul_f32_e32 v38, 0xbfb8aa3b, v38
	v_mul_f32_e32 v39, 0xbfb8aa3b, v39
	v_mul_f32_e32 v40, 0xbfb8aa3b, v40
	v_rcp_f32_e32 v65, v65
	v_exp_f32_e32 v38, v38
	v_exp_f32_e32 v39, v39
	v_exp_f32_e32 v40, v40
	v_add_f32_e32 v34, v150, v34
	v_add_f32_e32 v35, v150, v35
	v_add_f32_e32 v36, v150, v36
	v_mul_f32_e32 v34, 0xbfb8aa3b, v34
	v_mul_f32_e32 v35, 0xbfb8aa3b, v35
	v_mul_f32_e32 v36, 0xbfb8aa3b, v36
	v_add_f32_e32 v41, v151, v41
	v_fma_f32 v65, v65, -2.0, 2.0
	v_add_f32_e32 v38, 1.0, v38
	v_exp_f32_e32 v34, v34
	v_add_f32_e32 v39, 1.0, v39
	v_exp_f32_e32 v35, v35
	v_add_f32_e32 v40, 1.0, v40
	v_exp_f32_e32 v36, v36
	v_mul_f32_e32 v41, 0xbfb8aa3b, v41
	v_mul_f32_e32 v63, v63, v65
	v_rcp_f32_e32 v38, v38
	v_rcp_f32_e32 v39, v39
	v_rcp_f32_e32 v40, v40
	v_exp_f32_e32 v41, v41
	v_mul_f32_e32 v63, v64, v63
	v_add_f32_e32 v43, v138, v43
	v_mul_f32_e32 v45, v45, v46
	v_bfe_u32 v64, v63, 16, 1
	v_mul_f32_e32 v43, v43, v45
	v_add_f32_e32 v37, v150, v37
	v_add3_u32 v63, v63, v64, s27
	v_bfe_u32 v45, v43, 16, 1
	v_add_f32_e32 v34, 1.0, v34
	v_add_f32_e32 v35, 1.0, v35
	v_add_f32_e32 v36, 1.0, v36
	v_mul_f32_e32 v37, 0xbfb8aa3b, v37
	ds_write_b16_d16_hi v59, v63 offset:26400
	v_add3_u32 v43, v43, v45, s27
	v_rcp_f32_e32 v45, v34
	v_mul_f32_e32 v34, v57, v38
	v_rcp_f32_e32 v46, v35
	v_mul_f32_e32 v35, v57, v39
	v_rcp_f32_e32 v63, v36
	v_mul_f32_e32 v36, v57, v40
	v_add_f32_e32 v41, 1.0, v41
	v_exp_f32_e32 v37, v37
	v_mul_f32_e32 v34, 0x3fb8aa3b, v34
	v_mul_f32_e32 v35, 0x3fb8aa3b, v35
	v_mul_f32_e32 v36, 0x3fb8aa3b, v36
	v_rcp_f32_e32 v41, v41
	v_exp_f32_e32 v34, v34
	v_exp_f32_e32 v35, v35
	v_exp_f32_e32 v36, v36
	v_add_f32_e32 v37, 1.0, v37
	v_rcp_f32_e32 v64, v37
	v_mul_f32_e32 v37, v57, v41
	v_fma_f32 v38, -v34, v34, 1.0
	v_fma_f32 v39, -v35, v35, 1.0
	v_fma_f32 v40, -v36, v36, 1.0
	v_mul_f32_e32 v37, 0x3fb8aa3b, v37
	v_max_f32_e32 v38, 0, v38
	v_max_f32_e32 v39, 0, v39
	v_max_f32_e32 v40, 0, v40
	v_exp_f32_e32 v37, v37
	v_sqrt_f32_e32 v38, v38
	v_sqrt_f32_e32 v39, v39
	v_sqrt_f32_e32 v40, v40
	v_fma_f32 v41, -v37, v37, 1.0
	ds_write_b16_d16_hi v59, v43 offset:26928
	ds_read_u16 v43, v58 offset:25376
	v_mul_f32_e32 v38, v45, v38
	ds_read_u16 v45, v58 offset:25904
	v_mul_f32_e32 v39, v46, v39
	ds_read_u16 v46, v58 offset:26432
	v_mul_f32_e32 v40, v63, v40
	ds_read_u16 v63, v58 offset:26960
	v_max_f32_e32 v41, 0, v41
	v_sqrt_f32_e32 v41, v41
	s_waitcnt lgkmcnt(1)
	v_lshlrev_b32_e32 v46, 16, v46
	v_lshlrev_b32_e32 v45, 16, v45
	s_waitcnt lgkmcnt(0)
	v_lshlrev_b32_e32 v63, 16, v63
	v_mul_f32_e32 v41, v64, v41
	v_mul_f32_e32 v41, v41, v63
	v_mul_f32_e32 v63, v36, v37
	v_mul_f32_e32 v36, v36, v41
	v_fmac_f32_e32 v36, v40, v46
	v_mul_f32_e32 v40, v35, v63
	v_mul_f32_e32 v35, v35, v36
	v_fmac_f32_e32 v35, v39, v45
	v_lshlrev_b32_e32 v43, 16, v43
	v_mul_f32_e32 v39, v34, v40
	v_mul_f32_e32 v34, v34, v35
	v_fmac_f32_e32 v34, v38, v43
	s_nop 0
	s_nop 0
	s_nop 0
	s_nop 0
	s_nop 0
	s_nop 0
	v_mov_b32_e32 v45, v39
	v_mov_b32_e32 v65, v39
	s_nop 1
	v_permlane16_swap_b32_e32 v45, v65
	s_nop 1
	v_mov_b32_e32 v67, v45
	v_mov_b32_e32 v68, v65
	s_nop 1
	v_permlane32_swap_b32_e32 v45, v67
	v_permlane32_swap_b32_e32 v65, v68
	s_nop 1
	v_mov_b32_e32 v43, v34
	v_mov_b32_e32 v46, v34
	s_nop 1
	v_permlane16_swap_b32_e32 v43, v46
	s_nop 1
	v_mov_b32_e32 v64, v43
	v_mov_b32_e32 v38, v46
	s_nop 1
	v_permlane32_swap_b32_e32 v43, v64
	v_permlane32_swap_b32_e32 v46, v38
	s_nop 1
	v_fmac_f32_e32 v42, v49, v47
	s_waitcnt lgkmcnt(0)
	v_fmac_f32_e32 v38, v42, v68
	s_waitcnt lgkmcnt(0)
	v_fmac_f32_e32 v64, v38, v67
	s_waitcnt lgkmcnt(0)
	v_fmac_f32_e32 v46, v64, v65
	v_cmp_gt_i32_e64 s[0:1], 3, v51
	s_and_saveexec_b64 s[4:5], s[0:1]
	s_cbranch_execz .LBB0_701
	v_cmp_ne_u32_e64 s[0:1], 2, v51
	s_and_saveexec_b64 s[34:35], s[0:1]
	s_xor_b64 s[0:1], exec, s[34:35]
	v_cndmask_b32_e32 v42, v46, v64, vcc
	s_andn2_saveexec_b64 s[0:1], s[0:1]
	v_mov_b32_e32 v42, v38
	s_or_b64 exec, exec, s[0:1]
; template <int DIR, int MODE>
; __device__ __forceinline__ void lru_pass(const Args& a, const LAS bf16_t* cxb, LAS bf16_t* gyb, const LAS float* carry, const bf16x8 (&Bw)[2][2][2], const float (&prm)[2][3], int l, int tt, float (&hf)[8][2][4]) {
;     ...
;             for (int ks = 0; ks < 2; ++ks) { pr = __builtin_amdgcn_mfma_f32_16x16x32_bf16(Af[ks], Bw[0][nt][ks], pr, 0, 0, 0); pi = __builtin_amdgcn_mfma_f32_16x16x32_bf16(Af[ks], Bw[1][nt][ks], pi, 0, 0, 0); }
;             float av[4], bv[4];
; #pragma unroll
;             for (int reg = 0; reg < 4; ++reg) {
;                 const int tok = m * 16 + 4 * fq + reg;
;                 const float x = bf2f(cxb[tok * CXS + cc[nt]]);
;                 const float r = fsig(pr[reg] + ba[nt]), ig = fsig(pi[reg] + bxv[nt]);
;                 const float aa = __expf(k8[nt] * r);
;                 av[reg] = aa; bv[reg] = __builtin_amdgcn_sqrtf(fmaxf(1.0f - aa * aa, 0.f)) * ig * x;
;             }
;             float cum[4], hl[4];
;             if (DIR == 0) { cum[0] = av[0]; hl[0] = bv[0];
; #pragma unroll
;                 for (int reg = 1; reg < 4; ++reg) { cum[reg] = cum[reg - 1] * av[reg]; hl[reg] = av[reg] * hl[reg - 1] + bv[reg]; } }
;             else { cum[3] = av[3]; hl[3] = bv[3];
; #pragma unroll
;     ...
;             const float A4 = DIR ? cum[0] : cum[3], H4 = DIR ? hl[0] : hl[3];
;             float Aq[4], Hq[4];
; #pragma unroll
;             for (int q = 0; q < 4; ++q) { Aq[q] = __shfl(A4, fr + 16 * q); Hq[q] = __shfl(H4, fr + 16 * q); }
;             float hin;
;             if (DIR == 0) { const float s0 = C[nt], s1 = Aq[0] * s0 + Hq[0], s2 = Aq[1] * s1 + Hq[1], s3 = Aq[2] * s2 + Hq[2]; C[nt] = Aq[3] * s3 + Hq[3]; hin = fq == 0 ? s0 : (fq == 1 ? s1 : (fq == 2 ? s2 : s3)); }
;             else { const float s3 = C[nt], s2 = Aq[3] * s3 + Hq[3], s1 = Aq[2] * s2 + Hq[2], s0 = Aq[1] * s1 + Hq[1]; C[nt] = Aq[0] * s0 + Hq[0]; hin = fq == 3 ? s3 : (fq == 2 ? s2 : (fq == 1 ? s1 : s0)); }
;             if (MODE == 0) At[nt] *= (Aq[0] * Aq[1]) * (Aq[2] * Aq[3]);
;             else {
; #pragma unroll
;                 for (int reg = 0; reg < 4; ++reg) {
;                     const float hv = hl[reg] + cum[reg] * hin;
;                     if (DIR == 0) hf[m][nt][reg] = hv;
;                     else { LAS bf16_t* gp = gyb + (m * 16 + 4 * fq + reg) * CXS + cc[nt];
;                         const float g = bf2f(*gp);
.LBB0_701:
	s_or_b64 exec, exec, s[4:5]
	ds_read_u16 v38, v52 offset:25344
	ds_read_u16 v47, v52 offset:25872
	ds_read_u16 v49, v52 offset:26400
	ds_read_u16 v64, v52 offset:26928
	ds_read_u16 v65, v58 offset:18480
	s_waitcnt lgkmcnt(4)
	v_lshlrev_b32_e32 v38, 16, v38
	v_mul_f32_e32 v67, 0x3d372713, v38
	v_mul_f32_e32 v67, v67, v38
	v_fma_f32 v67, v67, v38, v38
	v_mul_f32_e32 v67, 0x3f4c422a, v67
	v_add_f32_e32 v67, v67, v67
	v_mul_f32_e32 v67, 0x3fb8aa3b, v67
	v_exp_f32_e32 v67, v67
	v_fmac_f32_e32 v129, v130, v128
	v_fmac_f32_e32 v34, v39, v42
	v_mul_f32_e32 v38, 0.5, v38
	v_add_f32_e32 v67, 1.0, v67
	v_rcp_f32_e32 v67, v67
	v_add_f32_e32 v34, v129, v34
	v_fmac_f32_e32 v133, v134, v128
	v_fmac_f32_e32 v35, v40, v42
	v_fma_f32 v39, v67, -2.0, 2.0
	v_mul_f32_e32 v38, v38, v39
	v_mul_f32_e32 v34, v34, v38
	s_waitcnt lgkmcnt(3)
	v_lshlrev_b32_e32 v38, 16, v47
	v_mul_f32_e32 v39, 0x3d372713, v38
	v_mul_f32_e32 v39, v39, v38
	v_fma_f32 v39, v39, v38, v38
	v_mul_f32_e32 v39, 0x3f4c422a, v39
	v_add_f32_e32 v39, v39, v39
	v_mul_f32_e32 v39, 0x3fb8aa3b, v39
	v_exp_f32_e32 v39, v39
	v_bfe_u32 v47, v34, 16, 1
	v_add3_u32 v34, v34, v47, s27
	ds_write_b16_d16_hi v52, v34 offset:25344
	v_add_f32_e32 v34, 1.0, v39
	v_rcp_f32_e32 v34, v34
	v_mul_f32_e32 v38, 0.5, v38
	v_add_f32_e32 v35, v133, v35
	v_fmac_f32_e32 v132, v135, v128
	v_fma_f32 v34, v34, -2.0, 2.0
	v_mul_f32_e32 v34, v38, v34
	v_mul_f32_e32 v34, v35, v34
	s_waitcnt lgkmcnt(3)
	v_lshlrev_b32_e32 v35, 16, v49
	v_mul_f32_e32 v38, 0x3d372713, v35
	v_mul_f32_e32 v38, v38, v35
	v_fma_f32 v38, v38, v35, v35
	v_mul_f32_e32 v38, 0x3f4c422a, v38
	v_add_f32_e32 v38, v38, v38
	v_mul_f32_e32 v38, 0x3fb8aa3b, v38
	v_exp_f32_e32 v38, v38
	v_bfe_u32 v39, v34, 16, 1
	v_add3_u32 v34, v34, v39, s27
	ds_write_b16_d16_hi v52, v34 offset:25872
	v_add_f32_e32 v34, 1.0, v38
	v_rcp_f32_e32 v34, v34
	v_fmac_f32_e32 v36, v63, v42
	v_mul_f32_e32 v35, 0.5, v35
	v_add_f32_e32 v36, v132, v36
	v_fma_f32 v34, v34, -2.0, 2.0
	v_mul_f32_e32 v34, v35, v34
	s_waitcnt lgkmcnt(3)
	v_lshlrev_b32_e32 v35, 16, v64
	v_mul_f32_e32 v34, v36, v34
	v_mul_f32_e32 v36, 0x3d372713, v35
	v_mul_f32_e32 v36, v36, v35
	v_fma_f32 v36, v36, v35, v35
	v_mul_f32_e32 v36, 0x3f4c422a, v36
	v_add_f32_e32 v36, v36, v36
	v_mul_f32_e32 v36, 0x3fb8aa3b, v36
	v_exp_f32_e32 v36, v36
	v_bfe_u32 v38, v34, 16, 1
	v_add3_u32 v34, v34, v38, s27
	ds_write_b16_d16_hi v52, v34 offset:26400
	v_add_f32_e32 v34, 1.0, v36
	v_rcp_f32_e32 v34, v34
	v_fmac_f32_e32 v131, v136, v128
	v_fmac_f32_e32 v41, v37, v42
	v_mul_f32_e32 v35, 0.5, v35
	v_fma_f32 v34, v34, -2.0, 2.0
	v_add_f32_e32 v36, v131, v41
	v_mul_f32_e32 v34, v35, v34
	v_mul_f32_e32 v34, v36, v34
	v_bfe_u32 v35, v34, 16, 1
	v_add3_u32 v34, v34, v35, s27
	ds_write_b16_d16_hi v52, v34 offset:26928
	ds_read_b128 v[38:41], v62 offset:16896
	ds_read_b128 v[34:37], v62 offset:16960
	s_waitcnt lgkmcnt(1)
	v_mfma_f32_16x16x32_bf16 v[68:71], v[38:41], v[22:25], 0
	ds_read_u16 v47, v58 offset:16896
	ds_read_u16 v49, v58 offset:17424
	ds_read_u16 v63, v58 offset:17952
	v_fmac_f32_e32 v44, v66, v48
	v_cmp_gt_i32_e64 s[0:1], 3, v51
	s_waitcnt lgkmcnt(3)
	v_mfma_f32_16x16x32_bf16 v[68:71], v[34:37], v[18:21], v[68:71]
	s_waitcnt lgkmcnt(2)
	v_lshlrev_b32_e32 v72, 16, v47
	s_waitcnt lgkmcnt(1)
	v_lshlrev_b32_e32 v73, 16, v49
	v_mfma_f32_16x16x32_bf16 v[80:83], v[38:41], v[30:33], 0
	v_mfma_f32_16x16x32_bf16 v[80:83], v[34:37], v[26:29], v[80:83]
	s_nop 1
	v_add_f32_e32 v42, v153, v68
	v_mul_f32_e32 v42, 0xbfb8aa3b, v42
	v_exp_f32_e32 v42, v42
	v_add_f32_e32 v67, v153, v69
	v_mul_f32_e32 v67, 0xbfb8aa3b, v67
	s_nop 0
	v_add_f32_e32 v64, v152, v80
	v_add_f32_e32 v42, 1.0, v42
	v_rcp_f32_e32 v42, v42
	v_mul_f32_e32 v64, 0xbfb8aa3b, v64
	v_exp_f32_e32 v67, v67
	v_exp_f32_e32 v64, v64
	v_mul_f32_e32 v42, v60, v42
	v_mul_f32_e32 v42, 0x3fb8aa3b, v42
	v_exp_f32_e32 v42, v42
	v_add_f32_e32 v67, 1.0, v67
	v_add_f32_e32 v47, 1.0, v64
	v_add_f32_e32 v68, v152, v81
	v_fma_f32 v64, -v42, v42, 1.0
	v_rcp_f32_e32 v67, v67
	v_max_f32_e32 v64, 0, v64
	v_mul_f32_e32 v68, 0xbfb8aa3b, v68
	v_rcp_f32_e32 v47, v47
	v_sqrt_f32_e32 v64, v64
	v_exp_f32_e32 v68, v68
	v_mul_f32_e32 v67, v60, v67
	v_mul_f32_e32 v67, 0x3fb8aa3b, v67
	v_mul_f32_e32 v64, v47, v64
	v_add_f32_e32 v47, 1.0, v68
	v_exp_f32_e32 v68, v67
	v_add_f32_e32 v67, v153, v70
	v_mul_f32_e32 v67, 0xbfb8aa3b, v67
	v_exp_f32_e32 v67, v67
	v_fma_f32 v69, -v68, v68, 1.0
	v_max_f32_e32 v69, 0, v69
	v_rcp_f32_e32 v47, v47
	v_add_f32_e32 v67, 1.0, v67
	v_rcp_f32_e32 v67, v67
	v_sqrt_f32_e32 v69, v69
	v_add_f32_e32 v70, v152, v82
	v_mul_f32_e32 v70, 0xbfb8aa3b, v70
	v_mul_f32_e32 v49, v60, v67
	v_mul_f32_e32 v49, 0x3fb8aa3b, v49
	v_mul_f32_e32 v80, v47, v69
	v_exp_f32_e32 v69, v49
	v_add_f32_e32 v49, v153, v71
	v_mul_f32_e32 v49, 0xbfb8aa3b, v49
	v_exp_f32_e32 v49, v49
	v_exp_f32_e32 v70, v70
	v_fma_f32 v67, -v69, v69, 1.0
	v_max_f32_e32 v67, 0, v67
	v_add_f32_e32 v49, 1.0, v49
	v_rcp_f32_e32 v49, v49
	v_add_f32_e32 v47, 1.0, v70
	v_add_f32_e32 v70, v152, v83
	v_mul_f32_e32 v70, 0xbfb8aa3b, v70
	v_mul_f32_e32 v49, v60, v49
	v_mul_f32_e32 v49, 0x3fb8aa3b, v49
	v_exp_f32_e32 v49, v49
	v_exp_f32_e32 v70, v70
	v_rcp_f32_e32 v47, v47
	v_sqrt_f32_e32 v67, v67
	v_fma_f32 v71, -v49, v49, 1.0
	v_add_f32_e32 v70, 1.0, v70
	v_max_f32_e32 v71, 0, v71
	v_rcp_f32_e32 v70, v70
	v_sqrt_f32_e32 v71, v71
	s_waitcnt lgkmcnt(0)
	v_lshlrev_b32_e32 v81, 16, v63
	v_mul_f32_e32 v82, v47, v67
	v_lshlrev_b32_e32 v47, 16, v65
	v_mul_f32_e32 v63, v70, v71
	v_mul_f32_e32 v47, v63, v47
	v_mul_f32_e32 v63, v69, v47
	v_mul_f32_e32 v67, v69, v49
	v_fmac_f32_e32 v63, v82, v81
	v_mul_f32_e32 v69, v68, v67
	v_mul_f32_e32 v68, v68, v63
	v_fmac_f32_e32 v68, v80, v73
	v_mul_f32_e32 v70, v42, v68
	v_mul_f32_e32 v71, v42, v69
	v_fmac_f32_e32 v70, v64, v72
	s_nop 0
	ds_bpermute_b32 v72, v54, v70
	s_nop 0
	ds_bpermute_b32 v73, v55, v70
	s_nop 0
	ds_bpermute_b32 v65, v56, v70
	v_mov_b32_e32 v64, v71
	v_mov_b32_e32 v128, v71
	s_nop 1
	v_permlane16_swap_b32_e32 v64, v128
	s_nop 1
	v_mov_b32_e32 v129, v64
	v_mov_b32_e32 v130, v128
	s_nop 1
	v_permlane32_swap_b32_e32 v64, v129
	v_permlane32_swap_b32_e32 v128, v130
	s_nop 1
	ds_bpermute_b32 v42, v61, v70
	s_waitcnt lgkmcnt(3)
	v_fmac_f32_e32 v72, v44, v130
	s_waitcnt lgkmcnt(2)
	v_fmac_f32_e32 v73, v72, v129
	s_waitcnt lgkmcnt(1)
	v_fmac_f32_e32 v65, v73, v128
	s_and_saveexec_b64 s[4:5], s[0:1]
	s_cbranch_execz .LBB0_707
	v_cmp_ne_u32_e64 s[0:1], 2, v51
	s_and_saveexec_b64 s[34:35], s[0:1]
	s_xor_b64 s[0:1], exec, s[34:35]
	v_cndmask_b32_e32 v44, v65, v73, vcc
	s_andn2_saveexec_b64 s[0:1], s[0:1]
	v_mov_b32_e32 v44, v72
	s_or_b64 exec, exec, s[0:1]
; template <int DIR, int MODE>
; __device__ __forceinline__ void lru_pass(const Args& a, const LAS bf16_t* cxb, LAS bf16_t* gyb, const LAS float* carry, const bf16x8 (&Bw)[2][2][2], const float (&prm)[2][3], int l, int tt, float (&hf)[8][2][4]) {
;     ...
;             for (int ks = 0; ks < 2; ++ks) { pr = __builtin_amdgcn_mfma_f32_16x16x32_bf16(Af[ks], Bw[0][nt][ks], pr, 0, 0, 0); pi = __builtin_amdgcn_mfma_f32_16x16x32_bf16(Af[ks], Bw[1][nt][ks], pi, 0, 0, 0); }
;             float av[4], bv[4];
; #pragma unroll
;             for (int reg = 0; reg < 4; ++reg) {
;                 const int tok = m * 16 + 4 * fq + reg;
;                 const float x = bf2f(cxb[tok * CXS + cc[nt]]);
;                 const float r = fsig(pr[reg] + ba[nt]), ig = fsig(pi[reg] + bxv[nt]);
;                 const float aa = __expf(k8[nt] * r);
;                 av[reg] = aa; bv[reg] = __builtin_amdgcn_sqrtf(fmaxf(1.0f - aa * aa, 0.f)) * ig * x;
;             }
;             float cum[4], hl[4];
;             if (DIR == 0) { cum[0] = av[0]; hl[0] = bv[0];
; #pragma unroll
;                 for (int reg = 1; reg < 4; ++reg) { cum[reg] = cum[reg - 1] * av[reg]; hl[reg] = av[reg] * hl[reg - 1] + bv[reg]; } }
;             else { cum[3] = av[3]; hl[3] = bv[3];
; #pragma unroll
;     ...
;             const float A4 = DIR ? cum[0] : cum[3], H4 = DIR ? hl[0] : hl[3];
;             float Aq[4], Hq[4];
; #pragma unroll
;             for (int q = 0; q < 4; ++q) { Aq[q] = __shfl(A4, fr + 16 * q); Hq[q] = __shfl(H4, fr + 16 * q); }
;             float hin;
;             if (DIR == 0) { const float s0 = C[nt], s1 = Aq[0] * s0 + Hq[0], s2 = Aq[1] * s1 + Hq[1], s3 = Aq[2] * s2 + Hq[2]; C[nt] = Aq[3] * s3 + Hq[3]; hin = fq == 0 ? s0 : (fq == 1 ? s1 : (fq == 2 ? s2 : s3)); }
;             else { const float s3 = C[nt], s2 = Aq[3] * s3 + Hq[3], s1 = Aq[2] * s2 + Hq[2], s0 = Aq[1] * s1 + Hq[1]; C[nt] = Aq[0] * s0 + Hq[0]; hin = fq == 3 ? s3 : (fq == 2 ? s2 : (fq == 1 ? s1 : s0)); }
;             if (MODE == 0) At[nt] *= (Aq[0] * Aq[1]) * (Aq[2] * Aq[3]);
;             else {
; #pragma unroll
;                 for (int reg = 0; reg < 4; ++reg) {
;                     const float hv = hl[reg] + cum[reg] * hin;
;                     if (DIR == 0) hf[m][nt][reg] = hv;
;                     else { LAS bf16_t* gp = gyb + (m * 16 + 4 * fq + reg) * CXS + cc[nt];
;                         const float g = bf2f(*gp);
.LBB0_707:
	s_or_b64 exec, exec, s[4:5]
	ds_read_u16 v48, v59 offset:16896
	v_fmac_f32_e32 v123, v124, v119
	v_fmac_f32_e32 v70, v71, v44
	v_fmac_f32_e32 v68, v69, v44
	v_fmac_f32_e32 v63, v67, v44
	v_fmac_f32_e32 v47, v49, v44
	ds_read_u16 v44, v59 offset:18480
	s_waitcnt lgkmcnt(1)
	v_lshlrev_b32_e32 v48, 16, v48
	v_add_f32_e32 v66, v123, v70
	v_mul_f32_e32 v70, 0x3d372713, v48
	v_mul_f32_e32 v70, v70, v48
	v_fma_f32 v70, v70, v48, v48
	v_mul_f32_e32 v70, 0x3f4c422a, v70
	v_add_f32_e32 v70, v70, v70
	v_mul_f32_e32 v70, 0x3fb8aa3b, v70
	v_exp_f32_e32 v70, v70
	v_mul_f32_e32 v48, 0.5, v48
	v_fmac_f32_e32 v122, v125, v119
	v_fmac_f32_e32 v121, v126, v119
	v_add_f32_e32 v70, 1.0, v70
	v_rcp_f32_e32 v70, v70
	v_add_f32_e32 v63, v121, v63
	s_waitcnt lgkmcnt(0)
	v_lshlrev_b32_e32 v44, 16, v44
	v_fmac_f32_e32 v120, v127, v119
	v_fma_f32 v70, v70, -2.0, 2.0
	v_mul_f32_e32 v48, v48, v70
	v_mul_f32_e32 v48, v66, v48
	v_bfe_u32 v66, v48, 16, 1
	v_add3_u32 v48, v48, v66, s27
	ds_write_b16_d16_hi v59, v48 offset:16896
	ds_read_u16 v48, v59 offset:17424
	v_add_f32_e32 v66, v122, v68
	v_mfma_f32_16x16x32_bf16 v[70:73], v[38:41], v[14:17], 0
	v_add_f32_e32 v47, v120, v47
	v_fmac_f32_e32 v43, v46, v45
	s_waitcnt lgkmcnt(0)
	v_lshlrev_b32_e32 v48, 16, v48
	v_mul_f32_e32 v68, 0x3d372713, v48
	v_mul_f32_e32 v68, v68, v48
	v_fma_f32 v68, v68, v48, v48
	v_mul_f32_e32 v68, 0x3f4c422a, v68
	v_add_f32_e32 v68, v68, v68
	v_mul_f32_e32 v68, 0x3fb8aa3b, v68
	v_exp_f32_e32 v68, v68
	v_mul_f32_e32 v48, 0.5, v48
	v_cmp_gt_i32_e64 s[0:1], 3, v51
	v_add_f32_e32 v68, 1.0, v68
	v_rcp_f32_e32 v68, v68
	s_nop 0
	v_fma_f32 v68, v68, -2.0, 2.0
	v_mul_f32_e32 v48, v48, v68
	v_mul_f32_e32 v48, v66, v48
	v_bfe_u32 v66, v48, 16, 1
	v_add3_u32 v48, v48, v66, s27
	ds_write_b16_d16_hi v59, v48 offset:17424
	ds_read_u16 v48, v59 offset:17952
	s_waitcnt lgkmcnt(0)
	v_lshlrev_b32_e32 v48, 16, v48
	v_mul_f32_e32 v66, 0x3d372713, v48
	v_mul_f32_e32 v66, v66, v48
	v_fma_f32 v66, v66, v48, v48
	v_mul_f32_e32 v66, 0x3f4c422a, v66
	v_add_f32_e32 v66, v66, v66
	v_mul_f32_e32 v66, 0x3fb8aa3b, v66
	v_exp_f32_e32 v66, v66
	v_mul_f32_e32 v48, 0.5, v48
	v_add_f32_e32 v66, 1.0, v66
	v_rcp_f32_e32 v66, v66
	s_nop 0
	v_fma_f32 v66, v66, -2.0, 2.0
	v_mul_f32_e32 v48, v48, v66
	v_mul_f32_e32 v48, v63, v48
	v_bfe_u32 v63, v48, 16, 1
	v_add3_u32 v48, v48, v63, s27
	ds_write_b16_d16_hi v59, v48 offset:17952
	v_mul_f32_e32 v48, 0x3d372713, v44
	v_mfma_f32_16x16x32_bf16 v[66:69], v[38:41], v[6:9], 0
	v_mul_f32_e32 v48, v48, v44
	v_fma_f32 v48, v48, v44, v44
	v_mul_f32_e32 v48, 0x3f4c422a, v48
	v_add_f32_e32 v48, v48, v48
	v_mfma_f32_16x16x32_bf16 v[38:41], v[34:37], v[2:5], v[66:69]
	v_mul_f32_e32 v48, 0x3fb8aa3b, v48
	v_exp_f32_e32 v48, v48
	v_mul_f32_e32 v44, 0.5, v44
	v_mfma_f32_16x16x32_bf16 v[34:37], v[34:37], v[10:13], v[70:73]
	v_add_f32_e32 v48, 1.0, v48
	s_nop 2
	v_add_f32_e32 v38, v151, v38
	v_add_f32_e32 v39, v151, v39
	v_add_f32_e32 v40, v151, v40
	v_mul_f32_e32 v38, 0xbfb8aa3b, v38
	v_mul_f32_e32 v39, 0xbfb8aa3b, v39
	v_mul_f32_e32 v40, 0xbfb8aa3b, v40
	v_exp_f32_e32 v38, v38
	v_exp_f32_e32 v39, v39
	v_exp_f32_e32 v40, v40
	v_rcp_f32_e32 v48, v48
	v_add_f32_e32 v34, v150, v34
	v_add_f32_e32 v35, v150, v35
	v_add_f32_e32 v36, v150, v36
	v_mul_f32_e32 v34, 0xbfb8aa3b, v34
	v_mul_f32_e32 v35, 0xbfb8aa3b, v35
	v_mul_f32_e32 v36, 0xbfb8aa3b, v36
	v_add_f32_e32 v41, v151, v41
	v_add_f32_e32 v38, 1.0, v38
	v_exp_f32_e32 v34, v34
	v_add_f32_e32 v39, 1.0, v39
	v_exp_f32_e32 v35, v35
	v_add_f32_e32 v40, 1.0, v40
	v_exp_f32_e32 v36, v36
	v_mul_f32_e32 v41, 0xbfb8aa3b, v41
	v_fma_f32 v48, v48, -2.0, 2.0
	v_rcp_f32_e32 v38, v38
	v_rcp_f32_e32 v39, v39
	v_rcp_f32_e32 v40, v40
	v_exp_f32_e32 v41, v41
	v_mul_f32_e32 v44, v44, v48
	v_mul_f32_e32 v44, v47, v44
	v_add_f32_e32 v37, v150, v37
	v_bfe_u32 v47, v44, 16, 1
	v_add_f32_e32 v34, 1.0, v34
	v_add_f32_e32 v35, 1.0, v35
	v_add_f32_e32 v36, 1.0, v36
	v_mul_f32_e32 v37, 0xbfb8aa3b, v37
	v_add3_u32 v44, v44, v47, s27
	v_rcp_f32_e32 v47, v34
	v_mul_f32_e32 v34, v57, v38
	v_rcp_f32_e32 v48, v35
	v_mul_f32_e32 v35, v57, v39
	v_rcp_f32_e32 v49, v36
	v_mul_f32_e32 v36, v57, v40
	v_add_f32_e32 v41, 1.0, v41
	v_exp_f32_e32 v37, v37
	v_mul_f32_e32 v34, 0x3fb8aa3b, v34
	v_mul_f32_e32 v35, 0x3fb8aa3b, v35
	v_mul_f32_e32 v36, 0x3fb8aa3b, v36
	v_rcp_f32_e32 v41, v41
	v_exp_f32_e32 v34, v34
	v_exp_f32_e32 v35, v35
	v_exp_f32_e32 v36, v36
	v_add_f32_e32 v37, 1.0, v37
	v_rcp_f32_e32 v63, v37
	v_mul_f32_e32 v37, v57, v41
	v_fma_f32 v38, -v34, v34, 1.0
	v_fma_f32 v39, -v35, v35, 1.0
	v_fma_f32 v40, -v36, v36, 1.0
	v_mul_f32_e32 v37, 0x3fb8aa3b, v37
	v_max_f32_e32 v38, 0, v38
	v_max_f32_e32 v39, 0, v39
	v_max_f32_e32 v40, 0, v40
	v_exp_f32_e32 v37, v37
	v_sqrt_f32_e32 v38, v38
	v_sqrt_f32_e32 v39, v39
	v_sqrt_f32_e32 v40, v40
	v_fma_f32 v41, -v37, v37, 1.0
	ds_write_b16_d16_hi v59, v44 offset:18480
	ds_read_u16 v44, v58 offset:16928
	v_mul_f32_e32 v38, v47, v38
	ds_read_u16 v47, v58 offset:17456
	v_mul_f32_e32 v39, v48, v39
	ds_read_u16 v48, v58 offset:17984
	v_mul_f32_e32 v40, v49, v40
	ds_read_u16 v49, v58 offset:18512
	v_max_f32_e32 v41, 0, v41
	v_sqrt_f32_e32 v41, v41
	s_waitcnt lgkmcnt(1)
	v_lshlrev_b32_e32 v48, 16, v48
	v_mul_f32_e32 v66, v36, v37
	s_waitcnt lgkmcnt(0)
	v_lshlrev_b32_e32 v49, 16, v49
	v_mul_f32_e32 v41, v63, v41
	v_mul_f32_e32 v41, v41, v49
	v_mul_f32_e32 v36, v36, v41
	v_fmac_f32_e32 v36, v40, v48
	v_lshlrev_b32_e32 v47, 16, v47
	v_mul_f32_e32 v40, v35, v66
	v_mul_f32_e32 v35, v35, v36
	v_fmac_f32_e32 v35, v39, v47
	v_lshlrev_b32_e32 v44, 16, v44
	v_mul_f32_e32 v39, v34, v40
	v_mul_f32_e32 v34, v34, v35
	v_fmac_f32_e32 v34, v38, v44
	s_nop 0
	s_nop 0
	s_nop 0
	s_nop 0
	s_nop 0
	s_nop 0
	v_mov_b32_e32 v49, v39
	v_mov_b32_e32 v47, v39
	s_nop 1
	v_permlane16_swap_b32_e32 v49, v47
	s_nop 1
	v_mov_b32_e32 v67, v49
	v_mov_b32_e32 v68, v47
	s_nop 1
	v_permlane32_swap_b32_e32 v49, v67
	v_permlane32_swap_b32_e32 v47, v68
	s_nop 1
	v_mov_b32_e32 v48, v34
	v_mov_b32_e32 v63, v34
	s_nop 1
	v_permlane16_swap_b32_e32 v48, v63
	s_nop 1
	v_mov_b32_e32 v44, v48
	v_mov_b32_e32 v38, v63
	s_nop 1
	v_permlane32_swap_b32_e32 v48, v44
	v_permlane32_swap_b32_e32 v63, v38
	s_nop 1
	s_waitcnt lgkmcnt(0)
	v_fmac_f32_e32 v38, v43, v68
	s_waitcnt lgkmcnt(0)
	v_fmac_f32_e32 v44, v38, v67
	s_waitcnt lgkmcnt(0)
	v_fmac_f32_e32 v63, v44, v47
	s_and_saveexec_b64 s[4:5], s[0:1]
	s_cbranch_execz .LBB0_713
	v_cmp_ne_u32_e64 s[0:1], 2, v51
	s_and_saveexec_b64 s[34:35], s[0:1]
	s_xor_b64 s[0:1], exec, s[34:35]
	v_cndmask_b32_e32 v43, v63, v44, vcc
	s_andn2_saveexec_b64 s[0:1], s[0:1]
	v_mov_b32_e32 v43, v38
	s_or_b64 exec, exec, s[0:1]
; template <int DIR, int MODE>
; __device__ __forceinline__ void lru_pass(const Args& a, const LAS bf16_t* cxb, LAS bf16_t* gyb, const LAS float* carry, const bf16x8 (&Bw)[2][2][2], const float (&prm)[2][3], int l, int tt, float (&hf)[8][2][4]) {
;     ...
;             for (int ks = 0; ks < 2; ++ks) { pr = __builtin_amdgcn_mfma_f32_16x16x32_bf16(Af[ks], Bw[0][nt][ks], pr, 0, 0, 0); pi = __builtin_amdgcn_mfma_f32_16x16x32_bf16(Af[ks], Bw[1][nt][ks], pi, 0, 0, 0); }
;             float av[4], bv[4];
; #pragma unroll
;             for (int reg = 0; reg < 4; ++reg) {
;                 const int tok = m * 16 + 4 * fq + reg;
;                 const float x = bf2f(cxb[tok * CXS + cc[nt]]);
;                 const float r = fsig(pr[reg] + ba[nt]), ig = fsig(pi[reg] + bxv[nt]);
;                 const float aa = __expf(k8[nt] * r);
;                 av[reg] = aa; bv[reg] = __builtin_amdgcn_sqrtf(fmaxf(1.0f - aa * aa, 0.f)) * ig * x;
;             }
;             float cum[4], hl[4];
;             if (DIR == 0) { cum[0] = av[0]; hl[0] = bv[0];
; #pragma unroll
;                 for (int reg = 1; reg < 4; ++reg) { cum[reg] = cum[reg - 1] * av[reg]; hl[reg] = av[reg] * hl[reg - 1] + bv[reg]; } }
;             else { cum[3] = av[3]; hl[3] = bv[3];
; #pragma unroll
;     ...
;             const float A4 = DIR ? cum[0] : cum[3], H4 = DIR ? hl[0] : hl[3];
;             float Aq[4], Hq[4];
; #pragma unroll
;             for (int q = 0; q < 4; ++q) { Aq[q] = __shfl(A4, fr + 16 * q); Hq[q] = __shfl(H4, fr + 16 * q); }
;             float hin;
;             if (DIR == 0) { const float s0 = C[nt], s1 = Aq[0] * s0 + Hq[0], s2 = Aq[1] * s1 + Hq[1], s3 = Aq[2] * s2 + Hq[2]; C[nt] = Aq[3] * s3 + Hq[3]; hin = fq == 0 ? s0 : (fq == 1 ? s1 : (fq == 2 ? s2 : s3)); }
;             else { const float s3 = C[nt], s2 = Aq[3] * s3 + Hq[3], s1 = Aq[2] * s2 + Hq[2], s0 = Aq[1] * s1 + Hq[1]; C[nt] = Aq[0] * s0 + Hq[0]; hin = fq == 3 ? s3 : (fq == 2 ? s2 : (fq == 1 ? s1 : s0)); }
;             if (MODE == 0) At[nt] *= (Aq[0] * Aq[1]) * (Aq[2] * Aq[3]);
;             else {
; #pragma unroll
;                 for (int reg = 0; reg < 4; ++reg) {
;                     const float hv = hl[reg] + cum[reg] * hin;
;                     if (DIR == 0) hf[m][nt][reg] = hv;
;                     else { LAS bf16_t* gp = gyb + (m * 16 + 4 * fq + reg) * CXS + cc[nt];
;                         const float g = bf2f(*gp);
.LBB0_713:
	s_or_b64 exec, exec, s[4:5]
	ds_read_u16 v38, v52 offset:16896
	ds_read_u16 v44, v52 offset:17424
	ds_read_u16 v45, v52 offset:17952
	ds_read_u16 v46, v52 offset:18480
	ds_read_u16 v70, v58 offset:10032
	s_waitcnt lgkmcnt(4)
	v_lshlrev_b32_e32 v38, 16, v38
	v_mul_f32_e32 v47, 0x3d372713, v38
	v_mul_f32_e32 v47, v47, v38
	v_fma_f32 v47, v47, v38, v38
	v_mul_f32_e32 v47, 0x3f4c422a, v47
	v_add_f32_e32 v47, v47, v47
	v_mul_f32_e32 v47, 0x3fb8aa3b, v47
	v_exp_f32_e32 v47, v47
	v_fmac_f32_e32 v111, v112, v110
	v_fmac_f32_e32 v34, v39, v43
	v_mul_f32_e32 v38, 0.5, v38
	v_add_f32_e32 v47, 1.0, v47
	v_rcp_f32_e32 v47, v47
	v_add_f32_e32 v34, v111, v34
	v_fmac_f32_e32 v115, v116, v110
	v_fmac_f32_e32 v35, v40, v43
	v_fma_f32 v39, v47, -2.0, 2.0
	v_mul_f32_e32 v38, v38, v39
	v_mul_f32_e32 v34, v34, v38
	s_waitcnt lgkmcnt(3)
	v_lshlrev_b32_e32 v38, 16, v44
	v_mul_f32_e32 v39, 0x3d372713, v38
	v_mul_f32_e32 v39, v39, v38
	v_fma_f32 v39, v39, v38, v38
	v_mul_f32_e32 v39, 0x3f4c422a, v39
	v_add_f32_e32 v39, v39, v39
	v_mul_f32_e32 v39, 0x3fb8aa3b, v39
	v_exp_f32_e32 v39, v39
	v_bfe_u32 v44, v34, 16, 1
	v_add3_u32 v34, v34, v44, s27
	ds_write_b16_d16_hi v52, v34 offset:16896
	v_add_f32_e32 v34, 1.0, v39
	v_rcp_f32_e32 v34, v34
	v_mul_f32_e32 v38, 0.5, v38
	v_add_f32_e32 v35, v115, v35
	v_fmac_f32_e32 v114, v117, v110
	v_fma_f32 v34, v34, -2.0, 2.0
	v_mul_f32_e32 v34, v38, v34
	v_mul_f32_e32 v34, v35, v34
	s_waitcnt lgkmcnt(3)
	v_lshlrev_b32_e32 v35, 16, v45
	v_mul_f32_e32 v38, 0x3d372713, v35
	v_mul_f32_e32 v38, v38, v35
	v_fma_f32 v38, v38, v35, v35
	v_mul_f32_e32 v38, 0x3f4c422a, v38
	v_add_f32_e32 v38, v38, v38
	v_mul_f32_e32 v38, 0x3fb8aa3b, v38
	v_exp_f32_e32 v38, v38
	v_bfe_u32 v39, v34, 16, 1
	v_add3_u32 v34, v34, v39, s27
	ds_write_b16_d16_hi v52, v34 offset:17424
	v_add_f32_e32 v34, 1.0, v38
	v_rcp_f32_e32 v34, v34
	v_fmac_f32_e32 v36, v66, v43
	v_mul_f32_e32 v35, 0.5, v35
	v_add_f32_e32 v36, v114, v36
	v_fma_f32 v34, v34, -2.0, 2.0
	v_mul_f32_e32 v34, v35, v34
	s_waitcnt lgkmcnt(3)
	v_lshlrev_b32_e32 v35, 16, v46
	v_mul_f32_e32 v34, v36, v34
	v_mul_f32_e32 v36, 0x3d372713, v35
	v_mul_f32_e32 v36, v36, v35
	v_fma_f32 v36, v36, v35, v35
	v_mul_f32_e32 v36, 0x3f4c422a, v36
	v_add_f32_e32 v36, v36, v36
	v_mul_f32_e32 v36, 0x3fb8aa3b, v36
	v_exp_f32_e32 v36, v36
	v_bfe_u32 v38, v34, 16, 1
	v_add3_u32 v34, v34, v38, s27
	ds_write_b16_d16_hi v52, v34 offset:17952
	v_add_f32_e32 v34, 1.0, v36
	v_rcp_f32_e32 v34, v34
	v_fmac_f32_e32 v113, v118, v110
	v_fmac_f32_e32 v41, v37, v43
	v_mul_f32_e32 v35, 0.5, v35
	v_fma_f32 v34, v34, -2.0, 2.0
	v_add_f32_e32 v36, v113, v41
	v_mul_f32_e32 v34, v35, v34
	v_mul_f32_e32 v34, v36, v34
	v_bfe_u32 v35, v34, 16, 1
	v_add3_u32 v34, v34, v35, s27
	ds_write_b16_d16_hi v52, v34 offset:18480
	ds_read_b128 v[38:41], v62 offset:8448
	ds_read_b128 v[34:37], v62 offset:8512
	s_waitcnt lgkmcnt(1)
	v_mfma_f32_16x16x32_bf16 v[44:47], v[38:41], v[22:25], 0
	v_fmac_f32_e32 v42, v65, v64
	v_cmp_gt_i32_e64 s[0:1], 3, v51
	s_waitcnt lgkmcnt(0)
	v_mfma_f32_16x16x32_bf16 v[44:47], v[34:37], v[18:21], v[44:47]
	v_mfma_f32_16x16x32_bf16 v[66:69], v[38:41], v[30:33], 0
	v_mfma_f32_16x16x32_bf16 v[66:69], v[34:37], v[26:29], v[66:69]
	s_nop 5
	v_add_f32_e32 v43, v153, v44
	v_mul_f32_e32 v43, 0xbfb8aa3b, v43
	v_exp_f32_e32 v43, v43
	v_add_f32_e32 v45, v153, v45
	v_mul_f32_e32 v45, 0xbfb8aa3b, v45
	v_exp_f32_e32 v45, v45
	v_add_f32_e32 v43, 1.0, v43
	v_rcp_f32_e32 v43, v43
	v_add_f32_e32 v66, v152, v66
	v_add_f32_e32 v45, 1.0, v45
	v_rcp_f32_e32 v45, v45
	v_mul_f32_e32 v43, v60, v43
	v_mul_f32_e32 v66, 0xbfb8aa3b, v66
	v_mul_f32_e32 v43, 0x3fb8aa3b, v43
	v_exp_f32_e32 v66, v66
	v_exp_f32_e32 v43, v43
	ds_read_u16 v44, v58 offset:8448
	ds_read_u16 v71, v58 offset:8976
	ds_read_u16 v72, v58 offset:9504
	v_mul_f32_e32 v45, v60, v45
	v_mul_f32_e32 v45, 0x3fb8aa3b, v45
	v_exp_f32_e32 v81, v45
	v_add_f32_e32 v45, v153, v46
	s_waitcnt lgkmcnt(2)
	v_lshlrev_b32_e32 v73, 16, v44
	v_add_f32_e32 v44, 1.0, v66
	v_fma_f32 v66, -v43, v43, 1.0
	v_mul_f32_e32 v45, 0xbfb8aa3b, v45
	v_max_f32_e32 v66, 0, v66
	v_add_f32_e32 v67, v152, v67
	v_exp_f32_e32 v45, v45
	v_rcp_f32_e32 v44, v44
	v_sqrt_f32_e32 v66, v66
	v_mul_f32_e32 v67, 0xbfb8aa3b, v67
	v_exp_f32_e32 v67, v67
	v_add_f32_e32 v45, 1.0, v45
	v_mul_f32_e32 v80, v44, v66
	v_fma_f32 v46, -v81, v81, 1.0
	v_add_f32_e32 v66, v152, v68
	v_rcp_f32_e32 v45, v45
	v_add_f32_e32 v44, 1.0, v67
	v_max_f32_e32 v46, 0, v46
	v_mul_f32_e32 v66, 0xbfb8aa3b, v66
	v_rcp_f32_e32 v44, v44
	v_sqrt_f32_e32 v46, v46
	v_exp_f32_e32 v66, v66
	v_mul_f32_e32 v45, v60, v45
	v_mul_f32_e32 v45, 0x3fb8aa3b, v45
	v_mul_f32_e32 v46, v44, v46
	v_add_f32_e32 v44, 1.0, v66
	v_exp_f32_e32 v66, v45
	v_add_f32_e32 v45, v153, v47
	v_mul_f32_e32 v45, 0xbfb8aa3b, v45
	v_exp_f32_e32 v45, v45
	v_add_f32_e32 v67, v152, v69
	v_mul_f32_e32 v67, 0xbfb8aa3b, v67
	v_exp_f32_e32 v67, v67
	v_add_f32_e32 v45, 1.0, v45
	v_rcp_f32_e32 v45, v45
	v_fma_f32 v47, -v66, v66, 1.0
	v_max_f32_e32 v47, 0, v47
	v_add_f32_e32 v67, 1.0, v67
	v_mul_f32_e32 v45, v60, v45
	v_mul_f32_e32 v45, 0x3fb8aa3b, v45
	v_exp_f32_e32 v45, v45
	v_rcp_f32_e32 v44, v44
	v_sqrt_f32_e32 v47, v47
	v_rcp_f32_e32 v67, v67
	v_fma_f32 v68, -v45, v45, 1.0
	v_max_f32_e32 v68, 0, v68
	v_sqrt_f32_e32 v68, v68
	v_mul_f32_e32 v47, v44, v47
	v_lshlrev_b32_e32 v44, 16, v70
	s_waitcnt lgkmcnt(0)
	v_lshlrev_b32_e32 v69, 16, v72
	v_mul_f32_e32 v67, v67, v68
	v_mul_f32_e32 v44, v67, v44
	v_mul_f32_e32 v67, v66, v45
	v_mul_f32_e32 v66, v66, v44
	v_fmac_f32_e32 v66, v47, v69
	v_lshlrev_b32_e32 v71, 16, v71
	v_mul_f32_e32 v68, v81, v66
	v_fmac_f32_e32 v68, v46, v71
	v_mul_f32_e32 v69, v81, v67
	v_mul_f32_e32 v70, v43, v68
	v_mul_f32_e32 v71, v43, v69
	v_fmac_f32_e32 v70, v80, v73
	s_nop 0
	ds_bpermute_b32 v72, v54, v70
	s_nop 0
	ds_bpermute_b32 v73, v55, v70
	s_nop 0
	ds_bpermute_b32 v47, v56, v70
	v_mov_b32_e32 v46, v71
	v_mov_b32_e32 v110, v71
	s_nop 1
	v_permlane16_swap_b32_e32 v46, v110
	s_nop 1
	v_mov_b32_e32 v111, v46
	v_mov_b32_e32 v112, v110
	s_nop 1
	v_permlane32_swap_b32_e32 v46, v111
	v_permlane32_swap_b32_e32 v110, v112
	s_nop 1
	ds_bpermute_b32 v43, v61, v70
	s_waitcnt lgkmcnt(3)
	v_fmac_f32_e32 v72, v42, v112
	s_waitcnt lgkmcnt(2)
	v_fmac_f32_e32 v73, v72, v111
	s_waitcnt lgkmcnt(1)
	v_fmac_f32_e32 v47, v73, v110
	s_and_saveexec_b64 s[4:5], s[0:1]
	s_cbranch_execz .LBB0_719
	v_cmp_ne_u32_e64 s[0:1], 2, v51
	s_and_saveexec_b64 s[34:35], s[0:1]
	s_xor_b64 s[0:1], exec, s[34:35]
	v_cndmask_b32_e32 v42, v47, v73, vcc
	s_andn2_saveexec_b64 s[0:1], s[0:1]
	v_mov_b32_e32 v42, v72
	s_or_b64 exec, exec, s[0:1]
; template <int DIR, int MODE>
; __device__ __forceinline__ void lru_pass(const Args& a, const LAS bf16_t* cxb, LAS bf16_t* gyb, const LAS float* carry, const bf16x8 (&Bw)[2][2][2], const float (&prm)[2][3], int l, int tt, float (&hf)[8][2][4]) {
;     ...
;             for (int ks = 0; ks < 2; ++ks) { pr = __builtin_amdgcn_mfma_f32_16x16x32_bf16(Af[ks], Bw[0][nt][ks], pr, 0, 0, 0); pi = __builtin_amdgcn_mfma_f32_16x16x32_bf16(Af[ks], Bw[1][nt][ks], pi, 0, 0, 0); }
;             float av[4], bv[4];
; #pragma unroll
;             for (int reg = 0; reg < 4; ++reg) {
;                 const int tok = m * 16 + 4 * fq + reg;
;                 const float x = bf2f(cxb[tok * CXS + cc[nt]]);
;                 const float r = fsig(pr[reg] + ba[nt]), ig = fsig(pi[reg] + bxv[nt]);
;                 const float aa = __expf(k8[nt] * r);
;                 av[reg] = aa; bv[reg] = __builtin_amdgcn_sqrtf(fmaxf(1.0f - aa * aa, 0.f)) * ig * x;
;             }
;             float cum[4], hl[4];
;             if (DIR == 0) { cum[0] = av[0]; hl[0] = bv[0];
; #pragma unroll
;                 for (int reg = 1; reg < 4; ++reg) { cum[reg] = cum[reg - 1] * av[reg]; hl[reg] = av[reg] * hl[reg - 1] + bv[reg]; } }
;             else { cum[3] = av[3]; hl[3] = bv[3];
; #pragma unroll
;     ...
;             const float A4 = DIR ? cum[0] : cum[3], H4 = DIR ? hl[0] : hl[3];
;             float Aq[4], Hq[4];
; #pragma unroll
;             for (int q = 0; q < 4; ++q) { Aq[q] = __shfl(A4, fr + 16 * q); Hq[q] = __shfl(H4, fr + 16 * q); }
;             float hin;
;             if (DIR == 0) { const float s0 = C[nt], s1 = Aq[0] * s0 + Hq[0], s2 = Aq[1] * s1 + Hq[1], s3 = Aq[2] * s2 + Hq[2]; C[nt] = Aq[3] * s3 + Hq[3]; hin = fq == 0 ? s0 : (fq == 1 ? s1 : (fq == 2 ? s2 : s3)); }
;             else { const float s3 = C[nt], s2 = Aq[3] * s3 + Hq[3], s1 = Aq[2] * s2 + Hq[2], s0 = Aq[1] * s1 + Hq[1]; C[nt] = Aq[0] * s0 + Hq[0]; hin = fq == 3 ? s3 : (fq == 2 ? s2 : (fq == 1 ? s1 : s0)); }
;             if (MODE == 0) At[nt] *= (Aq[0] * Aq[1]) * (Aq[2] * Aq[3]);
;             else {
; #pragma unroll
;                 for (int reg = 0; reg < 4; ++reg) {
;                     const float hv = hl[reg] + cum[reg] * hin;
;                     if (DIR == 0) hf[m][nt][reg] = hv;
;                     else { LAS bf16_t* gp = gyb + (m * 16 + 4 * fq + reg) * CXS + cc[nt];
;                         const float g = bf2f(*gp);
.LBB0_719:
	s_or_b64 exec, exec, s[4:5]
	ds_read_u16 v64, v59 offset:8448
	v_fmac_f32_e32 v105, v106, v101
	v_fmac_f32_e32 v70, v71, v42
	v_fmac_f32_e32 v68, v69, v42
	v_fmac_f32_e32 v66, v67, v42
	v_fmac_f32_e32 v44, v45, v42
	ds_read_u16 v42, v59 offset:10032
	s_waitcnt lgkmcnt(1)
	v_lshlrev_b32_e32 v64, 16, v64
	v_add_f32_e32 v65, v105, v70
	v_mul_f32_e32 v70, 0x3d372713, v64
	v_mul_f32_e32 v70, v70, v64
	v_fma_f32 v70, v70, v64, v64
	v_mul_f32_e32 v70, 0x3f4c422a, v70
	v_add_f32_e32 v70, v70, v70
	v_mul_f32_e32 v70, 0x3fb8aa3b, v70
	v_exp_f32_e32 v70, v70
	v_mul_f32_e32 v64, 0.5, v64
	v_fmac_f32_e32 v104, v107, v101
	v_fmac_f32_e32 v103, v108, v101
	v_add_f32_e32 v70, 1.0, v70
	v_rcp_f32_e32 v70, v70
	s_waitcnt lgkmcnt(0)
	v_lshlrev_b32_e32 v42, 16, v42
	v_mul_f32_e32 v45, 0x3d372713, v42
	v_mul_f32_e32 v45, v45, v42
	v_fma_f32 v70, v70, -2.0, 2.0
	v_mul_f32_e32 v64, v64, v70
	v_mul_f32_e32 v64, v65, v64
	v_bfe_u32 v65, v64, 16, 1
	v_add3_u32 v64, v64, v65, s27
	ds_write_b16_d16_hi v59, v64 offset:8448
	ds_read_u16 v64, v59 offset:8976
	v_add_f32_e32 v65, v104, v68
	v_fma_f32 v45, v45, v42, v42
	v_mul_f32_e32 v45, 0x3f4c422a, v45
	v_add_f32_e32 v45, v45, v45
	s_waitcnt lgkmcnt(0)
	v_lshlrev_b32_e32 v64, 16, v64
	v_mul_f32_e32 v68, 0x3d372713, v64
	v_mul_f32_e32 v68, v68, v64
	v_fma_f32 v68, v68, v64, v64
	v_mul_f32_e32 v68, 0x3f4c422a, v68
	v_add_f32_e32 v68, v68, v68
	v_mul_f32_e32 v68, 0x3fb8aa3b, v68
	v_exp_f32_e32 v68, v68
	v_mul_f32_e32 v64, 0.5, v64
	v_mul_f32_e32 v45, 0x3fb8aa3b, v45
	v_exp_f32_e32 v45, v45
	v_add_f32_e32 v68, 1.0, v68
	v_rcp_f32_e32 v68, v68
	v_fmac_f32_e32 v102, v109, v101
	v_add_f32_e32 v45, 1.0, v45
	v_rcp_f32_e32 v45, v45
	v_fma_f32 v68, v68, -2.0, 2.0
	v_mul_f32_e32 v64, v64, v68
	v_mul_f32_e32 v64, v65, v64
	v_bfe_u32 v65, v64, 16, 1
	v_add3_u32 v64, v64, v65, s27
	ds_write_b16_d16_hi v59, v64 offset:8976
	ds_read_u16 v64, v59 offset:9504
	v_add_f32_e32 v65, v103, v66
	v_mfma_f32_16x16x32_bf16 v[68:71], v[38:41], v[14:17], 0
	v_mul_f32_e32 v42, 0.5, v42
	v_fma_f32 v45, v45, -2.0, 2.0
	s_waitcnt lgkmcnt(0)
	v_lshlrev_b32_e32 v64, 16, v64
	v_mul_f32_e32 v66, 0x3d372713, v64
	v_mul_f32_e32 v66, v66, v64
	v_fma_f32 v66, v66, v64, v64
	v_mul_f32_e32 v66, 0x3f4c422a, v66
	v_add_f32_e32 v66, v66, v66
	v_mul_f32_e32 v66, 0x3fb8aa3b, v66
	v_exp_f32_e32 v66, v66
	v_mul_f32_e32 v64, 0.5, v64
	v_add_f32_e32 v44, v102, v44
	v_mul_f32_e32 v42, v42, v45
	v_add_f32_e32 v66, 1.0, v66
	v_rcp_f32_e32 v66, v66
	v_mul_f32_e32 v42, v44, v42
	v_bfe_u32 v44, v42, 16, 1
	v_add3_u32 v42, v42, v44, s27
	v_fma_f32 v66, v66, -2.0, 2.0
	v_mul_f32_e32 v64, v64, v66
	v_mul_f32_e32 v64, v65, v64
	v_bfe_u32 v65, v64, 16, 1
	v_add3_u32 v64, v64, v65, s27
	ds_write_b16_d16_hi v59, v64 offset:9504
	v_mfma_f32_16x16x32_bf16 v[64:67], v[38:41], v[6:9], 0
	ds_write_b16_d16_hi v59, v42 offset:10032
	ds_read_u16 v42, v58 offset:8480
	v_fmac_f32_e32 v48, v63, v49
	v_mfma_f32_16x16x32_bf16 v[38:41], v[34:37], v[2:5], v[64:67]
	v_cmp_gt_i32_e64 s[0:1], 3, v51
	v_mfma_f32_16x16x32_bf16 v[34:37], v[34:37], v[10:13], v[68:71]
	s_nop 5
	v_add_f32_e32 v38, v151, v38
	v_add_f32_e32 v39, v151, v39
	v_add_f32_e32 v40, v151, v40
	v_mul_f32_e32 v38, 0xbfb8aa3b, v38
	v_mul_f32_e32 v39, 0xbfb8aa3b, v39
	v_mul_f32_e32 v40, 0xbfb8aa3b, v40
	v_exp_f32_e32 v38, v38
	v_exp_f32_e32 v39, v39
	v_exp_f32_e32 v40, v40
	v_add_f32_e32 v34, v150, v34
	v_add_f32_e32 v35, v150, v35
	v_add_f32_e32 v36, v150, v36
	v_mul_f32_e32 v34, 0xbfb8aa3b, v34
	v_mul_f32_e32 v35, 0xbfb8aa3b, v35
	v_mul_f32_e32 v36, 0xbfb8aa3b, v36
	v_add_f32_e32 v41, v151, v41
	v_add_f32_e32 v38, 1.0, v38
	v_exp_f32_e32 v34, v34
	v_add_f32_e32 v39, 1.0, v39
	v_exp_f32_e32 v35, v35
	v_add_f32_e32 v40, 1.0, v40
	v_exp_f32_e32 v36, v36
	v_mul_f32_e32 v41, 0xbfb8aa3b, v41
	v_rcp_f32_e32 v38, v38
	v_rcp_f32_e32 v39, v39
	v_rcp_f32_e32 v40, v40
	v_exp_f32_e32 v41, v41
	v_add_f32_e32 v34, 1.0, v34
	v_add_f32_e32 v35, 1.0, v35
	v_add_f32_e32 v36, 1.0, v36
	v_rcp_f32_e32 v44, v34
	v_mul_f32_e32 v34, v57, v38
	v_rcp_f32_e32 v45, v35
	v_mul_f32_e32 v35, v57, v39
	v_rcp_f32_e32 v64, v36
	v_mul_f32_e32 v36, v57, v40
	v_add_f32_e32 v41, 1.0, v41
	v_mul_f32_e32 v34, 0x3fb8aa3b, v34
	v_mul_f32_e32 v35, 0x3fb8aa3b, v35
	v_mul_f32_e32 v36, 0x3fb8aa3b, v36
	v_rcp_f32_e32 v41, v41
	v_exp_f32_e32 v34, v34
	v_exp_f32_e32 v35, v35
	v_exp_f32_e32 v36, v36
	v_mul_f32_e32 v41, v57, v41
	v_fma_f32 v38, -v34, v34, 1.0
	v_fma_f32 v39, -v35, v35, 1.0
	v_fma_f32 v40, -v36, v36, 1.0
	v_add_f32_e32 v37, v150, v37
	v_mul_f32_e32 v41, 0x3fb8aa3b, v41
	v_max_f32_e32 v38, 0, v38
	v_max_f32_e32 v39, 0, v39
	v_max_f32_e32 v40, 0, v40
	v_mul_f32_e32 v37, 0xbfb8aa3b, v37
	v_exp_f32_e32 v41, v41
	v_sqrt_f32_e32 v38, v38
	v_sqrt_f32_e32 v39, v39
	v_sqrt_f32_e32 v40, v40
	v_exp_f32_e32 v37, v37
	v_fma_f32 v65, -v41, v41, 1.0
	v_mul_f32_e32 v38, v44, v38
	ds_read_u16 v44, v58 offset:9008
	v_mul_f32_e32 v39, v45, v39
	ds_read_u16 v45, v58 offset:9536
	v_mul_f32_e32 v40, v64, v40
	ds_read_u16 v64, v58 offset:10064
	v_add_f32_e32 v37, 1.0, v37
	v_max_f32_e32 v65, 0, v65
	v_rcp_f32_e32 v37, v37
	v_sqrt_f32_e32 v65, v65
	s_waitcnt lgkmcnt(0)
	v_lshlrev_b32_e32 v64, 16, v64
	v_lshlrev_b32_e32 v45, 16, v45
	v_lshlrev_b32_e32 v44, 16, v44
	v_mul_f32_e32 v37, v37, v65
	v_mul_f32_e32 v37, v37, v64
	v_mul_f32_e32 v64, v36, v41
	v_mul_f32_e32 v36, v36, v37
	v_fmac_f32_e32 v36, v40, v45
	v_mul_f32_e32 v40, v35, v64
	v_mul_f32_e32 v35, v35, v36
	v_fmac_f32_e32 v35, v39, v44
	v_lshlrev_b32_e32 v42, 16, v42
	v_mul_f32_e32 v39, v34, v40
	v_mul_f32_e32 v34, v34, v35
	v_fmac_f32_e32 v34, v38, v42
	s_nop 0
	s_nop 0
	s_nop 0
	s_nop 0
	s_nop 0
	s_nop 0
	v_mov_b32_e32 v44, v39
	v_mov_b32_e32 v65, v39
	s_nop 1
	v_permlane16_swap_b32_e32 v44, v65
	s_nop 1
	v_mov_b32_e32 v66, v44
	v_mov_b32_e32 v67, v65
	s_nop 1
	v_permlane32_swap_b32_e32 v44, v66
	v_permlane32_swap_b32_e32 v65, v67
	s_nop 1
	v_mov_b32_e32 v42, v34
	v_mov_b32_e32 v45, v34
	s_nop 1
	v_permlane16_swap_b32_e32 v42, v45
	s_nop 1
	v_mov_b32_e32 v61, v42
	v_mov_b32_e32 v38, v45
	s_nop 1
	v_permlane32_swap_b32_e32 v42, v61
	v_permlane32_swap_b32_e32 v45, v38
	s_nop 1
	s_waitcnt lgkmcnt(0)
	v_fmac_f32_e32 v38, v48, v67
	s_waitcnt lgkmcnt(0)
	v_fmac_f32_e32 v61, v38, v66
	s_waitcnt lgkmcnt(0)
	v_fmac_f32_e32 v45, v61, v65
	s_and_saveexec_b64 s[4:5], s[0:1]
	s_cbranch_execz .LBB0_725
	v_cmp_ne_u32_e64 s[0:1], 2, v51
	s_and_saveexec_b64 s[34:35], s[0:1]
	s_xor_b64 s[0:1], exec, s[34:35]
	v_cndmask_b32_e32 v48, v45, v61, vcc
	s_andn2_saveexec_b64 s[0:1], s[0:1]
	v_mov_b32_e32 v48, v38
	s_or_b64 exec, exec, s[0:1]

; #define LAS __attribute__((address_space(3)))
; __device__ __forceinline__ u32x4 pack8(const float (&f)[8]) { u32x4 o; o.x = pk2(f[0], f[1]); o.y = pk2(f[2], f[3]); o.z = pk2(f[4], f[5]); o.w = pk2(f[6], f[7]); return o; }
; __device__ __forceinline__ void lru_conv_tile(const Args& a, LAS bf16_t* cxb, int l, const Tile& T) {
;     ...
;     for (int i = 0; i < 11; ++i) {
;         const int tg = T.t0 + grp * 8 + i - 2;
;         u32x4 rv = raw[i]; if (!(tg >= 0 && tg < T.seqlen)) rv = (u32x4){0u, 0u, 0u, 0u};
; #pragma unroll
;         for (int e = 0; e < 8; ++e) { win[0][e] = win[1][e]; win[1][e] = win[2][e]; win[2][e] = win[3][e]; }
;         unpack8(rv, win[3]);
;         if (i >= 3) {
;             float o[8];
; #pragma unroll
;             for (int e = 0; e < 8; ++e) o[e] = bias[e] + w[0][e] * win[0][e] + w[1][e] * win[1][e] + w[2][e] * win[2][e] + w[3][e] * win[3][e];
;             *(LAS u32x4*)(cxb + (grp * 8 + i - 3) * CXS + c0) = pack8(o);
;         }
;     }
.LBB0_771:
	s_or_b64 exec, exec, s[4:5]
	s_waitcnt vmcnt(0)
	v_lshlrev_b32_e32 v166, 16, v146
	v_and_b32_e32 v168, 0xffff0000, v146
	v_add_u32_e32 v146, 1, v162
	v_cmp_lt_i32_e32 vcc, 1, v146
	v_add_u32_e32 v146, -1, v162
	v_cmp_gt_u32_e64 s[0:1], s34, v146
	s_and_b64 vcc, vcc, s[0:1]
	v_cndmask_b32_e32 v182, 0, v144, vcc
	v_add_u32_e32 v144, 2, v162
	v_cndmask_b32_e32 v180, 0, v145, vcc
	v_cndmask_b32_e32 v143, 0, v143, vcc
	v_cndmask_b32_e32 v142, 0, v142, vcc
	v_cmp_lt_i32_e32 vcc, 1, v144
	v_cmp_ge_i32_e64 s[0:1], s34, v144
	s_and_b64 vcc, vcc, s[0:1]
	v_or_b32_e32 v190, 3, v164
	v_cndmask_b32_e32 v186, 0, v136, vcc
	v_add_u32_e32 v136, s35, v190
	v_cndmask_b32_e32 v184, 0, v137, vcc
	v_cndmask_b32_e32 v135, 0, v135, vcc
	v_cndmask_b32_e32 v134, 0, v134, vcc
	v_cmp_lt_i32_e32 vcc, 1, v136
	v_add_u32_e32 v136, -2, v136
	v_cmp_gt_u32_e64 s[0:1], s34, v136
	s_and_b64 vcc, vcc, s[0:1]
	v_cndmask_b32_e32 v136, 0, v139, vcc
	v_cndmask_b32_e32 v137, 0, v138, vcc
	v_lshlrev_b32_e32 v167, 16, v147
	v_and_b32_e32 v169, 0xffff0000, v147
	v_lshlrev_b32_e32 v177, 16, v135
	v_lshlrev_b32_e32 v176, 16, v134
	v_and_b32_e32 v179, 0xffff0000, v135
	v_and_b32_e32 v178, 0xffff0000, v134
	v_lshlrev_b32_e32 v147, 16, v136
	v_lshlrev_b32_e32 v146, 16, v137
	v_and_b32_e32 v145, 0xffff0000, v136
	v_and_b32_e32 v144, 0xffff0000, v137
	v_mov_b32_e32 v134, v86
	v_mov_b32_e32 v135, v88
	v_mov_b32_e32 v136, v102
	v_mov_b32_e32 v137, v104
	v_mov_b32_e32 v88, v87
	v_mov_b32_e32 v104, v103
	v_cndmask_b32_e32 v188, 0, v141, vcc
	v_cndmask_b32_e32 v191, 0, v140, vcc
	v_lshlrev_b32_e32 v173, 16, v143
	v_lshlrev_b32_e32 v172, 16, v142
	v_and_b32_e32 v175, 0xffff0000, v143
	v_and_b32_e32 v174, 0xffff0000, v142
	v_pk_fma_f32 v[140:141], v[134:135], v[166:167], v[136:137]
	v_mov_b32_e32 v138, v90
	v_mov_b32_e32 v139, v92
	v_pk_fma_f32 v[86:87], v[88:89], v[168:169], v[104:105]
	v_mov_b32_e32 v92, v91
	v_pk_fma_f32 v[142:143], v[138:139], v[172:173], v[140:141]
	v_mov_b32_e32 v140, v94
	v_mov_b32_e32 v141, v96
	v_pk_fma_f32 v[86:87], v[92:93], v[174:175], v[86:87]
	v_mov_b32_e32 v96, v95
	v_pk_fma_f32 v[164:165], v[140:141], v[176:177], v[142:143]
	v_mov_b32_e32 v143, v100
	v_pk_fma_f32 v[86:87], v[96:97], v[178:179], v[86:87]
	v_mov_b32_e32 v100, v99
	v_lshlrev_b32_e32 v170, 16, v148
	v_lshlrev_b32_e32 v171, 16, v149
	v_pk_fma_f32 v[166:167], v[100:101], v[144:145], v[86:87]
	v_mov_b32_e32 v86, v66
	v_mov_b32_e32 v87, v68
	v_mov_b32_e32 v90, v82
	v_mov_b32_e32 v91, v84
	v_and_b32_e32 v148, 0xffff0000, v148
	v_and_b32_e32 v149, 0xffff0000, v149
	v_mov_b32_e32 v142, v98
	v_lshlrev_b32_e32 v169, 16, v180
	v_lshlrev_b32_e32 v168, 16, v182
	v_pk_fma_f32 v[98:99], v[86:87], v[170:171], v[90:91]
	v_mov_b32_e32 v94, v70
	v_mov_b32_e32 v95, v72
	v_mov_b32_e32 v68, v67
	v_mov_b32_e32 v84, v83
	v_and_b32_e32 v181, 0xffff0000, v180
	v_and_b32_e32 v180, 0xffff0000, v182
	v_lshlrev_b32_e32 v183, 16, v184
	v_lshlrev_b32_e32 v182, 16, v186
	v_pk_fma_f32 v[102:103], v[94:95], v[168:169], v[98:99]
	v_mov_b32_e32 v98, v74
	v_mov_b32_e32 v99, v76
	v_pk_fma_f32 v[66:67], v[68:69], v[148:149], v[84:85]
	v_mov_b32_e32 v72, v71
	v_and_b32_e32 v185, 0xffff0000, v184
	v_and_b32_e32 v184, 0xffff0000, v186
	v_lshlrev_b32_e32 v187, 16, v188
	v_lshlrev_b32_e32 v186, 16, v191
	v_pk_fma_f32 v[170:171], v[98:99], v[182:183], v[102:103]
	v_mov_b32_e32 v102, v78
	v_mov_b32_e32 v103, v80
	v_pk_fma_f32 v[66:67], v[72:73], v[180:181], v[66:67]
	v_mov_b32_e32 v76, v75
	v_and_b32_e32 v189, 0xffff0000, v188
	v_and_b32_e32 v188, 0xffff0000, v191
	v_pk_fma_f32 v[170:171], v[102:103], v[186:187], v[170:171]
	v_pk_fma_f32 v[66:67], v[76:77], v[184:185], v[66:67]
	v_mov_b32_e32 v80, v79
	v_pk_fma_f32 v[66:67], v[80:81], v[188:189], v[66:67]
	v_bfe_u32 v78, v170, 16, 1
	v_pk_fma_f32 v[164:165], v[142:143], v[146:147], v[164:165]
	v_bfe_u32 v70, v67, 16, 1
	v_bfe_u32 v71, v66, 16, 1
	v_add3_u32 v78, v170, v78, s27
	v_bfe_u32 v75, v166, 16, 1
	v_add3_u32 v66, v66, v71, s27
	v_add3_u32 v67, v67, v70, s27
	v_bfe_u32 v70, v164, 16, 1
	v_bfe_u32 v71, v165, 16, 1
	v_bfe_u32 v79, v171, 16, 1
	v_lshrrev_b32_e32 v78, 16, v78
	v_bfe_u32 v74, v167, 16, 1
	v_add3_u32 v75, v166, v75, s27
	v_add3_u32 v79, v171, v79, s27
	v_add3_u32 v71, v165, v71, s27
	v_add3_u32 v70, v164, v70, s27
	v_and_or_b32 v166, v66, s6, v78
	v_mul_lo_u32 v66, v190, s55
	v_add3_u32 v74, v167, v74, s27
	v_lshrrev_b32_e32 v70, 16, v70
	v_lshrrev_b32_e32 v71, 16, v71
	v_lshrrev_b32_e32 v79, 16, v79
	v_add3_u32 v170, 0, v66, v206
	v_and_or_b32 v167, v67, s6, v79
	v_and_or_b32 v165, v74, s6, v71
	v_and_or_b32 v164, v75, s6, v70
	v_add_u32_e32 v66, 0xfffff9d0, v170
	ds_write_b128 v66, v[164:167]
	v_add_u32_e32 v66, 4, v162
	v_cmp_lt_i32_e32 vcc, 1, v66
	v_cmp_ge_i32_e64 s[0:1], s34, v66
	s_and_b64 vcc, vcc, s[0:1]
	v_cndmask_b32_e32 v133, 0, v133, vcc
	v_cndmask_b32_e32 v132, 0, v132, vcc
	v_cndmask_b32_e32 v70, 0, v131, vcc
	v_cndmask_b32_e32 v74, 0, v130, vcc
	v_pk_fma_f32 v[78:79], v[88:89], v[174:175], v[104:105]
	v_lshlrev_b32_e32 v83, 16, v133
	v_lshlrev_b32_e32 v82, 16, v132
	v_and_b32_e32 v149, 0xffff0000, v133
	v_and_b32_e32 v148, 0xffff0000, v132
	v_pk_fma_f32 v[132:133], v[68:69], v[180:181], v[84:85]
	v_lshlrev_b32_e32 v67, 16, v70
	v_lshlrev_b32_e32 v66, 16, v74
	v_and_b32_e32 v71, 0xffff0000, v70
	v_and_b32_e32 v70, 0xffff0000, v74
	v_pk_fma_f32 v[74:75], v[134:135], v[172:173], v[136:137]
	v_pk_fma_f32 v[78:79], v[92:93], v[178:179], v[78:79]
	v_pk_fma_f32 v[130:131], v[86:87], v[168:169], v[90:91]
	v_pk_fma_f32 v[132:133], v[72:73], v[184:185], v[132:133]
	v_pk_fma_f32 v[74:75], v[138:139], v[176:177], v[74:75]
	v_pk_fma_f32 v[78:79], v[96:97], v[144:145], v[78:79]
; #define LAS __attribute__((address_space(3)))
; __device__ __forceinline__ u32x4 pack8(const float (&f)[8]) { u32x4 o; o.x = pk2(f[0], f[1]); o.y = pk2(f[2], f[3]); o.z = pk2(f[4], f[5]); o.w = pk2(f[6], f[7]); return o; }
; __device__ __forceinline__ void lru_conv_tile(const Args& a, LAS bf16_t* cxb, int l, const Tile& T) {
;     ...
;     for (int i = 0; i < 11; ++i) {
;         const int tg = T.t0 + grp * 8 + i - 2;
;         u32x4 rv = raw[i]; if (!(tg >= 0 && tg < T.seqlen)) rv = (u32x4){0u, 0u, 0u, 0u};
; #pragma unroll
;         for (int e = 0; e < 8; ++e) { win[0][e] = win[1][e]; win[1][e] = win[2][e]; win[2][e] = win[3][e]; }
;         unpack8(rv, win[3]);
;         if (i >= 3) {
;             float o[8];
; #pragma unroll
;             for (int e = 0; e < 8; ++e) o[e] = bias[e] + w[0][e] * win[0][e] + w[1][e] * win[1][e] + w[2][e] * win[2][e] + w[3][e] * win[3][e];
;             *(LAS u32x4*)(cxb + (grp * 8 + i - 3) * CXS + c0) = pack8(o);
;         }
;     }
	v_pk_fma_f32 v[130:131], v[94:95], v[182:183], v[130:131]
	v_pk_fma_f32 v[132:133], v[76:77], v[188:189], v[132:133]
	v_pk_fma_f32 v[74:75], v[140:141], v[146:147], v[74:75]
	v_pk_fma_f32 v[78:79], v[100:101], v[70:71], v[78:79]
	v_pk_fma_f32 v[130:131], v[98:99], v[186:187], v[130:131]
	v_pk_fma_f32 v[132:133], v[80:81], v[148:149], v[132:133]
	v_pk_fma_f32 v[74:75], v[142:143], v[66:67], v[74:75]
	v_pk_fma_f32 v[130:131], v[102:103], v[82:83], v[130:131]
	v_bfe_u32 v164, v133, 16, 1
	v_bfe_u32 v165, v132, 16, 1
	v_bfe_u32 v166, v79, 16, 1
	v_bfe_u32 v167, v78, 16, 1
	v_add3_u32 v78, v78, v167, s27
	v_add3_u32 v79, v79, v166, s27
	v_add3_u32 v132, v132, v165, s27
	v_add3_u32 v133, v133, v164, s27
	v_bfe_u32 v164, v74, 16, 1
	v_bfe_u32 v165, v75, 16, 1
	v_bfe_u32 v166, v130, 16, 1
	v_bfe_u32 v167, v131, 16, 1
	v_add3_u32 v131, v131, v167, s27
	v_add3_u32 v130, v130, v166, s27
	v_add3_u32 v75, v75, v165, s27
	v_add3_u32 v74, v74, v164, s27
	v_lshrrev_b32_e32 v74, 16, v74
	v_lshrrev_b32_e32 v75, 16, v75
	v_lshrrev_b32_e32 v130, 16, v130
	v_lshrrev_b32_e32 v131, 16, v131
	v_and_or_b32 v133, v133, s6, v131
	v_and_or_b32 v132, v132, s6, v130
	v_and_or_b32 v131, v79, s6, v75
	v_and_or_b32 v130, v78, s6, v74
	v_add_u32_e32 v74, 0xfffffbe0, v170
	ds_write_b128 v74, v[130:133]
	v_add_u32_e32 v74, 5, v162
	v_cmp_lt_i32_e32 vcc, 1, v74
	v_add_u32_e32 v74, 3, v162
	v_cmp_gt_u32_e64 s[0:1], s34, v74
	s_and_b64 vcc, vcc, s[0:1]
	v_cndmask_b32_e32 v132, 0, v129, vcc
	v_cndmask_b32_e32 v164, 0, v128, vcc
	v_cndmask_b32_e32 v78, 0, v127, vcc
	v_cndmask_b32_e32 v126, 0, v126, vcc
	v_pk_fma_f32 v[128:129], v[88:89], v[178:179], v[104:105]
	v_pk_fma_f32 v[166:167], v[68:69], v[184:185], v[84:85]
	v_lshlrev_b32_e32 v75, 16, v78
	v_lshlrev_b32_e32 v74, 16, v126
	v_and_b32_e32 v79, 0xffff0000, v78
	v_and_b32_e32 v78, 0xffff0000, v126
	v_pk_fma_f32 v[126:127], v[134:135], v[176:177], v[136:137]
	v_pk_fma_f32 v[128:129], v[92:93], v[144:145], v[128:129]
	v_lshlrev_b32_e32 v131, 16, v132
	v_lshlrev_b32_e32 v130, 16, v164
	v_and_b32_e32 v133, 0xffff0000, v132
	v_and_b32_e32 v132, 0xffff0000, v164
	v_pk_fma_f32 v[164:165], v[86:87], v[182:183], v[90:91]
	v_pk_fma_f32 v[166:167], v[72:73], v[188:189], v[166:167]
	v_pk_fma_f32 v[126:127], v[138:139], v[146:147], v[126:127]
	v_pk_fma_f32 v[128:129], v[96:97], v[70:71], v[128:129]
	v_pk_fma_f32 v[164:165], v[94:95], v[186:187], v[164:165]
	v_pk_fma_f32 v[166:167], v[76:77], v[148:149], v[166:167]
	v_pk_fma_f32 v[126:127], v[140:141], v[66:67], v[126:127]
	v_pk_fma_f32 v[128:129], v[100:101], v[78:79], v[128:129]
	v_pk_fma_f32 v[164:165], v[98:99], v[82:83], v[164:165]
	v_pk_fma_f32 v[166:167], v[80:81], v[132:133], v[166:167]
	v_pk_fma_f32 v[126:127], v[142:143], v[74:75], v[126:127]
	v_pk_fma_f32 v[164:165], v[102:103], v[130:131], v[164:165]
	v_bfe_u32 v168, v167, 16, 1
	v_bfe_u32 v169, v166, 16, 1
	v_bfe_u32 v171, v129, 16, 1
	v_bfe_u32 v172, v128, 16, 1
	v_add3_u32 v172, v128, v172, s27
	v_add3_u32 v171, v129, v171, s27
	v_add3_u32 v128, v166, v169, s27
	v_add3_u32 v129, v167, v168, s27
	v_bfe_u32 v166, v126, 16, 1
	v_bfe_u32 v167, v127, 16, 1
	v_bfe_u32 v168, v164, 16, 1
	v_bfe_u32 v169, v165, 16, 1
	v_add3_u32 v165, v165, v169, s27
	v_add3_u32 v164, v164, v168, s27
	v_add3_u32 v127, v127, v167, s27
	v_add3_u32 v126, v126, v166, s27
	v_lshrrev_b32_e32 v126, 16, v126
	v_lshrrev_b32_e32 v127, 16, v127
	v_lshrrev_b32_e32 v164, 16, v164
	v_lshrrev_b32_e32 v165, 16, v165
	v_and_or_b32 v129, v129, s6, v165
	v_and_or_b32 v128, v128, s6, v164
	v_and_or_b32 v127, v171, s6, v127
	v_and_or_b32 v126, v172, s6, v126
	v_add_u32_e32 v164, 0xfffffdf0, v170
	ds_write_b128 v164, v[126:129]
	v_add_u32_e32 v126, 6, v162
	v_cmp_lt_i32_e32 vcc, 1, v126
	v_cmp_ge_i32_e64 s[0:1], s34, v126
	s_and_b64 vcc, vcc, s[0:1]
	v_cndmask_b32_e32 v164, 0, v125, vcc
	v_cndmask_b32_e32 v165, 0, v124, vcc
	v_cndmask_b32_e32 v123, 0, v123, vcc
	v_cndmask_b32_e32 v122, 0, v122, vcc
	v_pk_fma_f32 v[124:125], v[88:89], v[144:145], v[104:105]
	v_pk_fma_f32 v[166:167], v[68:69], v[188:189], v[84:85]
	v_lshlrev_b32_e32 v127, 16, v123
	v_lshlrev_b32_e32 v126, 16, v122
	v_and_b32_e32 v129, 0xffff0000, v123
	v_and_b32_e32 v128, 0xffff0000, v122
	v_pk_fma_f32 v[122:123], v[134:135], v[146:147], v[136:137]
	v_pk_fma_f32 v[124:125], v[92:93], v[70:71], v[124:125]
	v_lshlrev_b32_e32 v145, 16, v164
	v_lshlrev_b32_e32 v144, 16, v165
	v_and_b32_e32 v147, 0xffff0000, v164
	v_and_b32_e32 v146, 0xffff0000, v165
	v_pk_fma_f32 v[164:165], v[86:87], v[186:187], v[90:91]
	v_pk_fma_f32 v[166:167], v[72:73], v[148:149], v[166:167]
	v_pk_fma_f32 v[122:123], v[138:139], v[66:67], v[122:123]
	v_pk_fma_f32 v[124:125], v[96:97], v[78:79], v[124:125]
	v_pk_fma_f32 v[164:165], v[94:95], v[82:83], v[164:165]
	v_pk_fma_f32 v[166:167], v[76:77], v[132:133], v[166:167]
	v_pk_fma_f32 v[122:123], v[140:141], v[74:75], v[122:123]
	v_pk_fma_f32 v[124:125], v[100:101], v[128:129], v[124:125]
	v_pk_fma_f32 v[164:165], v[98:99], v[130:131], v[164:165]
	v_pk_fma_f32 v[166:167], v[80:81], v[146:147], v[166:167]
	v_pk_fma_f32 v[122:123], v[142:143], v[126:127], v[122:123]
	v_pk_fma_f32 v[164:165], v[102:103], v[144:145], v[164:165]
	v_bfe_u32 v168, v167, 16, 1
	v_bfe_u32 v169, v166, 16, 1
	v_bfe_u32 v171, v125, 16, 1
	v_bfe_u32 v172, v124, 16, 1
	v_add3_u32 v172, v124, v172, s27
	v_add3_u32 v171, v125, v171, s27
	v_add3_u32 v124, v166, v169, s27
	v_add3_u32 v125, v167, v168, s27
	v_bfe_u32 v166, v122, 16, 1
	v_bfe_u32 v167, v123, 16, 1
	v_bfe_u32 v168, v164, 16, 1
	v_bfe_u32 v169, v165, 16, 1
	v_add3_u32 v165, v165, v169, s27
	v_add3_u32 v164, v164, v168, s27
	v_add3_u32 v123, v123, v167, s27
; #define LAS __attribute__((address_space(3)))
; __device__ __forceinline__ u32x4 pack8(const float (&f)[8]) { u32x4 o; o.x = pk2(f[0], f[1]); o.y = pk2(f[2], f[3]); o.z = pk2(f[4], f[5]); o.w = pk2(f[6], f[7]); return o; }
; __device__ __forceinline__ void lru_conv_tile(const Args& a, LAS bf16_t* cxb, int l, const Tile& T) {
;     ...
;     for (int i = 0; i < 11; ++i) {
;         const int tg = T.t0 + grp * 8 + i - 2;
;         u32x4 rv = raw[i]; if (!(tg >= 0 && tg < T.seqlen)) rv = (u32x4){0u, 0u, 0u, 0u};
; #pragma unroll
;         for (int e = 0; e < 8; ++e) { win[0][e] = win[1][e]; win[1][e] = win[2][e]; win[2][e] = win[3][e]; }
;         unpack8(rv, win[3]);
;         if (i >= 3) {
;             float o[8];
; #pragma unroll
;             for (int e = 0; e < 8; ++e) o[e] = bias[e] + w[0][e] * win[0][e] + w[1][e] * win[1][e] + w[2][e] * win[2][e] + w[3][e] * win[3][e];
;             *(LAS u32x4*)(cxb + (grp * 8 + i - 3) * CXS + c0) = pack8(o);
;         }
;     }
	v_add3_u32 v122, v122, v166, s27
	v_lshrrev_b32_e32 v122, 16, v122
	v_lshrrev_b32_e32 v123, 16, v123
	v_lshrrev_b32_e32 v164, 16, v164
	v_lshrrev_b32_e32 v165, 16, v165
	v_and_or_b32 v125, v125, s6, v165
	v_and_or_b32 v124, v124, s6, v164
	v_and_or_b32 v123, v171, s6, v123
	v_and_or_b32 v122, v172, s6, v122
	v_or_b32_e32 v163, 7, v163
	ds_write_b128 v170, v[122:125]
	v_add_u32_e32 v122, s35, v163
	v_cmp_lt_i32_e32 vcc, 1, v122
	v_add_u32_e32 v122, -2, v122
	v_cmp_gt_u32_e64 s[0:1], s34, v122
	s_and_b64 vcc, vcc, s[0:1]
	v_cndmask_b32_e32 v119, 0, v119, vcc
	v_cndmask_b32_e32 v118, 0, v118, vcc
	v_lshlrev_b32_e32 v123, 16, v119
	v_lshlrev_b32_e32 v122, 16, v118
	v_and_b32_e32 v125, 0xffff0000, v119
	v_and_b32_e32 v124, 0xffff0000, v118
	v_pk_fma_f32 v[70:71], v[88:89], v[70:71], v[104:105]
	v_pk_fma_f32 v[118:119], v[68:69], v[148:149], v[84:85]
	v_cndmask_b32_e32 v121, 0, v121, vcc
	v_cndmask_b32_e32 v120, 0, v120, vcc
	v_pk_fma_f32 v[66:67], v[134:135], v[66:67], v[136:137]
	v_pk_fma_f32 v[70:71], v[92:93], v[78:79], v[70:71]
	v_pk_fma_f32 v[82:83], v[86:87], v[82:83], v[90:91]
	v_pk_fma_f32 v[118:119], v[72:73], v[132:133], v[118:119]
	v_pk_fma_f32 v[66:67], v[138:139], v[74:75], v[66:67]
	v_pk_fma_f32 v[70:71], v[96:97], v[128:129], v[70:71]
	v_and_b32_e32 v167, 0xffff0000, v121
	v_and_b32_e32 v166, 0xffff0000, v120
	v_pk_fma_f32 v[82:83], v[94:95], v[130:131], v[82:83]
	v_pk_fma_f32 v[118:119], v[76:77], v[146:147], v[118:119]
	v_pk_fma_f32 v[66:67], v[140:141], v[126:127], v[66:67]
	v_pk_fma_f32 v[70:71], v[100:101], v[124:125], v[70:71]
	v_lshlrev_b32_e32 v165, 16, v121
	v_lshlrev_b32_e32 v164, 16, v120
	v_pk_fma_f32 v[82:83], v[98:99], v[144:145], v[82:83]
	v_pk_fma_f32 v[118:119], v[80:81], v[166:167], v[118:119]
	v_pk_fma_f32 v[66:67], v[142:143], v[122:123], v[66:67]
	v_pk_fma_f32 v[82:83], v[102:103], v[164:165], v[82:83]
	v_bfe_u32 v120, v119, 16, 1
	v_bfe_u32 v148, v71, 16, 1
	v_add3_u32 v71, v71, v148, s27
	v_add3_u32 v119, v119, v120, s27
	v_bfe_u32 v120, v66, 16, 1
	v_bfe_u32 v148, v82, 16, 1
	v_bfe_u32 v121, v118, 16, 1
	v_bfe_u32 v149, v70, 16, 1
	v_add3_u32 v82, v82, v148, s27
	v_add3_u32 v66, v66, v120, s27
	v_add3_u32 v70, v70, v149, s27
	v_add3_u32 v118, v118, v121, s27
	v_bfe_u32 v121, v67, 16, 1
	v_bfe_u32 v149, v83, 16, 1
	v_lshrrev_b32_e32 v66, 16, v66
	v_lshrrev_b32_e32 v82, 16, v82
	v_add3_u32 v83, v83, v149, s27
	v_add3_u32 v67, v67, v121, s27
	v_and_or_b32 v120, v118, s6, v82
	v_and_or_b32 v118, v70, s6, v66
	v_mul_lo_u32 v66, v163, s55
	v_lshrrev_b32_e32 v67, 16, v67
	v_lshrrev_b32_e32 v83, 16, v83
	v_add_u32_e32 v66, 0, v66
	s_movk_i32 s0, 0xf9d0
	v_and_or_b32 v121, v119, s6, v83
	v_and_or_b32 v119, v71, s6, v67
	v_add3_u32 v66, v66, v206, s0
	ds_write_b128 v66, v[118:121]
	v_add_u32_e32 v66, 8, v162
	v_cmp_lt_i32_e32 vcc, 1, v66
	v_cmp_ge_i32_e64 s[0:1], s34, v66
	s_and_b64 vcc, vcc, s[0:1]
	v_cndmask_b32_e32 v117, 0, v117, vcc
	v_cndmask_b32_e32 v116, 0, v116, vcc
	v_cndmask_b32_e32 v70, 0, v115, vcc
	v_cndmask_b32_e32 v82, 0, v114, vcc
	v_lshlrev_b32_e32 v67, 16, v70
	v_lshlrev_b32_e32 v66, 16, v82
	v_and_b32_e32 v71, 0xffff0000, v70
	v_and_b32_e32 v70, 0xffff0000, v82
	v_pk_fma_f32 v[78:79], v[88:89], v[78:79], v[104:105]
	v_lshlrev_b32_e32 v83, 16, v117
	v_lshlrev_b32_e32 v82, 16, v116
	v_and_b32_e32 v119, 0xffff0000, v117
	v_and_b32_e32 v118, 0xffff0000, v116
	v_pk_fma_f32 v[116:117], v[68:69], v[132:133], v[84:85]
	v_pk_fma_f32 v[74:75], v[134:135], v[74:75], v[136:137]
	v_pk_fma_f32 v[78:79], v[92:93], v[128:129], v[78:79]
	v_pk_fma_f32 v[114:115], v[86:87], v[130:131], v[90:91]
	v_pk_fma_f32 v[116:117], v[72:73], v[146:147], v[116:117]
	v_pk_fma_f32 v[74:75], v[138:139], v[126:127], v[74:75]
	v_pk_fma_f32 v[78:79], v[96:97], v[124:125], v[78:79]
	v_pk_fma_f32 v[114:115], v[94:95], v[144:145], v[114:115]
	v_pk_fma_f32 v[116:117], v[76:77], v[166:167], v[116:117]
	v_pk_fma_f32 v[74:75], v[140:141], v[122:123], v[74:75]
	v_pk_fma_f32 v[78:79], v[100:101], v[70:71], v[78:79]
	v_pk_fma_f32 v[114:115], v[98:99], v[164:165], v[114:115]
	v_pk_fma_f32 v[116:117], v[80:81], v[118:119], v[116:117]
	v_pk_fma_f32 v[74:75], v[142:143], v[66:67], v[74:75]
	v_pk_fma_f32 v[114:115], v[102:103], v[82:83], v[114:115]
	v_bfe_u32 v120, v117, 16, 1
	v_bfe_u32 v130, v79, 16, 1
	v_add3_u32 v79, v79, v130, s27
	v_add3_u32 v117, v117, v120, s27
	v_bfe_u32 v120, v74, 16, 1
	v_bfe_u32 v130, v114, 16, 1
	v_bfe_u32 v121, v116, 16, 1
	v_bfe_u32 v131, v78, 16, 1
	v_add3_u32 v114, v114, v130, s27
	v_add3_u32 v74, v74, v120, s27
	v_add3_u32 v78, v78, v131, s27
	v_add3_u32 v116, v116, v121, s27
	v_lshrrev_b32_e32 v74, 16, v74
	v_lshrrev_b32_e32 v114, 16, v114
	v_and_or_b32 v116, v116, s6, v114
	v_and_or_b32 v114, v78, s6, v74
	v_add_u32_e32 v74, 9, v162
	v_bfe_u32 v121, v75, 16, 1
	v_bfe_u32 v131, v115, 16, 1
	v_cmp_lt_i32_e32 vcc, 1, v74
	v_add_u32_e32 v74, 7, v162
	v_add3_u32 v115, v115, v131, s27
	v_add3_u32 v75, v75, v121, s27
	v_cmp_gt_u32_e64 s[0:1], s34, v74
	v_lshrrev_b32_e32 v75, 16, v75
	v_lshrrev_b32_e32 v115, 16, v115
	s_and_b64 vcc, vcc, s[0:1]
	v_and_or_b32 v117, v117, s6, v115
	v_and_or_b32 v115, v79, s6, v75
	v_cndmask_b32_e32 v78, 0, v111, vcc
	v_cndmask_b32_e32 v110, 0, v110, vcc
	ds_write_b128 v170, v[114:117] offset:1056
	v_cndmask_b32_e32 v116, 0, v113, vcc
	v_cndmask_b32_e32 v120, 0, v112, vcc
	v_lshlrev_b32_e32 v75, 16, v78
	v_lshlrev_b32_e32 v74, 16, v110
	v_and_b32_e32 v79, 0xffff0000, v78
	v_and_b32_e32 v78, 0xffff0000, v110
	v_pk_fma_f32 v[110:111], v[134:135], v[126:127], v[136:137]
	v_pk_fma_f32 v[112:113], v[88:89], v[128:129], v[104:105]
	v_pk_fma_f32 v[126:127], v[68:69], v[146:147], v[84:85]
; #define LAS __attribute__((address_space(3)))
; __device__ __forceinline__ u32x4 pack8(const float (&f)[8]) { u32x4 o; o.x = pk2(f[0], f[1]); o.y = pk2(f[2], f[3]); o.z = pk2(f[4], f[5]); o.w = pk2(f[6], f[7]); return o; }
; __device__ __forceinline__ void lru_conv_tile(const Args& a, LAS bf16_t* cxb, int l, const Tile& T) {
;     ...
;     for (int i = 0; i < 11; ++i) {
;         const int tg = T.t0 + grp * 8 + i - 2;
;         u32x4 rv = raw[i]; if (!(tg >= 0 && tg < T.seqlen)) rv = (u32x4){0u, 0u, 0u, 0u};
; #pragma unroll
;         for (int e = 0; e < 8; ++e) { win[0][e] = win[1][e]; win[1][e] = win[2][e]; win[2][e] = win[3][e]; }
;         unpack8(rv, win[3]);
;         if (i >= 3) {
;             float o[8];
; #pragma unroll
;             for (int e = 0; e < 8; ++e) o[e] = bias[e] + w[0][e] * win[0][e] + w[1][e] * win[1][e] + w[2][e] * win[2][e] + w[3][e] * win[3][e];
;             *(LAS u32x4*)(cxb + (grp * 8 + i - 3) * CXS + c0) = pack8(o);
;         }
;     }
; template <int MODE>
; __device__ __forceinline__ void lru_unit(const Args& a, LAS unsigned char* lds, int l, int tt) {
;     ...
;     for (int nt = 0; nt < 2; ++nt) { prm0[nt][2] = -8.0f * log1pf(__expf(-prm0[nt][2])); prm1[nt][2] = -8.0f * log1pf(__expf(-prm1[nt][2])); }
	v_pk_fma_f32 v[112:113], v[92:93], v[124:125], v[112:113]
	v_lshlrev_b32_e32 v115, 16, v116
	v_lshlrev_b32_e32 v114, 16, v120
	v_and_b32_e32 v117, 0xffff0000, v116
	v_and_b32_e32 v116, 0xffff0000, v120
	v_pk_fma_f32 v[120:121], v[86:87], v[144:145], v[90:91]
	v_pk_fma_f32 v[126:127], v[72:73], v[166:167], v[126:127]
	v_pk_fma_f32 v[110:111], v[138:139], v[122:123], v[110:111]
	v_pk_fma_f32 v[112:113], v[96:97], v[70:71], v[112:113]
	v_pk_fma_f32 v[120:121], v[94:95], v[164:165], v[120:121]
	v_pk_fma_f32 v[126:127], v[76:77], v[118:119], v[126:127]
	v_pk_fma_f32 v[110:111], v[140:141], v[66:67], v[110:111]
	v_pk_fma_f32 v[112:113], v[100:101], v[78:79], v[112:113]
	v_pk_fma_f32 v[120:121], v[98:99], v[82:83], v[120:121]
	v_pk_fma_f32 v[126:127], v[80:81], v[116:117], v[126:127]
	v_pk_fma_f32 v[110:111], v[142:143], v[74:75], v[110:111]
	v_pk_fma_f32 v[120:121], v[102:103], v[114:115], v[120:121]
	v_bfe_u32 v128, v127, 16, 1
	v_bfe_u32 v129, v126, 16, 1
	v_bfe_u32 v130, v113, 16, 1
	v_bfe_u32 v131, v112, 16, 1
	v_add3_u32 v131, v112, v131, s27
	v_add3_u32 v130, v113, v130, s27
	v_add3_u32 v112, v126, v129, s27
	v_add3_u32 v113, v127, v128, s27
	v_bfe_u32 v126, v110, 16, 1
	v_bfe_u32 v127, v111, 16, 1
	v_bfe_u32 v128, v120, 16, 1
	v_bfe_u32 v129, v121, 16, 1
	v_add3_u32 v121, v121, v129, s27
	v_add3_u32 v120, v120, v128, s27
	v_add3_u32 v111, v111, v127, s27
	v_add3_u32 v110, v110, v126, s27
	v_lshrrev_b32_e32 v110, 16, v110
	v_lshrrev_b32_e32 v111, 16, v111
	v_lshrrev_b32_e32 v120, 16, v120
	v_lshrrev_b32_e32 v121, 16, v121
	v_and_or_b32 v113, v113, s6, v121
	v_and_or_b32 v112, v112, s6, v120
	v_and_or_b32 v111, v130, s6, v111
	v_and_or_b32 v110, v131, s6, v110
	ds_write_b128 v170, v[110:113] offset:1584
	v_add_u32_e32 v110, 10, v162
	v_cmp_lt_i32_e32 vcc, 1, v110
	v_cmp_ge_i32_e64 s[0:1], s34, v110
	s_and_b64 vcc, vcc, s[0:1]
	v_cndmask_b32_e32 v113, 0, v108, vcc
	v_cndmask_b32_e32 v108, 0, v107, vcc
	v_cndmask_b32_e32 v110, 0, v106, vcc
	v_cndmask_b32_e32 v112, 0, v109, vcc
	v_and_b32_e32 v107, 0xffff0000, v108
	v_and_b32_e32 v106, 0xffff0000, v110
	v_lshlrev_b32_e32 v109, 16, v108
	v_lshlrev_b32_e32 v108, 16, v110
	v_pk_fma_f32 v[110:111], v[134:135], v[122:123], v[136:137]
	v_pk_fma_f32 v[86:87], v[86:87], v[164:165], v[90:91]
	v_pk_fma_f32 v[66:67], v[138:139], v[66:67], v[110:111]
	v_pk_fma_f32 v[68:69], v[68:69], v[166:167], v[84:85]
	v_pk_fma_f32 v[66:67], v[140:141], v[74:75], v[66:67]
	v_pk_fma_f32 v[74:75], v[88:89], v[124:125], v[104:105]
	v_pk_fma_f32 v[82:83], v[94:95], v[82:83], v[86:87]
	v_pk_fma_f32 v[70:71], v[92:93], v[70:71], v[74:75]
	v_pk_fma_f32 v[68:69], v[72:73], v[118:119], v[68:69]
	v_pk_fma_f32 v[70:71], v[96:97], v[78:79], v[70:71]
	v_and_b32_e32 v75, 0xffff0000, v112
	v_pk_fma_f32 v[70:71], v[100:101], v[106:107], v[70:71]
	v_and_b32_e32 v74, 0xffff0000, v113
	v_lshlrev_b32_e32 v79, 16, v112
	v_lshlrev_b32_e32 v78, 16, v113
	v_pk_fma_f32 v[82:83], v[98:99], v[114:115], v[82:83]
	v_pk_fma_f32 v[68:69], v[76:77], v[116:117], v[68:69]
	v_pk_fma_f32 v[78:79], v[102:103], v[78:79], v[82:83]
	v_pk_fma_f32 v[68:69], v[80:81], v[74:75], v[68:69]
	v_bfe_u32 v74, v71, 16, 1
	v_pk_fma_f32 v[66:67], v[142:143], v[108:109], v[66:67]
	v_bfe_u32 v72, v69, 16, 1
	v_add3_u32 v71, v71, v74, s27
	v_bfe_u32 v74, v78, 16, 1
	v_bfe_u32 v73, v68, 16, 1
	v_add3_u32 v69, v69, v72, s27
	v_bfe_u32 v72, v66, 16, 1
	v_add3_u32 v74, v78, v74, s27
	v_add3_u32 v68, v68, v73, s27
	v_add3_u32 v66, v66, v72, s27
	v_lshrrev_b32_e32 v72, 16, v74
	v_bfe_u32 v75, v70, 16, 1
	v_and_or_b32 v68, v68, s6, v72
	v_mul_f32_e32 v72, 0xbfb8aa3b, v161
	v_add3_u32 v70, v70, v75, s27
	v_bfe_u32 v73, v67, 16, 1
	v_bfe_u32 v75, v79, 16, 1
	v_exp_f32_e32 v72, v72
	v_add3_u32 v75, v79, v75, s27
	v_add3_u32 v67, v67, v73, s27
	v_lshrrev_b32_e32 v66, 16, v66
	v_lshrrev_b32_e32 v67, 16, v67
	v_lshrrev_b32_e32 v73, 16, v75
	v_and_or_b32 v69, v69, s6, v73
	v_and_or_b32 v67, v71, s6, v67
	v_and_or_b32 v66, v70, s6, v66
	ds_write_b128 v170, v[66:69] offset:2112
	v_add_f32_e32 v68, 1.0, v72
	v_add_f32_e32 v66, -1.0, v68
	v_sub_f32_e32 v67, v66, v68
	v_add_f32_e32 v67, 1.0, v67
	v_sub_f32_e32 v66, v72, v66
	v_add_f32_e32 v69, v66, v67
	v_frexp_mant_f32_e32 v70, v68
	v_cvt_f64_f32_e32 v[66:67], v68
	s_mov_b32 s28, 0x3f2aaaab
	v_frexp_exp_i32_f64_e32 v66, v[66:67]
	v_cmp_gt_f32_e32 vcc, s28, v70
	s_mov_b32 s4, 0x3f317218
	v_mov_b32_e32 v79, 0x3ecc95a3
	v_subbrev_co_u32_e32 v66, vcc, 0, v66, vcc
	v_sub_u32_e32 v67, 0, v66
	v_ldexp_f32 v68, v68, v67
	v_ldexp_f32 v67, v69, v67
	v_add_f32_e32 v69, -1.0, v68
	v_add_f32_e32 v73, 1.0, v68
	v_add_f32_e32 v70, 1.0, v69
	v_add_f32_e32 v74, -1.0, v73
	v_sub_f32_e32 v70, v68, v70
	v_sub_f32_e32 v68, v68, v74
	v_add_f32_e32 v70, v67, v70
	v_add_f32_e32 v67, v67, v68
	v_add_f32_e32 v68, v73, v67
	v_rcp_f32_e32 v74, v68
	v_add_f32_e32 v71, v69, v70
	v_sub_f32_e32 v69, v71, v69
	v_sub_f32_e32 v69, v70, v69
	v_sub_f32_e32 v70, v68, v73
	v_sub_f32_e32 v67, v67, v70
	v_mul_f32_e32 v70, v71, v74
	v_mul_f32_e32 v73, v68, v70
	v_fma_f32 v75, v70, v68, -v73
	v_fmac_f32_e32 v75, v70, v67
	v_add_f32_e32 v76, v73, v75
	v_sub_f32_e32 v77, v71, v76
	v_sub_f32_e32 v71, v71, v77
	v_sub_f32_e32 v73, v76, v73
	v_sub_f32_e32 v71, v71, v76
	v_add_f32_e32 v69, v69, v71
	v_sub_f32_e32 v71, v73, v75
	v_add_f32_e32 v69, v71, v69
	v_add_f32_e32 v71, v77, v69
	v_mul_f32_e32 v73, v74, v71
	v_mul_f32_e32 v75, v68, v73
	v_fma_f32 v68, v73, v68, -v75
	v_fmac_f32_e32 v68, v73, v67
	v_sub_f32_e32 v67, v77, v71
	v_add_f32_e32 v67, v69, v67
	v_add_f32_e32 v69, v75, v68
	v_sub_f32_e32 v76, v71, v69
	v_sub_f32_e32 v71, v71, v76
	v_sub_f32_e32 v75, v69, v75
; #define LAS __attribute__((address_space(3)))
; __device__ __forceinline__ int opaque_tid() { int t = threadIdx.x; asm volatile("" : "+v"(t)); return t; }
; template <int DIR, int MODE>
; __device__ __forceinline__ void lru_pass(const Args& a, const LAS bf16_t* cxb, LAS bf16_t* gyb, const LAS float* carry, const bf16x8 (&Bw)[2][2][2], const float (&prm)[2][3], int l, int tt, float (&hf)[8][2][4]) {
;     const int tid = opaque_tid(), lane = tid & 63, w = __builtin_amdgcn_readfirstlane(tid >> 6), h = w & 3, nh = w >> 2, fr = lane & 15, fq = lane >> 4;
;     float* SUM = (float*)(a.ws + WS_SUM);
;     float ba[2], bxv[2], k8[2], C[2], At[2]; int cc[2];
; #pragma unroll
;     for (int nt = 0; nt < 2; ++nt) {
;         const int c = 64 * h + 32 * nh + 16 * nt + fr; cc[nt] = c;
;         ba[nt] = prm[nt][0]; bxv[nt] = prm[nt][1]; k8[nt] = prm[nt][2];
;         C[nt] = MODE == 1 ? carry[DIR * 256 + c] : 0.f; At[nt] = 1.f;
;     }
; #pragma unroll
;     for (int mi = 0; mi < 8; ++mi) {
;         const int m = DIR ? 7 - mi : mi;
;         bf16x8 Af[2];
; #pragma unroll
;         for (int ks = 0; ks < 2; ++ks) Af[ks] = *(const LAS bf16x8*)(cxb + (m * 16 + fr) * CXS + 64 * h + 32 * ks + 8 * fq);
; template <int MODE>
; __device__ __forceinline__ void lru_unit(const Args& a, LAS unsigned char* lds, int l, int tt) {
;     ...
;     for (int nt = 0; nt < 2; ++nt) { prm0[nt][2] = -8.0f * log1pf(__expf(-prm0[nt][2])); prm1[nt][2] = -8.0f * log1pf(__expf(-prm1[nt][2])); }
	v_sub_f32_e32 v69, v71, v69
	v_add_f32_e32 v67, v67, v69
	v_sub_f32_e32 v68, v75, v68
	v_cvt_f32_i32_e32 v66, v66
	v_add_f32_e32 v67, v68, v67
	v_add_f32_e32 v68, v70, v73
	v_add_f32_e32 v67, v76, v67
	v_sub_f32_e32 v69, v68, v70
	v_mul_f32_e32 v67, v74, v67
	v_sub_f32_e32 v69, v73, v69
	v_add_f32_e32 v67, v69, v67
	v_mul_f32_e32 v73, 0x3f317218, v66
	v_add_f32_e32 v69, v68, v67
	v_fma_f32 v74, v66, s4, -v73
	v_mul_f32_e32 v70, v69, v69
	v_fmac_f32_e32 v74, 0xb102e308, v66
	v_sub_f32_e32 v66, v69, v68
	v_fmamk_f32 v71, v70, 0x3e9b6dac, v79
	v_sub_f32_e32 v66, v67, v66
	v_add_f32_e32 v67, v73, v74
	v_fmaak_f32 v71, v70, v71, 0x3f2aaada
	v_sub_f32_e32 v68, v67, v73
	v_ldexp_f32 v73, v69, 1
	v_mul_f32_e32 v69, v69, v70
	v_mul_f32_e32 v69, v69, v71
	v_add_f32_e32 v70, v73, v69
	v_sub_f32_e32 v71, v70, v73
	v_ldexp_f32 v66, v66, 1
	v_sub_f32_e32 v69, v69, v71
	v_add_f32_e32 v66, v66, v69
	v_add_f32_e32 v69, v70, v66
	v_sub_f32_e32 v70, v69, v70
	v_sub_f32_e32 v66, v66, v70
	v_add_f32_e32 v70, v67, v69
	v_sub_f32_e32 v71, v70, v67
	v_sub_f32_e32 v73, v70, v71
	v_sub_f32_e32 v68, v74, v68
	v_sub_f32_e32 v67, v67, v73
	v_sub_f32_e32 v69, v69, v71
	v_add_f32_e32 v67, v69, v67
	v_add_f32_e32 v69, v68, v66
	v_sub_f32_e32 v71, v69, v68
	v_sub_f32_e32 v73, v69, v71
	v_sub_f32_e32 v68, v68, v73
	v_sub_f32_e32 v66, v66, v71
	v_add_f32_e32 v67, v69, v67
	v_add_f32_e32 v66, v66, v68
	v_add_f32_e32 v68, v70, v67
	v_sub_f32_e32 v69, v68, v70
	v_sub_f32_e32 v67, v67, v69
	v_add_f32_e32 v66, v66, v67
	s_mov_b32 s5, 0x7f800000
	v_add_f32_e32 v66, v68, v66
	v_cmp_neq_f32_e32 vcc, s5, v72
	v_mov_b32_e32 v80, 0x7f800000
	v_mov_b32_e32 v81, 0x7fc00000
	v_cndmask_b32_e32 v66, v80, v66, vcc
	v_cmp_ngt_f32_e32 vcc, -1.0, v72
	v_mov_b32_e32 v82, 0xff800000
	s_mov_b32 s29, 0x33800000
	v_cndmask_b32_e32 v66, v81, v66, vcc
	v_cmp_neq_f32_e32 vcc, -1.0, v72
	v_mul_f32_e32 v67, 0xbfb8aa3b, v160
	v_exp_f32_e32 v116, v67
	v_cndmask_b32_e32 v66, v82, v66, vcc
	v_cmp_lt_f32_e64 vcc, |v72|, s29
	s_waitcnt lgkmcnt(0)
	v_add_f32_e32 v118, 1.0, v116
	v_cndmask_b32_e32 v66, v66, v72, vcc
	v_mul_f32_e32 v75, 0xc1000000, v66
	v_mul_f32_e32 v66, 0xbfb8aa3b, v159
	v_exp_f32_e32 v70, v66
	v_frexp_mant_f32_e32 v66, v118
	v_cmp_gt_f32_e32 vcc, s28, v66
	s_barrier
	v_add_f32_e32 v68, 1.0, v70
	v_add_f32_e32 v66, -1.0, v68
	v_sub_f32_e32 v67, v66, v68
	v_add_f32_e32 v67, 1.0, v67
	v_sub_f32_e32 v66, v70, v66
	v_add_f32_e32 v69, v66, v67
	v_frexp_mant_f32_e32 v71, v68
	v_cvt_f64_f32_e32 v[66:67], v68
	v_frexp_exp_i32_f64_e32 v66, v[66:67]
	v_cmp_gt_f32_e64 s[0:1], s28, v71
	v_and_b32_e32 v85, 64, v227
	s_nop 0
	v_subbrev_co_u32_e64 v66, s[0:1], 0, v66, s[0:1]
	v_sub_u32_e32 v67, 0, v66
	v_ldexp_f32 v68, v68, v67
	v_ldexp_f32 v67, v69, v67
	v_add_f32_e32 v69, -1.0, v68
	v_add_f32_e32 v73, 1.0, v68
	v_add_f32_e32 v71, 1.0, v69
	v_add_f32_e32 v74, -1.0, v73
	v_sub_f32_e32 v71, v68, v71
	v_sub_f32_e32 v68, v68, v74
	v_add_f32_e32 v71, v67, v71
	v_add_f32_e32 v67, v67, v68
	v_add_f32_e32 v68, v73, v67
	v_rcp_f32_e32 v74, v68
	v_add_f32_e32 v72, v69, v71
	v_sub_f32_e32 v69, v72, v69
	v_sub_f32_e32 v69, v71, v69
	v_sub_f32_e32 v71, v68, v73
	v_sub_f32_e32 v67, v67, v71
	v_mul_f32_e32 v71, v72, v74
	v_mul_f32_e32 v73, v68, v71
	v_fma_f32 v76, v71, v68, -v73
	v_fmac_f32_e32 v76, v71, v67
	v_add_f32_e32 v77, v73, v76
	v_sub_f32_e32 v78, v72, v77
	v_sub_f32_e32 v72, v72, v78
	v_sub_f32_e32 v73, v77, v73
	v_sub_f32_e32 v72, v72, v77
	v_add_f32_e32 v69, v69, v72
	v_sub_f32_e32 v72, v73, v76
	v_add_f32_e32 v69, v72, v69
	v_add_f32_e32 v72, v78, v69
	v_mul_f32_e32 v73, v74, v72
	v_mul_f32_e32 v76, v68, v73
	v_fma_f32 v68, v73, v68, -v76
	v_fmac_f32_e32 v68, v73, v67
	v_sub_f32_e32 v67, v78, v72
	v_add_f32_e32 v67, v69, v67
	v_add_f32_e32 v69, v76, v68
	v_sub_f32_e32 v77, v72, v69
	v_sub_f32_e32 v72, v72, v77
	v_sub_f32_e32 v76, v69, v76
	v_sub_f32_e32 v69, v72, v69
	v_add_f32_e32 v67, v67, v69
	v_sub_f32_e32 v68, v76, v68
	v_cvt_f32_i32_e32 v66, v66
	v_add_f32_e32 v67, v68, v67
	v_add_f32_e32 v68, v71, v73
	v_add_f32_e32 v67, v77, v67
	v_sub_f32_e32 v69, v68, v71
	v_mul_f32_e32 v67, v74, v67
	v_sub_f32_e32 v69, v73, v69
	v_add_f32_e32 v67, v69, v67
	v_mul_f32_e32 v73, 0x3f317218, v66
	v_add_f32_e32 v69, v68, v67
	v_fma_f32 v74, v66, s4, -v73
	v_mul_f32_e32 v71, v69, v69
	v_fmac_f32_e32 v74, 0xb102e308, v66
	v_sub_f32_e32 v66, v69, v68
	v_fmamk_f32 v72, v71, 0x3e9b6dac, v79
	v_sub_f32_e32 v66, v67, v66
	v_add_f32_e32 v67, v73, v74
	v_fmaak_f32 v72, v71, v72, 0x3f2aaada
	v_sub_f32_e32 v68, v67, v73
	v_ldexp_f32 v73, v69, 1
	v_mul_f32_e32 v69, v69, v71
	v_mul_f32_e32 v69, v69, v72
	v_add_f32_e32 v71, v73, v69
	v_sub_f32_e32 v72, v71, v73
	v_ldexp_f32 v66, v66, 1
	v_sub_f32_e32 v69, v69, v72
	v_add_f32_e32 v66, v66, v69
	v_add_f32_e32 v69, v71, v66
	v_sub_f32_e32 v71, v69, v71
	v_sub_f32_e32 v66, v66, v71
	v_add_f32_e32 v71, v67, v69
	v_sub_f32_e32 v72, v71, v67
	v_sub_f32_e32 v73, v71, v72
	v_sub_f32_e32 v68, v74, v68
	v_sub_f32_e32 v67, v67, v73
	v_sub_f32_e32 v69, v69, v72
	v_add_f32_e32 v67, v69, v67
	v_add_f32_e32 v69, v68, v66
	v_sub_f32_e32 v72, v69, v68
	v_sub_f32_e32 v73, v69, v72
	v_sub_f32_e32 v68, v68, v73
	v_sub_f32_e32 v66, v66, v72
	v_add_f32_e32 v67, v69, v67
	v_add_f32_e32 v66, v66, v68
	v_add_f32_e32 v68, v71, v67
	v_sub_f32_e32 v69, v68, v71
	v_sub_f32_e32 v67, v67, v69
	v_add_f32_e32 v66, v66, v67
	v_add_f32_e32 v66, v68, v66
	v_cmp_neq_f32_e64 s[0:1], s5, v70
	s_nop 1
	v_cndmask_b32_e64 v66, v80, v66, s[0:1]
	v_cmp_ngt_f32_e64 s[0:1], -1.0, v70
	s_nop 1
	v_cndmask_b32_e64 v71, v81, v66, s[0:1]
	v_mov_b32_e32 v66, v0
	s_nop 0
	v_readfirstlane_b32 s4, v66
	s_bfe_u32 s5, s4, 0x20006
	v_and_b32_e32 v84, 15, v66
	v_bfe_u32 v100, v66, 4, 2
	s_lshl_b32 s0, s5, 7
	s_add_i32 s0, s0, 0
	v_lshlrev_b32_e32 v66, 4, v100
	v_mul_u32_u24_e32 v67, 0x210, v84
	v_add3_u32 v127, s0, v66, v67
	ds_read_b128 v[66:69], v127
	v_cmp_neq_f32_e64 s[0:1], -1.0, v70
	v_cmp_eq_u32_e64 s[36:37], 0, v100
	s_nop 0
	v_cndmask_b32_e64 v71, v82, v71, s[0:1]
	v_cmp_lt_f32_e64 s[0:1], |v70|, s29
	s_nop 1
	v_cndmask_b32_e64 v70, v71, v70, s[0:1]
	v_mul_f32_e32 v104, 0xc1000000, v70
	v_mul_f32_e32 v70, 0xbfb8aa3b, v158
	v_exp_f32_e32 v117, v70
	ds_read_b128 v[70:73], v127 offset:64
	s_waitcnt lgkmcnt(1)
; __device__ __forceinline__ float fsig(float x) { return frcp(1.0f + __expf(-x)); }
; template <int DIR, int MODE>
; __device__ __forceinline__ void lru_pass(const Args& a, const LAS bf16_t* cxb, LAS bf16_t* gyb, const LAS float* carry, const bf16x8 (&Bw)[2][2][2], const float (&prm)[2][3], int l, int tt, float (&hf)[8][2][4]) {
;     ...
;         for (int nt = 0; nt < 2; ++nt) {
;             f32x4 pr = (f32x4){0.f, 0.f, 0.f, 0.f}, pi = (f32x4){0.f, 0.f, 0.f, 0.f};
; #pragma unroll
;             for (int ks = 0; ks < 2; ++ks) { pr = __builtin_amdgcn_mfma_f32_16x16x32_bf16(Af[ks], Bw[0][nt][ks], pr, 0, 0, 0); pi = __builtin_amdgcn_mfma_f32_16x16x32_bf16(Af[ks], Bw[1][nt][ks], pi, 0, 0, 0); }
;             float av[4], bv[4];
; #pragma unroll
;             for (int reg = 0; reg < 4; ++reg) {
;                 const int tok = m * 16 + 4 * fq + reg;
;                 const float x = bf2f(cxb[tok * CXS + cc[nt]]);
;                 const float r = fsig(pr[reg] + ba[nt]), ig = fsig(pi[reg] + bxv[nt]);
;                 const float aa = __expf(k8[nt] * r);
;                 av[reg] = aa; bv[reg] = __builtin_amdgcn_sqrtf(fmaxf(1.0f - aa * aa, 0.f)) * ig * x;
;             }
;             float cum[4], hl[4];
;             if (DIR == 0) { cum[0] = av[0]; hl[0] = bv[0];
; #pragma unroll
;                 for (int reg = 1; reg < 4; ++reg) { cum[reg] = cum[reg - 1] * av[reg]; hl[reg] = av[reg] * hl[reg - 1] + bv[reg]; } }
;             else { cum[3] = av[3]; hl[3] = bv[3];
; #pragma unroll
;     ...
;             const float A4 = DIR ? cum[0] : cum[3], H4 = DIR ? hl[0] : hl[3];
;             float Aq[4], Hq[4];
; #pragma unroll
;             for (int q = 0; q < 4; ++q) { Aq[q] = __shfl(A4, fr + 16 * q); Hq[q] = __shfl(H4, fr + 16 * q); }
	v_mfma_f32_16x16x32_bf16 v[76:79], v[66:69], v[54:57], 0
	s_ashr_i32 s1, s4, 3
	s_lshl_b32 s0, s5, 6
	s_andn2_b32 s1, s1, 31
	s_waitcnt lgkmcnt(0)
	v_mfma_f32_16x16x32_bf16 v[76:79], v[70:73], v[50:53], v[76:79]
	s_add_i32 s0, s0, s1
	v_or_b32_e32 v74, s0, v84
	v_or_b32_e32 v84, v85, v84
	s_nop 4
	v_add_f32_e32 v76, v157, v76
	v_mul_f32_e32 v76, 0xbfb8aa3b, v76
	v_exp_f32_e32 v76, v76
	v_mfma_f32_16x16x32_bf16 v[80:83], v[66:69], v[62:65], 0
	v_add_f32_e32 v77, v157, v77
	v_mul_f32_e32 v77, 0xbfb8aa3b, v77
	v_add_f32_e32 v76, 1.0, v76
	v_rcp_f32_e32 v76, v76
	v_mfma_f32_16x16x32_bf16 v[80:83], v[70:73], v[58:61], v[80:83]
	v_exp_f32_e32 v77, v77
	v_add_f32_e32 v78, v157, v78
	v_mul_f32_e32 v76, v75, v76
	v_mul_f32_e32 v76, 0x3fb8aa3b, v76
	v_add_f32_e32 v77, 1.0, v77
	s_nop 2
	v_add_f32_e32 v80, v156, v80
	v_mul_f32_e32 v80, 0xbfb8aa3b, v80
	v_exp_f32_e32 v76, v76
	v_rcp_f32_e32 v77, v77
	v_mul_f32_e32 v78, 0xbfb8aa3b, v78
	v_add_f32_e32 v79, v157, v79
	v_exp_f32_e32 v80, v80
	v_exp_f32_e32 v78, v78
	v_mul_f32_e32 v79, 0xbfb8aa3b, v79
	v_exp_f32_e32 v79, v79
	v_lshlrev_b32_e32 v102, 2, v84
	v_lshlrev_b32_e32 v84, 1, v74
	v_mul_u32_u24_e32 v85, 0x840, v100
	v_add3_u32 v106, 0, v84, v85
	v_fma_f32 v84, -v76, v76, 1.0
	v_mul_f32_e32 v77, v75, v77
	v_add_f32_e32 v80, 1.0, v80
	v_max_f32_e32 v84, 0, v84
	v_add_f32_e32 v81, v156, v81
	v_mul_f32_e32 v77, 0x3fb8aa3b, v77
	v_add_f32_e32 v78, 1.0, v78
	v_rcp_f32_e32 v80, v80
	v_sqrt_f32_e32 v84, v84
	v_mul_f32_e32 v81, 0xbfb8aa3b, v81
	v_exp_f32_e32 v77, v77
	v_rcp_f32_e32 v78, v78
	v_add_f32_e32 v79, 1.0, v79
	v_exp_f32_e32 v81, v81
	v_rcp_f32_e32 v79, v79
	v_mul_f32_e32 v80, v80, v84
	v_fma_f32 v84, -v77, v77, 1.0
	v_mul_f32_e32 v78, v75, v78
	v_add_f32_e32 v81, 1.0, v81
	v_max_f32_e32 v84, 0, v84
	v_add_f32_e32 v82, v156, v82
	v_mul_f32_e32 v78, 0x3fb8aa3b, v78
	v_mul_f32_e32 v79, v75, v79
	v_rcp_f32_e32 v81, v81
	v_sqrt_f32_e32 v84, v84
	v_mul_f32_e32 v82, 0xbfb8aa3b, v82
	v_exp_f32_e32 v78, v78
	v_add_f32_e32 v83, v156, v83
	v_mul_f32_e32 v79, 0x3fb8aa3b, v79
	v_exp_f32_e32 v82, v82
	v_mul_f32_e32 v83, 0xbfb8aa3b, v83
	v_exp_f32_e32 v79, v79
	v_exp_f32_e32 v83, v83
	ds_read_u16 v85, v106
	ds_read_u16 v86, v106 offset:32
	ds_read_u16 v87, v106 offset:528
	ds_read_u16 v88, v106 offset:1056
	ds_read_u16 v89, v106 offset:1584
	ds_read_u16 v90, v106 offset:1616
	ds_read_u16 v91, v106 offset:1088
	ds_read_u16 v92, v106 offset:560
	s_waitcnt lgkmcnt(7)
	v_lshlrev_b32_e32 v85, 16, v85
	v_mul_f32_e32 v81, v81, v84
	v_fma_f32 v84, -v78, v78, 1.0
	v_mul_f32_e32 v80, v80, v85
	s_waitcnt lgkmcnt(5)
	v_lshlrev_b32_e32 v85, 16, v87
	v_add_f32_e32 v82, 1.0, v82
	v_max_f32_e32 v84, 0, v84
	v_fma_f32 v87, -v79, v79, 1.0
	v_rcp_f32_e32 v82, v82
	v_sqrt_f32_e32 v84, v84
	v_add_f32_e32 v83, 1.0, v83
	v_max_f32_e32 v87, 0, v87
	v_rcp_f32_e32 v83, v83
	v_sqrt_f32_e32 v87, v87
	v_mul_f32_e32 v76, v77, v76
	v_mul_f32_e32 v77, v77, v80
	v_fmac_f32_e32 v77, v81, v85
	s_waitcnt lgkmcnt(4)
	v_lshlrev_b32_e32 v88, 16, v88
	v_mul_f32_e32 v82, v82, v84
	v_mul_f32_e32 v77, v78, v77
	v_mul_f32_e32 v87, v83, v87
	v_fmac_f32_e32 v77, v82, v88
	v_mfma_f32_16x16x32_bf16 v[80:83], v[66:69], v[38:41], 0
	s_waitcnt lgkmcnt(3)
	v_lshlrev_b32_e32 v84, 16, v89
	v_mul_f32_e32 v77, v79, v77
	v_fmac_f32_e32 v77, v87, v84
	v_mfma_f32_16x16x32_bf16 v[82:85], v[70:73], v[34:37], v[80:83]
	v_mul_f32_e32 v76, v78, v76
	v_mul_f32_e32 v88, v79, v76
	s_nop 0
	v_mfma_f32_16x16x32_bf16 v[66:69], v[66:69], v[46:49], 0
	s_nop 0
	s_nop 2
	v_add_f32_e32 v79, v155, v82
	v_mul_f32_e32 v79, 0xbfb8aa3b, v79
	v_exp_f32_e32 v79, v79
	v_mfma_f32_16x16x32_bf16 v[66:69], v[70:73], v[42:45], v[66:69]
	v_lshlrev_b32_e32 v72, 16, v86
	s_nop 0
	v_add_f32_e32 v70, 1.0, v79
	v_rcp_f32_e32 v70, v70
	v_mov_b32_e32 v119, v77
	v_mov_b32_e32 v120, v77
	s_nop 1
	v_permlane16_swap_b32_e32 v119, v120
	s_nop 1
	v_mov_b32_e32 v121, v119
	v_mov_b32_e32 v122, v120
	s_nop 1
	v_permlane32_swap_b32_e32 v119, v121
	v_permlane32_swap_b32_e32 v120, v122
	s_nop 1
	s_nop 2
	v_add_f32_e32 v66, v154, v66
	v_mul_f32_e32 v66, 0xbfb8aa3b, v66
	v_mul_f32_e32 v70, v104, v70
	v_mul_f32_e32 v70, 0x3fb8aa3b, v70
	v_exp_f32_e32 v70, v70
	v_exp_f32_e32 v66, v66
	v_add_f32_e32 v67, v154, v67
	v_mul_f32_e32 v67, 0xbfb8aa3b, v67
	v_fma_f32 v71, -v70, v70, 1.0
	v_add_f32_e32 v66, 1.0, v66
	v_max_f32_e32 v71, 0, v71
	v_rcp_f32_e32 v66, v66
	v_sqrt_f32_e32 v71, v71
	v_exp_f32_e32 v67, v67
	v_add_f32_e32 v68, v154, v68
	v_add_f32_e32 v69, v154, v69
	v_mul_f32_e32 v66, v66, v71
	v_mul_f32_e32 v66, v66, v72
	v_add_f32_e32 v72, v155, v84
	v_mul_f32_e32 v72, 0xbfb8aa3b, v72
	v_exp_f32_e32 v72, v72
	v_add_f32_e32 v71, v155, v83
	v_mul_f32_e32 v71, 0xbfb8aa3b, v71
	v_exp_f32_e32 v71, v71
	v_add_f32_e32 v72, 1.0, v72
	v_rcp_f32_e32 v72, v72
	v_add_f32_e32 v67, 1.0, v67
	v_add_f32_e32 v71, 1.0, v71
	v_rcp_f32_e32 v71, v71
	v_mul_f32_e32 v72, v104, v72
	v_mul_f32_e32 v72, 0x3fb8aa3b, v72
	v_exp_f32_e32 v79, v72
	v_add_f32_e32 v72, v155, v85
	v_mul_f32_e32 v72, 0xbfb8aa3b, v72
	v_exp_f32_e32 v72, v72
	v_mul_f32_e32 v71, v104, v71
	v_mul_f32_e32 v71, 0x3fb8aa3b, v71
	v_exp_f32_e32 v71, v71
	v_add_f32_e32 v72, 1.0, v72
	v_rcp_f32_e32 v72, v72
	v_rcp_f32_e32 v67, v67
	v_fma_f32 v73, -v71, v71, 1.0
	v_max_f32_e32 v73, 0, v73
	v_sqrt_f32_e32 v73, v73
	v_mul_f32_e32 v72, v104, v72
	v_mul_f32_e32 v72, 0x3fb8aa3b, v72
	v_mul_f32_e32 v68, 0xbfb8aa3b, v68
	v_mul_f32_e32 v69, 0xbfb8aa3b, v69
	v_exp_f32_e32 v81, v72
	v_exp_f32_e32 v68, v68
	v_exp_f32_e32 v69, v69
	v_mul_f32_e32 v67, v67, v73
	v_fma_f32 v73, -v79, v79, 1.0
	v_max_f32_e32 v73, 0, v73
	v_sqrt_f32_e32 v72, v73
	v_fma_f32 v73, -v81, v81, 1.0
	v_add_f32_e32 v68, 1.0, v68
	v_add_f32_e32 v69, 1.0, v69
	v_max_f32_e32 v73, 0, v73
	v_rcp_f32_e32 v68, v68
	v_rcp_f32_e32 v69, v69
	v_sqrt_f32_e32 v73, v73
	s_waitcnt lgkmcnt(0)
; __device__ __forceinline__ float fsig(float x) { return frcp(1.0f + __expf(-x)); }
; template <int DIR, int MODE>
; __device__ __forceinline__ void lru_pass(const Args& a, const LAS bf16_t* cxb, LAS bf16_t* gyb, const LAS float* carry, const bf16x8 (&Bw)[2][2][2], const float (&prm)[2][3], int l, int tt, float (&hf)[8][2][4]) {
;     ...
;         for (int nt = 0; nt < 2; ++nt) {
;             f32x4 pr = (f32x4){0.f, 0.f, 0.f, 0.f}, pi = (f32x4){0.f, 0.f, 0.f, 0.f};
; #pragma unroll
;             for (int ks = 0; ks < 2; ++ks) { pr = __builtin_amdgcn_mfma_f32_16x16x32_bf16(Af[ks], Bw[0][nt][ks], pr, 0, 0, 0); pi = __builtin_amdgcn_mfma_f32_16x16x32_bf16(Af[ks], Bw[1][nt][ks], pi, 0, 0, 0); }
;             float av[4], bv[4];
; #pragma unroll
;             for (int reg = 0; reg < 4; ++reg) {
;                 const int tok = m * 16 + 4 * fq + reg;
;                 const float x = bf2f(cxb[tok * CXS + cc[nt]]);
;                 const float r = fsig(pr[reg] + ba[nt]), ig = fsig(pi[reg] + bxv[nt]);
;                 const float aa = __expf(k8[nt] * r);
;                 av[reg] = aa; bv[reg] = __builtin_amdgcn_sqrtf(fmaxf(1.0f - aa * aa, 0.f)) * ig * x;
;             }
;             float cum[4], hl[4];
;             if (DIR == 0) { cum[0] = av[0]; hl[0] = bv[0];
; #pragma unroll
;                 for (int reg = 1; reg < 4; ++reg) { cum[reg] = cum[reg - 1] * av[reg]; hl[reg] = av[reg] * hl[reg - 1] + bv[reg]; } }
;             else { cum[3] = av[3]; hl[3] = bv[3];
; #pragma unroll
;     ...
;             const float A4 = DIR ? cum[0] : cum[3], H4 = DIR ? hl[0] : hl[3];
;             float Aq[4], Hq[4];
; #pragma unroll
;             for (int q = 0; q < 4; ++q) { Aq[q] = __shfl(A4, fr + 16 * q); Hq[q] = __shfl(H4, fr + 16 * q); }
;             float hin;
;             if (DIR == 0) { const float s0 = C[nt], s1 = Aq[0] * s0 + Hq[0], s2 = Aq[1] * s1 + Hq[1], s3 = Aq[2] * s2 + Hq[2]; C[nt] = Aq[3] * s3 + Hq[3]; hin = fq == 0 ? s0 : (fq == 1 ? s1 : (fq == 2 ? s2 : s3)); }
;             else { const float s3 = C[nt], s2 = Aq[3] * s3 + Hq[3], s1 = Aq[2] * s2 + Hq[2], s0 = Aq[1] * s1 + Hq[1]; C[nt] = Aq[0] * s0 + Hq[0]; hin = fq == 3 ? s3 : (fq == 2 ? s2 : (fq == 1 ? s1 : s0)); }
;             if (MODE == 0) At[nt] *= (Aq[0] * Aq[1]) * (Aq[2] * Aq[3]);
	v_lshlrev_b32_e32 v77, 16, v92
	v_mul_f32_e32 v66, v71, v66
	v_mul_f32_e32 v68, v68, v72
	v_mul_f32_e32 v69, v69, v73
	v_mul_f32_e32 v85, v71, v70
	ds_read_b128 v[70:73], v127 offset:8448
	v_fmac_f32_e32 v66, v67, v77
	v_lshlrev_b32_e32 v83, 16, v91
	v_mul_f32_e32 v66, v79, v66
	v_fmac_f32_e32 v66, v68, v83
	v_lshlrev_b32_e32 v84, 16, v90
	v_mul_f32_e32 v67, v79, v85
	v_mul_f32_e32 v79, v81, v66
	v_mul_f32_e32 v77, v81, v67
	v_fmac_f32_e32 v79, v69, v84
	ds_read_b128 v[66:69], v127 offset:8512
	s_waitcnt lgkmcnt(1)
	v_mfma_f32_16x16x32_bf16 v[90:93], v[70:73], v[54:57], 0
	s_nop 0
	s_nop 0
	s_nop 0
	s_waitcnt lgkmcnt(0)
	v_mfma_f32_16x16x32_bf16 v[90:93], v[66:69], v[50:53], v[90:93]
	v_mov_b32_e32 v76, v88
	v_mov_b32_e32 v78, v88
	s_nop 1
	v_permlane16_swap_b32_e32 v76, v78
	s_nop 1
	v_mov_b32_e32 v80, v76
	v_mov_b32_e32 v82, v78
	s_nop 1
	v_permlane32_swap_b32_e32 v76, v80
	v_permlane32_swap_b32_e32 v78, v82
	s_nop 1
	ds_bpermute_b32 v86, v102, v77
	ds_bpermute_b32 v84, v102, v77 offset:64
	s_nop 4
	v_add_f32_e32 v81, v157, v90
	v_mul_f32_e32 v81, 0xbfb8aa3b, v81
	v_exp_f32_e32 v81, v81
	v_mfma_f32_16x16x32_bf16 v[94:97], v[70:73], v[62:65], 0
	ds_bpermute_b32 v88, v102, v77 offset:128
	ds_bpermute_b32 v90, v102, v77 offset:192
	v_add_f32_e32 v77, 1.0, v81
	v_mfma_f32_16x16x32_bf16 v[94:97], v[66:69], v[58:61], v[94:97]
	v_rcp_f32_e32 v77, v77
	s_nop 0
	s_nop 0
	s_nop 0
	v_mul_f32_e32 v77, v75, v77
	s_nop 2
	v_add_f32_e32 v81, v156, v94
	v_mul_f32_e32 v81, 0xbfb8aa3b, v81
	v_mul_f32_e32 v77, 0x3fb8aa3b, v77
	v_exp_f32_e32 v81, v81
	v_exp_f32_e32 v77, v77
	v_mov_b32_e32 v123, v79
	v_mov_b32_e32 v124, v79
	s_nop 1
	v_permlane16_swap_b32_e32 v123, v124
	s_nop 1
	v_mov_b32_e32 v125, v123
	v_mov_b32_e32 v126, v124
	s_nop 1
	v_permlane32_swap_b32_e32 v123, v125
	v_permlane32_swap_b32_e32 v124, v126
	s_nop 1
	ds_read_u16 v83, v106 offset:8448
	ds_read_u16 v85, v106 offset:8976
	ds_read_u16 v87, v106 offset:9504
	ds_read_u16 v89, v106 offset:10032
	ds_read_u16 v98, v106 offset:10064
	ds_read_u16 v99, v106 offset:9536
	ds_read_u16 v101, v106 offset:9008
	ds_read_u16 v103, v106 offset:8480
	v_add_f32_e32 v79, 1.0, v81
	v_fma_f32 v81, -v77, v77, 1.0
	v_max_f32_e32 v81, 0, v81
	v_rcp_f32_e32 v79, v79
	v_sqrt_f32_e32 v81, v81
	s_waitcnt lgkmcnt(7)
	v_lshlrev_b32_e32 v83, 16, v83
	v_add_f32_e32 v93, v157, v93
	v_mul_f32_e32 v93, 0xbfb8aa3b, v93
	v_mul_f32_e32 v79, v79, v81
	v_add_f32_e32 v81, v157, v91
	v_add_f32_e32 v91, v156, v95
	v_mul_f32_e32 v81, 0xbfb8aa3b, v81
	v_mul_f32_e32 v91, 0xbfb8aa3b, v91
	v_exp_f32_e32 v81, v81
	v_exp_f32_e32 v91, v91
	v_mul_f32_e32 v79, v79, v83
	v_exp_f32_e32 v93, v93
	v_add_f32_e32 v81, 1.0, v81
	v_add_f32_e32 v83, 1.0, v91
	v_add_f32_e32 v91, v157, v92
	v_rcp_f32_e32 v81, v81
	v_mul_f32_e32 v91, 0xbfb8aa3b, v91
	v_exp_f32_e32 v91, v91
	v_add_f32_e32 v93, 1.0, v93
	v_mul_f32_e32 v81, v75, v81
	v_mul_f32_e32 v81, 0x3fb8aa3b, v81
	v_add_f32_e32 v91, 1.0, v91
	v_exp_f32_e32 v81, v81
	v_rcp_f32_e32 v91, v91
	v_rcp_f32_e32 v93, v93
	v_add_f32_e32 v94, v156, v96
	v_fma_f32 v92, -v81, v81, 1.0
	v_mul_f32_e32 v91, v75, v91
	v_max_f32_e32 v92, 0, v92
	v_mul_f32_e32 v94, 0xbfb8aa3b, v94
	v_mul_f32_e32 v91, 0x3fb8aa3b, v91
	v_rcp_f32_e32 v83, v83
	v_sqrt_f32_e32 v92, v92
	v_exp_f32_e32 v94, v94
	v_exp_f32_e32 v91, v91
	v_add_f32_e32 v95, v156, v97
	v_mul_f32_e32 v93, v75, v93
	v_mul_f32_e32 v95, 0xbfb8aa3b, v95
	v_mul_f32_e32 v93, 0x3fb8aa3b, v93
	v_exp_f32_e32 v95, v95
	v_exp_f32_e32 v96, v93
	v_mul_f32_e32 v83, v83, v92
	v_add_f32_e32 v92, 1.0, v94
	v_fma_f32 v94, -v91, v91, 1.0
	v_max_f32_e32 v94, 0, v94
	v_sqrt_f32_e32 v93, v94
	v_add_f32_e32 v94, 1.0, v95
	v_fma_f32 v95, -v96, v96, 1.0
	v_rcp_f32_e32 v92, v92
	v_max_f32_e32 v95, 0, v95
	v_rcp_f32_e32 v94, v94
	v_sqrt_f32_e32 v95, v95
	s_waitcnt lgkmcnt(6)
	v_lshlrev_b32_e32 v85, 16, v85
	v_mul_f32_e32 v79, v81, v79
	v_fmac_f32_e32 v79, v83, v85
	s_waitcnt lgkmcnt(5)
	v_lshlrev_b32_e32 v87, 16, v87
	v_mul_f32_e32 v92, v92, v93
	v_mul_f32_e32 v79, v91, v79
	v_mul_f32_e32 v97, v94, v95
	v_fmac_f32_e32 v79, v92, v87
	v_mfma_f32_16x16x32_bf16 v[92:95], v[70:73], v[38:41], 0
	v_mul_f32_e32 v77, v81, v77
	s_waitcnt lgkmcnt(4)
	v_lshlrev_b32_e32 v89, 16, v89
	v_mul_f32_e32 v85, v96, v79
	v_mfma_f32_16x16x32_bf16 v[92:95], v[66:69], v[34:37], v[92:95]
	v_fmac_f32_e32 v85, v97, v89
	s_nop 0
	s_nop 0
	v_mfma_f32_16x16x32_bf16 v[70:73], v[70:73], v[46:49], 0
	s_nop 0
	s_nop 2
	v_add_f32_e32 v81, v155, v92
	v_mul_f32_e32 v81, 0xbfb8aa3b, v81
	v_exp_f32_e32 v87, v81
	v_mfma_f32_16x16x32_bf16 v[66:69], v[66:69], v[42:45], v[70:73]
	v_mov_b32_e32 v128, v85
	v_mov_b32_e32 v129, v85
	s_nop 1
	v_permlane16_swap_b32_e32 v128, v129
	s_nop 1
	v_mov_b32_e32 v130, v128
	v_mov_b32_e32 v131, v129
	s_nop 1
	v_permlane32_swap_b32_e32 v128, v130
	v_permlane32_swap_b32_e32 v129, v131
	s_nop 1
	s_waitcnt lgkmcnt(1)
	v_lshlrev_b32_e32 v85, 16, v101
	v_mul_f32_e32 v77, v91, v77
	v_add_f32_e32 v70, 1.0, v87
	v_rcp_f32_e32 v70, v70
	s_nop 1
	v_add_f32_e32 v66, v154, v66
	v_mul_f32_e32 v66, 0xbfb8aa3b, v66
	v_exp_f32_e32 v66, v66
	v_mul_f32_e32 v70, v104, v70
	v_mul_f32_e32 v70, 0x3fb8aa3b, v70
	v_exp_f32_e32 v70, v70
	v_add_f32_e32 v66, 1.0, v66
	v_rcp_f32_e32 v66, v66
	s_waitcnt lgkmcnt(0)
; __device__ __forceinline__ float fsig(float x) { return frcp(1.0f + __expf(-x)); }
; template <int DIR, int MODE>
; __device__ __forceinline__ void lru_pass(const Args& a, const LAS bf16_t* cxb, LAS bf16_t* gyb, const LAS float* carry, const bf16x8 (&Bw)[2][2][2], const float (&prm)[2][3], int l, int tt, float (&hf)[8][2][4]) {
;     ...
;         for (int nt = 0; nt < 2; ++nt) {
;             f32x4 pr = (f32x4){0.f, 0.f, 0.f, 0.f}, pi = (f32x4){0.f, 0.f, 0.f, 0.f};
; #pragma unroll
;             for (int ks = 0; ks < 2; ++ks) { pr = __builtin_amdgcn_mfma_f32_16x16x32_bf16(Af[ks], Bw[0][nt][ks], pr, 0, 0, 0); pi = __builtin_amdgcn_mfma_f32_16x16x32_bf16(Af[ks], Bw[1][nt][ks], pi, 0, 0, 0); }
;             float av[4], bv[4];
; #pragma unroll
;             for (int reg = 0; reg < 4; ++reg) {
;                 const int tok = m * 16 + 4 * fq + reg;
;                 const float x = bf2f(cxb[tok * CXS + cc[nt]]);
;                 const float r = fsig(pr[reg] + ba[nt]), ig = fsig(pi[reg] + bxv[nt]);
;                 const float aa = __expf(k8[nt] * r);
;                 av[reg] = aa; bv[reg] = __builtin_amdgcn_sqrtf(fmaxf(1.0f - aa * aa, 0.f)) * ig * x;
;             }
;             float cum[4], hl[4];
;             if (DIR == 0) { cum[0] = av[0]; hl[0] = bv[0];
; #pragma unroll
;                 for (int reg = 1; reg < 4; ++reg) { cum[reg] = cum[reg - 1] * av[reg]; hl[reg] = av[reg] * hl[reg - 1] + bv[reg]; } }
;             else { cum[3] = av[3]; hl[3] = bv[3];
; #pragma unroll
;     ...
;             const float A4 = DIR ? cum[0] : cum[3], H4 = DIR ? hl[0] : hl[3];
;             float Aq[4], Hq[4];
; #pragma unroll
;             for (int q = 0; q < 4; ++q) { Aq[q] = __shfl(A4, fr + 16 * q); Hq[q] = __shfl(H4, fr + 16 * q); }
;             float hin;
;             if (DIR == 0) { const float s0 = C[nt], s1 = Aq[0] * s0 + Hq[0], s2 = Aq[1] * s1 + Hq[1], s3 = Aq[2] * s2 + Hq[2]; C[nt] = Aq[3] * s3 + Hq[3]; hin = fq == 0 ? s0 : (fq == 1 ? s1 : (fq == 2 ? s2 : s3)); }
;             else { const float s3 = C[nt], s2 = Aq[3] * s3 + Hq[3], s1 = Aq[2] * s2 + Hq[2], s0 = Aq[1] * s1 + Hq[1]; C[nt] = Aq[0] * s0 + Hq[0]; hin = fq == 3 ? s3 : (fq == 2 ? s2 : (fq == 1 ? s1 : s0)); }
;             if (MODE == 0) At[nt] *= (Aq[0] * Aq[1]) * (Aq[2] * Aq[3]);
	v_lshlrev_b32_e32 v72, 16, v103
	v_fma_f32 v71, -v70, v70, 1.0
	v_max_f32_e32 v71, 0, v71
	v_sqrt_f32_e32 v71, v71
	v_add_f32_e32 v67, v154, v67
	v_mul_f32_e32 v67, 0xbfb8aa3b, v67
	v_exp_f32_e32 v67, v67
	v_mul_f32_e32 v66, v66, v71
	v_mul_f32_e32 v66, v66, v72
	v_add_f32_e32 v72, v155, v94
	v_mul_f32_e32 v72, 0xbfb8aa3b, v72
	v_exp_f32_e32 v72, v72
	v_add_f32_e32 v71, v155, v93
	v_mul_f32_e32 v71, 0xbfb8aa3b, v71
	v_exp_f32_e32 v71, v71
	v_add_f32_e32 v72, 1.0, v72
	v_rcp_f32_e32 v72, v72
	v_add_f32_e32 v67, 1.0, v67
	v_add_f32_e32 v71, 1.0, v71
	v_rcp_f32_e32 v71, v71
	v_mul_f32_e32 v72, v104, v72
	v_mul_f32_e32 v72, 0x3fb8aa3b, v72
	v_exp_f32_e32 v87, v72
	v_add_f32_e32 v72, v155, v95
	v_mul_f32_e32 v72, 0xbfb8aa3b, v72
	v_exp_f32_e32 v72, v72
	v_mul_f32_e32 v71, v104, v71
	v_mul_f32_e32 v71, 0x3fb8aa3b, v71
	v_exp_f32_e32 v71, v71
	v_add_f32_e32 v72, 1.0, v72
	v_rcp_f32_e32 v72, v72
	v_rcp_f32_e32 v67, v67
	v_fma_f32 v73, -v71, v71, 1.0
	v_max_f32_e32 v73, 0, v73
	v_sqrt_f32_e32 v73, v73
	v_mul_f32_e32 v72, v104, v72
	v_add_f32_e32 v68, v154, v68
	v_add_f32_e32 v69, v154, v69
	v_mul_f32_e32 v72, 0x3fb8aa3b, v72
	v_mul_f32_e32 v68, 0xbfb8aa3b, v68
	v_mul_f32_e32 v69, 0xbfb8aa3b, v69
	v_exp_f32_e32 v89, v72
	v_exp_f32_e32 v68, v68
	v_exp_f32_e32 v69, v69
	v_mul_f32_e32 v67, v67, v73
	v_fma_f32 v73, -v87, v87, 1.0
	v_max_f32_e32 v73, 0, v73
	v_sqrt_f32_e32 v72, v73
	v_fma_f32 v73, -v89, v89, 1.0
	v_add_f32_e32 v68, 1.0, v68
	v_add_f32_e32 v69, 1.0, v69
	v_max_f32_e32 v73, 0, v73
	v_rcp_f32_e32 v68, v68
	v_rcp_f32_e32 v69, v69
	v_sqrt_f32_e32 v73, v73
	v_mul_f32_e32 v66, v71, v66
	v_mul_f32_e32 v68, v68, v72
	v_mul_f32_e32 v93, v71, v70
	v_mul_f32_e32 v69, v69, v73
	ds_read_b128 v[70:73], v127 offset:16896
	v_fmac_f32_e32 v66, v67, v85
	v_lshlrev_b32_e32 v91, 16, v99
	v_mul_f32_e32 v66, v87, v66
	v_fmac_f32_e32 v66, v68, v91
	v_lshlrev_b32_e32 v92, 16, v98
	v_mul_f32_e32 v67, v87, v93
	v_mul_f32_e32 v101, v89, v66
	v_mul_f32_e32 v91, v89, v67
	v_fmac_f32_e32 v101, v69, v92
	ds_read_b128 v[66:69], v127 offset:16960
	s_waitcnt lgkmcnt(1)
	v_mfma_f32_16x16x32_bf16 v[92:95], v[70:73], v[54:57], 0
	v_mul_f32_e32 v83, v96, v77
	s_nop 0
	s_nop 0
	s_waitcnt lgkmcnt(0)
	v_mfma_f32_16x16x32_bf16 v[92:95], v[66:69], v[50:53], v[92:95]
	s_nop 0
	v_mov_b32_e32 v132, v101
	v_mov_b32_e32 v133, v101
	s_nop 1
	v_permlane16_swap_b32_e32 v132, v133
	s_nop 1
	v_mov_b32_e32 v134, v132
	v_mov_b32_e32 v135, v133
	s_nop 1
	v_permlane32_swap_b32_e32 v132, v134
	v_permlane32_swap_b32_e32 v133, v135
	s_nop 1
	ds_read_u16 v103, v106 offset:16896
	ds_read_u16 v105, v106 offset:17424
	ds_read_u16 v107, v106 offset:17952
	ds_read_u16 v108, v106 offset:18480
	ds_read_u16 v109, v106 offset:18512
	ds_read_u16 v110, v106 offset:17984
	ds_read_u16 v111, v106 offset:17456
	ds_read_u16 v112, v106 offset:16928
	v_add_f32_e32 v92, v157, v92
	v_mul_f32_e32 v92, 0xbfb8aa3b, v92
	v_exp_f32_e32 v92, v92
	v_mfma_f32_16x16x32_bf16 v[96:99], v[70:73], v[62:65], 0
	v_add_f32_e32 v93, v157, v93
	v_mul_f32_e32 v93, 0xbfb8aa3b, v93
	v_add_f32_e32 v92, 1.0, v92
	v_rcp_f32_e32 v92, v92
	v_mfma_f32_16x16x32_bf16 v[96:99], v[66:69], v[58:61], v[96:99]
	v_exp_f32_e32 v93, v93
	v_add_f32_e32 v94, v157, v94
	v_mul_f32_e32 v92, v75, v92
	v_mul_f32_e32 v92, 0x3fb8aa3b, v92
	v_add_f32_e32 v93, 1.0, v93
	s_nop 2
	v_add_f32_e32 v96, v156, v96
	v_mul_f32_e32 v96, 0xbfb8aa3b, v96
	v_exp_f32_e32 v92, v92
	v_rcp_f32_e32 v93, v93
	v_mul_f32_e32 v94, 0xbfb8aa3b, v94
	v_add_f32_e32 v95, v157, v95
	v_exp_f32_e32 v96, v96
	v_exp_f32_e32 v94, v94
	v_mul_f32_e32 v95, 0xbfb8aa3b, v95
	v_exp_f32_e32 v95, v95
	v_fma_f32 v101, -v92, v92, 1.0
	v_mul_f32_e32 v93, v75, v93
	v_add_f32_e32 v96, 1.0, v96
	v_max_f32_e32 v101, 0, v101
	v_add_f32_e32 v97, v156, v97
	v_mul_f32_e32 v93, 0x3fb8aa3b, v93
	v_add_f32_e32 v94, 1.0, v94
	v_rcp_f32_e32 v96, v96
	v_sqrt_f32_e32 v101, v101
	v_mul_f32_e32 v97, 0xbfb8aa3b, v97
	v_exp_f32_e32 v93, v93
	v_rcp_f32_e32 v94, v94
	v_add_f32_e32 v95, 1.0, v95
	v_exp_f32_e32 v97, v97
	v_rcp_f32_e32 v95, v95
	v_mul_f32_e32 v96, v96, v101
	v_fma_f32 v101, -v93, v93, 1.0
	v_mul_f32_e32 v94, v75, v94
	v_add_f32_e32 v97, 1.0, v97
	v_max_f32_e32 v101, 0, v101
	v_add_f32_e32 v98, v156, v98
	v_mul_f32_e32 v94, 0x3fb8aa3b, v94
	v_mul_f32_e32 v95, v75, v95
	v_rcp_f32_e32 v97, v97
	v_sqrt_f32_e32 v101, v101
	v_mul_f32_e32 v98, 0xbfb8aa3b, v98
	v_exp_f32_e32 v94, v94
	v_add_f32_e32 v99, v156, v99
	v_mul_f32_e32 v95, 0x3fb8aa3b, v95
	v_exp_f32_e32 v98, v98
	v_mul_f32_e32 v99, 0xbfb8aa3b, v99
	v_exp_f32_e32 v95, v95
	v_exp_f32_e32 v99, v99
	s_waitcnt lgkmcnt(7)
	v_lshlrev_b32_e32 v103, 16, v103
	v_mul_f32_e32 v97, v97, v101
	v_fma_f32 v101, -v94, v94, 1.0
	v_mul_f32_e32 v96, v96, v103
	s_waitcnt lgkmcnt(6)
	v_lshlrev_b32_e32 v103, 16, v105
	v_add_f32_e32 v98, 1.0, v98
	v_max_f32_e32 v101, 0, v101
	v_fma_f32 v105, -v95, v95, 1.0
	v_rcp_f32_e32 v98, v98
	v_sqrt_f32_e32 v101, v101
	v_add_f32_e32 v99, 1.0, v99
	v_max_f32_e32 v105, 0, v105
	v_rcp_f32_e32 v99, v99
	v_sqrt_f32_e32 v105, v105
	v_mul_f32_e32 v92, v93, v92
	v_mul_f32_e32 v93, v93, v96
	v_fmac_f32_e32 v93, v97, v103
	s_waitcnt lgkmcnt(5)
	v_lshlrev_b32_e32 v107, 16, v107
	v_mul_f32_e32 v98, v98, v101
	v_mul_f32_e32 v93, v94, v93
	v_mul_f32_e32 v105, v99, v105
	v_fmac_f32_e32 v93, v98, v107
	v_mfma_f32_16x16x32_bf16 v[96:99], v[70:73], v[38:41], 0
	v_mul_f32_e32 v107, v95, v93
	v_mul_f32_e32 v92, v94, v92
	v_mul_f32_e32 v103, v95, v92
	v_mfma_f32_16x16x32_bf16 v[96:99], v[66:69], v[34:37], v[96:99]
	ds_bpermute_b32 v92, v102, v103
	ds_bpermute_b32 v94, v102, v103 offset:64
	s_waitcnt lgkmcnt(6)
; __device__ __forceinline__ float fsig(float x) { return frcp(1.0f + __expf(-x)); }
; template <int DIR, int MODE>
; __device__ __forceinline__ void lru_pass(const Args& a, const LAS bf16_t* cxb, LAS bf16_t* gyb, const LAS float* carry, const bf16x8 (&Bw)[2][2][2], const float (&prm)[2][3], int l, int tt, float (&hf)[8][2][4]) {
;     ...
;         for (int nt = 0; nt < 2; ++nt) {
;             f32x4 pr = (f32x4){0.f, 0.f, 0.f, 0.f}, pi = (f32x4){0.f, 0.f, 0.f, 0.f};
; #pragma unroll
;             for (int ks = 0; ks < 2; ++ks) { pr = __builtin_amdgcn_mfma_f32_16x16x32_bf16(Af[ks], Bw[0][nt][ks], pr, 0, 0, 0); pi = __builtin_amdgcn_mfma_f32_16x16x32_bf16(Af[ks], Bw[1][nt][ks], pi, 0, 0, 0); }
;             float av[4], bv[4];
; #pragma unroll
;             for (int reg = 0; reg < 4; ++reg) {
;                 const int tok = m * 16 + 4 * fq + reg;
;                 const float x = bf2f(cxb[tok * CXS + cc[nt]]);
;                 const float r = fsig(pr[reg] + ba[nt]), ig = fsig(pi[reg] + bxv[nt]);
;                 const float aa = __expf(k8[nt] * r);
;                 av[reg] = aa; bv[reg] = __builtin_amdgcn_sqrtf(fmaxf(1.0f - aa * aa, 0.f)) * ig * x;
;             }
;             float cum[4], hl[4];
;             if (DIR == 0) { cum[0] = av[0]; hl[0] = bv[0];
; #pragma unroll
;                 for (int reg = 1; reg < 4; ++reg) { cum[reg] = cum[reg - 1] * av[reg]; hl[reg] = av[reg] * hl[reg - 1] + bv[reg]; } }
;             else { cum[3] = av[3]; hl[3] = bv[3];
; #pragma unroll
;     ...
;             const float A4 = DIR ? cum[0] : cum[3], H4 = DIR ? hl[0] : hl[3];
;             float Aq[4], Hq[4];
; #pragma unroll
;             for (int q = 0; q < 4; ++q) { Aq[q] = __shfl(A4, fr + 16 * q); Hq[q] = __shfl(H4, fr + 16 * q); }
;             float hin;
;             if (DIR == 0) { const float s0 = C[nt], s1 = Aq[0] * s0 + Hq[0], s2 = Aq[1] * s1 + Hq[1], s3 = Aq[2] * s2 + Hq[2]; C[nt] = Aq[3] * s3 + Hq[3]; hin = fq == 0 ? s0 : (fq == 1 ? s1 : (fq == 2 ? s2 : s3)); }
;             else { const float s3 = C[nt], s2 = Aq[3] * s3 + Hq[3], s1 = Aq[2] * s2 + Hq[2], s0 = Aq[1] * s1 + Hq[1]; C[nt] = Aq[0] * s0 + Hq[0]; hin = fq == 3 ? s3 : (fq == 2 ? s2 : (fq == 1 ? s1 : s0)); }
;             if (MODE == 0) At[nt] *= (Aq[0] * Aq[1]) * (Aq[2] * Aq[3]);
	v_lshlrev_b32_e32 v101, 16, v108
	v_mfma_f32_16x16x32_bf16 v[70:73], v[70:73], v[46:49], 0
	v_fmac_f32_e32 v107, v105, v101
	s_nop 1
	v_add_f32_e32 v93, v155, v96
	v_mul_f32_e32 v93, 0xbfb8aa3b, v93
	v_exp_f32_e32 v95, v93
	v_mfma_f32_16x16x32_bf16 v[66:69], v[66:69], v[42:45], v[70:73]
	s_waitcnt lgkmcnt(3)
	v_lshlrev_b32_e32 v96, 16, v111
	ds_bpermute_b32 v93, v102, v103 offset:128
	v_lshlrev_b32_e32 v101, 16, v109
	v_add_f32_e32 v70, 1.0, v95
	v_rcp_f32_e32 v70, v70
	s_nop 1
	v_add_f32_e32 v66, v154, v66
	v_mul_f32_e32 v66, 0xbfb8aa3b, v66
	v_exp_f32_e32 v66, v66
	v_mul_f32_e32 v70, v104, v70
	v_mul_f32_e32 v70, 0x3fb8aa3b, v70
	v_exp_f32_e32 v70, v70
	v_add_f32_e32 v66, 1.0, v66
	v_rcp_f32_e32 v66, v66
	s_waitcnt lgkmcnt(3)
	v_lshlrev_b32_e32 v72, 16, v112
	v_fma_f32 v71, -v70, v70, 1.0
	v_max_f32_e32 v71, 0, v71
	v_sqrt_f32_e32 v71, v71
	v_add_f32_e32 v67, v154, v67
	v_mul_f32_e32 v67, 0xbfb8aa3b, v67
	v_exp_f32_e32 v67, v67
	v_mul_f32_e32 v66, v66, v71
	v_mul_f32_e32 v66, v66, v72
	v_add_f32_e32 v72, v155, v98
	v_mul_f32_e32 v72, 0xbfb8aa3b, v72
	v_exp_f32_e32 v72, v72
	v_add_f32_e32 v71, v155, v97
	v_mul_f32_e32 v71, 0xbfb8aa3b, v71
	v_exp_f32_e32 v71, v71
	v_add_f32_e32 v72, 1.0, v72
	v_rcp_f32_e32 v72, v72
	v_add_f32_e32 v67, 1.0, v67
	v_add_f32_e32 v71, 1.0, v71
	v_rcp_f32_e32 v71, v71
	v_mul_f32_e32 v72, v104, v72
	v_mul_f32_e32 v72, 0x3fb8aa3b, v72
	v_exp_f32_e32 v97, v72
	v_add_f32_e32 v72, v155, v99
	v_mul_f32_e32 v72, 0xbfb8aa3b, v72
	v_exp_f32_e32 v72, v72
	v_mul_f32_e32 v71, v104, v71
	v_mul_f32_e32 v71, 0x3fb8aa3b, v71
	v_exp_f32_e32 v71, v71
	v_add_f32_e32 v72, 1.0, v72
	v_rcp_f32_e32 v72, v72
	v_rcp_f32_e32 v67, v67
	v_fma_f32 v73, -v71, v71, 1.0
	v_max_f32_e32 v73, 0, v73
	v_sqrt_f32_e32 v73, v73
	v_mul_f32_e32 v72, v104, v72
	v_add_f32_e32 v68, v154, v68
	v_add_f32_e32 v69, v154, v69
	v_mul_f32_e32 v72, 0x3fb8aa3b, v72
	v_mul_f32_e32 v68, 0xbfb8aa3b, v68
	v_mul_f32_e32 v69, 0xbfb8aa3b, v69
	v_exp_f32_e32 v98, v72
	v_exp_f32_e32 v68, v68
	v_exp_f32_e32 v69, v69
	v_mul_f32_e32 v67, v67, v73
	v_fma_f32 v73, -v97, v97, 1.0
	v_max_f32_e32 v73, 0, v73
	v_sqrt_f32_e32 v72, v73
	v_fma_f32 v73, -v98, v98, 1.0
	v_add_f32_e32 v68, 1.0, v68
	v_add_f32_e32 v69, 1.0, v69
	v_max_f32_e32 v73, 0, v73
	v_rcp_f32_e32 v68, v68
	v_rcp_f32_e32 v69, v69
	v_sqrt_f32_e32 v73, v73
	v_mul_f32_e32 v66, v71, v66
	ds_bpermute_b32 v95, v102, v103 offset:192
	v_mul_f32_e32 v68, v68, v72
	v_mul_f32_e32 v69, v69, v73
	v_mul_f32_e32 v103, v71, v70
	ds_read_b128 v[70:73], v127 offset:25344
	v_fmac_f32_e32 v66, v67, v96
	v_lshlrev_b32_e32 v99, 16, v110
	v_mul_f32_e32 v66, v97, v66
	v_fmac_f32_e32 v66, v68, v99
	v_mul_f32_e32 v67, v97, v103
	v_mul_f32_e32 v103, v98, v66
	v_mul_f32_e32 v97, v98, v67
	v_fmac_f32_e32 v103, v69, v101
	ds_read_b128 v[66:69], v127 offset:25408
	s_waitcnt lgkmcnt(1)
	v_mfma_f32_16x16x32_bf16 v[108:111], v[70:73], v[54:57], 0
	s_nop 0
	s_nop 0
	s_nop 0
	s_waitcnt lgkmcnt(0)
	v_mfma_f32_16x16x32_bf16 v[108:111], v[66:69], v[50:53], v[108:111]
	v_mov_b32_e32 v140, v103
	v_mov_b32_e32 v141, v103
	s_nop 1
	v_permlane16_swap_b32_e32 v140, v141
	s_nop 1
	v_mov_b32_e32 v142, v140
	v_mov_b32_e32 v143, v141
	s_nop 1
	v_permlane32_swap_b32_e32 v140, v142
	v_permlane32_swap_b32_e32 v141, v143
	s_nop 1
	s_nop 0
	s_nop 0
	s_nop 4
	v_add_f32_e32 v101, v157, v108
	v_mul_f32_e32 v101, 0xbfb8aa3b, v101
	v_exp_f32_e32 v101, v101
	v_mfma_f32_16x16x32_bf16 v[112:115], v[70:73], v[62:65], 0
	s_nop 0
	v_mov_b32_e32 v136, v107
	v_mov_b32_e32 v137, v107
	s_nop 1
	v_permlane16_swap_b32_e32 v136, v137
	s_nop 1
	v_mov_b32_e32 v138, v136
	v_mov_b32_e32 v139, v137
	s_nop 1
	v_permlane32_swap_b32_e32 v136, v138
	v_permlane32_swap_b32_e32 v137, v139
	s_nop 1
	v_add_f32_e32 v101, 1.0, v101
	v_mfma_f32_16x16x32_bf16 v[112:115], v[66:69], v[58:61], v[112:115]
	v_rcp_f32_e32 v101, v101
	v_add_f32_e32 v111, v157, v111
	v_mul_f32_e32 v111, 0xbfb8aa3b, v111
	v_exp_f32_e32 v111, v111
	v_mul_f32_e32 v101, v75, v101
	s_nop 2
	v_add_f32_e32 v105, v156, v112
	v_mul_f32_e32 v105, 0xbfb8aa3b, v105
	v_mul_f32_e32 v101, 0x3fb8aa3b, v101
	v_exp_f32_e32 v105, v105
	v_exp_f32_e32 v101, v101
	ds_read_u16 v107, v106 offset:25344
	ds_read_u16 v108, v106 offset:25872
	ds_read_u16 v112, v106 offset:26400
	ds_read_u16 v144, v106 offset:26928
	ds_read_u16 v160, v106 offset:26960
	ds_read_u16 v161, v106 offset:26432
	ds_read_u16 v162, v106 offset:25904
	ds_read_u16 v163, v106 offset:25376
	s_waitcnt lgkmcnt(7)
	v_lshlrev_b32_e32 v107, 16, v107
	v_add_f32_e32 v103, 1.0, v105
	v_fma_f32 v105, -v101, v101, 1.0
	v_max_f32_e32 v105, 0, v105
	v_rcp_f32_e32 v103, v103
	v_sqrt_f32_e32 v105, v105
	v_add_f32_e32 v111, 1.0, v111
	v_rcp_f32_e32 v111, v111
	s_waitcnt lgkmcnt(6)
	v_lshlrev_b32_e32 v108, 16, v108
	v_mul_f32_e32 v103, v103, v105
	v_add_f32_e32 v105, v157, v109
	v_add_f32_e32 v109, v156, v113
	v_mul_f32_e32 v105, 0xbfb8aa3b, v105
	v_mul_f32_e32 v109, 0xbfb8aa3b, v109
	v_exp_f32_e32 v105, v105
	v_exp_f32_e32 v109, v109
	v_mul_f32_e32 v103, v103, v107
	v_add_f32_e32 v113, v156, v114
	v_add_f32_e32 v105, 1.0, v105
	v_add_f32_e32 v107, 1.0, v109
	v_add_f32_e32 v109, v157, v110
	v_rcp_f32_e32 v105, v105
	v_mul_f32_e32 v109, 0xbfb8aa3b, v109
	v_exp_f32_e32 v109, v109
	v_mul_f32_e32 v113, 0xbfb8aa3b, v113
	v_mul_f32_e32 v105, v75, v105
	v_mul_f32_e32 v105, 0x3fb8aa3b, v105
	v_add_f32_e32 v109, 1.0, v109
	v_exp_f32_e32 v105, v105
	v_rcp_f32_e32 v109, v109
	v_rcp_f32_e32 v107, v107
	v_exp_f32_e32 v113, v113
	v_fma_f32 v110, -v105, v105, 1.0
	v_mul_f32_e32 v109, v75, v109
	v_max_f32_e32 v110, 0, v110
	v_mul_f32_e32 v109, 0x3fb8aa3b, v109
	v_sqrt_f32_e32 v110, v110
	v_exp_f32_e32 v109, v109
	v_mul_f32_e32 v111, v75, v111
	v_mul_f32_e32 v111, 0x3fb8aa3b, v111
	v_mul_f32_e32 v107, v107, v110
	v_add_f32_e32 v110, 1.0, v113
	v_fma_f32 v113, -v109, v109, 1.0
	v_max_f32_e32 v113, 0, v113
	v_rcp_f32_e32 v110, v110
	v_add_f32_e32 v114, v156, v115
	v_exp_f32_e32 v115, v111
	v_sqrt_f32_e32 v111, v113
	v_mul_f32_e32 v103, v105, v103
	v_fmac_f32_e32 v103, v107, v108
	s_waitcnt lgkmcnt(5)
; __device__ __forceinline__ float fsig(float x) { return frcp(1.0f + __expf(-x)); }
; template <int DIR, int MODE>
; __device__ __forceinline__ void lru_pass(const Args& a, const LAS bf16_t* cxb, LAS bf16_t* gyb, const LAS float* carry, const bf16x8 (&Bw)[2][2][2], const float (&prm)[2][3], int l, int tt, float (&hf)[8][2][4]) {
;     ...
;         for (int nt = 0; nt < 2; ++nt) {
;             f32x4 pr = (f32x4){0.f, 0.f, 0.f, 0.f}, pi = (f32x4){0.f, 0.f, 0.f, 0.f};
; #pragma unroll
;             for (int ks = 0; ks < 2; ++ks) { pr = __builtin_amdgcn_mfma_f32_16x16x32_bf16(Af[ks], Bw[0][nt][ks], pr, 0, 0, 0); pi = __builtin_amdgcn_mfma_f32_16x16x32_bf16(Af[ks], Bw[1][nt][ks], pi, 0, 0, 0); }
;             float av[4], bv[4];
; #pragma unroll
;             for (int reg = 0; reg < 4; ++reg) {
;                 const int tok = m * 16 + 4 * fq + reg;
;                 const float x = bf2f(cxb[tok * CXS + cc[nt]]);
;                 const float r = fsig(pr[reg] + ba[nt]), ig = fsig(pi[reg] + bxv[nt]);
;                 const float aa = __expf(k8[nt] * r);
;                 av[reg] = aa; bv[reg] = __builtin_amdgcn_sqrtf(fmaxf(1.0f - aa * aa, 0.f)) * ig * x;
;             }
;             float cum[4], hl[4];
;             if (DIR == 0) { cum[0] = av[0]; hl[0] = bv[0];
; #pragma unroll
;                 for (int reg = 1; reg < 4; ++reg) { cum[reg] = cum[reg - 1] * av[reg]; hl[reg] = av[reg] * hl[reg - 1] + bv[reg]; } }
;             else { cum[3] = av[3]; hl[3] = bv[3];
; #pragma unroll
;     ...
;             const float A4 = DIR ? cum[0] : cum[3], H4 = DIR ? hl[0] : hl[3];
;             float Aq[4], Hq[4];
; #pragma unroll
;             for (int q = 0; q < 4; ++q) { Aq[q] = __shfl(A4, fr + 16 * q); Hq[q] = __shfl(H4, fr + 16 * q); }
;             float hin;
;             if (DIR == 0) { const float s0 = C[nt], s1 = Aq[0] * s0 + Hq[0], s2 = Aq[1] * s1 + Hq[1], s3 = Aq[2] * s2 + Hq[2]; C[nt] = Aq[3] * s3 + Hq[3]; hin = fq == 0 ? s0 : (fq == 1 ? s1 : (fq == 2 ? s2 : s3)); }
;             else { const float s3 = C[nt], s2 = Aq[3] * s3 + Hq[3], s1 = Aq[2] * s2 + Hq[2], s0 = Aq[1] * s1 + Hq[1]; C[nt] = Aq[0] * s0 + Hq[0]; hin = fq == 3 ? s3 : (fq == 2 ? s2 : (fq == 1 ? s1 : s0)); }
;             if (MODE == 0) At[nt] *= (Aq[0] * Aq[1]) * (Aq[2] * Aq[3]);
	v_lshlrev_b32_e32 v112, 16, v112
	v_mul_f32_e32 v110, v110, v111
	v_mul_f32_e32 v101, v105, v101
	v_mul_f32_e32 v103, v109, v103
	v_mul_f32_e32 v101, v109, v101
	v_fmac_f32_e32 v103, v110, v112
	v_mfma_f32_16x16x32_bf16 v[108:111], v[70:73], v[38:41], 0
	v_mul_f32_e32 v114, 0xbfb8aa3b, v114
	v_exp_f32_e32 v114, v114
	s_waitcnt lgkmcnt(4)
	v_lshlrev_b32_e32 v144, 16, v144
	v_mfma_f32_16x16x32_bf16 v[108:111], v[66:69], v[34:37], v[108:111]
	v_mul_f32_e32 v103, v115, v103
	v_add_f32_e32 v113, 1.0, v114
	v_fma_f32 v114, -v115, v115, 1.0
	v_mfma_f32_16x16x32_bf16 v[70:73], v[70:73], v[46:49], 0
	v_max_f32_e32 v114, 0, v114
	s_nop 2
	v_add_f32_e32 v105, v155, v108
	v_mul_f32_e32 v105, 0xbfb8aa3b, v105
	v_exp_f32_e32 v105, v105
	v_mfma_f32_16x16x32_bf16 v[66:69], v[66:69], v[42:45], v[70:73]
	v_rcp_f32_e32 v113, v113
	v_sqrt_f32_e32 v114, v114
	v_mul_f32_e32 v101, v115, v101
	v_add_f32_e32 v70, 1.0, v105
	v_rcp_f32_e32 v70, v70
	s_nop 2
	v_add_f32_e32 v66, v154, v66
	v_mul_f32_e32 v66, 0xbfb8aa3b, v66
	v_exp_f32_e32 v66, v66
	v_mul_f32_e32 v70, v104, v70
	v_mul_f32_e32 v70, 0x3fb8aa3b, v70
	v_exp_f32_e32 v70, v70
	v_add_f32_e32 v66, 1.0, v66
	v_rcp_f32_e32 v66, v66
	s_waitcnt lgkmcnt(0)
	v_lshlrev_b32_e32 v72, 16, v163
	v_fma_f32 v71, -v70, v70, 1.0
	v_max_f32_e32 v71, 0, v71
	v_sqrt_f32_e32 v71, v71
	v_mul_f32_e32 v113, v113, v114
	v_fmac_f32_e32 v103, v113, v144
	s_nop 0
	v_mul_f32_e32 v66, v66, v71
	v_mul_f32_e32 v66, v66, v72
	v_add_f32_e32 v72, v155, v110
	v_mul_f32_e32 v72, 0xbfb8aa3b, v72
	v_exp_f32_e32 v72, v72
	v_add_f32_e32 v71, v155, v109
	v_mul_f32_e32 v71, 0xbfb8aa3b, v71
	v_exp_f32_e32 v71, v71
	v_add_f32_e32 v72, 1.0, v72
	v_rcp_f32_e32 v72, v72
	s_nop 0
	v_add_f32_e32 v71, 1.0, v71
	v_rcp_f32_e32 v71, v71
	v_mul_f32_e32 v72, v104, v72
	v_mul_f32_e32 v72, 0x3fb8aa3b, v72
	s_nop 0
	v_mov_b32_e32 v145, v103
	v_mov_b32_e32 v146, v103
	s_nop 1
	v_permlane16_swap_b32_e32 v145, v146
	s_nop 1
	v_mov_b32_e32 v149, v145
	v_mov_b32_e32 v158, v146
	s_nop 1
	v_permlane32_swap_b32_e32 v145, v149
	v_permlane32_swap_b32_e32 v146, v158
	s_nop 1
	v_exp_f32_e32 v103, v72
	v_add_f32_e32 v72, v155, v111
	v_mul_f32_e32 v72, 0xbfb8aa3b, v72
	v_exp_f32_e32 v72, v72
	v_mul_f32_e32 v71, v104, v71
	v_add_f32_e32 v67, v154, v67
	v_mul_f32_e32 v71, 0x3fb8aa3b, v71
	v_mul_f32_e32 v67, 0xbfb8aa3b, v67
	v_exp_f32_e32 v71, v71
	v_exp_f32_e32 v67, v67
	v_add_f32_e32 v72, 1.0, v72
	v_rcp_f32_e32 v72, v72
	v_fma_f32 v73, -v71, v71, 1.0
	v_add_f32_e32 v67, 1.0, v67
	v_max_f32_e32 v73, 0, v73
	v_rcp_f32_e32 v67, v67
	v_sqrt_f32_e32 v73, v73
	v_mul_f32_e32 v72, v104, v72
	v_add_f32_e32 v68, v154, v68
	v_add_f32_e32 v69, v154, v69
	v_mul_f32_e32 v72, 0x3fb8aa3b, v72
	v_mul_f32_e32 v68, 0xbfb8aa3b, v68
	v_mul_f32_e32 v69, 0xbfb8aa3b, v69
	v_exp_f32_e32 v105, v72
	v_exp_f32_e32 v68, v68
	v_exp_f32_e32 v69, v69
	v_mul_f32_e32 v67, v67, v73
	v_fma_f32 v73, -v103, v103, 1.0
	v_max_f32_e32 v73, 0, v73
	v_sqrt_f32_e32 v72, v73
	v_fma_f32 v73, -v105, v105, 1.0
	v_add_f32_e32 v68, 1.0, v68
	v_add_f32_e32 v69, 1.0, v69
	v_max_f32_e32 v73, 0, v73
	v_rcp_f32_e32 v68, v68
	v_rcp_f32_e32 v69, v69
	v_sqrt_f32_e32 v73, v73
	s_nop 0
	s_nop 0
	s_nop 0
	v_mov_b32_e32 v144, v101
	v_mov_b32_e32 v147, v101
	s_nop 1
	v_permlane16_swap_b32_e32 v144, v147
	s_nop 1
	v_mov_b32_e32 v148, v144
	v_mov_b32_e32 v159, v147
	s_nop 1
	v_permlane32_swap_b32_e32 v144, v148
	v_permlane32_swap_b32_e32 v147, v159
	s_nop 1
	v_lshlrev_b32_e32 v101, 16, v162
	v_mul_f32_e32 v66, v71, v66
	v_mul_f32_e32 v68, v68, v72
	v_mul_f32_e32 v69, v69, v73
	v_mul_f32_e32 v109, v71, v70
	ds_read_b128 v[70:73], v127 offset:33792
	v_fmac_f32_e32 v66, v67, v101
	v_lshlrev_b32_e32 v107, 16, v161
	v_mul_f32_e32 v66, v103, v66
	v_fmac_f32_e32 v66, v68, v107
	v_lshlrev_b32_e32 v108, 16, v160
	v_mul_f32_e32 v67, v103, v109
	v_mul_f32_e32 v103, v105, v66
	v_mul_f32_e32 v101, v105, v67
	v_fmac_f32_e32 v103, v69, v108
	ds_read_b128 v[66:69], v127 offset:33856
	s_waitcnt lgkmcnt(1)
	v_mfma_f32_16x16x32_bf16 v[108:111], v[70:73], v[54:57], 0
	s_nop 0
	s_nop 0
	s_nop 0
	s_waitcnt lgkmcnt(0)
	v_mfma_f32_16x16x32_bf16 v[108:111], v[66:69], v[50:53], v[108:111]
	v_mov_b32_e32 v161, v101
	v_mov_b32_e32 v162, v101
	s_nop 1
	v_permlane16_swap_b32_e32 v161, v162
	s_nop 1
	v_mov_b32_e32 v165, v161
	v_mov_b32_e32 v166, v162
	s_nop 1
	v_permlane32_swap_b32_e32 v161, v165
	v_permlane32_swap_b32_e32 v162, v166
	s_nop 1
	s_nop 0
	s_nop 0
	s_nop 4
	v_add_f32_e32 v105, v157, v108
	v_mul_f32_e32 v105, 0xbfb8aa3b, v105
	v_exp_f32_e32 v105, v105
	v_mfma_f32_16x16x32_bf16 v[112:115], v[70:73], v[62:65], 0
	s_nop 0
	v_mov_b32_e32 v160, v103
	v_mov_b32_e32 v163, v103
	s_nop 1
	v_permlane16_swap_b32_e32 v160, v163
	s_nop 1
	v_mov_b32_e32 v164, v160
	v_mov_b32_e32 v167, v163
	s_nop 1
	v_permlane32_swap_b32_e32 v160, v164
	v_permlane32_swap_b32_e32 v163, v167
	s_nop 1
	v_add_f32_e32 v101, 1.0, v105
	v_mfma_f32_16x16x32_bf16 v[112:115], v[66:69], v[58:61], v[112:115]
	v_rcp_f32_e32 v101, v101
	v_add_f32_e32 v111, v157, v111
	v_mul_f32_e32 v111, 0xbfb8aa3b, v111
	v_exp_f32_e32 v111, v111
	v_mul_f32_e32 v101, v75, v101
	s_nop 2
	v_add_f32_e32 v105, v156, v112
	v_mul_f32_e32 v105, 0xbfb8aa3b, v105
	v_mul_f32_e32 v101, 0x3fb8aa3b, v101
	v_exp_f32_e32 v105, v105
	v_exp_f32_e32 v101, v101
	ds_read_u16 v107, v106 offset:33792
	ds_read_u16 v108, v106 offset:34320
	ds_read_u16 v112, v106 offset:34848
	ds_read_u16 v168, v106 offset:35376
	ds_read_u16 v174, v106 offset:35408
	ds_read_u16 v175, v106 offset:34880
	ds_read_u16 v176, v106 offset:34352
	ds_read_u16 v177, v106 offset:33824
	s_waitcnt lgkmcnt(7)
; __device__ __forceinline__ float fsig(float x) { return frcp(1.0f + __expf(-x)); }
; template <int DIR, int MODE>
; __device__ __forceinline__ void lru_pass(const Args& a, const LAS bf16_t* cxb, LAS bf16_t* gyb, const LAS float* carry, const bf16x8 (&Bw)[2][2][2], const float (&prm)[2][3], int l, int tt, float (&hf)[8][2][4]) {
;     ...
;         for (int nt = 0; nt < 2; ++nt) {
;             f32x4 pr = (f32x4){0.f, 0.f, 0.f, 0.f}, pi = (f32x4){0.f, 0.f, 0.f, 0.f};
; #pragma unroll
;             for (int ks = 0; ks < 2; ++ks) { pr = __builtin_amdgcn_mfma_f32_16x16x32_bf16(Af[ks], Bw[0][nt][ks], pr, 0, 0, 0); pi = __builtin_amdgcn_mfma_f32_16x16x32_bf16(Af[ks], Bw[1][nt][ks], pi, 0, 0, 0); }
;             float av[4], bv[4];
; #pragma unroll
;             for (int reg = 0; reg < 4; ++reg) {
;                 const int tok = m * 16 + 4 * fq + reg;
;                 const float x = bf2f(cxb[tok * CXS + cc[nt]]);
;                 const float r = fsig(pr[reg] + ba[nt]), ig = fsig(pi[reg] + bxv[nt]);
;                 const float aa = __expf(k8[nt] * r);
;                 av[reg] = aa; bv[reg] = __builtin_amdgcn_sqrtf(fmaxf(1.0f - aa * aa, 0.f)) * ig * x;
;             }
;             float cum[4], hl[4];
;             if (DIR == 0) { cum[0] = av[0]; hl[0] = bv[0];
; #pragma unroll
;                 for (int reg = 1; reg < 4; ++reg) { cum[reg] = cum[reg - 1] * av[reg]; hl[reg] = av[reg] * hl[reg - 1] + bv[reg]; } }
;             else { cum[3] = av[3]; hl[3] = bv[3];
; #pragma unroll
;     ...
;             const float A4 = DIR ? cum[0] : cum[3], H4 = DIR ? hl[0] : hl[3];
;             float Aq[4], Hq[4];
; #pragma unroll
;             for (int q = 0; q < 4; ++q) { Aq[q] = __shfl(A4, fr + 16 * q); Hq[q] = __shfl(H4, fr + 16 * q); }
;             float hin;
;             if (DIR == 0) { const float s0 = C[nt], s1 = Aq[0] * s0 + Hq[0], s2 = Aq[1] * s1 + Hq[1], s3 = Aq[2] * s2 + Hq[2]; C[nt] = Aq[3] * s3 + Hq[3]; hin = fq == 0 ? s0 : (fq == 1 ? s1 : (fq == 2 ? s2 : s3)); }
;             else { const float s3 = C[nt], s2 = Aq[3] * s3 + Hq[3], s1 = Aq[2] * s2 + Hq[2], s0 = Aq[1] * s1 + Hq[1]; C[nt] = Aq[0] * s0 + Hq[0]; hin = fq == 3 ? s3 : (fq == 2 ? s2 : (fq == 1 ? s1 : s0)); }
;             if (MODE == 0) At[nt] *= (Aq[0] * Aq[1]) * (Aq[2] * Aq[3]);
	v_lshlrev_b32_e32 v107, 16, v107
	v_add_f32_e32 v103, 1.0, v105
	v_fma_f32 v105, -v101, v101, 1.0
	v_max_f32_e32 v105, 0, v105
	v_rcp_f32_e32 v103, v103
	v_sqrt_f32_e32 v105, v105
	v_add_f32_e32 v111, 1.0, v111
	v_rcp_f32_e32 v111, v111
	s_waitcnt lgkmcnt(6)
	v_lshlrev_b32_e32 v108, 16, v108
	v_mul_f32_e32 v103, v103, v105
	v_add_f32_e32 v105, v157, v109
	v_add_f32_e32 v109, v156, v113
	v_mul_f32_e32 v105, 0xbfb8aa3b, v105
	v_mul_f32_e32 v109, 0xbfb8aa3b, v109
	v_exp_f32_e32 v105, v105
	v_exp_f32_e32 v109, v109
	v_mul_f32_e32 v103, v103, v107
	v_add_f32_e32 v113, v156, v114
	v_add_f32_e32 v105, 1.0, v105
	v_add_f32_e32 v107, 1.0, v109
	v_add_f32_e32 v109, v157, v110
	v_rcp_f32_e32 v105, v105
	v_mul_f32_e32 v109, 0xbfb8aa3b, v109
	v_exp_f32_e32 v109, v109
	v_mul_f32_e32 v113, 0xbfb8aa3b, v113
	v_mul_f32_e32 v105, v75, v105
	v_mul_f32_e32 v105, 0x3fb8aa3b, v105
	v_add_f32_e32 v109, 1.0, v109
	v_exp_f32_e32 v105, v105
	v_rcp_f32_e32 v109, v109
	v_rcp_f32_e32 v107, v107
	v_exp_f32_e32 v113, v113
	v_fma_f32 v110, -v105, v105, 1.0
	v_mul_f32_e32 v109, v75, v109
	v_max_f32_e32 v110, 0, v110
	v_mul_f32_e32 v109, 0x3fb8aa3b, v109
	v_sqrt_f32_e32 v110, v110
	v_exp_f32_e32 v109, v109
	v_mul_f32_e32 v111, v75, v111
	v_mul_f32_e32 v111, 0x3fb8aa3b, v111
	v_mul_f32_e32 v107, v107, v110
	v_add_f32_e32 v110, 1.0, v113
	v_fma_f32 v113, -v109, v109, 1.0
	v_max_f32_e32 v113, 0, v113
	v_rcp_f32_e32 v110, v110
	v_add_f32_e32 v114, v156, v115
	v_exp_f32_e32 v115, v111
	v_sqrt_f32_e32 v111, v113
	v_mul_f32_e32 v103, v105, v103
	v_fmac_f32_e32 v103, v107, v108
	s_waitcnt lgkmcnt(5)
	v_lshlrev_b32_e32 v112, 16, v112
	v_mul_f32_e32 v110, v110, v111
	v_mul_f32_e32 v101, v105, v101
	v_mul_f32_e32 v103, v109, v103
	v_mul_f32_e32 v101, v109, v101
	v_fmac_f32_e32 v103, v110, v112
	v_mfma_f32_16x16x32_bf16 v[108:111], v[70:73], v[38:41], 0
	v_mul_f32_e32 v105, v115, v101
	v_mul_f32_e32 v107, v115, v103
	v_mul_f32_e32 v114, 0xbfb8aa3b, v114
	v_mfma_f32_16x16x32_bf16 v[108:111], v[66:69], v[34:37], v[108:111]
	v_exp_f32_e32 v114, v114
	s_waitcnt lgkmcnt(4)
	v_lshlrev_b32_e32 v168, 16, v168
	ds_bpermute_b32 v171, v102, v105 offset:64
	v_mfma_f32_16x16x32_bf16 v[70:73], v[70:73], v[46:49], 0
	v_add_f32_e32 v113, 1.0, v114
	s_nop 1
	v_add_f32_e32 v101, v155, v108
	v_mul_f32_e32 v101, 0xbfb8aa3b, v101
	v_exp_f32_e32 v103, v101
	v_mfma_f32_16x16x32_bf16 v[66:69], v[66:69], v[42:45], v[70:73]
	v_fma_f32 v114, -v115, v115, 1.0
	v_max_f32_e32 v114, 0, v114
	v_rcp_f32_e32 v113, v113
	v_add_f32_e32 v70, 1.0, v103
	v_rcp_f32_e32 v70, v70
	s_nop 2
	v_add_f32_e32 v66, v154, v66
	v_mul_f32_e32 v66, 0xbfb8aa3b, v66
	v_exp_f32_e32 v66, v66
	v_mul_f32_e32 v70, v104, v70
	v_mul_f32_e32 v70, 0x3fb8aa3b, v70
	v_exp_f32_e32 v70, v70
	v_add_f32_e32 v66, 1.0, v66
	v_rcp_f32_e32 v66, v66
	s_waitcnt lgkmcnt(1)
	v_lshlrev_b32_e32 v72, 16, v177
	v_fma_f32 v71, -v70, v70, 1.0
	v_max_f32_e32 v71, 0, v71
	v_sqrt_f32_e32 v71, v71
	v_sqrt_f32_e32 v114, v114
	v_add_f32_e32 v67, v154, v67
	v_mul_f32_e32 v67, 0xbfb8aa3b, v67
	v_mul_f32_e32 v66, v66, v71
	v_mul_f32_e32 v66, v66, v72
	v_add_f32_e32 v72, v155, v110
	v_mul_f32_e32 v72, 0xbfb8aa3b, v72
	v_exp_f32_e32 v72, v72
	v_add_f32_e32 v71, v155, v109
	v_mul_f32_e32 v71, 0xbfb8aa3b, v71
	v_exp_f32_e32 v71, v71
	v_add_f32_e32 v72, 1.0, v72
	v_rcp_f32_e32 v72, v72
	v_mul_f32_e32 v113, v113, v114
	v_add_f32_e32 v71, 1.0, v71
	v_fmac_f32_e32 v107, v113, v168
	v_mul_f32_e32 v72, v104, v72
	v_rcp_f32_e32 v71, v71
	v_mul_f32_e32 v72, 0x3fb8aa3b, v72
	s_nop 0
	s_nop 0
	s_nop 0
	v_mov_b32_e32 v169, v107
	v_mov_b32_e32 v170, v107
	s_nop 1
	v_permlane16_swap_b32_e32 v169, v170
	s_nop 1
	v_mov_b32_e32 v172, v169
	v_mov_b32_e32 v173, v170
	s_nop 1
	v_permlane32_swap_b32_e32 v169, v172
	v_permlane32_swap_b32_e32 v170, v173
	s_nop 1
	v_exp_f32_e32 v107, v72
	v_add_f32_e32 v72, v155, v111
	v_mul_f32_e32 v72, 0xbfb8aa3b, v72
	v_exp_f32_e32 v72, v72
	v_mul_f32_e32 v71, v104, v71
	v_mul_f32_e32 v71, 0x3fb8aa3b, v71
	v_exp_f32_e32 v71, v71
	v_exp_f32_e32 v67, v67
	v_add_f32_e32 v72, 1.0, v72
	v_rcp_f32_e32 v72, v72
	v_fma_f32 v73, -v71, v71, 1.0
	v_add_f32_e32 v67, 1.0, v67
	v_max_f32_e32 v73, 0, v73
	v_rcp_f32_e32 v67, v67
	v_sqrt_f32_e32 v73, v73
	v_mul_f32_e32 v72, v104, v72
	v_add_f32_e32 v68, v154, v68
	v_add_f32_e32 v69, v154, v69
	v_mul_f32_e32 v72, 0x3fb8aa3b, v72
	v_mul_f32_e32 v68, 0xbfb8aa3b, v68
	v_mul_f32_e32 v69, 0xbfb8aa3b, v69
	v_exp_f32_e32 v108, v72
	v_exp_f32_e32 v68, v68
	v_exp_f32_e32 v69, v69
	v_mul_f32_e32 v67, v67, v73
	v_fma_f32 v73, -v107, v107, 1.0
	v_max_f32_e32 v73, 0, v73
	v_sqrt_f32_e32 v72, v73
	v_fma_f32 v73, -v108, v108, 1.0
	v_add_f32_e32 v68, 1.0, v68
	v_add_f32_e32 v69, 1.0, v69
	v_max_f32_e32 v73, 0, v73
	v_rcp_f32_e32 v68, v68
	v_rcp_f32_e32 v69, v69
	v_sqrt_f32_e32 v73, v73
	ds_bpermute_b32 v168, v102, v105
	ds_bpermute_b32 v101, v102, v105 offset:128
	ds_bpermute_b32 v103, v102, v105 offset:192
	v_lshlrev_b32_e32 v105, 16, v176
	v_mul_f32_e32 v66, v71, v66
	v_mul_f32_e32 v68, v68, v72
	v_mul_f32_e32 v69, v69, v73
	v_mul_f32_e32 v111, v71, v70
	ds_read_b128 v[70:73], v127 offset:42240
	v_fmac_f32_e32 v66, v67, v105
	v_lshlrev_b32_e32 v109, 16, v175
	v_mul_f32_e32 v66, v107, v66
	v_fmac_f32_e32 v66, v68, v109
	v_lshlrev_b32_e32 v110, 16, v174
	v_mul_f32_e32 v67, v107, v111
	v_mul_f32_e32 v179, v108, v66
	v_mul_f32_e32 v107, v108, v67
	v_fmac_f32_e32 v179, v69, v110
	ds_read_b128 v[66:69], v127 offset:42304
	s_waitcnt lgkmcnt(1)
	v_mfma_f32_16x16x32_bf16 v[108:111], v[70:73], v[54:57], 0
	ds_read_u16 v181, v106 offset:42240
	ds_read_u16 v182, v106 offset:42768
	ds_read_u16 v183, v106 offset:43296
	ds_read_u16 v184, v106 offset:43824
	ds_read_u16 v185, v106 offset:43856
	ds_read_u16 v186, v106 offset:43328
	ds_read_u16 v187, v106 offset:42800
	ds_read_u16 v188, v106 offset:42272
	s_waitcnt lgkmcnt(7)
; __device__ __forceinline__ float fsig(float x) { return frcp(1.0f + __expf(-x)); }
; template <int DIR, int MODE>
; __device__ __forceinline__ void lru_pass(const Args& a, const LAS bf16_t* cxb, LAS bf16_t* gyb, const LAS float* carry, const bf16x8 (&Bw)[2][2][2], const float (&prm)[2][3], int l, int tt, float (&hf)[8][2][4]) {
;     ...
;         for (int nt = 0; nt < 2; ++nt) {
;             f32x4 pr = (f32x4){0.f, 0.f, 0.f, 0.f}, pi = (f32x4){0.f, 0.f, 0.f, 0.f};
; #pragma unroll
;             for (int ks = 0; ks < 2; ++ks) { pr = __builtin_amdgcn_mfma_f32_16x16x32_bf16(Af[ks], Bw[0][nt][ks], pr, 0, 0, 0); pi = __builtin_amdgcn_mfma_f32_16x16x32_bf16(Af[ks], Bw[1][nt][ks], pi, 0, 0, 0); }
;             float av[4], bv[4];
; #pragma unroll
;             for (int reg = 0; reg < 4; ++reg) {
;                 const int tok = m * 16 + 4 * fq + reg;
;                 const float x = bf2f(cxb[tok * CXS + cc[nt]]);
;                 const float r = fsig(pr[reg] + ba[nt]), ig = fsig(pi[reg] + bxv[nt]);
;                 const float aa = __expf(k8[nt] * r);
;                 av[reg] = aa; bv[reg] = __builtin_amdgcn_sqrtf(fmaxf(1.0f - aa * aa, 0.f)) * ig * x;
;             }
;             float cum[4], hl[4];
;             if (DIR == 0) { cum[0] = av[0]; hl[0] = bv[0];
; #pragma unroll
;                 for (int reg = 1; reg < 4; ++reg) { cum[reg] = cum[reg - 1] * av[reg]; hl[reg] = av[reg] * hl[reg - 1] + bv[reg]; } }
;             else { cum[3] = av[3]; hl[3] = bv[3];
; #pragma unroll
;     ...
;             const float A4 = DIR ? cum[0] : cum[3], H4 = DIR ? hl[0] : hl[3];
;             float Aq[4], Hq[4];
; #pragma unroll
;             for (int q = 0; q < 4; ++q) { Aq[q] = __shfl(A4, fr + 16 * q); Hq[q] = __shfl(H4, fr + 16 * q); }
;             float hin;
;             if (DIR == 0) { const float s0 = C[nt], s1 = Aq[0] * s0 + Hq[0], s2 = Aq[1] * s1 + Hq[1], s3 = Aq[2] * s2 + Hq[2]; C[nt] = Aq[3] * s3 + Hq[3]; hin = fq == 0 ? s0 : (fq == 1 ? s1 : (fq == 2 ? s2 : s3)); }
;             else { const float s3 = C[nt], s2 = Aq[3] * s3 + Hq[3], s1 = Aq[2] * s2 + Hq[2], s0 = Aq[1] * s1 + Hq[1]; C[nt] = Aq[0] * s0 + Hq[0]; hin = fq == 3 ? s3 : (fq == 2 ? s2 : (fq == 1 ? s1 : s0)); }
;             if (MODE == 0) At[nt] *= (Aq[0] * Aq[1]) * (Aq[2] * Aq[3]);
	v_lshlrev_b32_e32 v181, 16, v181
	s_waitcnt lgkmcnt(5)
	v_lshlrev_b32_e32 v183, 16, v183
	v_mfma_f32_16x16x32_bf16 v[108:111], v[66:69], v[50:53], v[108:111]
	ds_bpermute_b32 v77, v102, v83
	ds_bpermute_b32 v79, v102, v83 offset:64
	ds_bpermute_b32 v81, v102, v83 offset:128
	s_nop 4
	v_add_f32_e32 v108, v157, v108
	v_mul_f32_e32 v108, 0xbfb8aa3b, v108
	v_exp_f32_e32 v108, v108
	v_mfma_f32_16x16x32_bf16 v[112:115], v[70:73], v[62:65], 0
	v_add_f32_e32 v109, v157, v109
	v_mul_f32_e32 v109, 0xbfb8aa3b, v109
	v_add_f32_e32 v108, 1.0, v108
	v_rcp_f32_e32 v108, v108
	v_mfma_f32_16x16x32_bf16 v[112:115], v[66:69], v[58:61], v[112:115]
	v_exp_f32_e32 v109, v109
	v_add_f32_e32 v110, v157, v110
	v_mul_f32_e32 v108, v75, v108
	v_mul_f32_e32 v108, 0x3fb8aa3b, v108
	v_add_f32_e32 v109, 1.0, v109
	s_nop 2
	v_add_f32_e32 v112, v156, v112
	v_mul_f32_e32 v112, 0xbfb8aa3b, v112
	v_exp_f32_e32 v108, v108
	v_rcp_f32_e32 v109, v109
	v_mul_f32_e32 v110, 0xbfb8aa3b, v110
	v_add_f32_e32 v111, v157, v111
	v_exp_f32_e32 v112, v112
	v_exp_f32_e32 v110, v110
	v_mul_f32_e32 v111, 0xbfb8aa3b, v111
	v_exp_f32_e32 v111, v111
	v_fma_f32 v180, -v108, v108, 1.0
	v_mul_f32_e32 v109, v75, v109
	v_add_f32_e32 v112, 1.0, v112
	v_max_f32_e32 v180, 0, v180
	v_add_f32_e32 v113, v156, v113
	v_mul_f32_e32 v109, 0x3fb8aa3b, v109
	v_add_f32_e32 v110, 1.0, v110
	v_rcp_f32_e32 v112, v112
	v_sqrt_f32_e32 v180, v180
	v_mul_f32_e32 v113, 0xbfb8aa3b, v113
	v_exp_f32_e32 v109, v109
	v_rcp_f32_e32 v110, v110
	v_add_f32_e32 v111, 1.0, v111
	v_exp_f32_e32 v113, v113
	v_rcp_f32_e32 v111, v111
	v_mul_f32_e32 v112, v112, v180
	v_fma_f32 v180, -v109, v109, 1.0
	v_mul_f32_e32 v110, v75, v110
	v_add_f32_e32 v113, 1.0, v113
	v_max_f32_e32 v180, 0, v180
	v_add_f32_e32 v114, v156, v114
	v_mul_f32_e32 v110, 0x3fb8aa3b, v110
	v_mul_f32_e32 v111, v75, v111
	v_rcp_f32_e32 v113, v113
	v_sqrt_f32_e32 v180, v180
	v_mul_f32_e32 v114, 0xbfb8aa3b, v114
	v_exp_f32_e32 v110, v110
	v_add_f32_e32 v115, v156, v115
	v_mul_f32_e32 v111, 0x3fb8aa3b, v111
	v_exp_f32_e32 v114, v114
	v_mul_f32_e32 v115, 0xbfb8aa3b, v115
	v_exp_f32_e32 v111, v111
	v_exp_f32_e32 v115, v115
	v_mul_f32_e32 v113, v113, v180
	v_fma_f32 v180, -v110, v110, 1.0
	v_mul_f32_e32 v112, v112, v181
	v_lshlrev_b32_e32 v181, 16, v182
	v_add_f32_e32 v114, 1.0, v114
	v_max_f32_e32 v180, 0, v180
	v_fma_f32 v182, -v111, v111, 1.0
	v_rcp_f32_e32 v114, v114
	v_sqrt_f32_e32 v180, v180
	v_add_f32_e32 v115, 1.0, v115
	v_max_f32_e32 v182, 0, v182
	v_rcp_f32_e32 v115, v115
	v_sqrt_f32_e32 v182, v182
	v_mul_f32_e32 v108, v109, v108
	v_mul_f32_e32 v109, v109, v112
	v_fmac_f32_e32 v109, v113, v181
	v_mul_f32_e32 v114, v114, v180
	v_mul_f32_e32 v109, v110, v109
	v_mul_f32_e32 v182, v115, v182
	v_fmac_f32_e32 v109, v114, v183
	v_mfma_f32_16x16x32_bf16 v[112:115], v[70:73], v[38:41], 0
	s_waitcnt lgkmcnt(7)
	v_lshlrev_b32_e32 v180, 16, v184
	v_mul_f32_e32 v184, v111, v109
	v_mul_f32_e32 v108, v110, v108
	v_mfma_f32_16x16x32_bf16 v[112:115], v[66:69], v[34:37], v[112:115]
	v_mul_f32_e32 v183, v111, v108
	v_fmac_f32_e32 v184, v182, v180
	ds_bpermute_b32 v108, v102, v183
	v_mfma_f32_16x16x32_bf16 v[70:73], v[70:73], v[46:49], 0
	ds_bpermute_b32 v180, v102, v184
	s_nop 2
	v_add_f32_e32 v109, v155, v112
	v_mul_f32_e32 v109, 0xbfb8aa3b, v109
	v_exp_f32_e32 v111, v109
	v_mfma_f32_16x16x32_bf16 v[66:69], v[66:69], v[42:45], v[70:73]
	s_waitcnt lgkmcnt(6)
	v_lshlrev_b32_e32 v112, 16, v187
	ds_bpermute_b32 v110, v102, v183 offset:64
	ds_bpermute_b32 v181, v102, v184 offset:64
	v_add_f32_e32 v70, 1.0, v111
	v_rcp_f32_e32 v70, v70
	s_nop 1
	v_add_f32_e32 v66, v154, v66
	v_mul_f32_e32 v66, 0xbfb8aa3b, v66
	v_exp_f32_e32 v66, v66
	v_mul_f32_e32 v70, v104, v70
	v_mul_f32_e32 v70, 0x3fb8aa3b, v70
	v_exp_f32_e32 v70, v70
	v_add_f32_e32 v66, 1.0, v66
	v_rcp_f32_e32 v66, v66
	s_waitcnt lgkmcnt(7)
	v_lshlrev_b32_e32 v72, 16, v188
	v_fma_f32 v71, -v70, v70, 1.0
	v_max_f32_e32 v71, 0, v71
	v_sqrt_f32_e32 v71, v71
	v_add_f32_e32 v67, v154, v67
	v_mul_f32_e32 v67, 0xbfb8aa3b, v67
	v_exp_f32_e32 v67, v67
	v_mul_f32_e32 v66, v66, v71
	v_mul_f32_e32 v66, v66, v72
	v_add_f32_e32 v72, v155, v114
	v_mul_f32_e32 v72, 0xbfb8aa3b, v72
	v_exp_f32_e32 v72, v72
	v_add_f32_e32 v71, v155, v113
	v_mul_f32_e32 v71, 0xbfb8aa3b, v71
	v_exp_f32_e32 v71, v71
	v_add_f32_e32 v72, 1.0, v72
	v_rcp_f32_e32 v72, v72
	v_add_f32_e32 v67, 1.0, v67
	v_add_f32_e32 v71, 1.0, v71
	v_rcp_f32_e32 v71, v71
	v_mul_f32_e32 v72, v104, v72
	v_mul_f32_e32 v72, 0x3fb8aa3b, v72
	v_exp_f32_e32 v113, v72
	v_add_f32_e32 v72, v155, v115
	v_mul_f32_e32 v72, 0xbfb8aa3b, v72
	v_exp_f32_e32 v72, v72
	v_mul_f32_e32 v71, v104, v71
	v_mul_f32_e32 v71, 0x3fb8aa3b, v71
	v_exp_f32_e32 v71, v71
	v_add_f32_e32 v72, 1.0, v72
	v_rcp_f32_e32 v72, v72
	v_rcp_f32_e32 v67, v67
	v_fma_f32 v73, -v71, v71, 1.0
	v_max_f32_e32 v73, 0, v73
	v_sqrt_f32_e32 v73, v73
	v_mul_f32_e32 v72, v104, v72
	v_add_f32_e32 v68, v154, v68
	v_add_f32_e32 v69, v154, v69
	v_mul_f32_e32 v72, 0x3fb8aa3b, v72
	v_mul_f32_e32 v68, 0xbfb8aa3b, v68
	v_mul_f32_e32 v69, 0xbfb8aa3b, v69
	v_exp_f32_e32 v114, v72
	v_exp_f32_e32 v68, v68
	v_exp_f32_e32 v69, v69
	v_mul_f32_e32 v67, v67, v73
	v_fma_f32 v73, -v113, v113, 1.0
	v_max_f32_e32 v73, 0, v73
	v_sqrt_f32_e32 v72, v73
	v_fma_f32 v73, -v114, v114, 1.0
	v_add_f32_e32 v68, 1.0, v68
	v_add_f32_e32 v69, 1.0, v69
	v_max_f32_e32 v73, 0, v73
	v_rcp_f32_e32 v68, v68
	v_rcp_f32_e32 v69, v69
	v_sqrt_f32_e32 v73, v73
	v_mul_f32_e32 v66, v71, v66
	ds_bpermute_b32 v109, v102, v183 offset:128
	ds_bpermute_b32 v182, v102, v184 offset:128
	ds_bpermute_b32 v111, v102, v183 offset:192
	ds_bpermute_b32 v183, v102, v184 offset:192
	v_mul_f32_e32 v68, v68, v72
	v_lshlrev_b32_e32 v184, 16, v185
	v_mul_f32_e32 v69, v69, v73
	v_mul_f32_e32 v185, v71, v70
	ds_read_b128 v[70:73], v127 offset:50688
	v_fmac_f32_e32 v66, v67, v112
	v_lshlrev_b32_e32 v115, 16, v186
	v_mul_f32_e32 v66, v113, v66
	v_fmac_f32_e32 v66, v68, v115
	v_mul_f32_e32 v67, v113, v185
	v_mul_f32_e32 v187, v114, v66
	v_mul_f32_e32 v113, v114, v67
	v_fmac_f32_e32 v187, v69, v184
	ds_read_b128 v[66:69], v127 offset:50752
	s_waitcnt lgkmcnt(1)
; __device__ __forceinline__ float fsig(float x) { return frcp(1.0f + __expf(-x)); }
; template <int DIR, int MODE>
; __device__ __forceinline__ void lru_pass(const Args& a, const LAS bf16_t* cxb, LAS bf16_t* gyb, const LAS float* carry, const bf16x8 (&Bw)[2][2][2], const float (&prm)[2][3], int l, int tt, float (&hf)[8][2][4]) {
;     ...
;         for (int nt = 0; nt < 2; ++nt) {
;             f32x4 pr = (f32x4){0.f, 0.f, 0.f, 0.f}, pi = (f32x4){0.f, 0.f, 0.f, 0.f};
; #pragma unroll
;             for (int ks = 0; ks < 2; ++ks) { pr = __builtin_amdgcn_mfma_f32_16x16x32_bf16(Af[ks], Bw[0][nt][ks], pr, 0, 0, 0); pi = __builtin_amdgcn_mfma_f32_16x16x32_bf16(Af[ks], Bw[1][nt][ks], pi, 0, 0, 0); }
;             float av[4], bv[4];
; #pragma unroll
;             for (int reg = 0; reg < 4; ++reg) {
;                 const int tok = m * 16 + 4 * fq + reg;
;                 const float x = bf2f(cxb[tok * CXS + cc[nt]]);
;                 const float r = fsig(pr[reg] + ba[nt]), ig = fsig(pi[reg] + bxv[nt]);
;                 const float aa = __expf(k8[nt] * r);
;                 av[reg] = aa; bv[reg] = __builtin_amdgcn_sqrtf(fmaxf(1.0f - aa * aa, 0.f)) * ig * x;
;             }
;             float cum[4], hl[4];
;             if (DIR == 0) { cum[0] = av[0]; hl[0] = bv[0];
; #pragma unroll
;                 for (int reg = 1; reg < 4; ++reg) { cum[reg] = cum[reg - 1] * av[reg]; hl[reg] = av[reg] * hl[reg - 1] + bv[reg]; } }
;             else { cum[3] = av[3]; hl[3] = bv[3];
; #pragma unroll
;     ...
;             const float A4 = DIR ? cum[0] : cum[3], H4 = DIR ? hl[0] : hl[3];
;             float Aq[4], Hq[4];
; #pragma unroll
;             for (int q = 0; q < 4; ++q) { Aq[q] = __shfl(A4, fr + 16 * q); Hq[q] = __shfl(H4, fr + 16 * q); }
;             float hin;
;             if (DIR == 0) { const float s0 = C[nt], s1 = Aq[0] * s0 + Hq[0], s2 = Aq[1] * s1 + Hq[1], s3 = Aq[2] * s2 + Hq[2]; C[nt] = Aq[3] * s3 + Hq[3]; hin = fq == 0 ? s0 : (fq == 1 ? s1 : (fq == 2 ? s2 : s3)); }
;             else { const float s3 = C[nt], s2 = Aq[3] * s3 + Hq[3], s1 = Aq[2] * s2 + Hq[2], s0 = Aq[1] * s1 + Hq[1]; C[nt] = Aq[0] * s0 + Hq[0]; hin = fq == 3 ? s3 : (fq == 2 ? s2 : (fq == 1 ? s1 : s0)); }
;             if (MODE == 0) At[nt] *= (Aq[0] * Aq[1]) * (Aq[2] * Aq[3]);
	v_mfma_f32_16x16x32_bf16 v[188:191], v[70:73], v[54:57], 0
	ds_read_u16 v197, v106 offset:50688
	ds_read_u16 v198, v106 offset:51216
	ds_read_u16 v199, v106 offset:51744
	ds_read_u16 v200, v106 offset:52272
	ds_read_u16 v201, v106 offset:52304
	ds_read_u16 v202, v106 offset:51776
	ds_read_u16 v203, v106 offset:51248
	ds_read_u16 v204, v106 offset:50720
	s_waitcnt lgkmcnt(7)
	v_lshlrev_b32_e32 v197, 16, v197
	s_waitcnt lgkmcnt(5)
	v_lshlrev_b32_e32 v199, 16, v199
	v_mfma_f32_16x16x32_bf16 v[188:191], v[66:69], v[50:53], v[188:191]
	ds_bpermute_b32 v83, v102, v83 offset:192
	ds_bpermute_b32 v87, v102, v91
	ds_bpermute_b32 v85, v102, v91 offset:64
	s_nop 4
	v_add_f32_e32 v188, v157, v188
	v_mul_f32_e32 v188, 0xbfb8aa3b, v188
	v_exp_f32_e32 v188, v188
	v_mfma_f32_16x16x32_bf16 v[192:195], v[70:73], v[62:65], 0
	v_add_f32_e32 v189, v157, v189
	v_mul_f32_e32 v189, 0xbfb8aa3b, v189
	v_add_f32_e32 v188, 1.0, v188
	v_rcp_f32_e32 v188, v188
	v_mfma_f32_16x16x32_bf16 v[192:195], v[66:69], v[58:61], v[192:195]
	v_exp_f32_e32 v189, v189
	v_add_f32_e32 v190, v157, v190
	v_mul_f32_e32 v188, v75, v188
	v_mul_f32_e32 v188, 0x3fb8aa3b, v188
	v_add_f32_e32 v189, 1.0, v189
	s_nop 2
	v_add_f32_e32 v192, v156, v192
	v_mul_f32_e32 v192, 0xbfb8aa3b, v192
	v_exp_f32_e32 v188, v188
	v_rcp_f32_e32 v189, v189
	v_mul_f32_e32 v190, 0xbfb8aa3b, v190
	v_add_f32_e32 v191, v157, v191
	v_exp_f32_e32 v192, v192
	v_exp_f32_e32 v190, v190
	v_mul_f32_e32 v191, 0xbfb8aa3b, v191
	v_exp_f32_e32 v191, v191
	v_fma_f32 v196, -v188, v188, 1.0
	v_mul_f32_e32 v189, v75, v189
	v_add_f32_e32 v192, 1.0, v192
	v_max_f32_e32 v196, 0, v196
	v_add_f32_e32 v193, v156, v193
	v_mul_f32_e32 v189, 0x3fb8aa3b, v189
	v_add_f32_e32 v190, 1.0, v190
	v_rcp_f32_e32 v192, v192
	v_sqrt_f32_e32 v196, v196
	v_mul_f32_e32 v193, 0xbfb8aa3b, v193
	v_exp_f32_e32 v189, v189
	v_rcp_f32_e32 v190, v190
	v_add_f32_e32 v191, 1.0, v191
	v_exp_f32_e32 v193, v193
	v_rcp_f32_e32 v191, v191
	v_mul_f32_e32 v192, v192, v196
	v_fma_f32 v196, -v189, v189, 1.0
	v_mul_f32_e32 v190, v75, v190
	v_add_f32_e32 v193, 1.0, v193
	v_max_f32_e32 v196, 0, v196
	v_add_f32_e32 v194, v156, v194
	v_mul_f32_e32 v190, 0x3fb8aa3b, v190
	v_mul_f32_e32 v191, v75, v191
	v_rcp_f32_e32 v193, v193
	v_sqrt_f32_e32 v196, v196
	v_mul_f32_e32 v194, 0xbfb8aa3b, v194
	v_exp_f32_e32 v190, v190
	v_add_f32_e32 v195, v156, v195
	v_mul_f32_e32 v191, 0x3fb8aa3b, v191
	v_exp_f32_e32 v194, v194
	v_mul_f32_e32 v195, 0xbfb8aa3b, v195
	v_exp_f32_e32 v191, v191
	v_exp_f32_e32 v195, v195
	v_mul_f32_e32 v193, v193, v196
	v_fma_f32 v196, -v190, v190, 1.0
	v_mul_f32_e32 v192, v192, v197
	v_lshlrev_b32_e32 v197, 16, v198
	v_add_f32_e32 v194, 1.0, v194
	v_max_f32_e32 v196, 0, v196
	v_fma_f32 v198, -v191, v191, 1.0
	v_rcp_f32_e32 v194, v194
	v_sqrt_f32_e32 v196, v196
	v_add_f32_e32 v195, 1.0, v195
	v_max_f32_e32 v198, 0, v198
	v_rcp_f32_e32 v195, v195
	v_sqrt_f32_e32 v198, v198
	v_mul_f32_e32 v188, v189, v188
	v_mul_f32_e32 v189, v189, v192
	v_fmac_f32_e32 v189, v193, v197
	v_mul_f32_e32 v194, v194, v196
	v_mul_f32_e32 v189, v190, v189
	v_mul_f32_e32 v198, v195, v198
	v_fmac_f32_e32 v189, v194, v199
	v_mfma_f32_16x16x32_bf16 v[192:195], v[70:73], v[38:41], 0
	s_waitcnt lgkmcnt(7)
	v_lshlrev_b32_e32 v196, 16, v200
	v_mul_f32_e32 v205, v191, v189
	v_fmac_f32_e32 v205, v198, v196
	v_mfma_f32_16x16x32_bf16 v[196:199], v[66:69], v[34:37], v[192:195]
	v_mul_f32_e32 v188, v190, v188
	v_mul_f32_e32 v200, v191, v188
	ds_bpermute_b32 v188, v102, v200
	v_mfma_f32_16x16x32_bf16 v[70:73], v[70:73], v[46:49], 0
	ds_bpermute_b32 v191, v102, v200 offset:64
	s_nop 2
	v_add_f32_e32 v192, v155, v196
	v_mul_f32_e32 v192, 0xbfb8aa3b, v192
	v_exp_f32_e32 v193, v192
	v_mfma_f32_16x16x32_bf16 v[66:69], v[66:69], v[42:45], v[70:73]
	s_waitcnt lgkmcnt(6)
	v_lshlrev_b32_e32 v196, 16, v203
	ds_bpermute_b32 v192, v102, v200 offset:128
	ds_bpermute_b32 v195, v102, v200 offset:192
	v_add_f32_e32 v70, 1.0, v193
	v_rcp_f32_e32 v70, v70
	s_nop 1
	v_add_f32_e32 v66, v154, v66
	v_mul_f32_e32 v66, 0xbfb8aa3b, v66
	v_exp_f32_e32 v66, v66
	v_mul_f32_e32 v70, v104, v70
	v_mul_f32_e32 v70, 0x3fb8aa3b, v70
	v_exp_f32_e32 v70, v70
	v_add_f32_e32 v66, 1.0, v66
	v_rcp_f32_e32 v66, v66
	s_waitcnt lgkmcnt(7)
	v_lshlrev_b32_e32 v72, 16, v204
	v_fma_f32 v71, -v70, v70, 1.0
	v_max_f32_e32 v71, 0, v71
	v_sqrt_f32_e32 v71, v71
	v_add_f32_e32 v67, v154, v67
	v_mul_f32_e32 v67, 0xbfb8aa3b, v67
	v_exp_f32_e32 v67, v67
	v_mul_f32_e32 v66, v66, v71
	v_mul_f32_e32 v66, v66, v72
	v_add_f32_e32 v72, v155, v198
	v_mul_f32_e32 v72, 0xbfb8aa3b, v72
	v_exp_f32_e32 v72, v72
	v_add_f32_e32 v71, v155, v197
	v_mul_f32_e32 v71, 0xbfb8aa3b, v71
	v_exp_f32_e32 v71, v71
	v_add_f32_e32 v72, 1.0, v72
	v_rcp_f32_e32 v72, v72
	v_add_f32_e32 v67, 1.0, v67
	v_add_f32_e32 v71, 1.0, v71
	v_rcp_f32_e32 v71, v71
	v_mul_f32_e32 v72, v104, v72
	v_mul_f32_e32 v72, 0x3fb8aa3b, v72
	v_exp_f32_e32 v197, v72
	v_add_f32_e32 v72, v155, v199
	v_mul_f32_e32 v72, 0xbfb8aa3b, v72
	v_exp_f32_e32 v72, v72
	v_mul_f32_e32 v71, v104, v71
	v_mul_f32_e32 v71, 0x3fb8aa3b, v71
	v_exp_f32_e32 v71, v71
	v_add_f32_e32 v72, 1.0, v72
	v_rcp_f32_e32 v72, v72
	v_rcp_f32_e32 v67, v67
	v_fma_f32 v73, -v71, v71, 1.0
	v_max_f32_e32 v73, 0, v73
	v_sqrt_f32_e32 v73, v73
	v_mul_f32_e32 v72, v104, v72
	v_add_f32_e32 v68, v154, v68
	v_add_f32_e32 v69, v154, v69
	v_mul_f32_e32 v72, 0x3fb8aa3b, v72
	v_mul_f32_e32 v68, 0xbfb8aa3b, v68
	v_mul_f32_e32 v69, 0xbfb8aa3b, v69
	v_exp_f32_e32 v198, v72
	v_exp_f32_e32 v68, v68
	v_exp_f32_e32 v69, v69
	v_mul_f32_e32 v67, v67, v73
	v_fma_f32 v73, -v197, v197, 1.0
	v_max_f32_e32 v73, 0, v73
	v_sqrt_f32_e32 v72, v73
	v_fma_f32 v73, -v198, v198, 1.0
	v_add_f32_e32 v68, 1.0, v68
	v_add_f32_e32 v69, 1.0, v69
	v_max_f32_e32 v73, 0, v73
	v_rcp_f32_e32 v68, v68
	v_rcp_f32_e32 v69, v69
	v_sqrt_f32_e32 v73, v73
	v_mul_f32_e32 v66, v71, v66
	v_mul_f32_e32 v68, v68, v72
	v_lshlrev_b32_e32 v200, 16, v201
	v_mul_f32_e32 v69, v69, v73
	v_mul_f32_e32 v201, v71, v70
	ds_read_b128 v[70:73], v127 offset:59136
	v_fmac_f32_e32 v66, v67, v196
	v_lshlrev_b32_e32 v199, 16, v202
	v_mul_f32_e32 v66, v197, v66
	v_fmac_f32_e32 v66, v68, v199
	s_nop 0
	s_nop 0
	s_nop 0
	v_mov_b32_e32 v189, v205
	v_mov_b32_e32 v190, v205
	s_nop 1
	v_permlane16_swap_b32_e32 v189, v190
	s_nop 1
	v_mov_b32_e32 v193, v189
	v_mov_b32_e32 v194, v190
	s_nop 1
	v_permlane32_swap_b32_e32 v189, v193
	v_permlane32_swap_b32_e32 v190, v194
	s_nop 1
	v_mul_f32_e32 v67, v197, v201
	v_mul_f32_e32 v205, v198, v66
	v_mul_f32_e32 v204, v198, v67
	v_fmac_f32_e32 v205, v69, v200
	ds_read_b128 v[66:69], v127 offset:59200
	s_waitcnt lgkmcnt(1)
; __device__ __forceinline__ float fsig(float x) { return frcp(1.0f + __expf(-x)); }
; template <int DIR, int MODE>
; __device__ __forceinline__ void lru_pass(const Args& a, const LAS bf16_t* cxb, LAS bf16_t* gyb, const LAS float* carry, const bf16x8 (&Bw)[2][2][2], const float (&prm)[2][3], int l, int tt, float (&hf)[8][2][4]) {
;     ...
;         for (int nt = 0; nt < 2; ++nt) {
;             f32x4 pr = (f32x4){0.f, 0.f, 0.f, 0.f}, pi = (f32x4){0.f, 0.f, 0.f, 0.f};
; #pragma unroll
;             for (int ks = 0; ks < 2; ++ks) { pr = __builtin_amdgcn_mfma_f32_16x16x32_bf16(Af[ks], Bw[0][nt][ks], pr, 0, 0, 0); pi = __builtin_amdgcn_mfma_f32_16x16x32_bf16(Af[ks], Bw[1][nt][ks], pi, 0, 0, 0); }
;             float av[4], bv[4];
; #pragma unroll
;             for (int reg = 0; reg < 4; ++reg) {
;                 const int tok = m * 16 + 4 * fq + reg;
;                 const float x = bf2f(cxb[tok * CXS + cc[nt]]);
;                 const float r = fsig(pr[reg] + ba[nt]), ig = fsig(pi[reg] + bxv[nt]);
;                 const float aa = __expf(k8[nt] * r);
;                 av[reg] = aa; bv[reg] = __builtin_amdgcn_sqrtf(fmaxf(1.0f - aa * aa, 0.f)) * ig * x;
;             }
;             float cum[4], hl[4];
;             if (DIR == 0) { cum[0] = av[0]; hl[0] = bv[0];
; #pragma unroll
;                 for (int reg = 1; reg < 4; ++reg) { cum[reg] = cum[reg - 1] * av[reg]; hl[reg] = av[reg] * hl[reg - 1] + bv[reg]; } }
;             else { cum[3] = av[3]; hl[3] = bv[3];
; #pragma unroll
;     ...
;             const float A4 = DIR ? cum[0] : cum[3], H4 = DIR ? hl[0] : hl[3];
;             float Aq[4], Hq[4];
; #pragma unroll
;             for (int q = 0; q < 4; ++q) { Aq[q] = __shfl(A4, fr + 16 * q); Hq[q] = __shfl(H4, fr + 16 * q); }
;             float hin;
;             if (DIR == 0) { const float s0 = C[nt], s1 = Aq[0] * s0 + Hq[0], s2 = Aq[1] * s1 + Hq[1], s3 = Aq[2] * s2 + Hq[2]; C[nt] = Aq[3] * s3 + Hq[3]; hin = fq == 0 ? s0 : (fq == 1 ? s1 : (fq == 2 ? s2 : s3)); }
;             else { const float s3 = C[nt], s2 = Aq[3] * s3 + Hq[3], s1 = Aq[2] * s2 + Hq[2], s0 = Aq[1] * s1 + Hq[1]; C[nt] = Aq[0] * s0 + Hq[0]; hin = fq == 3 ? s3 : (fq == 2 ? s2 : (fq == 1 ? s1 : s0)); }
;             if (MODE == 0) At[nt] *= (Aq[0] * Aq[1]) * (Aq[2] * Aq[3]);
	v_mfma_f32_16x16x32_bf16 v[196:199], v[70:73], v[54:57], 0
	ds_bpermute_b32 v89, v102, v91 offset:128
	ds_bpermute_b32 v91, v102, v91 offset:192
	ds_bpermute_b32 v98, v102, v97
	s_waitcnt lgkmcnt(3)
	v_mfma_f32_16x16x32_bf16 v[196:199], v[66:69], v[50:53], v[196:199]
	ds_bpermute_b32 v96, v102, v97 offset:64
	ds_bpermute_b32 v99, v102, v97 offset:128
	ds_bpermute_b32 v97, v102, v97 offset:192
	s_nop 4
	v_add_f32_e32 v50, v157, v196
	v_mul_f32_e32 v50, 0xbfb8aa3b, v50
	v_exp_f32_e32 v51, v50
	v_mfma_f32_16x16x32_bf16 v[200:203], v[70:73], v[62:65], 0
	ds_bpermute_b32 v175, v102, v107
	ds_bpermute_b32 v174, v102, v179
	v_add_f32_e32 v51, 1.0, v51
	v_rcp_f32_e32 v51, v51
	v_mfma_f32_16x16x32_bf16 v[58:61], v[66:69], v[58:61], v[200:203]
	ds_read_u16 v64, v106 offset:59136
	ds_read_u16 v65, v106 offset:59664
	ds_read_u16 v127, v106 offset:60192
	ds_read_u16 v196, v106 offset:60720
	ds_read_u16 v200, v106 offset:60752
	ds_read_u16 v201, v106 offset:60224
	ds_read_u16 v202, v106 offset:59696
	ds_read_u16 v106, v106 offset:59168
	s_waitcnt lgkmcnt(7)
	v_lshlrev_b32_e32 v64, 16, v64
	v_mul_f32_e32 v51, v75, v51
	v_add_f32_e32 v52, v156, v58
	v_mul_f32_e32 v51, 0x3fb8aa3b, v51
	v_mul_f32_e32 v52, 0xbfb8aa3b, v52
	v_exp_f32_e32 v53, v51
	v_exp_f32_e32 v52, v52
	v_add_f32_e32 v59, v156, v59
	v_mul_f32_e32 v59, 0xbfb8aa3b, v59
	v_fma_f32 v58, -v53, v53, 1.0
	v_add_f32_e32 v52, 1.0, v52
	v_max_f32_e32 v58, 0, v58
	v_rcp_f32_e32 v52, v52
	v_sqrt_f32_e32 v58, v58
	v_exp_f32_e32 v59, v59
	v_add_f32_e32 v60, v156, v60
	v_mul_f32_e32 v60, 0xbfb8aa3b, v60
	v_mul_f32_e32 v52, v52, v58
	v_add_f32_e32 v58, v157, v197
	v_mul_f32_e32 v58, 0xbfb8aa3b, v58
	v_exp_f32_e32 v58, v58
	v_mul_f32_e32 v52, v52, v64
	v_add_f32_e32 v64, v157, v198
	v_mul_f32_e32 v64, 0xbfb8aa3b, v64
	v_add_f32_e32 v58, 1.0, v58
	v_rcp_f32_e32 v58, v58
	v_add_f32_e32 v157, v157, v199
	v_exp_f32_e32 v64, v64
	v_mul_f32_e32 v157, 0xbfb8aa3b, v157
	v_exp_f32_e32 v157, v157
	v_mul_f32_e32 v58, v75, v58
	v_mul_f32_e32 v58, 0x3fb8aa3b, v58
	v_add_f32_e32 v64, 1.0, v64
	v_exp_f32_e32 v58, v58
	v_rcp_f32_e32 v64, v64
	v_add_f32_e32 v157, 1.0, v157
	v_rcp_f32_e32 v157, v157
	v_fma_f32 v197, -v58, v58, 1.0
	v_mul_f32_e32 v64, v75, v64
	v_add_f32_e32 v59, 1.0, v59
	v_max_f32_e32 v197, 0, v197
	v_mul_f32_e32 v64, 0x3fb8aa3b, v64
	v_mul_f32_e32 v75, v75, v157
	v_rcp_f32_e32 v59, v59
	v_sqrt_f32_e32 v197, v197
	v_exp_f32_e32 v64, v64
	v_add_f32_e32 v61, v156, v61
	v_mul_f32_e32 v75, 0x3fb8aa3b, v75
	v_exp_f32_e32 v60, v60
	v_mul_f32_e32 v61, 0xbfb8aa3b, v61
	v_exp_f32_e32 v75, v75
	v_exp_f32_e32 v61, v61
	v_mul_f32_e32 v59, v59, v197
	v_fma_f32 v197, -v64, v64, 1.0
	v_add_f32_e32 v60, 1.0, v60
	v_max_f32_e32 v197, 0, v197
	v_fma_f32 v157, -v75, v75, 1.0
	v_rcp_f32_e32 v60, v60
	v_sqrt_f32_e32 v156, v197
	v_add_f32_e32 v61, 1.0, v61
	v_max_f32_e32 v157, 0, v157
	v_rcp_f32_e32 v61, v61
	v_sqrt_f32_e32 v157, v157
	s_waitcnt lgkmcnt(6)
	v_lshlrev_b32_e32 v65, 16, v65
	v_mul_f32_e32 v52, v58, v52
	v_fmac_f32_e32 v52, v59, v65
	s_waitcnt lgkmcnt(5)
	v_lshlrev_b32_e32 v127, 16, v127
	v_mul_f32_e32 v60, v60, v156
	v_mul_f32_e32 v52, v64, v52
	v_mul_f32_e32 v157, v61, v157
	v_mul_f32_e32 v53, v58, v53
	v_fmac_f32_e32 v52, v60, v127
	v_mfma_f32_16x16x32_bf16 v[58:61], v[70:73], v[38:41], 0
	s_waitcnt lgkmcnt(4)
	v_lshlrev_b32_e32 v156, 16, v196
	v_mul_f32_e32 v38, v75, v52
	v_fmac_f32_e32 v38, v157, v156
	v_mfma_f32_16x16x32_bf16 v[58:61], v[66:69], v[34:37], v[58:61]
	v_mul_f32_e32 v53, v64, v53
	v_mul_f32_e32 v53, v75, v53
	ds_bpermute_b32 v39, v102, v53
	v_mfma_f32_16x16x32_bf16 v[70:73], v[70:73], v[46:49], 0
	ds_bpermute_b32 v46, v102, v38
	s_nop 2
	v_add_f32_e32 v34, v155, v58
	v_mul_f32_e32 v34, 0xbfb8aa3b, v34
	v_exp_f32_e32 v34, v34
	v_mfma_f32_16x16x32_bf16 v[40:43], v[66:69], v[42:45], v[70:73]
	ds_bpermute_b32 v47, v102, v38 offset:64
	ds_bpermute_b32 v49, v102, v38 offset:128
	v_add_f32_e32 v34, 1.0, v34
	v_rcp_f32_e32 v34, v34
	ds_bpermute_b32 v45, v102, v38 offset:192
	s_nop 2
	v_add_f32_e32 v36, v154, v40
	v_mul_f32_e32 v36, 0xbfb8aa3b, v36
	v_mul_f32_e32 v34, v104, v34
	v_mul_f32_e32 v34, 0x3fb8aa3b, v34
	v_exp_f32_e32 v34, v34
	v_exp_f32_e32 v36, v36
	v_add_f32_e32 v41, v154, v41
	v_mul_f32_e32 v41, 0xbfb8aa3b, v41
	v_fma_f32 v37, -v34, v34, 1.0
	v_add_f32_e32 v36, 1.0, v36
	v_max_f32_e32 v37, 0, v37
	v_rcp_f32_e32 v36, v36
	v_sqrt_f32_e32 v40, v37
	v_exp_f32_e32 v41, v41
	s_waitcnt lgkmcnt(5)
; #define LAS __attribute__((address_space(3)))
; __device__ __forceinline__ unsigned f2bf(float f) { unsigned u = __builtin_bit_cast(unsigned, f); return (u + 0x7fffu + ((u >> 16) & 1u)) >> 16; }
; __device__ __forceinline__ float fgelu(float x) { const float u = 0.7978845608028654f * (x + 0.044715f * x * x * x); return 0.5f * x * (2.0f - 2.0f * frcp(__expf(2.0f * u) + 1.0f)); }
; template <int DIR, int MODE>
; __device__ __forceinline__ void lru_pass(const Args& a, const LAS bf16_t* cxb, LAS bf16_t* gyb, const LAS float* carry, const bf16x8 (&Bw)[2][2][2], const float (&prm)[2][3], int l, int tt, float (&hf)[8][2][4]) {
;     ...
;             for (int q = 0; q < 4; ++q) { Aq[q] = __shfl(A4, fr + 16 * q); Hq[q] = __shfl(H4, fr + 16 * q); }
;             float hin;
;             if (DIR == 0) { const float s0 = C[nt], s1 = Aq[0] * s0 + Hq[0], s2 = Aq[1] * s1 + Hq[1], s3 = Aq[2] * s2 + Hq[2]; C[nt] = Aq[3] * s3 + Hq[3]; hin = fq == 0 ? s0 : (fq == 1 ? s1 : (fq == 2 ? s2 : s3)); }
;             else { const float s3 = C[nt], s2 = Aq[3] * s3 + Hq[3], s1 = Aq[2] * s2 + Hq[2], s0 = Aq[1] * s1 + Hq[1]; C[nt] = Aq[0] * s0 + Hq[0]; hin = fq == 3 ? s3 : (fq == 2 ? s2 : (fq == 1 ? s1 : s0)); }
;             if (MODE == 0) At[nt] *= (Aq[0] * Aq[1]) * (Aq[2] * Aq[3]);
;             else {
; #pragma unroll
;                 for (int reg = 0; reg < 4; ++reg) {
;                     const float hv = hl[reg] + cum[reg] * hin;
;                     if (DIR == 0) hf[m][nt][reg] = hv;
;                     else { LAS bf16_t* gp = gyb + (m * 16 + 4 * fq + reg) * CXS + cc[nt];
;                         const float g = bf2f(*gp);
;                         *gp = (bf16_t)f2bf((hf[m][nt][reg] + hv) * fgelu(g)); }
;                 }
;             }
;         }
;     }
;     if (MODE == 0 && fq == 0) {
; #pragma unroll
;         for (int nt = 0; nt < 2; ++nt) { f32x2 sm; sm[0] = At[nt]; sm[1] = C[nt]; *(f32x2*)(SUM + ((size_t)(tt * 2 + DIR) * 256 + cc[nt]) * 2) = sm; }
	v_lshlrev_b32_e32 v38, 16, v106
	v_add_f32_e32 v42, v154, v42
	v_mul_f32_e32 v36, v36, v40
	v_add_f32_e32 v40, v155, v59
	v_mul_f32_e32 v40, 0xbfb8aa3b, v40
	v_exp_f32_e32 v40, v40
	v_mul_f32_e32 v36, v36, v38
	v_add_f32_e32 v38, 1.0, v41
	v_rcp_f32_e32 v38, v38
	v_add_f32_e32 v40, 1.0, v40
	v_rcp_f32_e32 v40, v40
	v_add_f32_e32 v41, v155, v60
	v_mul_f32_e32 v41, 0xbfb8aa3b, v41
	v_exp_f32_e32 v41, v41
	v_mul_f32_e32 v40, v104, v40
	v_mul_f32_e32 v40, 0x3fb8aa3b, v40
	v_exp_f32_e32 v40, v40
	v_add_f32_e32 v41, 1.0, v41
	v_rcp_f32_e32 v41, v41
	v_mul_f32_e32 v42, 0xbfb8aa3b, v42
	v_fma_f32 v44, -v40, v40, 1.0
	v_max_f32_e32 v44, 0, v44
	v_sqrt_f32_e32 v44, v44
	v_mul_f32_e32 v41, v104, v41
	v_mul_f32_e32 v41, 0x3fb8aa3b, v41
	v_exp_f32_e32 v41, v41
	v_mul_f32_e32 v38, v38, v44
	v_add_f32_e32 v44, v155, v61
	v_mul_f32_e32 v44, 0xbfb8aa3b, v44
	v_exp_f32_e32 v44, v44
	v_exp_f32_e32 v42, v42
	v_add_f32_e32 v43, v154, v43
	v_mul_f32_e32 v43, 0xbfb8aa3b, v43
	v_add_f32_e32 v44, 1.0, v44
	v_rcp_f32_e32 v44, v44
	v_exp_f32_e32 v43, v43
	ds_bpermute_b32 v48, v102, v53 offset:64
	ds_bpermute_b32 v35, v102, v53 offset:128
	v_mul_f32_e32 v44, v104, v44
	v_mul_f32_e32 v44, 0x3fb8aa3b, v44
	v_exp_f32_e32 v44, v44
	ds_bpermute_b32 v37, v102, v53 offset:192
	v_fma_f32 v53, -v41, v41, 1.0
	v_add_f32_e32 v42, 1.0, v42
	v_max_f32_e32 v53, 0, v53
	v_rcp_f32_e32 v42, v42
	v_sqrt_f32_e32 v53, v53
	v_fma_f32 v58, -v44, v44, 1.0
	v_add_f32_e32 v43, 1.0, v43
	v_max_f32_e32 v58, 0, v58
	v_lshlrev_b32_e32 v52, 16, v202
	v_rcp_f32_e32 v43, v43
	v_sqrt_f32_e32 v58, v58
	v_mul_f32_e32 v36, v40, v36
	v_fmac_f32_e32 v36, v38, v52
	v_lshlrev_b32_e32 v59, 16, v201
	v_mul_f32_e32 v42, v42, v53
	v_mul_f32_e32 v36, v41, v36
	v_mul_f32_e32 v34, v40, v34
	v_fmac_f32_e32 v36, v42, v59
	v_lshlrev_b32_e32 v53, 16, v200
	v_mul_f32_e32 v43, v43, v58
	v_mul_f32_e32 v34, v41, v34
	v_mul_f32_e32 v40, v44, v36
	v_mul_f32_e32 v38, v44, v34
	v_fmac_f32_e32 v40, v43, v53
	ds_bpermute_b32 v176, v102, v107 offset:64
	ds_bpermute_b32 v177, v102, v179 offset:64
	ds_bpermute_b32 v105, v102, v107 offset:128
	ds_bpermute_b32 v178, v102, v179 offset:128
	ds_bpermute_b32 v107, v102, v107 offset:192
	ds_bpermute_b32 v179, v102, v179 offset:192
	ds_bpermute_b32 v114, v102, v113
	ds_bpermute_b32 v184, v102, v187
	ds_bpermute_b32 v112, v102, v113 offset:64
	ds_bpermute_b32 v185, v102, v187 offset:64
	ds_bpermute_b32 v115, v102, v113 offset:128
	ds_bpermute_b32 v186, v102, v187 offset:128
	ds_bpermute_b32 v113, v102, v113 offset:192
	ds_bpermute_b32 v187, v102, v187 offset:192
	s_nop 0
	s_nop 0
	s_nop 0
	s_nop 0
	s_nop 0
	s_nop 0
	v_mov_b32_e32 v55, v204
	v_mov_b32_e32 v56, v204
	s_nop 1
	v_permlane16_swap_b32_e32 v55, v56
	s_nop 1
	v_mov_b32_e32 v63, v55
	v_mov_b32_e32 v50, v56
	s_nop 1
	v_permlane32_swap_b32_e32 v55, v63
	v_permlane32_swap_b32_e32 v56, v50
	s_nop 1
	v_mov_b32_e32 v54, v205
	v_mov_b32_e32 v57, v205
	s_nop 1
	v_permlane16_swap_b32_e32 v54, v57
	s_nop 1
	v_mov_b32_e32 v62, v54
	v_mov_b32_e32 v51, v57
	s_nop 1
	v_permlane32_swap_b32_e32 v54, v62
	v_permlane32_swap_b32_e32 v57, v51
	s_nop 1
	s_nop 0
	s_nop 0
	s_nop 0
	s_nop 0
	s_nop 0
	s_nop 0
	v_mov_b32_e32 v58, v38
	v_mov_b32_e32 v59, v38
	s_nop 1
	v_permlane16_swap_b32_e32 v58, v59
	s_nop 1
	v_mov_b32_e32 v43, v58
	v_mov_b32_e32 v41, v59
	s_nop 1
	v_permlane32_swap_b32_e32 v58, v43
	v_permlane32_swap_b32_e32 v59, v41
	s_nop 1
	v_mov_b32_e32 v34, v40
	v_mov_b32_e32 v36, v40
	s_nop 1
	v_permlane16_swap_b32_e32 v34, v36
	s_nop 1
	v_mov_b32_e32 v53, v34
	v_mov_b32_e32 v52, v36
	s_nop 1
	v_permlane32_swap_b32_e32 v34, v53
	v_permlane32_swap_b32_e32 v36, v52
	s_nop 1
	v_add_f32_e32 v44, 1.0, v117
	v_frexp_mant_f32_e32 v38, v44
	v_cmp_gt_f32_e64 s[0:1], s28, v38
	s_and_saveexec_b64 s[4:5], s[36:37]
	s_cbranch_execz .LBB0_773
	v_fmac_f32_e32 v123, 0, v86
	v_fmac_f32_e32 v124, v123, v84
	v_fmac_f32_e32 v125, v124, v88
	v_fmac_f32_e32 v126, v125, v90
	v_fmac_f32_e32 v132, v126, v87
	v_fmac_f32_e32 v133, v132, v85
	v_fmac_f32_e32 v134, v133, v89
	v_fmac_f32_e32 v135, v134, v91
	v_fmac_f32_e32 v140, v135, v98
	v_fmac_f32_e32 v119, 0, v76
	v_fmac_f32_e32 v141, v140, v96
	v_fmac_f32_e32 v120, v119, v78
	v_fmac_f32_e32 v142, v141, v99
	v_fmac_f32_e32 v121, v120, v80
	v_fmac_f32_e32 v143, v142, v97
	v_fmac_f32_e32 v122, v121, v82
	v_fmac_f32_e32 v160, v143, v161
	v_fmac_f32_e32 v128, v122, v77
	v_fmac_f32_e32 v163, v160, v162
	v_fmac_f32_e32 v129, v128, v79
	v_fmac_f32_e32 v164, v163, v165
	v_fmac_f32_e32 v130, v129, v81
	v_fmac_f32_e32 v167, v164, v166
	v_fmac_f32_e32 v131, v130, v83
	v_fmac_f32_e32 v174, v167, v175
	v_fmac_f32_e32 v136, v131, v92
	s_waitcnt lgkmcnt(0)
	v_fmac_f32_e32 v177, v174, v176
	v_fmac_f32_e32 v137, v136, v94
	v_fmac_f32_e32 v178, v177, v105
	v_fmac_f32_e32 v138, v137, v93
	v_fmac_f32_e32 v179, v178, v107
	v_fmac_f32_e32 v139, v138, v95
	v_fmac_f32_e32 v184, v179, v114
	v_fmac_f32_e32 v145, v139, v144
	v_fmac_f32_e32 v185, v184, v112
	v_fmac_f32_e32 v146, v145, v147
	v_fmac_f32_e32 v186, v185, v115
	v_fmac_f32_e32 v149, v146, v148
	v_fmac_f32_e32 v187, v186, v113
	v_fmac_f32_e32 v158, v149, v159
	v_fmac_f32_e32 v54, v187, v55
	v_fmac_f32_e32 v169, v158, v168
	s_waitcnt lgkmcnt(0)
	v_fmac_f32_e32 v57, v54, v56
	v_fmac_f32_e32 v170, v169, v171
	v_pk_mul_f32 v[66:67], v[86:87], v[84:85]
	v_pk_mul_f32 v[68:69], v[88:89], v[90:91]
	s_waitcnt lgkmcnt(0)
	v_fmac_f32_e32 v62, v57, v63
	v_fmac_f32_e32 v172, v170, v101
	v_pk_mul_f32 v[64:65], v[98:99], v[96:97]
	v_pk_mul_f32 v[66:67], v[66:67], v[68:69]
	s_waitcnt lgkmcnt(0)
; #define LAS __attribute__((address_space(3)))
; __device__ __forceinline__ unsigned f2bf(float f) { unsigned u = __builtin_bit_cast(unsigned, f); return (u + 0x7fffu + ((u >> 16) & 1u)) >> 16; }
; __device__ __forceinline__ float fgelu(float x) { const float u = 0.7978845608028654f * (x + 0.044715f * x * x * x); return 0.5f * x * (2.0f - 2.0f * frcp(__expf(2.0f * u) + 1.0f)); }
; template <int DIR, int MODE>
; __device__ __forceinline__ void lru_pass(const Args& a, const LAS bf16_t* cxb, LAS bf16_t* gyb, const LAS float* carry, const bf16x8 (&Bw)[2][2][2], const float (&prm)[2][3], int l, int tt, float (&hf)[8][2][4]) {
;     ...
;             if (DIR == 0) { const float s0 = C[nt], s1 = Aq[0] * s0 + Hq[0], s2 = Aq[1] * s1 + Hq[1], s3 = Aq[2] * s2 + Hq[2]; C[nt] = Aq[3] * s3 + Hq[3]; hin = fq == 0 ? s0 : (fq == 1 ? s1 : (fq == 2 ? s2 : s3)); }
;             else { const float s3 = C[nt], s2 = Aq[3] * s3 + Hq[3], s1 = Aq[2] * s2 + Hq[2], s0 = Aq[1] * s1 + Hq[1]; C[nt] = Aq[0] * s0 + Hq[0]; hin = fq == 3 ? s3 : (fq == 2 ? s2 : (fq == 1 ? s1 : s0)); }
;             if (MODE == 0) At[nt] *= (Aq[0] * Aq[1]) * (Aq[2] * Aq[3]);
;             else {
; #pragma unroll
;                 for (int reg = 0; reg < 4; ++reg) {
;                     const float hv = hl[reg] + cum[reg] * hin;
;                     if (DIR == 0) hf[m][nt][reg] = hv;
;                     else { LAS bf16_t* gp = gyb + (m * 16 + 4 * fq + reg) * CXS + cc[nt];
;                         const float g = bf2f(*gp);
;                         *gp = (bf16_t)f2bf((hf[m][nt][reg] + hv) * fgelu(g)); }
;                 }
;             }
;         }
;     }
;     if (MODE == 0 && fq == 0) {
; #pragma unroll
;         for (int nt = 0; nt < 2; ++nt) { f32x2 sm; sm[0] = At[nt]; sm[1] = C[nt]; *(f32x2*)(SUM + ((size_t)(tt * 2 + DIR) * 256 + cc[nt]) * 2) = sm; }
; template <int MODE>
; __device__ __forceinline__ void lru_unit(const Args& a, LAS unsigned char* lds, int l, int tt) {
;     ...
;     for (int nt = 0; nt < 2; ++nt) { prm0[nt][2] = -8.0f * log1pf(__expf(-prm0[nt][2])); prm1[nt][2] = -8.0f * log1pf(__expf(-prm1[nt][2])); }
	v_fmac_f32_e32 v51, v62, v50
	v_fmac_f32_e32 v173, v172, v103
	v_pk_mul_f32 v[66:67], v[66:67], v[66:67] op_sel:[0,1] op_sel_hi:[1,0]
	v_pk_mul_f32 v[64:65], v[64:65], v[64:65] op_sel:[0,1] op_sel_hi:[1,0]
	s_waitcnt lgkmcnt(0)
	v_fmac_f32_e32 v34, v51, v58
	v_fmac_f32_e32 v180, v173, v108
	v_mul_f32_e32 v42, v55, v56
	v_mul_f32_e32 v40, v63, v50
	v_mov_b32_e32 v67, v175
	v_mov_b32_e32 v65, v176
	s_waitcnt lgkmcnt(0)
	v_fmac_f32_e32 v36, v34, v59
	v_pk_mul_f32 v[50:51], v[76:77], v[78:79]
	v_pk_mul_f32 v[54:55], v[80:81], v[82:83]
	v_fmac_f32_e32 v181, v180, v110
	v_pk_mul_f32 v[64:65], v[66:67], v[64:65]
	s_waitcnt lgkmcnt(0)
	v_pk_mul_f32 v[66:67], v[42:43], v[40:41]
	v_fmac_f32_e32 v53, v36, v43
	v_pk_mul_f32 v[42:43], v[92:93], v[94:95]
	v_pk_mul_f32 v[50:51], v[50:51], v[54:55]
	v_fmac_f32_e32 v182, v181, v109
	v_pk_mul_f32 v[50:51], v[50:51], v[50:51] op_sel:[0,1] op_sel_hi:[1,0]
	v_pk_mul_f32 v[42:43], v[42:43], v[42:43] op_sel:[0,1] op_sel_hi:[1,0]
	v_fmac_f32_e32 v183, v182, v111
	v_mul_f32_e32 v100, v144, v147
	v_mul_f32_e32 v102, v148, v159
	v_mov_b32_e32 v51, v168
	v_mov_b32_e32 v43, v171
	v_fmac_f32_e32 v189, v183, v188
	v_pk_mul_f32 v[54:55], v[100:101], v[102:103]
	v_pk_mul_f32 v[42:43], v[50:51], v[42:43]
	v_fmac_f32_e32 v190, v189, v191
	v_mul_f32_e32 v104, v161, v162
	v_mul_f32_e32 v106, v165, v166
	s_waitcnt lgkmcnt(0)
	v_fmac_f32_e32 v52, v53, v41
	v_pk_mul_f32 v[40:41], v[108:109], v[110:111]
	v_pk_mul_f32 v[42:43], v[42:43], v[54:55]
	v_fmac_f32_e32 v193, v190, v192
	v_pk_mul_f32 v[68:69], v[104:105], v[106:107]
	v_pk_mul_f32 v[42:43], v[42:43], v[42:43] op_sel:[0,1] op_sel_hi:[1,0]
	v_pk_mul_f32 v[40:41], v[40:41], v[40:41] op_sel:[0,1] op_sel_hi:[1,0]
	v_fmac_f32_e32 v194, v193, v195
	s_lshl_b32 s34, s82, 1
	v_pk_mul_f32 v[60:61], v[114:115], v[112:113]
	v_pk_mul_f32 v[64:65], v[64:65], v[68:69]
	v_mul_f32_e32 v34, v188, v191
	v_mul_f32_e32 v36, v192, v195
	v_mov_b32_e32 v43, v39
	v_mov_b32_e32 v41, v48
	v_fmac_f32_e32 v46, v194, v39
	s_ashr_i32 s35, s34, 31
	v_pk_mul_f32 v[64:65], v[64:65], v[64:65] op_sel:[0,1] op_sel_hi:[1,0]
	v_pk_mul_f32 v[60:61], v[60:61], v[60:61] op_sel:[0,1] op_sel_hi:[1,0]
	v_pk_mul_f32 v[50:51], v[34:35], v[36:37]
	v_pk_mul_f32 v[40:41], v[42:43], v[40:41]
	v_fmac_f32_e32 v47, v46, v48
	s_lshl_b64 s[34:35], s[34:35], 11
	v_readlane_b32 s28, v253, 43
	v_mov_b32_e32 v65, v58
	v_mov_b32_e32 v61, v59
	v_pk_mul_f32 v[40:41], v[40:41], v[50:51]
	v_fmac_f32_e32 v49, v47, v35
	v_readlane_b32 s29, v253, 44
	s_add_u32 s34, s28, s34
	v_pk_mul_f32 v[60:61], v[64:65], v[60:61]
	v_fmac_f32_e32 v45, v49, v37
	s_addc_u32 s35, s29, s35
	v_pk_mul_f32 v[34:35], v[40:41], v[40:41] op_sel:[0,1] op_sel_hi:[1,0]
	v_ashrrev_i32_e32 v75, 31, v74
	v_or_b32_e32 v38, 16, v74
	v_pk_mul_f32 v[60:61], v[60:61], v[66:67]
	v_mov_b32_e32 v35, v45
	v_lshl_add_u64 v[36:37], v[74:75], 3, s[34:35]
	global_store_dwordx2 v[36:37], v[34:35], off
	v_pk_mul_f32 v[34:35], v[60:61], v[60:61] op_sel:[0,1] op_sel_hi:[1,0]
	v_ashrrev_i32_e32 v39, 31, v38
	v_mov_b32_e32 v35, v52
	v_lshl_add_u64 v[36:37], v[38:39], 3, s[34:35]
	global_store_dwordx2 v[36:37], v[34:35], off
.LBB0_773:
	s_or_b64 exec, exec, s[4:5]
	s_waitcnt lgkmcnt(0)
	v_add_f32_e32 v34, -1.0, v118
	v_sub_f32_e32 v35, v34, v118
	v_add_f32_e32 v35, 1.0, v35
	v_sub_f32_e32 v34, v116, v34
	s_waitcnt lgkmcnt(0)
	v_add_f32_e32 v36, v34, v35
	v_cvt_f64_f32_e32 v[34:35], v118
	v_frexp_exp_i32_f64_e32 v34, v[34:35]
	v_subbrev_co_u32_e32 v34, vcc, 0, v34, vcc
	v_sub_u32_e32 v35, 0, v34
	v_ldexp_f32 v37, v118, v35
	v_ldexp_f32 v35, v36, v35
	v_add_f32_e32 v36, -1.0, v37
	v_add_f32_e32 v40, 1.0, v37
	v_add_f32_e32 v38, 1.0, v36
	s_waitcnt lgkmcnt(0)
	v_add_f32_e32 v41, -1.0, v40
	v_sub_f32_e32 v38, v37, v38
	v_sub_f32_e32 v37, v37, v41
	v_add_f32_e32 v38, v35, v38
	v_add_f32_e32 v35, v35, v37
	v_add_f32_e32 v37, v40, v35
	v_rcp_f32_e32 v41, v37
	v_add_f32_e32 v39, v36, v38
	v_sub_f32_e32 v36, v39, v36
	v_sub_f32_e32 v36, v38, v36
	v_sub_f32_e32 v38, v37, v40
	v_sub_f32_e32 v35, v35, v38
	v_mul_f32_e32 v38, v39, v41
	v_mul_f32_e32 v40, v37, v38
	v_fma_f32 v42, v38, v37, -v40
	v_fmac_f32_e32 v42, v38, v35
	v_add_f32_e32 v43, v40, v42
	v_sub_f32_e32 v45, v39, v43
	v_sub_f32_e32 v39, v39, v45
	v_sub_f32_e32 v40, v43, v40
	v_sub_f32_e32 v39, v39, v43
	v_add_f32_e32 v36, v36, v39
	v_sub_f32_e32 v39, v40, v42
	v_add_f32_e32 v36, v39, v36
	v_add_f32_e32 v39, v45, v36
	v_mul_f32_e32 v40, v41, v39
	v_mul_f32_e32 v42, v37, v40
	v_fma_f32 v37, v40, v37, -v42
	v_fmac_f32_e32 v37, v40, v35
	v_sub_f32_e32 v35, v45, v39
	v_add_f32_e32 v35, v36, v35
	v_add_f32_e32 v36, v42, v37
	v_sub_f32_e32 v43, v39, v36
	v_sub_f32_e32 v39, v39, v43
	v_sub_f32_e32 v42, v36, v42
	v_sub_f32_e32 v36, v39, v36
	v_add_f32_e32 v35, v35, v36
	v_sub_f32_e32 v36, v42, v37
	v_cvt_f32_i32_e32 v34, v34
	v_add_f32_e32 v35, v36, v35
	v_add_f32_e32 v36, v38, v40
	v_add_f32_e32 v35, v43, v35
	v_sub_f32_e32 v37, v36, v38
	v_mul_f32_e32 v35, v41, v35
	v_sub_f32_e32 v37, v40, v37
	v_add_f32_e32 v35, v37, v35
	v_mul_f32_e32 v40, 0x3f317218, v34
	s_mov_b32 s4, 0x3f317218
	v_add_f32_e32 v37, v36, v35
	v_fma_f32 v41, v34, s4, -v40
	v_fmac_f32_e32 v41, 0xb102e308, v34
	v_sub_f32_e32 v34, v37, v36
	v_sub_f32_e32 v34, v35, v34
	v_ldexp_f32 v42, v34, 1
	v_add_f32_e32 v34, -1.0, v44
	v_sub_f32_e32 v35, v34, v44
	v_add_f32_e32 v35, 1.0, v35
	v_sub_f32_e32 v34, v117, v34
	v_add_f32_e32 v45, v34, v35
	v_cvt_f64_f32_e32 v[34:35], v44
	v_frexp_exp_i32_f64_e32 v34, v[34:35]
	v_subbrev_co_u32_e64 v34, vcc, 0, v34, s[0:1]
	v_sub_u32_e32 v35, 0, v34
	v_ldexp_f32 v44, v44, v35
	v_ldexp_f32 v35, v45, v35
	v_add_f32_e32 v45, -1.0, v44
	v_add_f32_e32 v48, 1.0, v44
	v_add_f32_e32 v46, 1.0, v45
	v_add_f32_e32 v49, -1.0, v48
	v_sub_f32_e32 v46, v44, v46
	v_sub_f32_e32 v44, v44, v49
	v_add_f32_e32 v46, v35, v46
	v_add_f32_e32 v35, v35, v44
	v_add_f32_e32 v44, v48, v35
	v_rcp_f32_e32 v49, v44
	v_add_f32_e32 v47, v45, v46
	v_sub_f32_e32 v45, v47, v45
	v_sub_f32_e32 v45, v46, v45
	v_sub_f32_e32 v46, v44, v48
	v_sub_f32_e32 v35, v35, v46
	v_mul_f32_e32 v46, v47, v49
	v_mul_f32_e32 v48, v44, v46
	v_fma_f32 v50, v46, v44, -v48
	v_fmac_f32_e32 v50, v46, v35
	v_add_f32_e32 v51, v48, v50
	s_waitcnt lgkmcnt(0)
; #define LAS __attribute__((address_space(3)))
; __device__ __forceinline__ int opaque_tid() { int t = threadIdx.x; asm volatile("" : "+v"(t)); return t; }
; template <int DIR, int MODE>
; __device__ __forceinline__ void lru_pass(const Args& a, const LAS bf16_t* cxb, LAS bf16_t* gyb, const LAS float* carry, const bf16x8 (&Bw)[2][2][2], const float (&prm)[2][3], int l, int tt, float (&hf)[8][2][4]) {
;     const int tid = opaque_tid(), lane = tid & 63, w = __builtin_amdgcn_readfirstlane(tid >> 6), h = w & 3, nh = w >> 2, fr = lane & 15, fq = lane >> 4;
;     float* SUM = (float*)(a.ws + WS_SUM);
;     float ba[2], bxv[2], k8[2], C[2], At[2]; int cc[2];
; #pragma unroll
;     for (int nt = 0; nt < 2; ++nt) {
;         const int c = 64 * h + 32 * nh + 16 * nt + fr; cc[nt] = c;
;         ba[nt] = prm[nt][0]; bxv[nt] = prm[nt][1]; k8[nt] = prm[nt][2];
;         C[nt] = MODE == 1 ? carry[DIR * 256 + c] : 0.f; At[nt] = 1.f;
;     }
; #pragma unroll
;     for (int mi = 0; mi < 8; ++mi) {
;         const int m = DIR ? 7 - mi : mi;
;         bf16x8 Af[2];
; #pragma unroll
;         for (int ks = 0; ks < 2; ++ks) Af[ks] = *(const LAS bf16x8*)(cxb + (m * 16 + fr) * CXS + 64 * h + 32 * ks + 8 * fq);
; #pragma unroll
;         for (int nt = 0; nt < 2; ++nt) {
;             f32x4 pr = (f32x4){0.f, 0.f, 0.f, 0.f}, pi = (f32x4){0.f, 0.f, 0.f, 0.f};
; #pragma unroll
;             for (int ks = 0; ks < 2; ++ks) { pr = __builtin_amdgcn_mfma_f32_16x16x32_bf16(Af[ks], Bw[0][nt][ks], pr, 0, 0, 0); pi = __builtin_amdgcn_mfma_f32_16x16x32_bf16(Af[ks], Bw[1][nt][ks], pi, 0, 0, 0); }
;             float av[4], bv[4];
; #pragma unroll
;             for (int reg = 0; reg < 4; ++reg) {
;                 const int tok = m * 16 + 4 * fq + reg;
;                 const float x = bf2f(cxb[tok * CXS + cc[nt]]);
;                 const float r = fsig(pr[reg] + ba[nt]), ig = fsig(pi[reg] + bxv[nt]);
;                 const float aa = __expf(k8[nt] * r);
;                 av[reg] = aa; bv[reg] = __builtin_amdgcn_sqrtf(fmaxf(1.0f - aa * aa, 0.f)) * ig * x;
; template <int MODE>
; __device__ __forceinline__ void lru_unit(const Args& a, LAS unsigned char* lds, int l, int tt) {
;     ...
;     for (int nt = 0; nt < 2; ++nt) { prm0[nt][2] = -8.0f * log1pf(__expf(-prm0[nt][2])); prm1[nt][2] = -8.0f * log1pf(__expf(-prm1[nt][2])); }
	v_sub_f32_e32 v52, v47, v51
	v_sub_f32_e32 v47, v47, v52
	v_sub_f32_e32 v48, v51, v48
	v_sub_f32_e32 v47, v47, v51
	v_add_f32_e32 v45, v45, v47
	v_sub_f32_e32 v47, v48, v50
	v_mul_f32_e32 v38, v37, v37
	v_mov_b32_e32 v53, 0x3ecc95a3
	v_add_f32_e32 v45, v47, v45
	v_fmamk_f32 v39, v38, 0x3e9b6dac, v53
	v_add_f32_e32 v47, v52, v45
	v_fmaak_f32 v39, v38, v39, 0x3f2aaada
	v_ldexp_f32 v36, v37, 1
	v_mul_f32_e32 v48, v49, v47
	v_mul_f32_e32 v37, v37, v38
	v_mul_f32_e32 v50, v44, v48
	v_mul_f32_e32 v37, v37, v39
	v_fma_f32 v44, v48, v44, -v50
	v_add_f32_e32 v38, v36, v37
	v_fmac_f32_e32 v44, v48, v35
	v_sub_f32_e32 v35, v52, v47
	v_sub_f32_e32 v36, v38, v36
	v_add_f32_e32 v35, v45, v35
	v_add_f32_e32 v45, v50, v44
	v_sub_f32_e32 v36, v37, v36
	v_sub_f32_e32 v51, v47, v45
	v_add_f32_e32 v36, v42, v36
	v_sub_f32_e32 v50, v45, v50
	v_sub_f32_e32 v47, v47, v51
	v_add_f32_e32 v37, v38, v36
	v_sub_f32_e32 v45, v47, v45
	v_sub_f32_e32 v44, v50, v44
	v_add_f32_e32 v50, v40, v41
	v_sub_f32_e32 v38, v37, v38
	v_add_f32_e32 v35, v35, v45
	v_sub_f32_e32 v36, v36, v38
	v_add_f32_e32 v38, v50, v37
	v_add_f32_e32 v35, v44, v35
	v_add_f32_e32 v44, v46, v48
	v_sub_f32_e32 v40, v50, v40
	v_sub_f32_e32 v39, v38, v50
	v_add_f32_e32 v35, v51, v35
	v_sub_f32_e32 v45, v44, v46
	v_cvt_f32_i32_e32 v34, v34
	v_sub_f32_e32 v40, v41, v40
	v_sub_f32_e32 v41, v38, v39
	v_mul_f32_e32 v35, v49, v35
	v_sub_f32_e32 v45, v48, v45
	v_sub_f32_e32 v41, v50, v41
	v_sub_f32_e32 v37, v37, v39
	v_add_f32_e32 v35, v45, v35
	v_add_f32_e32 v37, v37, v41
	v_add_f32_e32 v39, v40, v36
	v_add_f32_e32 v45, v44, v35
	v_sub_f32_e32 v41, v39, v40
	v_add_f32_e32 v37, v39, v37
	v_mul_f32_e32 v46, v45, v45
	v_mul_f32_e32 v48, 0x3f317218, v34
	v_sub_f32_e32 v42, v39, v41
	v_add_f32_e32 v39, v38, v37
	v_fmamk_f32 v47, v46, 0x3e9b6dac, v53
	v_fma_f32 v49, v34, s4, -v48
	v_sub_f32_e32 v40, v40, v42
	v_sub_f32_e32 v36, v36, v41
	v_sub_f32_e32 v38, v39, v38
	v_fmaak_f32 v47, v46, v47, 0x3f2aaada
	v_fmac_f32_e32 v49, 0xb102e308, v34
	v_sub_f32_e32 v34, v45, v44
	v_add_f32_e32 v36, v36, v40
	v_sub_f32_e32 v37, v37, v38
	v_mul_f32_e32 v38, v45, v46
	v_sub_f32_e32 v34, v35, v34
	v_ldexp_f32 v35, v45, 1
	v_add_f32_e32 v36, v36, v37
	s_mov_b32 s5, 0x7f800000
	v_mul_f32_e32 v38, v38, v47
	v_add_f32_e32 v36, v39, v36
	v_cmp_neq_f32_e32 vcc, s5, v116
	v_mov_b32_e32 v41, 0x7f800000
	v_add_f32_e32 v39, v35, v38
	v_cndmask_b32_e32 v36, v41, v36, vcc
	v_cmp_ngt_f32_e32 vcc, -1.0, v116
	v_mov_b32_e32 v42, 0x7fc00000
	v_sub_f32_e32 v35, v39, v35
	v_and_b32_e32 v43, 0x7fffffff, v116
	v_ldexp_f32 v34, v34, 1
	v_cndmask_b32_e32 v36, v42, v36, vcc
	v_cmp_neq_f32_e32 vcc, -1.0, v116
	v_mov_b32_e32 v50, 0xff800000
	s_mov_b32 s28, 0x33800000
	v_sub_f32_e32 v35, v38, v35
	v_cndmask_b32_e32 v36, v50, v36, vcc
	v_cmp_gt_f32_e32 vcc, s28, v43
	v_add_f32_e32 v34, v34, v35
	v_add_f32_e32 v35, v39, v34
	v_cndmask_b32_e32 v36, v36, v116, vcc
	v_mul_f32_e32 v74, 0xc1000000, v36
	v_add_f32_e32 v36, v48, v49
	v_sub_f32_e32 v38, v35, v39
	v_sub_f32_e32 v34, v34, v38
	v_add_f32_e32 v38, v36, v35
	v_sub_f32_e32 v39, v38, v36
	v_sub_f32_e32 v37, v36, v48
	v_sub_f32_e32 v40, v38, v39
	v_sub_f32_e32 v37, v49, v37
	v_sub_f32_e32 v36, v36, v40
	v_sub_f32_e32 v35, v35, v39
	v_add_f32_e32 v35, v35, v36
	v_add_f32_e32 v36, v37, v34
	v_sub_f32_e32 v39, v36, v37
	v_sub_f32_e32 v40, v36, v39
	v_add_f32_e32 v35, v36, v35
	v_sub_f32_e32 v37, v37, v40
	v_sub_f32_e32 v34, v34, v39
	v_add_f32_e32 v36, v38, v35
	v_add_f32_e32 v34, v34, v37
	v_sub_f32_e32 v37, v36, v38
	v_sub_f32_e32 v35, v35, v37
	v_add_f32_e32 v34, v34, v35
	v_add_f32_e32 v38, v36, v34
	v_mov_b32_e32 v34, v0
	v_cmp_neq_f32_e32 vcc, s5, v117
	v_readfirstlane_b32 s0, v34
	s_bfe_u32 s1, s0, 0x20006
	v_and_b32_e32 v52, 15, v34
	v_bfe_u32 v43, v34, 4, 2
	s_lshl_b32 s4, s1, 7
	s_add_i32 s4, s4, 0
	v_lshlrev_b32_e32 v34, 4, v43
	v_mul_u32_u24_e32 v35, 0x210, v52
	v_add3_u32 v89, s4, v34, v35
	ds_read_b128 v[34:37], v89 offset:59136
	v_cndmask_b32_e32 v38, v41, v38, vcc
	v_cmp_ngt_f32_e32 vcc, -1.0, v117
	v_and_b32_e32 v44, 0x7fffffff, v117
	s_ashr_i32 s0, s0, 3
	v_cndmask_b32_e32 v38, v42, v38, vcc
	v_cmp_neq_f32_e32 vcc, -1.0, v117
	s_lshl_b32 s1, s1, 6
	s_andn2_b32 s0, s0, 31
	v_cndmask_b32_e32 v42, v50, v38, vcc
	ds_read_b128 v[38:41], v89 offset:59200
	v_cmp_gt_f32_e32 vcc, s28, v44
	s_waitcnt lgkmcnt(1)
	v_mfma_f32_16x16x32_bf16 v[44:47], v[34:37], v[26:29], 0
	s_add_i32 s1, s1, s0
	v_cndmask_b32_e32 v42, v42, v117, vcc
	v_and_b32_e32 v53, 64, v227
	s_waitcnt lgkmcnt(0)
	v_mfma_f32_16x16x32_bf16 v[44:47], v[38:41], v[18:21], v[44:47]
	v_mul_f32_e32 v72, 0xc1000000, v42
	v_or_b32_e32 v42, s1, v52
	v_or_b32_e32 v52, v52, v53
	s_nop 4
	v_add_f32_e32 v44, v153, v44
	v_add_f32_e32 v45, v153, v45
	v_mul_f32_e32 v44, 0xbfb8aa3b, v44
	v_mul_f32_e32 v45, 0xbfb8aa3b, v45
	v_exp_f32_e32 v44, v44
	v_exp_f32_e32 v45, v45
	v_mfma_f32_16x16x32_bf16 v[48:51], v[34:37], v[30:33], 0
	v_add_f32_e32 v46, v153, v46
	v_add_f32_e32 v44, 1.0, v44
	v_add_f32_e32 v45, 1.0, v45
	v_add_f32_e32 v47, v153, v47
	v_rcp_f32_e32 v44, v44
	v_rcp_f32_e32 v45, v45
	v_mul_f32_e32 v46, 0xbfb8aa3b, v46
	v_mul_f32_e32 v47, 0xbfb8aa3b, v47
	v_mfma_f32_16x16x32_bf16 v[48:51], v[38:41], v[22:25], v[48:51]
	v_exp_f32_e32 v46, v46
	v_exp_f32_e32 v47, v47
	v_mul_f32_e32 v44, v74, v44
	v_mul_f32_e32 v45, v74, v45
	v_mul_f32_e32 v44, 0x3fb8aa3b, v44
	s_nop 2
	v_add_f32_e32 v48, v152, v48
	v_add_f32_e32 v49, v152, v49
	v_mul_f32_e32 v45, 0x3fb8aa3b, v45
	v_add_f32_e32 v46, 1.0, v46
	v_add_f32_e32 v47, 1.0, v47
	v_mul_f32_e32 v48, 0xbfb8aa3b, v48
	v_exp_f32_e32 v44, v44
	v_mul_f32_e32 v49, 0xbfb8aa3b, v49
	v_exp_f32_e32 v45, v45
	v_rcp_f32_e32 v46, v46
	v_rcp_f32_e32 v47, v47
	v_exp_f32_e32 v48, v48
	v_exp_f32_e32 v49, v49
	v_lshlrev_b32_e32 v68, 2, v52
	v_lshlrev_b32_e32 v52, 1, v42
	v_mul_u32_u24_e32 v53, 0x840, v43
	v_add3_u32 v70, 0, v52, v53
	v_fma_f32 v53, -v44, v44, 1.0
	v_fma_f32 v55, -v45, v45, 1.0
	v_mul_f32_e32 v46, v74, v46
	v_mul_f32_e32 v47, v74, v47
	ds_read_u16 v52, v70 offset:59136
	ds_read_u16 v54, v70 offset:59664
	v_add_f32_e32 v48, 1.0, v48
	v_max_f32_e32 v53, 0, v53
	v_add_f32_e32 v49, 1.0, v49
	v_max_f32_e32 v55, 0, v55
	v_add_f32_e32 v50, v152, v50
	v_mul_f32_e32 v46, 0x3fb8aa3b, v46
	v_add_f32_e32 v51, v152, v51
	v_mul_f32_e32 v47, 0x3fb8aa3b, v47
	v_rcp_f32_e32 v48, v48
	v_sqrt_f32_e32 v53, v53
	v_rcp_f32_e32 v49, v49
	v_sqrt_f32_e32 v55, v55
	v_mul_f32_e32 v50, 0xbfb8aa3b, v50
	v_exp_f32_e32 v46, v46
	v_mul_f32_e32 v51, 0xbfb8aa3b, v51
	v_exp_f32_e32 v47, v47
	v_exp_f32_e32 v50, v50
	v_exp_f32_e32 v51, v51
	v_mul_f32_e32 v48, v48, v53
	v_mul_f32_e32 v49, v49, v55
	ds_read_u16 v53, v70 offset:60192
	ds_read_u16 v55, v70 offset:60720
	s_waitcnt lgkmcnt(3)
; template <int DIR, int MODE>
; __device__ __forceinline__ void lru_pass(const Args& a, const LAS bf16_t* cxb, LAS bf16_t* gyb, const LAS float* carry, const bf16x8 (&Bw)[2][2][2], const float (&prm)[2][3], int l, int tt, float (&hf)[8][2][4]) {
;     ...
;     for (int mi = 0; mi < 8; ++mi) {
;         const int m = DIR ? 7 - mi : mi;
;         bf16x8 Af[2];
; #pragma unroll
;         for (int ks = 0; ks < 2; ++ks) Af[ks] = *(const LAS bf16x8*)(cxb + (m * 16 + fr) * CXS + 64 * h + 32 * ks + 8 * fq);
; #pragma unroll
;         for (int nt = 0; nt < 2; ++nt) {
;             f32x4 pr = (f32x4){0.f, 0.f, 0.f, 0.f}, pi = (f32x4){0.f, 0.f, 0.f, 0.f};
; #pragma unroll
;             for (int ks = 0; ks < 2; ++ks) { pr = __builtin_amdgcn_mfma_f32_16x16x32_bf16(Af[ks], Bw[0][nt][ks], pr, 0, 0, 0); pi = __builtin_amdgcn_mfma_f32_16x16x32_bf16(Af[ks], Bw[1][nt][ks], pi, 0, 0, 0); }
;             float av[4], bv[4];
; #pragma unroll
;             for (int reg = 0; reg < 4; ++reg) {
;                 const int tok = m * 16 + 4 * fq + reg;
;                 const float x = bf2f(cxb[tok * CXS + cc[nt]]);
;                 const float r = fsig(pr[reg] + ba[nt]), ig = fsig(pi[reg] + bxv[nt]);
;                 const float aa = __expf(k8[nt] * r);
;                 av[reg] = aa; bv[reg] = __builtin_amdgcn_sqrtf(fmaxf(1.0f - aa * aa, 0.f)) * ig * x;
;             }
;             float cum[4], hl[4];
;             if (DIR == 0) { cum[0] = av[0]; hl[0] = bv[0];
; #pragma unroll
;                 for (int reg = 1; reg < 4; ++reg) { cum[reg] = cum[reg - 1] * av[reg]; hl[reg] = av[reg] * hl[reg - 1] + bv[reg]; } }
;             else { cum[3] = av[3]; hl[3] = bv[3];
; #pragma unroll
;     ...
;             const float A4 = DIR ? cum[0] : cum[3], H4 = DIR ? hl[0] : hl[3];
;             float Aq[4], Hq[4];
; #pragma unroll
;             for (int q = 0; q < 4; ++q) { Aq[q] = __shfl(A4, fr + 16 * q); Hq[q] = __shfl(H4, fr + 16 * q); }
;             float hin;
;             if (DIR == 0) { const float s0 = C[nt], s1 = Aq[0] * s0 + Hq[0], s2 = Aq[1] * s1 + Hq[1], s3 = Aq[2] * s2 + Hq[2]; C[nt] = Aq[3] * s3 + Hq[3]; hin = fq == 0 ? s0 : (fq == 1 ? s1 : (fq == 2 ? s2 : s3)); }
;             else { const float s3 = C[nt], s2 = Aq[3] * s3 + Hq[3], s1 = Aq[2] * s2 + Hq[2], s0 = Aq[1] * s1 + Hq[1]; C[nt] = Aq[0] * s0 + Hq[0]; hin = fq == 3 ? s3 : (fq == 2 ? s2 : (fq == 1 ? s1 : s0)); }
	v_lshlrev_b32_e32 v56, 16, v52
	s_waitcnt lgkmcnt(2)
	v_lshlrev_b32_e32 v52, 16, v54
	v_fma_f32 v54, -v46, v46, 1.0
	v_fma_f32 v57, -v47, v47, 1.0
	v_add_f32_e32 v50, 1.0, v50
	v_max_f32_e32 v54, 0, v54
	v_add_f32_e32 v51, 1.0, v51
	v_max_f32_e32 v57, 0, v57
	v_rcp_f32_e32 v50, v50
	v_sqrt_f32_e32 v54, v54
	v_rcp_f32_e32 v51, v51
	v_sqrt_f32_e32 v57, v57
	s_waitcnt lgkmcnt(1)
	v_lshlrev_b32_e32 v53, 16, v53
	v_mul_f32_e32 v50, v50, v54
	s_waitcnt lgkmcnt(0)
	v_lshlrev_b32_e32 v54, 16, v55
	v_mul_f32_e32 v51, v51, v57
	v_mul_f32_e32 v51, v51, v54
	v_mul_f32_e32 v47, v46, v47
	v_mul_f32_e32 v46, v46, v51
	v_fmac_f32_e32 v46, v50, v53
	v_mul_f32_e32 v47, v45, v47
	v_mul_f32_e32 v45, v45, v46
	v_fmac_f32_e32 v45, v49, v52
	v_mfma_f32_16x16x32_bf16 v[50:53], v[34:37], v[6:9], 0
	v_mul_f32_e32 v47, v44, v47
	v_mul_f32_e32 v45, v44, v45
	v_fmac_f32_e32 v45, v48, v56
	v_mfma_f32_16x16x32_bf16 v[34:37], v[34:37], v[14:17], 0
	ds_bpermute_b32 v44, v68, v47
	ds_bpermute_b32 v46, v68, v47 offset:64
	ds_bpermute_b32 v48, v68, v47 offset:128
	v_mfma_f32_16x16x32_bf16 v[52:55], v[38:41], v[2:5], v[50:53]
	s_nop 0
	s_nop 0
	s_nop 0
	v_mfma_f32_16x16x32_bf16 v[34:37], v[38:41], v[10:13], v[34:37]
	ds_bpermute_b32 v50, v68, v47 offset:192
	s_nop 2
	v_add_f32_e32 v38, v151, v52
	v_mul_f32_e32 v38, 0xbfb8aa3b, v38
	v_exp_f32_e32 v38, v38
	v_add_f32_e32 v39, v151, v53
	v_mul_f32_e32 v39, 0xbfb8aa3b, v39
	v_exp_f32_e32 v39, v39
	v_add_f32_e32 v38, 1.0, v38
	v_rcp_f32_e32 v38, v38
	v_add_f32_e32 v34, v150, v34
	v_mul_f32_e32 v34, 0xbfb8aa3b, v34
	v_add_f32_e32 v39, 1.0, v39
	v_mul_f32_e32 v38, v72, v38
	v_mul_f32_e32 v38, 0x3fb8aa3b, v38
	v_exp_f32_e32 v38, v38
	v_exp_f32_e32 v34, v34
	v_rcp_f32_e32 v39, v39
	v_add_f32_e32 v35, v150, v35
	v_fma_f32 v41, -v38, v38, 1.0
	v_add_f32_e32 v34, 1.0, v34
	v_max_f32_e32 v41, 0, v41
	v_mul_f32_e32 v39, v72, v39
	v_rcp_f32_e32 v34, v34
	v_sqrt_f32_e32 v41, v41
	v_mul_f32_e32 v39, 0x3fb8aa3b, v39
	v_mul_f32_e32 v35, 0xbfb8aa3b, v35
	v_exp_f32_e32 v39, v39
	v_exp_f32_e32 v35, v35
	v_mul_f32_e32 v47, v34, v41
	v_add_f32_e32 v34, v151, v54
	v_mov_b32_e32 v84, v45
	v_mov_b32_e32 v85, v45
	s_nop 1
	v_permlane16_swap_b32_e32 v84, v85
	s_nop 1
	v_mov_b32_e32 v86, v84
	v_mov_b32_e32 v87, v85
	s_nop 1
	v_permlane32_swap_b32_e32 v84, v86
	v_permlane32_swap_b32_e32 v85, v87
	s_nop 1
	v_fma_f32 v45, -v39, v39, 1.0
	v_mul_f32_e32 v34, 0xbfb8aa3b, v34
	v_add_f32_e32 v35, 1.0, v35
	v_max_f32_e32 v45, 0, v45
	v_exp_f32_e32 v34, v34
	v_rcp_f32_e32 v35, v35
	v_sqrt_f32_e32 v51, v45
	ds_read_u16 v40, v70 offset:59168
	ds_read_u16 v49, v70 offset:59696
	v_add_f32_e32 v34, 1.0, v34
	v_mul_f32_e32 v41, v35, v51
	v_add_f32_e32 v35, v150, v36
	v_rcp_f32_e32 v36, v34
	ds_read_u16 v34, v70 offset:60224
	s_waitcnt lgkmcnt(2)
	v_lshlrev_b32_e32 v45, 16, v40
	s_waitcnt lgkmcnt(1)
	v_lshlrev_b32_e32 v40, 16, v49
	v_mul_f32_e32 v36, v72, v36
	v_mul_f32_e32 v36, 0x3fb8aa3b, v36
	v_exp_f32_e32 v49, v36
	v_add_f32_e32 v36, v151, v55
	v_mul_f32_e32 v36, 0xbfb8aa3b, v36
	v_exp_f32_e32 v51, v36
	v_add_f32_e32 v37, v150, v37
	v_mul_f32_e32 v37, 0xbfb8aa3b, v37
	v_mul_f32_e32 v35, 0xbfb8aa3b, v35
	v_add_f32_e32 v51, 1.0, v51
	v_rcp_f32_e32 v52, v51
	v_exp_f32_e32 v51, v37
	v_exp_f32_e32 v35, v35
	v_fma_f32 v36, -v49, v49, 1.0
	v_mul_f32_e32 v37, v72, v52
	v_mul_f32_e32 v37, 0x3fb8aa3b, v37
	v_exp_f32_e32 v37, v37
	v_add_f32_e32 v35, 1.0, v35
	v_max_f32_e32 v36, 0, v36
	ds_read_u16 v52, v70 offset:60752
	v_fma_f32 v53, -v37, v37, 1.0
	v_add_f32_e32 v51, 1.0, v51
	v_max_f32_e32 v53, 0, v53
	v_rcp_f32_e32 v35, v35
	v_sqrt_f32_e32 v36, v36
	v_rcp_f32_e32 v51, v51
	v_sqrt_f32_e32 v53, v53
	s_waitcnt lgkmcnt(1)
	v_lshlrev_b32_e32 v54, 16, v34
	v_mul_f32_e32 v55, v35, v36
	s_waitcnt lgkmcnt(0)
	v_lshlrev_b32_e32 v34, 16, v52
	v_mul_f32_e32 v35, v51, v53
	v_mul_f32_e32 v51, v35, v34
	v_mul_f32_e32 v52, v49, v37
	ds_read_b128 v[34:37], v89 offset:50688
	v_mul_f32_e32 v49, v49, v51
	v_fmac_f32_e32 v49, v55, v54
	v_mul_f32_e32 v51, v39, v52
	v_mul_f32_e32 v39, v39, v49
	v_fmac_f32_e32 v39, v41, v40
	v_mul_f32_e32 v49, v38, v51
	v_mul_f32_e32 v51, v38, v39
	ds_read_b128 v[38:41], v89 offset:50752
	s_waitcnt lgkmcnt(1)
	v_mfma_f32_16x16x32_bf16 v[58:61], v[34:37], v[26:29], 0
	v_fmac_f32_e32 v51, v47, v45
	s_nop 0
	s_nop 0
	s_waitcnt lgkmcnt(0)
	v_mfma_f32_16x16x32_bf16 v[76:79], v[38:41], v[18:21], v[58:61]
	s_nop 0
	v_mov_b32_e32 v88, v51
	v_mov_b32_e32 v90, v51
	s_nop 1
	v_permlane16_swap_b32_e32 v88, v90
	s_nop 1
	v_mov_b32_e32 v91, v88
	v_mov_b32_e32 v92, v90
	s_nop 1
	v_permlane32_swap_b32_e32 v88, v91
	v_permlane32_swap_b32_e32 v90, v92
	s_nop 1
	ds_read_u16 v57, v70 offset:51216
	s_nop 4
	v_add_f32_e32 v45, v153, v76
	v_mul_f32_e32 v45, 0xbfb8aa3b, v45
	v_exp_f32_e32 v45, v45
	v_mfma_f32_16x16x32_bf16 v[62:65], v[34:37], v[30:33], 0
	v_add_f32_e32 v51, v153, v77
	v_mul_f32_e32 v51, 0xbfb8aa3b, v51
	v_add_f32_e32 v45, 1.0, v45
	v_rcp_f32_e32 v45, v45
	v_mfma_f32_16x16x32_bf16 v[60:63], v[38:41], v[22:25], v[62:65]
	v_exp_f32_e32 v51, v51
	s_nop 0
	v_mul_f32_e32 v45, v74, v45
	v_mul_f32_e32 v45, 0x3fb8aa3b, v45
	v_exp_f32_e32 v45, v45
	s_nop 2
	v_add_f32_e32 v47, v152, v60
	v_mul_f32_e32 v47, 0xbfb8aa3b, v47
	v_exp_f32_e32 v47, v47
	v_fma_f32 v53, -v45, v45, 1.0
	v_max_f32_e32 v53, 0, v53
	v_add_f32_e32 v51, 1.0, v51
	v_add_f32_e32 v47, 1.0, v47
	v_rcp_f32_e32 v47, v47
	v_sqrt_f32_e32 v53, v53
	v_rcp_f32_e32 v51, v51
	v_add_f32_e32 v55, v152, v61
	ds_read_u16 v60, v70 offset:51744
	ds_read_u16 v64, v70 offset:52272
	v_mul_f32_e32 v51, v74, v51
	v_mul_f32_e32 v47, v47, v53
	s_waitcnt lgkmcnt(2)
; template <int DIR, int MODE>
; __device__ __forceinline__ void lru_pass(const Args& a, const LAS bf16_t* cxb, LAS bf16_t* gyb, const LAS float* carry, const bf16x8 (&Bw)[2][2][2], const float (&prm)[2][3], int l, int tt, float (&hf)[8][2][4]) {
;     ...
;     for (int mi = 0; mi < 8; ++mi) {
;         const int m = DIR ? 7 - mi : mi;
;         bf16x8 Af[2];
; #pragma unroll
;         for (int ks = 0; ks < 2; ++ks) Af[ks] = *(const LAS bf16x8*)(cxb + (m * 16 + fr) * CXS + 64 * h + 32 * ks + 8 * fq);
; #pragma unroll
;         for (int nt = 0; nt < 2; ++nt) {
;             f32x4 pr = (f32x4){0.f, 0.f, 0.f, 0.f}, pi = (f32x4){0.f, 0.f, 0.f, 0.f};
; #pragma unroll
;             for (int ks = 0; ks < 2; ++ks) { pr = __builtin_amdgcn_mfma_f32_16x16x32_bf16(Af[ks], Bw[0][nt][ks], pr, 0, 0, 0); pi = __builtin_amdgcn_mfma_f32_16x16x32_bf16(Af[ks], Bw[1][nt][ks], pi, 0, 0, 0); }
;             float av[4], bv[4];
; #pragma unroll
;             for (int reg = 0; reg < 4; ++reg) {
;                 const int tok = m * 16 + 4 * fq + reg;
;                 const float x = bf2f(cxb[tok * CXS + cc[nt]]);
;                 const float r = fsig(pr[reg] + ba[nt]), ig = fsig(pi[reg] + bxv[nt]);
;                 const float aa = __expf(k8[nt] * r);
;                 av[reg] = aa; bv[reg] = __builtin_amdgcn_sqrtf(fmaxf(1.0f - aa * aa, 0.f)) * ig * x;
;             }
;             float cum[4], hl[4];
;             if (DIR == 0) { cum[0] = av[0]; hl[0] = bv[0];
; #pragma unroll
;                 for (int reg = 1; reg < 4; ++reg) { cum[reg] = cum[reg - 1] * av[reg]; hl[reg] = av[reg] * hl[reg - 1] + bv[reg]; } }
;             else { cum[3] = av[3]; hl[3] = bv[3];
; #pragma unroll
;     ...
;             const float A4 = DIR ? cum[0] : cum[3], H4 = DIR ? hl[0] : hl[3];
;             float Aq[4], Hq[4];
; #pragma unroll
;             for (int q = 0; q < 4; ++q) { Aq[q] = __shfl(A4, fr + 16 * q); Hq[q] = __shfl(H4, fr + 16 * q); }
;             float hin;
;             if (DIR == 0) { const float s0 = C[nt], s1 = Aq[0] * s0 + Hq[0], s2 = Aq[1] * s1 + Hq[1], s3 = Aq[2] * s2 + Hq[2]; C[nt] = Aq[3] * s3 + Hq[3]; hin = fq == 0 ? s0 : (fq == 1 ? s1 : (fq == 2 ? s2 : s3)); }
;             else { const float s3 = C[nt], s2 = Aq[3] * s3 + Hq[3], s1 = Aq[2] * s2 + Hq[2], s0 = Aq[1] * s1 + Hq[1]; C[nt] = Aq[0] * s0 + Hq[0]; hin = fq == 3 ? s3 : (fq == 2 ? s2 : (fq == 1 ? s1 : s0)); }
	v_lshlrev_b32_e32 v53, 16, v57
	v_add_f32_e32 v57, v153, v78
	v_add_f32_e32 v61, v153, v79
	v_mul_f32_e32 v51, 0x3fb8aa3b, v51
	v_mul_f32_e32 v57, 0xbfb8aa3b, v57
	v_mul_f32_e32 v61, 0xbfb8aa3b, v61
	v_mul_f32_e32 v55, 0xbfb8aa3b, v55
	v_exp_f32_e32 v51, v51
	v_exp_f32_e32 v57, v57
	v_exp_f32_e32 v61, v61
	v_exp_f32_e32 v55, v55
	v_fma_f32 v59, -v51, v51, 1.0
	v_add_f32_e32 v57, 1.0, v57
	v_add_f32_e32 v61, 1.0, v61
	v_add_f32_e32 v55, 1.0, v55
	v_max_f32_e32 v59, 0, v59
	v_rcp_f32_e32 v57, v57
	v_rcp_f32_e32 v61, v61
	v_rcp_f32_e32 v55, v55
	v_sqrt_f32_e32 v59, v59
	v_mul_f32_e32 v57, v74, v57
	v_mul_f32_e32 v61, v74, v61
	v_mul_f32_e32 v57, 0x3fb8aa3b, v57
	v_mul_f32_e32 v55, v55, v59
	v_add_f32_e32 v59, v152, v62
	v_add_f32_e32 v63, v152, v63
	v_mul_f32_e32 v61, 0x3fb8aa3b, v61
	v_mul_f32_e32 v59, 0xbfb8aa3b, v59
	v_exp_f32_e32 v57, v57
	v_mul_f32_e32 v63, 0xbfb8aa3b, v63
	v_exp_f32_e32 v61, v61
	v_exp_f32_e32 v59, v59
	v_exp_f32_e32 v63, v63
	v_fma_f32 v62, -v57, v57, 1.0
	v_fma_f32 v65, -v61, v61, 1.0
	v_add_f32_e32 v59, 1.0, v59
	v_max_f32_e32 v62, 0, v62
	v_add_f32_e32 v63, 1.0, v63
	v_max_f32_e32 v65, 0, v65
	v_rcp_f32_e32 v59, v59
	v_sqrt_f32_e32 v62, v62
	v_rcp_f32_e32 v63, v63
	v_sqrt_f32_e32 v65, v65
	s_waitcnt lgkmcnt(1)
	v_lshlrev_b32_e32 v60, 16, v60
	v_mul_f32_e32 v59, v59, v62
	s_waitcnt lgkmcnt(0)
	v_lshlrev_b32_e32 v62, 16, v64
	v_mul_f32_e32 v63, v63, v65
	v_mul_f32_e32 v62, v63, v62
	v_mul_f32_e32 v61, v57, v61
	v_mul_f32_e32 v57, v57, v62
	v_fmac_f32_e32 v57, v59, v60
	v_mul_f32_e32 v59, v51, v61
	v_mfma_f32_16x16x32_bf16 v[60:63], v[34:37], v[6:9], 0
	s_nop 0
	s_nop 0
	v_mov_b32_e32 v52, v49
	v_mov_b32_e32 v54, v49
	s_nop 1
	v_permlane16_swap_b32_e32 v52, v54
	s_nop 1
	v_mov_b32_e32 v56, v52
	v_mov_b32_e32 v58, v54
	s_nop 1
	v_permlane32_swap_b32_e32 v52, v56
	v_permlane32_swap_b32_e32 v54, v58
	s_nop 1
	v_mfma_f32_16x16x32_bf16 v[34:37], v[34:37], v[14:17], 0
	ds_read_u16 v49, v70 offset:50688
	ds_read_u16 v73, v70 offset:42768
	v_mul_f32_e32 v51, v51, v57
	v_mfma_f32_16x16x32_bf16 v[60:63], v[38:41], v[2:5], v[60:63]
	v_fmac_f32_e32 v51, v55, v53
	v_mul_f32_e32 v55, v45, v51
	ds_read_u16 v57, v70 offset:51248
	v_mfma_f32_16x16x32_bf16 v[34:37], v[38:41], v[10:13], v[34:37]
	ds_read_u16 v40, v70 offset:50720
	ds_read_u16 v76, v70 offset:43824
	s_nop 1
	v_add_f32_e32 v38, v151, v60
	v_mul_f32_e32 v38, 0xbfb8aa3b, v38
	v_exp_f32_e32 v38, v38
	v_add_f32_e32 v39, v151, v61
	v_mul_f32_e32 v39, 0xbfb8aa3b, v39
	v_exp_f32_e32 v39, v39
	v_add_f32_e32 v38, 1.0, v38
	v_rcp_f32_e32 v38, v38
	v_add_f32_e32 v34, v150, v34
	v_mul_f32_e32 v34, 0xbfb8aa3b, v34
	v_add_f32_e32 v39, 1.0, v39
	v_mul_f32_e32 v38, v72, v38
	v_mul_f32_e32 v38, 0x3fb8aa3b, v38
	v_exp_f32_e32 v38, v38
	v_exp_f32_e32 v34, v34
	v_rcp_f32_e32 v39, v39
	v_add_f32_e32 v35, v150, v35
	v_fma_f32 v41, -v38, v38, 1.0
	v_add_f32_e32 v34, 1.0, v34
	v_max_f32_e32 v41, 0, v41
	v_mul_f32_e32 v39, v72, v39
	v_rcp_f32_e32 v34, v34
	v_sqrt_f32_e32 v41, v41
	v_mul_f32_e32 v39, 0x3fb8aa3b, v39
	v_mul_f32_e32 v35, 0xbfb8aa3b, v35
	v_exp_f32_e32 v39, v39
	s_waitcnt lgkmcnt(4)
	v_lshlrev_b32_e32 v49, 16, v49
	v_exp_f32_e32 v35, v35
	v_fmac_f32_e32 v55, v47, v49
	v_mul_f32_e32 v53, v45, v59
	s_nop 0
	s_nop 0
	s_nop 0
	v_mov_b32_e32 v93, v55
	v_mov_b32_e32 v94, v55
	s_nop 1
	v_permlane16_swap_b32_e32 v93, v94
	s_nop 1
	v_mov_b32_e32 v95, v93
	v_mov_b32_e32 v96, v94
	s_nop 1
	v_permlane32_swap_b32_e32 v93, v95
	v_permlane32_swap_b32_e32 v94, v96
	s_nop 1
	v_mul_f32_e32 v55, v34, v41
	v_add_f32_e32 v34, v151, v62
	s_nop 0
	s_nop 0
	s_nop 0
	v_mov_b32_e32 v45, v53
	v_mov_b32_e32 v47, v53
	s_nop 1
	v_permlane16_swap_b32_e32 v45, v47
	s_nop 1
	v_mov_b32_e32 v49, v45
	v_mov_b32_e32 v51, v47
	s_nop 1
	v_permlane32_swap_b32_e32 v45, v49
	v_permlane32_swap_b32_e32 v47, v51
	s_nop 1
	v_fma_f32 v53, -v39, v39, 1.0
	v_mul_f32_e32 v34, 0xbfb8aa3b, v34
	v_add_f32_e32 v35, 1.0, v35
	v_max_f32_e32 v53, 0, v53
	v_exp_f32_e32 v34, v34
	v_rcp_f32_e32 v35, v35
	v_sqrt_f32_e32 v59, v53
	s_waitcnt lgkmcnt(1)
	v_lshlrev_b32_e32 v53, 16, v40
	v_add_f32_e32 v34, 1.0, v34
	v_lshlrev_b32_e32 v40, 16, v57
	v_mul_f32_e32 v41, v35, v59
	v_add_f32_e32 v35, v150, v36
	v_rcp_f32_e32 v36, v34
	v_add_f32_e32 v37, v150, v37
	v_mul_f32_e32 v37, 0xbfb8aa3b, v37
	v_mul_f32_e32 v35, 0xbfb8aa3b, v35
	v_mul_f32_e32 v36, v72, v36
	v_mul_f32_e32 v36, 0x3fb8aa3b, v36
	v_exp_f32_e32 v57, v36
	v_add_f32_e32 v36, v151, v63
	v_mul_f32_e32 v36, 0xbfb8aa3b, v36
	v_exp_f32_e32 v59, v36
	v_exp_f32_e32 v35, v35
	v_fma_f32 v36, -v57, v57, 1.0
	ds_read_u16 v34, v70 offset:51776
	v_add_f32_e32 v59, 1.0, v59
	v_rcp_f32_e32 v60, v59
	v_exp_f32_e32 v59, v37
	v_add_f32_e32 v35, 1.0, v35
	v_max_f32_e32 v36, 0, v36
	v_mul_f32_e32 v37, v72, v60
	v_mul_f32_e32 v37, 0x3fb8aa3b, v37
	v_exp_f32_e32 v37, v37
	ds_read_u16 v60, v70 offset:52304
	v_add_f32_e32 v59, 1.0, v59
	v_rcp_f32_e32 v35, v35
	v_fma_f32 v61, -v37, v37, 1.0
	v_max_f32_e32 v61, 0, v61
	v_sqrt_f32_e32 v36, v36
	v_rcp_f32_e32 v59, v59
	v_sqrt_f32_e32 v61, v61
	s_waitcnt lgkmcnt(1)
	v_lshlrev_b32_e32 v62, 16, v34
	v_mul_f32_e32 v63, v35, v36
	s_waitcnt lgkmcnt(0)
	v_lshlrev_b32_e32 v34, 16, v60
	v_mul_f32_e32 v35, v59, v61
	v_mul_f32_e32 v59, v35, v34
	v_mul_f32_e32 v60, v57, v37
	ds_read_b128 v[34:37], v89 offset:42240
	v_mul_f32_e32 v57, v57, v59
	v_fmac_f32_e32 v57, v63, v62
	v_mul_f32_e32 v59, v39, v60
	v_mul_f32_e32 v39, v39, v57
	v_fmac_f32_e32 v39, v41, v40
	v_mul_f32_e32 v59, v38, v59
	v_mul_f32_e32 v69, v38, v39
	ds_read_b128 v[38:41], v89 offset:42304
	s_waitcnt lgkmcnt(1)
	v_mfma_f32_16x16x32_bf16 v[60:63], v[34:37], v[26:29], 0
	v_fmac_f32_e32 v69, v55, v53
	s_nop 0
	s_nop 0
	s_waitcnt lgkmcnt(0)
; template <int DIR, int MODE>
; __device__ __forceinline__ void lru_pass(const Args& a, const LAS bf16_t* cxb, LAS bf16_t* gyb, const LAS float* carry, const bf16x8 (&Bw)[2][2][2], const float (&prm)[2][3], int l, int tt, float (&hf)[8][2][4]) {
;     ...
;     for (int mi = 0; mi < 8; ++mi) {
;         const int m = DIR ? 7 - mi : mi;
;         bf16x8 Af[2];
; #pragma unroll
;         for (int ks = 0; ks < 2; ++ks) Af[ks] = *(const LAS bf16x8*)(cxb + (m * 16 + fr) * CXS + 64 * h + 32 * ks + 8 * fq);
; #pragma unroll
;         for (int nt = 0; nt < 2; ++nt) {
;             f32x4 pr = (f32x4){0.f, 0.f, 0.f, 0.f}, pi = (f32x4){0.f, 0.f, 0.f, 0.f};
; #pragma unroll
;             for (int ks = 0; ks < 2; ++ks) { pr = __builtin_amdgcn_mfma_f32_16x16x32_bf16(Af[ks], Bw[0][nt][ks], pr, 0, 0, 0); pi = __builtin_amdgcn_mfma_f32_16x16x32_bf16(Af[ks], Bw[1][nt][ks], pi, 0, 0, 0); }
;             float av[4], bv[4];
; #pragma unroll
;             for (int reg = 0; reg < 4; ++reg) {
;                 const int tok = m * 16 + 4 * fq + reg;
;                 const float x = bf2f(cxb[tok * CXS + cc[nt]]);
;                 const float r = fsig(pr[reg] + ba[nt]), ig = fsig(pi[reg] + bxv[nt]);
;                 const float aa = __expf(k8[nt] * r);
;                 av[reg] = aa; bv[reg] = __builtin_amdgcn_sqrtf(fmaxf(1.0f - aa * aa, 0.f)) * ig * x;
;             }
;             float cum[4], hl[4];
;             if (DIR == 0) { cum[0] = av[0]; hl[0] = bv[0];
; #pragma unroll
;                 for (int reg = 1; reg < 4; ++reg) { cum[reg] = cum[reg - 1] * av[reg]; hl[reg] = av[reg] * hl[reg - 1] + bv[reg]; } }
;             else { cum[3] = av[3]; hl[3] = bv[3];
; #pragma unroll
;     ...
;             const float A4 = DIR ? cum[0] : cum[3], H4 = DIR ? hl[0] : hl[3];
;             float Aq[4], Hq[4];
; #pragma unroll
;             for (int q = 0; q < 4; ++q) { Aq[q] = __shfl(A4, fr + 16 * q); Hq[q] = __shfl(H4, fr + 16 * q); }
;             float hin;
;             if (DIR == 0) { const float s0 = C[nt], s1 = Aq[0] * s0 + Hq[0], s2 = Aq[1] * s1 + Hq[1], s3 = Aq[2] * s2 + Hq[2]; C[nt] = Aq[3] * s3 + Hq[3]; hin = fq == 0 ? s0 : (fq == 1 ? s1 : (fq == 2 ? s2 : s3)); }
;             else { const float s3 = C[nt], s2 = Aq[3] * s3 + Hq[3], s1 = Aq[2] * s2 + Hq[2], s0 = Aq[1] * s1 + Hq[1]; C[nt] = Aq[0] * s0 + Hq[0]; hin = fq == 3 ? s3 : (fq == 2 ? s2 : (fq == 1 ? s1 : s0)); }
	v_mfma_f32_16x16x32_bf16 v[60:63], v[38:41], v[18:21], v[60:63]
	s_nop 0
	v_mov_b32_e32 v97, v69
	v_mov_b32_e32 v98, v69
	s_nop 1
	v_permlane16_swap_b32_e32 v97, v98
	s_nop 1
	v_mov_b32_e32 v99, v97
	v_mov_b32_e32 v100, v98
	s_nop 1
	v_permlane32_swap_b32_e32 v97, v99
	v_permlane32_swap_b32_e32 v98, v100
	s_nop 1
	ds_read_u16 v69, v70 offset:42240
	s_nop 4
	v_add_f32_e32 v61, v153, v61
	v_mul_f32_e32 v61, 0xbfb8aa3b, v61
	v_exp_f32_e32 v61, v61
	v_add_f32_e32 v60, v153, v60
	v_mfma_f32_16x16x32_bf16 v[64:67], v[34:37], v[30:33], 0
	v_mul_f32_e32 v60, 0xbfb8aa3b, v60
	v_exp_f32_e32 v60, v60
	v_add_f32_e32 v61, 1.0, v61
	v_add_f32_e32 v62, v153, v62
	v_add_f32_e32 v63, v153, v63
	v_rcp_f32_e32 v61, v61
	v_mul_f32_e32 v62, 0xbfb8aa3b, v62
	v_mul_f32_e32 v63, 0xbfb8aa3b, v63
	v_mfma_f32_16x16x32_bf16 v[64:67], v[38:41], v[22:25], v[64:67]
	v_exp_f32_e32 v62, v62
	v_exp_f32_e32 v63, v63
	v_add_f32_e32 v60, 1.0, v60
	v_rcp_f32_e32 v60, v60
	v_mul_f32_e32 v61, v74, v61
	s_nop 2
	v_add_f32_e32 v65, v152, v65
	v_mul_f32_e32 v61, 0x3fb8aa3b, v61
	v_add_f32_e32 v62, 1.0, v62
	v_add_f32_e32 v63, 1.0, v63
	v_mul_f32_e32 v65, 0xbfb8aa3b, v65
	v_exp_f32_e32 v61, v61
	v_rcp_f32_e32 v62, v62
	v_rcp_f32_e32 v63, v63
	v_mul_f32_e32 v60, v74, v60
	v_exp_f32_e32 v65, v65
	v_add_f32_e32 v64, v152, v64
	v_mul_f32_e32 v60, 0x3fb8aa3b, v60
	v_mul_f32_e32 v64, 0xbfb8aa3b, v64
	v_exp_f32_e32 v60, v60
	v_exp_f32_e32 v64, v64
	v_fma_f32 v75, -v61, v61, 1.0
	v_mul_f32_e32 v62, v74, v62
	v_mul_f32_e32 v63, v74, v63
	v_add_f32_e32 v65, 1.0, v65
	v_max_f32_e32 v75, 0, v75
	v_add_f32_e32 v66, v152, v66
	v_mul_f32_e32 v62, 0x3fb8aa3b, v62
	v_add_f32_e32 v67, v152, v67
	v_mul_f32_e32 v63, 0x3fb8aa3b, v63
	v_rcp_f32_e32 v65, v65
	v_sqrt_f32_e32 v75, v75
	v_mul_f32_e32 v66, 0xbfb8aa3b, v66
	v_exp_f32_e32 v62, v62
	v_mul_f32_e32 v67, 0xbfb8aa3b, v67
	v_exp_f32_e32 v63, v63
	v_fma_f32 v71, -v60, v60, 1.0
	v_exp_f32_e32 v66, v66
	v_exp_f32_e32 v67, v67
	v_add_f32_e32 v64, 1.0, v64
	v_max_f32_e32 v71, 0, v71
	v_rcp_f32_e32 v64, v64
	v_sqrt_f32_e32 v71, v71
	v_mul_f32_e32 v65, v65, v75
	v_fma_f32 v75, -v62, v62, 1.0
	v_fma_f32 v77, -v63, v63, 1.0
	v_add_f32_e32 v66, 1.0, v66
	v_max_f32_e32 v75, 0, v75
	v_add_f32_e32 v67, 1.0, v67
	v_max_f32_e32 v77, 0, v77
	v_rcp_f32_e32 v66, v66
	v_sqrt_f32_e32 v75, v75
	v_rcp_f32_e32 v67, v67
	v_sqrt_f32_e32 v77, v77
	v_mul_f32_e32 v71, v64, v71
	v_lshlrev_b32_e32 v64, 16, v73
	ds_read_u16 v73, v70 offset:43296
	v_mul_f32_e32 v66, v66, v75
	v_lshlrev_b32_e32 v75, 16, v76
	v_mul_f32_e32 v67, v67, v77
	v_mul_f32_e32 v67, v67, v75
	s_waitcnt lgkmcnt(0)
	v_lshlrev_b32_e32 v73, 16, v73
	v_mul_f32_e32 v63, v62, v63
	v_mul_f32_e32 v62, v62, v67
	v_fmac_f32_e32 v62, v66, v73
	v_mul_f32_e32 v63, v61, v63
	v_mul_f32_e32 v61, v61, v62
	v_fmac_f32_e32 v61, v65, v64
	v_mfma_f32_16x16x32_bf16 v[64:67], v[34:37], v[6:9], 0
	v_mul_f32_e32 v73, v60, v61
	ds_read_u16 v109, v70 offset:35376
	ds_read_u16 v141, v70 offset:18480
	v_mfma_f32_16x16x32_bf16 v[34:37], v[34:37], v[14:17], 0
	ds_read_u16 v159, v70 offset:8976
	ds_read_u16 v139, v70 offset:17424
	ds_read_u16 v125, v70 offset:26928
	v_mfma_f32_16x16x32_bf16 v[64:67], v[38:41], v[2:5], v[64:67]
	v_mul_f32_e32 v63, v60, v63
	ds_bpermute_b32 v53, v68, v59
	ds_bpermute_b32 v55, v68, v59 offset:64
	v_mfma_f32_16x16x32_bf16 v[34:37], v[38:41], v[10:13], v[34:37]
	ds_read_u16 v40, v70 offset:42272
	s_nop 2
	v_add_f32_e32 v38, v151, v64
	v_mul_f32_e32 v38, 0xbfb8aa3b, v38
	v_exp_f32_e32 v38, v38
	v_add_f32_e32 v39, v151, v65
	v_mul_f32_e32 v39, 0xbfb8aa3b, v39
	v_exp_f32_e32 v39, v39
	v_add_f32_e32 v38, 1.0, v38
	v_rcp_f32_e32 v38, v38
	v_add_f32_e32 v34, v150, v34
	v_mul_f32_e32 v34, 0xbfb8aa3b, v34
	v_add_f32_e32 v39, 1.0, v39
	v_mul_f32_e32 v38, v72, v38
	v_mul_f32_e32 v38, 0x3fb8aa3b, v38
	v_exp_f32_e32 v38, v38
	v_exp_f32_e32 v34, v34
	v_rcp_f32_e32 v39, v39
	v_add_f32_e32 v35, v150, v35
	v_fma_f32 v41, -v38, v38, 1.0
	v_add_f32_e32 v34, 1.0, v34
	v_max_f32_e32 v41, 0, v41
	v_mul_f32_e32 v39, v72, v39
	v_rcp_f32_e32 v34, v34
	v_sqrt_f32_e32 v41, v41
	v_mul_f32_e32 v39, 0x3fb8aa3b, v39
	v_mul_f32_e32 v35, 0xbfb8aa3b, v35
	v_exp_f32_e32 v39, v39
	v_exp_f32_e32 v35, v35
	v_mul_f32_e32 v65, v34, v41
	v_add_f32_e32 v34, v151, v66
	v_fma_f32 v64, -v39, v39, 1.0
	v_mul_f32_e32 v34, 0xbfb8aa3b, v34
	v_lshlrev_b32_e32 v69, 16, v69
	v_add_f32_e32 v35, 1.0, v35
	v_max_f32_e32 v64, 0, v64
	v_exp_f32_e32 v34, v34
	v_fmac_f32_e32 v73, v71, v69
	v_rcp_f32_e32 v35, v35
	v_sqrt_f32_e32 v71, v64
	v_add_f32_e32 v34, 1.0, v34
	ds_read_u16 v69, v70 offset:42800
	s_waitcnt lgkmcnt(1)
	v_lshlrev_b32_e32 v64, 16, v40
	v_mul_f32_e32 v41, v35, v71
	v_add_f32_e32 v35, v150, v36
	v_rcp_f32_e32 v36, v34
	ds_read_u16 v34, v70 offset:43328
	s_waitcnt lgkmcnt(1)
	v_lshlrev_b32_e32 v40, 16, v69
	v_add_f32_e32 v37, v150, v37
	v_mul_f32_e32 v36, v72, v36
	v_mul_f32_e32 v36, 0x3fb8aa3b, v36
	v_exp_f32_e32 v66, v36
	v_add_f32_e32 v36, v151, v67
	v_mul_f32_e32 v36, 0xbfb8aa3b, v36
	v_exp_f32_e32 v67, v36
	v_mul_f32_e32 v37, 0xbfb8aa3b, v37
	v_mul_f32_e32 v35, 0xbfb8aa3b, v35
	v_exp_f32_e32 v35, v35
	v_add_f32_e32 v67, 1.0, v67
	v_rcp_f32_e32 v69, v67
	v_exp_f32_e32 v67, v37
	v_fma_f32 v36, -v66, v66, 1.0
	v_add_f32_e32 v35, 1.0, v35
	v_mul_f32_e32 v37, v72, v69
	v_mul_f32_e32 v37, 0x3fb8aa3b, v37
	v_exp_f32_e32 v37, v37
	v_max_f32_e32 v36, 0, v36
	ds_read_u16 v69, v70 offset:43856
	v_add_f32_e32 v67, 1.0, v67
	v_fma_f32 v71, -v37, v37, 1.0
	v_max_f32_e32 v71, 0, v71
	v_rcp_f32_e32 v35, v35
	v_sqrt_f32_e32 v36, v36
	v_rcp_f32_e32 v67, v67
	v_sqrt_f32_e32 v71, v71
	s_nop 0
	s_nop 0
	s_nop 0
	v_mov_b32_e32 v101, v73
	v_mov_b32_e32 v102, v73
	s_nop 1
	v_permlane16_swap_b32_e32 v101, v102
	s_nop 1
	v_mov_b32_e32 v103, v101
	v_mov_b32_e32 v104, v102
	s_nop 1
	v_permlane32_swap_b32_e32 v101, v103
	v_permlane32_swap_b32_e32 v102, v104
	s_nop 1
	s_waitcnt lgkmcnt(1)
; template <int DIR, int MODE>
; __device__ __forceinline__ void lru_pass(const Args& a, const LAS bf16_t* cxb, LAS bf16_t* gyb, const LAS float* carry, const bf16x8 (&Bw)[2][2][2], const float (&prm)[2][3], int l, int tt, float (&hf)[8][2][4]) {
;     ...
;     for (int mi = 0; mi < 8; ++mi) {
;         const int m = DIR ? 7 - mi : mi;
;         bf16x8 Af[2];
; #pragma unroll
;         for (int ks = 0; ks < 2; ++ks) Af[ks] = *(const LAS bf16x8*)(cxb + (m * 16 + fr) * CXS + 64 * h + 32 * ks + 8 * fq);
; #pragma unroll
;         for (int nt = 0; nt < 2; ++nt) {
;             f32x4 pr = (f32x4){0.f, 0.f, 0.f, 0.f}, pi = (f32x4){0.f, 0.f, 0.f, 0.f};
; #pragma unroll
;             for (int ks = 0; ks < 2; ++ks) { pr = __builtin_amdgcn_mfma_f32_16x16x32_bf16(Af[ks], Bw[0][nt][ks], pr, 0, 0, 0); pi = __builtin_amdgcn_mfma_f32_16x16x32_bf16(Af[ks], Bw[1][nt][ks], pi, 0, 0, 0); }
;             float av[4], bv[4];
; #pragma unroll
;             for (int reg = 0; reg < 4; ++reg) {
;                 const int tok = m * 16 + 4 * fq + reg;
;                 const float x = bf2f(cxb[tok * CXS + cc[nt]]);
;                 const float r = fsig(pr[reg] + ba[nt]), ig = fsig(pi[reg] + bxv[nt]);
;                 const float aa = __expf(k8[nt] * r);
;                 av[reg] = aa; bv[reg] = __builtin_amdgcn_sqrtf(fmaxf(1.0f - aa * aa, 0.f)) * ig * x;
;             }
;             float cum[4], hl[4];
;             if (DIR == 0) { cum[0] = av[0]; hl[0] = bv[0];
; #pragma unroll
;                 for (int reg = 1; reg < 4; ++reg) { cum[reg] = cum[reg - 1] * av[reg]; hl[reg] = av[reg] * hl[reg - 1] + bv[reg]; } }
;             else { cum[3] = av[3]; hl[3] = bv[3];
; #pragma unroll
;     ...
;             const float A4 = DIR ? cum[0] : cum[3], H4 = DIR ? hl[0] : hl[3];
;             float Aq[4], Hq[4];
; #pragma unroll
;             for (int q = 0; q < 4; ++q) { Aq[q] = __shfl(A4, fr + 16 * q); Hq[q] = __shfl(H4, fr + 16 * q); }
;             float hin;
;             if (DIR == 0) { const float s0 = C[nt], s1 = Aq[0] * s0 + Hq[0], s2 = Aq[1] * s1 + Hq[1], s3 = Aq[2] * s2 + Hq[2]; C[nt] = Aq[3] * s3 + Hq[3]; hin = fq == 0 ? s0 : (fq == 1 ? s1 : (fq == 2 ? s2 : s3)); }
;             else { const float s3 = C[nt], s2 = Aq[3] * s3 + Hq[3], s1 = Aq[2] * s2 + Hq[2], s0 = Aq[1] * s1 + Hq[1]; C[nt] = Aq[0] * s0 + Hq[0]; hin = fq == 3 ? s3 : (fq == 2 ? s2 : (fq == 1 ? s1 : s0)); }
	v_lshlrev_b32_e32 v73, 16, v34
	v_mul_f32_e32 v75, v35, v36
	s_waitcnt lgkmcnt(0)
	v_lshlrev_b32_e32 v34, 16, v69
	v_mul_f32_e32 v35, v67, v71
	v_mul_f32_e32 v67, v35, v34
	v_mul_f32_e32 v69, v66, v37
	ds_read_b128 v[34:37], v89 offset:33792
	v_mul_f32_e32 v66, v66, v67
	v_fmac_f32_e32 v66, v75, v73
	v_mul_f32_e32 v67, v39, v69
	v_mul_f32_e32 v39, v39, v66
	v_fmac_f32_e32 v39, v41, v40
	v_mul_f32_e32 v67, v38, v67
	v_mul_f32_e32 v69, v38, v39
	ds_read_b128 v[38:41], v89 offset:33856
	s_waitcnt lgkmcnt(1)
	v_mfma_f32_16x16x32_bf16 v[76:79], v[34:37], v[26:29], 0
	v_fmac_f32_e32 v69, v65, v64
	s_nop 0
	s_nop 0
	s_waitcnt lgkmcnt(0)
	v_mfma_f32_16x16x32_bf16 v[76:79], v[38:41], v[18:21], v[76:79]
	s_nop 0
	v_mov_b32_e32 v105, v69
	v_mov_b32_e32 v106, v69
	s_nop 1
	v_permlane16_swap_b32_e32 v105, v106
	s_nop 1
	v_mov_b32_e32 v107, v105
	v_mov_b32_e32 v108, v106
	s_nop 1
	v_permlane32_swap_b32_e32 v105, v107
	v_permlane32_swap_b32_e32 v106, v108
	s_nop 1
	ds_read_u16 v73, v70 offset:33792
	s_nop 4
	v_add_f32_e32 v69, v153, v76
	v_add_f32_e32 v75, v153, v77
	v_mul_f32_e32 v69, 0xbfb8aa3b, v69
	v_mul_f32_e32 v75, 0xbfb8aa3b, v75
	v_exp_f32_e32 v69, v69
	v_exp_f32_e32 v75, v75
	v_mfma_f32_16x16x32_bf16 v[80:83], v[34:37], v[30:33], 0
	v_add_f32_e32 v78, v153, v78
	v_add_f32_e32 v69, 1.0, v69
	v_add_f32_e32 v75, 1.0, v75
	v_rcp_f32_e32 v69, v69
	v_rcp_f32_e32 v75, v75
	v_mfma_f32_16x16x32_bf16 v[80:83], v[38:41], v[22:25], v[80:83]
	v_add_f32_e32 v79, v153, v79
	v_mul_f32_e32 v69, v74, v69
	v_mul_f32_e32 v75, v74, v75
	v_mul_f32_e32 v69, 0x3fb8aa3b, v69
	v_mul_f32_e32 v75, 0x3fb8aa3b, v75
	s_nop 2
	v_add_f32_e32 v71, v152, v80
	v_add_f32_e32 v77, v152, v81
	v_mul_f32_e32 v78, 0xbfb8aa3b, v78
	v_mul_f32_e32 v79, 0xbfb8aa3b, v79
	v_mul_f32_e32 v71, 0xbfb8aa3b, v71
	v_exp_f32_e32 v69, v69
	v_mul_f32_e32 v77, 0xbfb8aa3b, v77
	v_exp_f32_e32 v75, v75
	v_exp_f32_e32 v78, v78
	v_exp_f32_e32 v79, v79
	v_exp_f32_e32 v71, v71
	v_exp_f32_e32 v77, v77
	v_fma_f32 v76, -v69, v69, 1.0
	v_fma_f32 v81, -v75, v75, 1.0
	v_add_f32_e32 v78, 1.0, v78
	v_add_f32_e32 v79, 1.0, v79
	v_add_f32_e32 v71, 1.0, v71
	v_max_f32_e32 v76, 0, v76
	ds_read_u16 v80, v70 offset:34320
	v_add_f32_e32 v77, 1.0, v77
	v_max_f32_e32 v81, 0, v81
	v_rcp_f32_e32 v78, v78
	v_rcp_f32_e32 v79, v79
	v_rcp_f32_e32 v71, v71
	v_sqrt_f32_e32 v76, v76
	v_rcp_f32_e32 v77, v77
	v_sqrt_f32_e32 v81, v81
	v_mul_f32_e32 v78, v74, v78
	v_mul_f32_e32 v79, v74, v79
	v_mul_f32_e32 v71, v71, v76
	v_mul_f32_e32 v77, v77, v81
	ds_read_u16 v81, v70 offset:34848
	s_waitcnt lgkmcnt(1)
	v_lshlrev_b32_e32 v76, 16, v80
	v_add_f32_e32 v80, v152, v82
	v_mul_f32_e32 v78, 0x3fb8aa3b, v78
	v_add_f32_e32 v83, v152, v83
	v_mul_f32_e32 v79, 0x3fb8aa3b, v79
	v_mul_f32_e32 v80, 0xbfb8aa3b, v80
	v_exp_f32_e32 v78, v78
	v_mul_f32_e32 v83, 0xbfb8aa3b, v83
	v_exp_f32_e32 v79, v79
	v_exp_f32_e32 v80, v80
	v_exp_f32_e32 v83, v83
	v_fma_f32 v82, -v78, v78, 1.0
	v_fma_f32 v110, -v79, v79, 1.0
	v_add_f32_e32 v80, 1.0, v80
	v_max_f32_e32 v82, 0, v82
	v_add_f32_e32 v83, 1.0, v83
	v_max_f32_e32 v110, 0, v110
	v_rcp_f32_e32 v80, v80
	v_sqrt_f32_e32 v82, v82
	v_rcp_f32_e32 v83, v83
	v_sqrt_f32_e32 v110, v110
	s_waitcnt lgkmcnt(0)
	v_lshlrev_b32_e32 v81, 16, v81
	v_mul_f32_e32 v80, v80, v82
	v_lshlrev_b32_e32 v82, 16, v109
	v_mul_f32_e32 v83, v83, v110
	v_mul_f32_e32 v82, v83, v82
	v_mul_f32_e32 v79, v78, v79
	v_mul_f32_e32 v78, v78, v82
	v_fmac_f32_e32 v78, v80, v81
	v_mul_f32_e32 v79, v75, v79
	v_mul_f32_e32 v75, v75, v78
	v_fmac_f32_e32 v75, v77, v76
	v_mul_f32_e32 v80, v69, v79
	v_mfma_f32_16x16x32_bf16 v[76:79], v[34:37], v[6:9], 0
	v_mul_f32_e32 v69, v69, v75
	s_nop 0
	s_nop 0
	v_mfma_f32_16x16x32_bf16 v[34:37], v[34:37], v[14:17], 0
	s_nop 0
	v_mov_b32_e32 v110, v80
	v_mov_b32_e32 v112, v80
	s_nop 1
	v_permlane16_swap_b32_e32 v110, v112
	s_nop 1
	v_mov_b32_e32 v113, v110
	v_mov_b32_e32 v116, v112
	s_nop 1
	v_permlane32_swap_b32_e32 v110, v113
	v_permlane32_swap_b32_e32 v112, v116
	s_nop 1
	ds_bpermute_b32 v57, v68, v59 offset:128
	v_mfma_f32_16x16x32_bf16 v[76:79], v[38:41], v[2:5], v[76:79]
	ds_bpermute_b32 v59, v68, v59 offset:192
	ds_bpermute_b32 v60, v68, v63
	ds_bpermute_b32 v62, v68, v63 offset:64
	v_mfma_f32_16x16x32_bf16 v[34:37], v[38:41], v[10:13], v[34:37]
	ds_read_u16 v40, v70 offset:33824
	s_nop 2
	v_add_f32_e32 v38, v151, v76
	v_mul_f32_e32 v38, 0xbfb8aa3b, v38
	v_exp_f32_e32 v38, v38
	v_add_f32_e32 v39, v151, v77
	v_mul_f32_e32 v39, 0xbfb8aa3b, v39
	v_exp_f32_e32 v39, v39
	v_add_f32_e32 v38, 1.0, v38
	v_rcp_f32_e32 v38, v38
	v_add_f32_e32 v34, v150, v34
	v_mul_f32_e32 v34, 0xbfb8aa3b, v34
	v_add_f32_e32 v39, 1.0, v39
	v_mul_f32_e32 v38, v72, v38
	v_mul_f32_e32 v38, 0x3fb8aa3b, v38
	v_exp_f32_e32 v38, v38
	v_exp_f32_e32 v34, v34
	v_rcp_f32_e32 v39, v39
	v_add_f32_e32 v35, v150, v35
	v_fma_f32 v41, -v38, v38, 1.0
	v_add_f32_e32 v34, 1.0, v34
	v_max_f32_e32 v41, 0, v41
	v_mul_f32_e32 v39, v72, v39
	v_rcp_f32_e32 v34, v34
	v_sqrt_f32_e32 v41, v41
	v_mul_f32_e32 v39, 0x3fb8aa3b, v39
	v_mul_f32_e32 v35, 0xbfb8aa3b, v35
	v_exp_f32_e32 v39, v39
	v_exp_f32_e32 v35, v35
	v_lshlrev_b32_e32 v73, 16, v73
	v_fmac_f32_e32 v69, v71, v73
	v_mul_f32_e32 v71, v34, v41
	v_add_f32_e32 v34, v151, v78
	s_nop 0
	s_nop 0
	s_nop 0
	v_mov_b32_e32 v109, v69
	v_mov_b32_e32 v111, v69
	s_nop 1
	v_permlane16_swap_b32_e32 v109, v111
	s_nop 1
	v_mov_b32_e32 v114, v109
	v_mov_b32_e32 v115, v111
	s_nop 1
	v_permlane32_swap_b32_e32 v109, v114
	v_permlane32_swap_b32_e32 v111, v115
	s_nop 1
	v_fma_f32 v69, -v39, v39, 1.0
	v_mul_f32_e32 v34, 0xbfb8aa3b, v34
	v_add_f32_e32 v35, 1.0, v35
	v_max_f32_e32 v69, 0, v69
	v_exp_f32_e32 v34, v34
	v_rcp_f32_e32 v35, v35
	v_sqrt_f32_e32 v75, v69
	ds_read_u16 v73, v70 offset:34352
	v_add_f32_e32 v34, 1.0, v34
	s_waitcnt lgkmcnt(1)
; template <int DIR, int MODE>
; __device__ __forceinline__ void lru_pass(const Args& a, const LAS bf16_t* cxb, LAS bf16_t* gyb, const LAS float* carry, const bf16x8 (&Bw)[2][2][2], const float (&prm)[2][3], int l, int tt, float (&hf)[8][2][4]) {
;     ...
;     for (int mi = 0; mi < 8; ++mi) {
;         const int m = DIR ? 7 - mi : mi;
;         bf16x8 Af[2];
; #pragma unroll
;         for (int ks = 0; ks < 2; ++ks) Af[ks] = *(const LAS bf16x8*)(cxb + (m * 16 + fr) * CXS + 64 * h + 32 * ks + 8 * fq);
; #pragma unroll
;         for (int nt = 0; nt < 2; ++nt) {
;             f32x4 pr = (f32x4){0.f, 0.f, 0.f, 0.f}, pi = (f32x4){0.f, 0.f, 0.f, 0.f};
; #pragma unroll
;             for (int ks = 0; ks < 2; ++ks) { pr = __builtin_amdgcn_mfma_f32_16x16x32_bf16(Af[ks], Bw[0][nt][ks], pr, 0, 0, 0); pi = __builtin_amdgcn_mfma_f32_16x16x32_bf16(Af[ks], Bw[1][nt][ks], pi, 0, 0, 0); }
;             float av[4], bv[4];
; #pragma unroll
;             for (int reg = 0; reg < 4; ++reg) {
;                 const int tok = m * 16 + 4 * fq + reg;
;                 const float x = bf2f(cxb[tok * CXS + cc[nt]]);
;                 const float r = fsig(pr[reg] + ba[nt]), ig = fsig(pi[reg] + bxv[nt]);
;                 const float aa = __expf(k8[nt] * r);
;                 av[reg] = aa; bv[reg] = __builtin_amdgcn_sqrtf(fmaxf(1.0f - aa * aa, 0.f)) * ig * x;
;             }
;             float cum[4], hl[4];
;             if (DIR == 0) { cum[0] = av[0]; hl[0] = bv[0];
; #pragma unroll
;                 for (int reg = 1; reg < 4; ++reg) { cum[reg] = cum[reg - 1] * av[reg]; hl[reg] = av[reg] * hl[reg - 1] + bv[reg]; } }
;             else { cum[3] = av[3]; hl[3] = bv[3];
; #pragma unroll
;     ...
;             const float A4 = DIR ? cum[0] : cum[3], H4 = DIR ? hl[0] : hl[3];
;             float Aq[4], Hq[4];
; #pragma unroll
;             for (int q = 0; q < 4; ++q) { Aq[q] = __shfl(A4, fr + 16 * q); Hq[q] = __shfl(H4, fr + 16 * q); }
;             float hin;
;             if (DIR == 0) { const float s0 = C[nt], s1 = Aq[0] * s0 + Hq[0], s2 = Aq[1] * s1 + Hq[1], s3 = Aq[2] * s2 + Hq[2]; C[nt] = Aq[3] * s3 + Hq[3]; hin = fq == 0 ? s0 : (fq == 1 ? s1 : (fq == 2 ? s2 : s3)); }
;             else { const float s3 = C[nt], s2 = Aq[3] * s3 + Hq[3], s1 = Aq[2] * s2 + Hq[2], s0 = Aq[1] * s1 + Hq[1]; C[nt] = Aq[0] * s0 + Hq[0]; hin = fq == 3 ? s3 : (fq == 2 ? s2 : (fq == 1 ? s1 : s0)); }
	v_lshlrev_b32_e32 v69, 16, v40
	v_mul_f32_e32 v41, v35, v75
	v_add_f32_e32 v35, v150, v36
	v_rcp_f32_e32 v36, v34
	ds_read_u16 v34, v70 offset:34880
	s_waitcnt lgkmcnt(1)
	v_lshlrev_b32_e32 v40, 16, v73
	v_add_f32_e32 v37, v150, v37
	v_mul_f32_e32 v36, v72, v36
	v_mul_f32_e32 v36, 0x3fb8aa3b, v36
	v_exp_f32_e32 v73, v36
	v_add_f32_e32 v36, v151, v79
	v_mul_f32_e32 v36, 0xbfb8aa3b, v36
	v_exp_f32_e32 v75, v36
	v_mul_f32_e32 v37, 0xbfb8aa3b, v37
	v_mul_f32_e32 v35, 0xbfb8aa3b, v35
	v_exp_f32_e32 v35, v35
	v_add_f32_e32 v75, 1.0, v75
	v_rcp_f32_e32 v76, v75
	v_exp_f32_e32 v75, v37
	v_fma_f32 v36, -v73, v73, 1.0
	v_add_f32_e32 v35, 1.0, v35
	v_mul_f32_e32 v37, v72, v76
	v_mul_f32_e32 v37, 0x3fb8aa3b, v37
	v_exp_f32_e32 v37, v37
	v_max_f32_e32 v36, 0, v36
	ds_read_u16 v76, v70 offset:35408
	v_add_f32_e32 v75, 1.0, v75
	v_fma_f32 v77, -v37, v37, 1.0
	v_max_f32_e32 v77, 0, v77
	v_rcp_f32_e32 v35, v35
	v_sqrt_f32_e32 v36, v36
	v_rcp_f32_e32 v75, v75
	v_sqrt_f32_e32 v77, v77
	s_waitcnt lgkmcnt(1)
	v_lshlrev_b32_e32 v78, 16, v34
	v_mul_f32_e32 v79, v35, v36
	s_waitcnt lgkmcnt(0)
	v_lshlrev_b32_e32 v34, 16, v76
	v_mul_f32_e32 v35, v75, v77
	v_mul_f32_e32 v75, v35, v34
	v_mul_f32_e32 v76, v73, v37
	ds_read_b128 v[34:37], v89 offset:25344
	v_mul_f32_e32 v73, v73, v75
	v_fmac_f32_e32 v73, v79, v78
	v_mul_f32_e32 v75, v39, v76
	v_mul_f32_e32 v39, v39, v73
	v_fmac_f32_e32 v39, v41, v40
	v_mul_f32_e32 v73, v38, v75
	v_mul_f32_e32 v75, v38, v39
	ds_read_b128 v[38:41], v89 offset:25408
	s_waitcnt lgkmcnt(1)
	v_mfma_f32_16x16x32_bf16 v[76:79], v[34:37], v[26:29], 0
	v_fmac_f32_e32 v75, v71, v69
	s_nop 0
	s_nop 0
	s_waitcnt lgkmcnt(0)
	v_mfma_f32_16x16x32_bf16 v[76:79], v[38:41], v[18:21], v[76:79]
	s_nop 0
	v_mov_b32_e32 v117, v75
	v_mov_b32_e32 v119, v75
	s_nop 1
	v_permlane16_swap_b32_e32 v117, v119
	s_nop 1
	v_mov_b32_e32 v122, v117
	v_mov_b32_e32 v123, v119
	s_nop 1
	v_permlane32_swap_b32_e32 v117, v122
	v_permlane32_swap_b32_e32 v119, v123
	s_nop 1
	s_nop 0
	s_nop 4
	v_add_f32_e32 v69, v153, v76
	v_add_f32_e32 v75, v153, v77
	v_mul_f32_e32 v69, 0xbfb8aa3b, v69
	v_mul_f32_e32 v75, 0xbfb8aa3b, v75
	v_exp_f32_e32 v69, v69
	v_exp_f32_e32 v75, v75
	v_mfma_f32_16x16x32_bf16 v[80:83], v[34:37], v[30:33], 0
	v_add_f32_e32 v78, v153, v78
	v_add_f32_e32 v69, 1.0, v69
	v_add_f32_e32 v75, 1.0, v75
	v_rcp_f32_e32 v69, v69
	v_rcp_f32_e32 v75, v75
	v_mfma_f32_16x16x32_bf16 v[80:83], v[38:41], v[22:25], v[80:83]
	v_add_f32_e32 v79, v153, v79
	v_mul_f32_e32 v69, v74, v69
	v_mul_f32_e32 v75, v74, v75
	v_mul_f32_e32 v69, 0x3fb8aa3b, v69
	v_mul_f32_e32 v75, 0x3fb8aa3b, v75
	s_nop 2
	v_add_f32_e32 v71, v152, v80
	v_add_f32_e32 v77, v152, v81
	v_mul_f32_e32 v78, 0xbfb8aa3b, v78
	v_mul_f32_e32 v79, 0xbfb8aa3b, v79
	v_mul_f32_e32 v71, 0xbfb8aa3b, v71
	v_exp_f32_e32 v69, v69
	v_mul_f32_e32 v77, 0xbfb8aa3b, v77
	v_exp_f32_e32 v75, v75
	v_exp_f32_e32 v78, v78
	v_exp_f32_e32 v79, v79
	v_exp_f32_e32 v71, v71
	v_exp_f32_e32 v77, v77
	v_fma_f32 v76, -v69, v69, 1.0
	v_fma_f32 v81, -v75, v75, 1.0
	v_add_f32_e32 v78, 1.0, v78
	v_add_f32_e32 v79, 1.0, v79
	v_add_f32_e32 v71, 1.0, v71
	v_max_f32_e32 v76, 0, v76
	ds_read_u16 v80, v70 offset:25872
	v_add_f32_e32 v77, 1.0, v77
	v_max_f32_e32 v81, 0, v81
	v_rcp_f32_e32 v78, v78
	v_rcp_f32_e32 v79, v79
	v_rcp_f32_e32 v71, v71
	v_sqrt_f32_e32 v76, v76
	v_rcp_f32_e32 v77, v77
	v_sqrt_f32_e32 v81, v81
	v_mul_f32_e32 v78, v74, v78
	v_mul_f32_e32 v79, v74, v79
	v_mul_f32_e32 v71, v71, v76
	v_mul_f32_e32 v77, v77, v81
	ds_read_u16 v81, v70 offset:26400
	s_waitcnt lgkmcnt(1)
	v_lshlrev_b32_e32 v76, 16, v80
	v_add_f32_e32 v80, v152, v82
	v_mul_f32_e32 v78, 0x3fb8aa3b, v78
	v_add_f32_e32 v83, v152, v83
	v_mul_f32_e32 v79, 0x3fb8aa3b, v79
	v_mul_f32_e32 v80, 0xbfb8aa3b, v80
	v_exp_f32_e32 v78, v78
	v_mul_f32_e32 v83, 0xbfb8aa3b, v83
	v_exp_f32_e32 v79, v79
	v_exp_f32_e32 v80, v80
	v_exp_f32_e32 v83, v83
	v_fma_f32 v82, -v78, v78, 1.0
	v_fma_f32 v126, -v79, v79, 1.0
	v_add_f32_e32 v80, 1.0, v80
	v_max_f32_e32 v82, 0, v82
	v_add_f32_e32 v83, 1.0, v83
	v_max_f32_e32 v126, 0, v126
	v_rcp_f32_e32 v80, v80
	v_sqrt_f32_e32 v82, v82
	v_rcp_f32_e32 v83, v83
	v_sqrt_f32_e32 v126, v126
	s_waitcnt lgkmcnt(0)
	v_lshlrev_b32_e32 v81, 16, v81
	v_mul_f32_e32 v80, v80, v82
	v_lshlrev_b32_e32 v82, 16, v125
	v_mul_f32_e32 v83, v83, v126
	v_mul_f32_e32 v82, v83, v82
	v_mul_f32_e32 v79, v78, v79
	v_mul_f32_e32 v78, v78, v82
	v_fmac_f32_e32 v78, v80, v81
	v_mul_f32_e32 v79, v75, v79
	v_mul_f32_e32 v75, v75, v78
	v_fmac_f32_e32 v75, v77, v76
	v_mul_f32_e32 v80, v69, v79
	v_mfma_f32_16x16x32_bf16 v[76:79], v[34:37], v[6:9], 0
	s_nop 0
	s_nop 0
	v_mov_b32_e32 v118, v73
	v_mov_b32_e32 v120, v73
	s_nop 1
	v_permlane16_swap_b32_e32 v118, v120
	s_nop 1
	v_mov_b32_e32 v121, v118
	v_mov_b32_e32 v124, v120
	s_nop 1
	v_permlane32_swap_b32_e32 v118, v121
	v_permlane32_swap_b32_e32 v120, v124
	s_nop 1
	v_mfma_f32_16x16x32_bf16 v[34:37], v[34:37], v[14:17], 0
	ds_read_u16 v73, v70 offset:25344
	v_mul_f32_e32 v75, v69, v75
	ds_bpermute_b32 v126, v68, v80
	v_mfma_f32_16x16x32_bf16 v[76:79], v[38:41], v[2:5], v[76:79]
	ds_bpermute_b32 v128, v68, v80 offset:64
	ds_bpermute_b32 v69, v68, v80 offset:128
	ds_bpermute_b32 v61, v68, v63 offset:128
	v_mfma_f32_16x16x32_bf16 v[34:37], v[38:41], v[10:13], v[34:37]
	ds_read_u16 v40, v70 offset:25376
	s_nop 2
	v_add_f32_e32 v38, v151, v76
	v_mul_f32_e32 v38, 0xbfb8aa3b, v38
	v_exp_f32_e32 v38, v38
	v_add_f32_e32 v39, v151, v77
	v_mul_f32_e32 v39, 0xbfb8aa3b, v39
	v_exp_f32_e32 v39, v39
	v_add_f32_e32 v38, 1.0, v38
	v_rcp_f32_e32 v38, v38
	v_add_f32_e32 v34, v150, v34
	v_mul_f32_e32 v34, 0xbfb8aa3b, v34
	v_add_f32_e32 v39, 1.0, v39
	v_mul_f32_e32 v38, v72, v38
	v_mul_f32_e32 v38, 0x3fb8aa3b, v38
	v_exp_f32_e32 v38, v38
	v_exp_f32_e32 v34, v34
	v_rcp_f32_e32 v39, v39
	v_add_f32_e32 v35, v150, v35
	v_fma_f32 v41, -v38, v38, 1.0
	v_add_f32_e32 v34, 1.0, v34
	v_max_f32_e32 v41, 0, v41
	v_mul_f32_e32 v39, v72, v39
	v_rcp_f32_e32 v34, v34
	v_sqrt_f32_e32 v41, v41
	v_mul_f32_e32 v39, 0x3fb8aa3b, v39
	v_mul_f32_e32 v35, 0xbfb8aa3b, v35
	v_exp_f32_e32 v39, v39
	v_exp_f32_e32 v35, v35
	ds_read_u16 v76, v70 offset:25904
	s_waitcnt lgkmcnt(6)
; template <int DIR, int MODE>
; __device__ __forceinline__ void lru_pass(const Args& a, const LAS bf16_t* cxb, LAS bf16_t* gyb, const LAS float* carry, const bf16x8 (&Bw)[2][2][2], const float (&prm)[2][3], int l, int tt, float (&hf)[8][2][4]) {
;     ...
;     for (int mi = 0; mi < 8; ++mi) {
;         const int m = DIR ? 7 - mi : mi;
;         bf16x8 Af[2];
; #pragma unroll
;         for (int ks = 0; ks < 2; ++ks) Af[ks] = *(const LAS bf16x8*)(cxb + (m * 16 + fr) * CXS + 64 * h + 32 * ks + 8 * fq);
; #pragma unroll
;         for (int nt = 0; nt < 2; ++nt) {
;             f32x4 pr = (f32x4){0.f, 0.f, 0.f, 0.f}, pi = (f32x4){0.f, 0.f, 0.f, 0.f};
; #pragma unroll
;             for (int ks = 0; ks < 2; ++ks) { pr = __builtin_amdgcn_mfma_f32_16x16x32_bf16(Af[ks], Bw[0][nt][ks], pr, 0, 0, 0); pi = __builtin_amdgcn_mfma_f32_16x16x32_bf16(Af[ks], Bw[1][nt][ks], pi, 0, 0, 0); }
;             float av[4], bv[4];
; #pragma unroll
;             for (int reg = 0; reg < 4; ++reg) {
;                 const int tok = m * 16 + 4 * fq + reg;
;                 const float x = bf2f(cxb[tok * CXS + cc[nt]]);
;                 const float r = fsig(pr[reg] + ba[nt]), ig = fsig(pi[reg] + bxv[nt]);
;                 const float aa = __expf(k8[nt] * r);
;                 av[reg] = aa; bv[reg] = __builtin_amdgcn_sqrtf(fmaxf(1.0f - aa * aa, 0.f)) * ig * x;
;             }
;             float cum[4], hl[4];
;             if (DIR == 0) { cum[0] = av[0]; hl[0] = bv[0];
; #pragma unroll
;                 for (int reg = 1; reg < 4; ++reg) { cum[reg] = cum[reg - 1] * av[reg]; hl[reg] = av[reg] * hl[reg - 1] + bv[reg]; } }
;             else { cum[3] = av[3]; hl[3] = bv[3];
; #pragma unroll
;     ...
;             const float A4 = DIR ? cum[0] : cum[3], H4 = DIR ? hl[0] : hl[3];
;             float Aq[4], Hq[4];
; #pragma unroll
;             for (int q = 0; q < 4; ++q) { Aq[q] = __shfl(A4, fr + 16 * q); Hq[q] = __shfl(H4, fr + 16 * q); }
;             float hin;
;             if (DIR == 0) { const float s0 = C[nt], s1 = Aq[0] * s0 + Hq[0], s2 = Aq[1] * s1 + Hq[1], s3 = Aq[2] * s2 + Hq[2]; C[nt] = Aq[3] * s3 + Hq[3]; hin = fq == 0 ? s0 : (fq == 1 ? s1 : (fq == 2 ? s2 : s3)); }
;             else { const float s3 = C[nt], s2 = Aq[3] * s3 + Hq[3], s1 = Aq[2] * s2 + Hq[2], s0 = Aq[1] * s1 + Hq[1]; C[nt] = Aq[0] * s0 + Hq[0]; hin = fq == 3 ? s3 : (fq == 2 ? s2 : (fq == 1 ? s1 : s0)); }
	v_lshlrev_b32_e32 v73, 16, v73
	v_fmac_f32_e32 v75, v71, v73
	s_nop 0
	s_nop 0
	s_nop 0
	v_mov_b32_e32 v125, v75
	v_mov_b32_e32 v127, v75
	s_nop 1
	v_permlane16_swap_b32_e32 v125, v127
	s_nop 1
	v_mov_b32_e32 v129, v125
	v_mov_b32_e32 v130, v127
	s_nop 1
	v_permlane32_swap_b32_e32 v125, v129
	v_permlane32_swap_b32_e32 v127, v130
	s_nop 1
	v_mul_f32_e32 v75, v34, v41
	v_add_f32_e32 v34, v151, v78
	v_fma_f32 v73, -v39, v39, 1.0
	v_mul_f32_e32 v34, 0xbfb8aa3b, v34
	v_add_f32_e32 v35, 1.0, v35
	v_max_f32_e32 v73, 0, v73
	v_exp_f32_e32 v34, v34
	v_rcp_f32_e32 v35, v35
	v_sqrt_f32_e32 v77, v73
	s_waitcnt lgkmcnt(1)
	v_lshlrev_b32_e32 v73, 16, v40
	v_add_f32_e32 v34, 1.0, v34
	s_waitcnt lgkmcnt(0)
	v_lshlrev_b32_e32 v40, 16, v76
	v_mul_f32_e32 v41, v35, v77
	v_add_f32_e32 v35, v150, v36
	v_rcp_f32_e32 v36, v34
	v_add_f32_e32 v37, v150, v37
	v_mul_f32_e32 v37, 0xbfb8aa3b, v37
	v_mul_f32_e32 v35, 0xbfb8aa3b, v35
	v_mul_f32_e32 v36, v72, v36
	v_mul_f32_e32 v36, 0x3fb8aa3b, v36
	v_exp_f32_e32 v76, v36
	v_add_f32_e32 v36, v151, v79
	v_mul_f32_e32 v36, 0xbfb8aa3b, v36
	v_exp_f32_e32 v77, v36
	v_exp_f32_e32 v35, v35
	v_fma_f32 v36, -v76, v76, 1.0
	ds_read_u16 v34, v70 offset:26432
	v_add_f32_e32 v77, 1.0, v77
	v_rcp_f32_e32 v78, v77
	v_exp_f32_e32 v77, v37
	v_add_f32_e32 v35, 1.0, v35
	v_max_f32_e32 v36, 0, v36
	v_mul_f32_e32 v37, v72, v78
	v_mul_f32_e32 v37, 0x3fb8aa3b, v37
	v_exp_f32_e32 v37, v37
	ds_read_u16 v78, v70 offset:26960
	v_add_f32_e32 v77, 1.0, v77
	v_rcp_f32_e32 v35, v35
	v_fma_f32 v79, -v37, v37, 1.0
	v_max_f32_e32 v79, 0, v79
	v_sqrt_f32_e32 v36, v36
	v_rcp_f32_e32 v77, v77
	v_sqrt_f32_e32 v79, v79
	ds_bpermute_b32 v71, v68, v80 offset:192
	s_waitcnt lgkmcnt(2)
	v_lshlrev_b32_e32 v80, 16, v34
	v_mul_f32_e32 v81, v35, v36
	s_waitcnt lgkmcnt(1)
	v_lshlrev_b32_e32 v34, 16, v78
	v_mul_f32_e32 v35, v77, v79
	v_mul_f32_e32 v77, v35, v34
	v_mul_f32_e32 v78, v76, v37
	ds_read_b128 v[34:37], v89 offset:16896
	v_mul_f32_e32 v76, v76, v77
	v_fmac_f32_e32 v76, v81, v80
	v_mul_f32_e32 v77, v39, v78
	v_mul_f32_e32 v39, v39, v76
	v_fmac_f32_e32 v39, v41, v40
	v_mul_f32_e32 v136, v38, v77
	v_mul_f32_e32 v137, v38, v39
	ds_read_b128 v[38:41], v89 offset:16960
	s_waitcnt lgkmcnt(1)
	v_mfma_f32_16x16x32_bf16 v[76:79], v[34:37], v[26:29], 0
	v_fmac_f32_e32 v137, v75, v73
	s_nop 0
	ds_bpermute_b32 v131, v68, v137
	s_waitcnt lgkmcnt(1)
	v_mfma_f32_16x16x32_bf16 v[76:79], v[38:41], v[18:21], v[76:79]
	s_nop 0
	ds_bpermute_b32 v133, v68, v137 offset:64
	s_nop 0
	s_nop 4
	v_add_f32_e32 v77, v153, v77
	v_mul_f32_e32 v77, 0xbfb8aa3b, v77
	v_exp_f32_e32 v77, v77
	v_add_f32_e32 v76, v153, v76
	v_mfma_f32_16x16x32_bf16 v[80:83], v[34:37], v[30:33], 0
	v_mul_f32_e32 v76, 0xbfb8aa3b, v76
	v_exp_f32_e32 v76, v76
	v_add_f32_e32 v77, 1.0, v77
	v_add_f32_e32 v78, v153, v78
	v_add_f32_e32 v79, v153, v79
	v_rcp_f32_e32 v77, v77
	v_mul_f32_e32 v78, 0xbfb8aa3b, v78
	v_mul_f32_e32 v79, 0xbfb8aa3b, v79
	v_mfma_f32_16x16x32_bf16 v[80:83], v[38:41], v[22:25], v[80:83]
	v_exp_f32_e32 v78, v78
	v_exp_f32_e32 v79, v79
	v_add_f32_e32 v76, 1.0, v76
	v_rcp_f32_e32 v76, v76
	v_mul_f32_e32 v77, v74, v77
	s_nop 2
	v_add_f32_e32 v81, v152, v81
	v_mul_f32_e32 v77, 0x3fb8aa3b, v77
	v_add_f32_e32 v78, 1.0, v78
	v_add_f32_e32 v79, 1.0, v79
	v_mul_f32_e32 v81, 0xbfb8aa3b, v81
	v_exp_f32_e32 v77, v77
	v_rcp_f32_e32 v78, v78
	v_rcp_f32_e32 v79, v79
	v_mul_f32_e32 v76, v74, v76
	v_exp_f32_e32 v81, v81
	v_add_f32_e32 v80, v152, v80
	v_mul_f32_e32 v76, 0x3fb8aa3b, v76
	v_mul_f32_e32 v80, 0xbfb8aa3b, v80
	v_exp_f32_e32 v76, v76
	v_exp_f32_e32 v80, v80
	v_fma_f32 v140, -v77, v77, 1.0
	v_mul_f32_e32 v78, v74, v78
	v_mul_f32_e32 v79, v74, v79
	v_add_f32_e32 v81, 1.0, v81
	v_max_f32_e32 v140, 0, v140
	v_add_f32_e32 v82, v152, v82
	v_mul_f32_e32 v78, 0x3fb8aa3b, v78
	v_add_f32_e32 v83, v152, v83
	v_mul_f32_e32 v79, 0x3fb8aa3b, v79
	v_rcp_f32_e32 v81, v81
	v_sqrt_f32_e32 v140, v140
	v_mul_f32_e32 v82, 0xbfb8aa3b, v82
	v_exp_f32_e32 v78, v78
	v_mul_f32_e32 v83, 0xbfb8aa3b, v83
	v_exp_f32_e32 v79, v79
	v_fma_f32 v138, -v76, v76, 1.0
	v_exp_f32_e32 v82, v82
	v_exp_f32_e32 v83, v83
	v_add_f32_e32 v80, 1.0, v80
	v_max_f32_e32 v138, 0, v138
	v_rcp_f32_e32 v80, v80
	v_sqrt_f32_e32 v138, v138
	v_mul_f32_e32 v81, v81, v140
	v_fma_f32 v140, -v78, v78, 1.0
	v_fma_f32 v142, -v79, v79, 1.0
	v_add_f32_e32 v82, 1.0, v82
	v_max_f32_e32 v140, 0, v140
	v_add_f32_e32 v83, 1.0, v83
	v_max_f32_e32 v142, 0, v142
	v_rcp_f32_e32 v82, v82
	v_sqrt_f32_e32 v140, v140
	v_rcp_f32_e32 v83, v83
	v_sqrt_f32_e32 v142, v142
	v_mul_f32_e32 v138, v80, v138
	v_lshlrev_b32_e32 v80, 16, v139
	ds_read_u16 v139, v70 offset:17952
	v_mul_f32_e32 v82, v82, v140
	v_lshlrev_b32_e32 v140, 16, v141
	v_mul_f32_e32 v83, v83, v142
	v_mul_f32_e32 v83, v83, v140
	s_waitcnt lgkmcnt(0)
; template <int DIR, int MODE>
; __device__ __forceinline__ void lru_pass(const Args& a, const LAS bf16_t* cxb, LAS bf16_t* gyb, const LAS float* carry, const bf16x8 (&Bw)[2][2][2], const float (&prm)[2][3], int l, int tt, float (&hf)[8][2][4]) {
;     ...
;     for (int mi = 0; mi < 8; ++mi) {
;         const int m = DIR ? 7 - mi : mi;
;         bf16x8 Af[2];
; #pragma unroll
;         for (int ks = 0; ks < 2; ++ks) Af[ks] = *(const LAS bf16x8*)(cxb + (m * 16 + fr) * CXS + 64 * h + 32 * ks + 8 * fq);
; #pragma unroll
;         for (int nt = 0; nt < 2; ++nt) {
;             f32x4 pr = (f32x4){0.f, 0.f, 0.f, 0.f}, pi = (f32x4){0.f, 0.f, 0.f, 0.f};
; #pragma unroll
;             for (int ks = 0; ks < 2; ++ks) { pr = __builtin_amdgcn_mfma_f32_16x16x32_bf16(Af[ks], Bw[0][nt][ks], pr, 0, 0, 0); pi = __builtin_amdgcn_mfma_f32_16x16x32_bf16(Af[ks], Bw[1][nt][ks], pi, 0, 0, 0); }
;             float av[4], bv[4];
; #pragma unroll
;             for (int reg = 0; reg < 4; ++reg) {
;                 const int tok = m * 16 + 4 * fq + reg;
;                 const float x = bf2f(cxb[tok * CXS + cc[nt]]);
;                 const float r = fsig(pr[reg] + ba[nt]), ig = fsig(pi[reg] + bxv[nt]);
;                 const float aa = __expf(k8[nt] * r);
;                 av[reg] = aa; bv[reg] = __builtin_amdgcn_sqrtf(fmaxf(1.0f - aa * aa, 0.f)) * ig * x;
;             }
;             float cum[4], hl[4];
;             if (DIR == 0) { cum[0] = av[0]; hl[0] = bv[0];
; #pragma unroll
;                 for (int reg = 1; reg < 4; ++reg) { cum[reg] = cum[reg - 1] * av[reg]; hl[reg] = av[reg] * hl[reg - 1] + bv[reg]; } }
;             else { cum[3] = av[3]; hl[3] = bv[3];
; #pragma unroll
;     ...
;             const float A4 = DIR ? cum[0] : cum[3], H4 = DIR ? hl[0] : hl[3];
;             float Aq[4], Hq[4];
; #pragma unroll
;             for (int q = 0; q < 4; ++q) { Aq[q] = __shfl(A4, fr + 16 * q); Hq[q] = __shfl(H4, fr + 16 * q); }
;             float hin;
;             if (DIR == 0) { const float s0 = C[nt], s1 = Aq[0] * s0 + Hq[0], s2 = Aq[1] * s1 + Hq[1], s3 = Aq[2] * s2 + Hq[2]; C[nt] = Aq[3] * s3 + Hq[3]; hin = fq == 0 ? s0 : (fq == 1 ? s1 : (fq == 2 ? s2 : s3)); }
;             else { const float s3 = C[nt], s2 = Aq[3] * s3 + Hq[3], s1 = Aq[2] * s2 + Hq[2], s0 = Aq[1] * s1 + Hq[1]; C[nt] = Aq[0] * s0 + Hq[0]; hin = fq == 3 ? s3 : (fq == 2 ? s2 : (fq == 1 ? s1 : s0)); }
	v_lshlrev_b32_e32 v139, 16, v139
	v_mul_f32_e32 v79, v78, v79
	v_mul_f32_e32 v78, v78, v83
	v_fmac_f32_e32 v78, v82, v139
	v_mul_f32_e32 v79, v77, v79
	v_mul_f32_e32 v77, v77, v78
	v_fmac_f32_e32 v77, v81, v80
	v_mfma_f32_16x16x32_bf16 v[80:83], v[34:37], v[6:9], 0
	ds_bpermute_b32 v135, v68, v137 offset:128
	v_mov_b32_e32 v132, v136
	v_mov_b32_e32 v134, v136
	s_nop 1
	v_permlane16_swap_b32_e32 v132, v134
	s_nop 1
	v_mov_b32_e32 v73, v132
	v_mov_b32_e32 v75, v134
	s_nop 1
	v_permlane32_swap_b32_e32 v132, v73
	v_permlane32_swap_b32_e32 v134, v75
	s_nop 1
	ds_bpermute_b32 v136, v68, v137 offset:192
	v_mfma_f32_16x16x32_bf16 v[34:37], v[34:37], v[14:17], 0
	ds_read_u16 v137, v70 offset:16896
	ds_read_u16 v141, v70 offset:17456
	v_mul_f32_e32 v140, v76, v77
	v_mfma_f32_16x16x32_bf16 v[80:83], v[38:41], v[2:5], v[80:83]
	v_mul_f32_e32 v79, v76, v79
	ds_bpermute_b32 v63, v68, v63 offset:192
	ds_bpermute_b32 v64, v68, v67
	v_mfma_f32_16x16x32_bf16 v[34:37], v[38:41], v[10:13], v[34:37]
	ds_read_u16 v40, v70 offset:16928
	s_nop 2
	v_add_f32_e32 v38, v151, v80
	v_mul_f32_e32 v38, 0xbfb8aa3b, v38
	v_exp_f32_e32 v38, v38
	v_add_f32_e32 v39, v151, v81
	v_mul_f32_e32 v39, 0xbfb8aa3b, v39
	v_exp_f32_e32 v39, v39
	v_add_f32_e32 v38, 1.0, v38
	v_rcp_f32_e32 v38, v38
	v_add_f32_e32 v34, v150, v34
	v_mul_f32_e32 v34, 0xbfb8aa3b, v34
	v_add_f32_e32 v39, 1.0, v39
	v_mul_f32_e32 v38, v72, v38
	v_mul_f32_e32 v38, 0x3fb8aa3b, v38
	v_exp_f32_e32 v38, v38
	v_exp_f32_e32 v34, v34
	v_rcp_f32_e32 v39, v39
	v_add_f32_e32 v35, v150, v35
	v_fma_f32 v41, -v38, v38, 1.0
	v_add_f32_e32 v34, 1.0, v34
	v_max_f32_e32 v41, 0, v41
	v_mul_f32_e32 v39, v72, v39
	v_rcp_f32_e32 v34, v34
	v_sqrt_f32_e32 v41, v41
	v_mul_f32_e32 v39, 0x3fb8aa3b, v39
	v_mul_f32_e32 v35, 0xbfb8aa3b, v35
	v_exp_f32_e32 v39, v39
	v_exp_f32_e32 v35, v35
	v_mul_f32_e32 v81, v34, v41
	v_add_f32_e32 v34, v151, v82
	v_fma_f32 v80, -v39, v39, 1.0
	v_mul_f32_e32 v34, 0xbfb8aa3b, v34
	v_add_f32_e32 v35, 1.0, v35
	v_max_f32_e32 v80, 0, v80
	v_exp_f32_e32 v34, v34
	v_rcp_f32_e32 v35, v35
	v_sqrt_f32_e32 v142, v80
	v_add_f32_e32 v37, v150, v37
	v_add_f32_e32 v34, 1.0, v34
	v_mul_f32_e32 v37, 0xbfb8aa3b, v37
	v_mul_f32_e32 v41, v35, v142
	v_add_f32_e32 v35, v150, v36
	v_rcp_f32_e32 v36, v34
	ds_read_u16 v34, v70 offset:17984
	s_waitcnt lgkmcnt(1)
	v_lshlrev_b32_e32 v80, 16, v40
	v_lshlrev_b32_e32 v40, 16, v141
	v_mul_f32_e32 v36, v72, v36
	v_mul_f32_e32 v36, 0x3fb8aa3b, v36
	v_exp_f32_e32 v82, v36
	v_add_f32_e32 v36, v151, v83
	v_mul_f32_e32 v36, 0xbfb8aa3b, v36
	v_exp_f32_e32 v83, v36
	v_mul_f32_e32 v35, 0xbfb8aa3b, v35
	v_exp_f32_e32 v35, v35
	v_fma_f32 v36, -v82, v82, 1.0
	v_add_f32_e32 v83, 1.0, v83
	v_rcp_f32_e32 v141, v83
	v_exp_f32_e32 v83, v37
	v_add_f32_e32 v35, 1.0, v35
	v_max_f32_e32 v36, 0, v36
	v_mul_f32_e32 v37, v72, v141
	v_mul_f32_e32 v37, 0x3fb8aa3b, v37
	v_exp_f32_e32 v37, v37
	ds_read_u16 v141, v70 offset:18512
	v_add_f32_e32 v83, 1.0, v83
	v_rcp_f32_e32 v35, v35
	v_fma_f32 v142, -v37, v37, 1.0
	v_max_f32_e32 v142, 0, v142
	v_sqrt_f32_e32 v36, v36
	v_rcp_f32_e32 v83, v83
	v_sqrt_f32_e32 v142, v142
	s_waitcnt lgkmcnt(1)
	v_lshlrev_b32_e32 v143, 16, v34
	v_mul_f32_e32 v144, v35, v36
	s_waitcnt lgkmcnt(0)
	v_lshlrev_b32_e32 v34, 16, v141
	v_mul_f32_e32 v35, v83, v142
	v_mul_f32_e32 v83, v35, v34
	v_mul_f32_e32 v141, v82, v37
	ds_read_b128 v[34:37], v89 offset:8448
	v_mul_f32_e32 v82, v82, v83
	v_fmac_f32_e32 v82, v144, v143
	v_mul_f32_e32 v83, v39, v141
	v_mul_f32_e32 v39, v39, v82
	v_fmac_f32_e32 v39, v41, v40
	v_mul_f32_e32 v83, v38, v83
	v_mul_f32_e32 v158, v38, v39
	ds_read_b128 v[38:41], v89 offset:8512
	s_waitcnt lgkmcnt(1)
	v_mfma_f32_16x16x32_bf16 v[144:147], v[34:37], v[26:29], 0
	v_fmac_f32_e32 v158, v81, v80
	ds_bpermute_b32 v141, v68, v158
	ds_bpermute_b32 v142, v68, v158 offset:64
	s_waitcnt lgkmcnt(2)
	v_mfma_f32_16x16x32_bf16 v[146:149], v[38:41], v[18:21], v[144:147]
	ds_bpermute_b32 v143, v68, v158 offset:128
	s_nop 1
	ds_bpermute_b32 v144, v68, v158 offset:192
	ds_bpermute_b32 v66, v68, v67 offset:64
	s_nop 2
	v_add_f32_e32 v145, v153, v146
	v_add_f32_e32 v147, v153, v147
	v_mul_f32_e32 v145, 0xbfb8aa3b, v145
	v_mul_f32_e32 v147, 0xbfb8aa3b, v147
	v_exp_f32_e32 v145, v145
	v_exp_f32_e32 v147, v147
	v_mfma_f32_16x16x32_bf16 v[154:157], v[34:37], v[30:33], 0
	v_add_f32_e32 v148, v153, v148
	v_add_f32_e32 v145, 1.0, v145
	v_add_f32_e32 v147, 1.0, v147
	v_add_f32_e32 v149, v153, v149
	v_rcp_f32_e32 v145, v145
	v_rcp_f32_e32 v147, v147
	v_mul_f32_e32 v148, 0xbfb8aa3b, v148
	v_mul_f32_e32 v149, 0xbfb8aa3b, v149
	v_mfma_f32_16x16x32_bf16 v[154:157], v[38:41], v[22:25], v[154:157]
	v_exp_f32_e32 v148, v148
	v_exp_f32_e32 v149, v149
	v_mul_f32_e32 v145, v74, v145
	v_mul_f32_e32 v147, v74, v147
	v_mul_f32_e32 v145, 0x3fb8aa3b, v145
	s_nop 2
	v_add_f32_e32 v146, v152, v154
	v_add_f32_e32 v155, v152, v155
	v_mul_f32_e32 v147, 0x3fb8aa3b, v147
	v_add_f32_e32 v148, 1.0, v148
	v_add_f32_e32 v149, 1.0, v149
	v_mul_f32_e32 v146, 0xbfb8aa3b, v146
	v_exp_f32_e32 v145, v145
	v_mul_f32_e32 v155, 0xbfb8aa3b, v155
	v_exp_f32_e32 v147, v147
	v_rcp_f32_e32 v148, v148
	v_rcp_f32_e32 v149, v149
	v_exp_f32_e32 v146, v146
	v_exp_f32_e32 v155, v155
	v_fma_f32 v158, -v145, v145, 1.0
	v_fma_f32 v160, -v147, v147, 1.0
	v_mul_f32_e32 v148, v74, v148
	v_mul_f32_e32 v149, v74, v149
	ds_read_u16 v154, v70 offset:8448
	v_add_f32_e32 v146, 1.0, v146
	v_max_f32_e32 v158, 0, v158
	v_add_f32_e32 v155, 1.0, v155
	v_max_f32_e32 v160, 0, v160
	v_add_f32_e32 v156, v152, v156
	v_mul_f32_e32 v148, 0x3fb8aa3b, v148
	v_add_f32_e32 v157, v152, v157
	v_mul_f32_e32 v149, 0x3fb8aa3b, v149
	v_rcp_f32_e32 v146, v146
	v_sqrt_f32_e32 v158, v158
	v_rcp_f32_e32 v155, v155
	v_sqrt_f32_e32 v160, v160
	v_mul_f32_e32 v156, 0xbfb8aa3b, v156
	v_exp_f32_e32 v148, v148
	v_mul_f32_e32 v157, 0xbfb8aa3b, v157
	v_exp_f32_e32 v149, v149
	v_exp_f32_e32 v156, v156
	v_exp_f32_e32 v157, v157
	v_mul_f32_e32 v146, v146, v158
	v_mul_f32_e32 v155, v155, v160
	ds_read_u16 v158, v70 offset:9504
	ds_read_u16 v160, v70 offset:10032
	s_waitcnt lgkmcnt(2)
; #define LAS __attribute__((address_space(3)))
; __device__ __forceinline__ float fsig(float x) { return frcp(1.0f + __expf(-x)); }
; template <int DIR, int MODE>
; __device__ __forceinline__ void lru_pass(const Args& a, const LAS bf16_t* cxb, LAS bf16_t* gyb, const LAS float* carry, const bf16x8 (&Bw)[2][2][2], const float (&prm)[2][3], int l, int tt, float (&hf)[8][2][4]) {
;     ...
;         for (int ks = 0; ks < 2; ++ks) Af[ks] = *(const LAS bf16x8*)(cxb + (m * 16 + fr) * CXS + 64 * h + 32 * ks + 8 * fq);
; #pragma unroll
;         for (int nt = 0; nt < 2; ++nt) {
;             f32x4 pr = (f32x4){0.f, 0.f, 0.f, 0.f}, pi = (f32x4){0.f, 0.f, 0.f, 0.f};
; #pragma unroll
;             for (int ks = 0; ks < 2; ++ks) { pr = __builtin_amdgcn_mfma_f32_16x16x32_bf16(Af[ks], Bw[0][nt][ks], pr, 0, 0, 0); pi = __builtin_amdgcn_mfma_f32_16x16x32_bf16(Af[ks], Bw[1][nt][ks], pi, 0, 0, 0); }
;             float av[4], bv[4];
; #pragma unroll
;             for (int reg = 0; reg < 4; ++reg) {
;                 const int tok = m * 16 + 4 * fq + reg;
;                 const float x = bf2f(cxb[tok * CXS + cc[nt]]);
;                 const float r = fsig(pr[reg] + ba[nt]), ig = fsig(pi[reg] + bxv[nt]);
;                 const float aa = __expf(k8[nt] * r);
;                 av[reg] = aa; bv[reg] = __builtin_amdgcn_sqrtf(fmaxf(1.0f - aa * aa, 0.f)) * ig * x;
;             }
;             float cum[4], hl[4];
;             if (DIR == 0) { cum[0] = av[0]; hl[0] = bv[0];
; #pragma unroll
;                 for (int reg = 1; reg < 4; ++reg) { cum[reg] = cum[reg - 1] * av[reg]; hl[reg] = av[reg] * hl[reg - 1] + bv[reg]; } }
;             else { cum[3] = av[3]; hl[3] = bv[3];
; #pragma unroll
;     ...
;             const float A4 = DIR ? cum[0] : cum[3], H4 = DIR ? hl[0] : hl[3];
;             float Aq[4], Hq[4];
; #pragma unroll
;             for (int q = 0; q < 4; ++q) { Aq[q] = __shfl(A4, fr + 16 * q); Hq[q] = __shfl(H4, fr + 16 * q); }
	v_lshlrev_b32_e32 v161, 16, v154
	v_lshlrev_b32_e32 v154, 16, v159
	v_fma_f32 v159, -v148, v148, 1.0
	v_fma_f32 v162, -v149, v149, 1.0
	v_add_f32_e32 v156, 1.0, v156
	v_max_f32_e32 v159, 0, v159
	v_add_f32_e32 v157, 1.0, v157
	v_max_f32_e32 v162, 0, v162
	v_rcp_f32_e32 v156, v156
	v_sqrt_f32_e32 v159, v159
	v_rcp_f32_e32 v157, v157
	v_sqrt_f32_e32 v162, v162
	s_waitcnt lgkmcnt(1)
	v_lshlrev_b32_e32 v158, 16, v158
	v_mul_f32_e32 v156, v156, v159
	s_waitcnt lgkmcnt(0)
	v_lshlrev_b32_e32 v159, 16, v160
	v_mul_f32_e32 v157, v157, v162
	v_mul_f32_e32 v157, v157, v159
	v_mul_f32_e32 v149, v148, v149
	v_mul_f32_e32 v148, v148, v157
	v_fmac_f32_e32 v148, v156, v158
	v_mul_f32_e32 v149, v147, v149
	v_mul_f32_e32 v147, v147, v148
	v_fmac_f32_e32 v147, v155, v154
	v_mfma_f32_16x16x32_bf16 v[154:157], v[34:37], v[6:9], 0
	v_mul_f32_e32 v163, v145, v147
	v_fmac_f32_e32 v163, v146, v161
	v_mul_f32_e32 v162, v145, v149
	v_mfma_f32_16x16x32_bf16 v[34:37], v[34:37], v[14:17], 0
	ds_bpermute_b32 v146, v68, v162
	ds_bpermute_b32 v148, v68, v162 offset:64
	ds_bpermute_b32 v149, v68, v162 offset:128
	v_mfma_f32_16x16x32_bf16 v[158:161], v[38:41], v[2:5], v[154:157]
	s_nop 0
	s_nop 0
	ds_bpermute_b32 v65, v68, v67 offset:128
	v_mfma_f32_16x16x32_bf16 v[34:37], v[38:41], v[10:13], v[34:37]
	ds_bpermute_b32 v156, v68, v162 offset:192
	s_nop 2
	v_add_f32_e32 v38, v151, v158
	v_mul_f32_e32 v38, 0xbfb8aa3b, v38
	v_exp_f32_e32 v38, v38
	v_add_f32_e32 v39, v151, v159
	v_mul_f32_e32 v39, 0xbfb8aa3b, v39
	v_exp_f32_e32 v39, v39
	v_add_f32_e32 v38, 1.0, v38
	v_rcp_f32_e32 v38, v38
	v_add_f32_e32 v34, v150, v34
	v_mul_f32_e32 v34, 0xbfb8aa3b, v34
	v_add_f32_e32 v39, 1.0, v39
	v_mul_f32_e32 v38, v72, v38
	v_mul_f32_e32 v38, 0x3fb8aa3b, v38
	v_exp_f32_e32 v38, v38
	v_exp_f32_e32 v34, v34
	v_rcp_f32_e32 v39, v39
	v_add_f32_e32 v35, v150, v35
	v_fma_f32 v41, -v38, v38, 1.0
	v_add_f32_e32 v34, 1.0, v34
	v_max_f32_e32 v41, 0, v41
	v_mul_f32_e32 v39, v72, v39
	v_rcp_f32_e32 v34, v34
	v_sqrt_f32_e32 v41, v41
	v_mul_f32_e32 v39, 0x3fb8aa3b, v39
	v_mul_f32_e32 v35, 0xbfb8aa3b, v35
	v_exp_f32_e32 v39, v39
	v_exp_f32_e32 v35, v35
	v_mul_f32_e32 v158, v34, v41
	v_add_f32_e32 v34, v151, v160
	v_fma_f32 v157, -v39, v39, 1.0
	v_mul_f32_e32 v34, 0xbfb8aa3b, v34
	v_add_f32_e32 v35, 1.0, v35
	v_max_f32_e32 v157, 0, v157
	v_exp_f32_e32 v34, v34
	v_rcp_f32_e32 v35, v35
	v_sqrt_f32_e32 v162, v157
	ds_read_u16 v40, v70 offset:8480
	ds_read_u16 v159, v70 offset:9008
	v_add_f32_e32 v34, 1.0, v34
	v_mul_f32_e32 v41, v35, v162
	v_add_f32_e32 v35, v150, v36
	v_rcp_f32_e32 v36, v34
	ds_read_u16 v34, v70 offset:9536
	s_waitcnt lgkmcnt(2)
	v_lshlrev_b32_e32 v157, 16, v40
	s_waitcnt lgkmcnt(1)
	v_lshlrev_b32_e32 v40, 16, v159
	v_mul_f32_e32 v36, v72, v36
	v_mul_f32_e32 v36, 0x3fb8aa3b, v36
	v_exp_f32_e32 v159, v36
	v_add_f32_e32 v36, v151, v161
	v_mul_f32_e32 v36, 0xbfb8aa3b, v36
	v_exp_f32_e32 v160, v36
	v_add_f32_e32 v37, v150, v37
	v_mul_f32_e32 v37, 0xbfb8aa3b, v37
	v_mul_f32_e32 v35, 0xbfb8aa3b, v35
	v_add_f32_e32 v160, 1.0, v160
	v_rcp_f32_e32 v161, v160
	v_exp_f32_e32 v160, v37
	v_exp_f32_e32 v35, v35
	v_fma_f32 v36, -v159, v159, 1.0
	v_mul_f32_e32 v37, v72, v161
	v_mul_f32_e32 v37, 0x3fb8aa3b, v37
	v_exp_f32_e32 v37, v37
	v_add_f32_e32 v35, 1.0, v35
	v_max_f32_e32 v36, 0, v36
	ds_read_u16 v161, v70 offset:10064
	v_fma_f32 v162, -v37, v37, 1.0
	v_add_f32_e32 v160, 1.0, v160
	v_max_f32_e32 v162, 0, v162
	v_rcp_f32_e32 v35, v35
	v_sqrt_f32_e32 v36, v36
	v_rcp_f32_e32 v160, v160
	v_sqrt_f32_e32 v162, v162
	s_nop 0
	v_mov_b32_e32 v145, v163
	v_mov_b32_e32 v147, v163
	s_nop 1
	v_permlane16_swap_b32_e32 v145, v147
	s_nop 1
	v_mov_b32_e32 v154, v145
	v_mov_b32_e32 v155, v147
	s_nop 1
	v_permlane32_swap_b32_e32 v145, v154
	v_permlane32_swap_b32_e32 v147, v155
	s_nop 1
	s_waitcnt lgkmcnt(1)
	v_lshlrev_b32_e32 v163, 16, v34
	v_mul_f32_e32 v164, v35, v36
	s_waitcnt lgkmcnt(0)
	v_lshlrev_b32_e32 v34, 16, v161
	v_mul_f32_e32 v35, v160, v162
	v_mul_f32_e32 v160, v35, v34
	v_mul_f32_e32 v161, v159, v37
	ds_read_b128 v[34:37], v89
	v_mul_f32_e32 v159, v159, v160
	v_fmac_f32_e32 v159, v164, v163
	v_mul_f32_e32 v160, v39, v161
	v_mul_f32_e32 v39, v39, v159
	v_fmac_f32_e32 v39, v41, v40
	v_mul_f32_e32 v168, v38, v160
	v_mul_f32_e32 v169, v38, v39
	ds_read_b128 v[38:41], v89 offset:64
	s_waitcnt lgkmcnt(1)
	v_mfma_f32_16x16x32_bf16 v[160:163], v[34:37], v[26:29], 0
	v_fmac_f32_e32 v169, v158, v157
	ds_read_u16 v89, v70 offset:32
	ds_read_u16 v157, v70 offset:528
	s_waitcnt lgkmcnt(2)
	v_mfma_f32_16x16x32_bf16 v[158:161], v[38:41], v[18:21], v[160:163]
	ds_read_u16 v21, v70
	ds_bpermute_b32 v67, v68, v67 offset:192
	ds_bpermute_b32 v76, v68, v79
	v_mfma_f32_16x16x32_bf16 v[164:167], v[34:37], v[30:33], 0
	s_nop 3
	v_add_f32_e32 v31, v153, v158
	v_add_f32_e32 v32, v153, v159
	v_mul_f32_e32 v31, 0xbfb8aa3b, v31
	v_mul_f32_e32 v32, 0xbfb8aa3b, v32
	v_exp_f32_e32 v31, v31
	v_exp_f32_e32 v32, v32
	v_mfma_f32_16x16x32_bf16 v[22:25], v[38:41], v[22:25], v[164:167]
	ds_bpermute_b32 v78, v68, v79 offset:64
	v_add_f32_e32 v31, 1.0, v31
	v_add_f32_e32 v32, 1.0, v32
	v_rcp_f32_e32 v31, v31
	v_rcp_f32_e32 v32, v32
	s_nop 2
	v_add_f32_e32 v22, v152, v22
	v_add_f32_e32 v23, v152, v23
	v_mul_f32_e32 v31, v74, v31
	v_mul_f32_e32 v32, v74, v32
	v_mul_f32_e32 v31, 0x3fb8aa3b, v31
	v_mul_f32_e32 v32, 0x3fb8aa3b, v32
	v_mul_f32_e32 v22, 0xbfb8aa3b, v22
	v_exp_f32_e32 v31, v31
	v_mul_f32_e32 v23, 0xbfb8aa3b, v23
	v_exp_f32_e32 v32, v32
	v_exp_f32_e32 v22, v22
	v_exp_f32_e32 v23, v23
	v_fma_f32 v33, -v31, v31, 1.0
	v_fma_f32 v158, -v32, v32, 1.0
	v_add_f32_e32 v22, 1.0, v22
	v_max_f32_e32 v33, 0, v33
	v_add_f32_e32 v23, 1.0, v23
	v_max_f32_e32 v158, 0, v158
	v_rcp_f32_e32 v22, v22
	v_sqrt_f32_e32 v33, v33
	v_rcp_f32_e32 v23, v23
	v_sqrt_f32_e32 v158, v158
	v_add_f32_e32 v24, v152, v24
	v_mul_f32_e32 v33, v22, v33
	v_add_f32_e32 v25, v152, v25
	v_mul_f32_e32 v23, v23, v158
	ds_read_u16 v158, v70 offset:1056
	ds_read_u16 v152, v70 offset:1584
	s_waitcnt lgkmcnt(6)
; #define LAS __attribute__((address_space(3)))
; __device__ __forceinline__ float fsig(float x) { return frcp(1.0f + __expf(-x)); }
; template <int DIR, int MODE>
; __device__ __forceinline__ void lru_pass(const Args& a, const LAS bf16_t* cxb, LAS bf16_t* gyb, const LAS float* carry, const bf16x8 (&Bw)[2][2][2], const float (&prm)[2][3], int l, int tt, float (&hf)[8][2][4]) {
;     ...
;         for (int ks = 0; ks < 2; ++ks) Af[ks] = *(const LAS bf16x8*)(cxb + (m * 16 + fr) * CXS + 64 * h + 32 * ks + 8 * fq);
; #pragma unroll
;         for (int nt = 0; nt < 2; ++nt) {
;             f32x4 pr = (f32x4){0.f, 0.f, 0.f, 0.f}, pi = (f32x4){0.f, 0.f, 0.f, 0.f};
; #pragma unroll
;             for (int ks = 0; ks < 2; ++ks) { pr = __builtin_amdgcn_mfma_f32_16x16x32_bf16(Af[ks], Bw[0][nt][ks], pr, 0, 0, 0); pi = __builtin_amdgcn_mfma_f32_16x16x32_bf16(Af[ks], Bw[1][nt][ks], pi, 0, 0, 0); }
;             float av[4], bv[4];
; #pragma unroll
;             for (int reg = 0; reg < 4; ++reg) {
;                 const int tok = m * 16 + 4 * fq + reg;
;                 const float x = bf2f(cxb[tok * CXS + cc[nt]]);
;                 const float r = fsig(pr[reg] + ba[nt]), ig = fsig(pi[reg] + bxv[nt]);
;                 const float aa = __expf(k8[nt] * r);
;                 av[reg] = aa; bv[reg] = __builtin_amdgcn_sqrtf(fmaxf(1.0f - aa * aa, 0.f)) * ig * x;
;             }
;             float cum[4], hl[4];
;             if (DIR == 0) { cum[0] = av[0]; hl[0] = bv[0];
; #pragma unroll
;                 for (int reg = 1; reg < 4; ++reg) { cum[reg] = cum[reg - 1] * av[reg]; hl[reg] = av[reg] * hl[reg - 1] + bv[reg]; } }
;             else { cum[3] = av[3]; hl[3] = bv[3];
; #pragma unroll
;     ...
;             const float A4 = DIR ? cum[0] : cum[3], H4 = DIR ? hl[0] : hl[3];
;             float Aq[4], Hq[4];
; #pragma unroll
;             for (int q = 0; q < 4; ++q) { Aq[q] = __shfl(A4, fr + 16 * q); Hq[q] = __shfl(H4, fr + 16 * q); }
;             float hin;
;             if (DIR == 0) { const float s0 = C[nt], s1 = Aq[0] * s0 + Hq[0], s2 = Aq[1] * s1 + Hq[1], s3 = Aq[2] * s2 + Hq[2]; C[nt] = Aq[3] * s3 + Hq[3]; hin = fq == 0 ? s0 : (fq == 1 ? s1 : (fq == 2 ? s2 : s3)); }
	v_lshlrev_b32_e32 v22, 16, v157
	v_add_f32_e32 v157, v153, v160
	v_add_f32_e32 v153, v153, v161
	v_mul_f32_e32 v157, 0xbfb8aa3b, v157
	v_mul_f32_e32 v153, 0xbfb8aa3b, v153
	v_exp_f32_e32 v157, v157
	v_exp_f32_e32 v153, v153
	v_mul_f32_e32 v25, 0xbfb8aa3b, v25
	v_exp_f32_e32 v25, v25
	v_add_f32_e32 v157, 1.0, v157
	v_add_f32_e32 v153, 1.0, v153
	v_rcp_f32_e32 v157, v157
	v_rcp_f32_e32 v153, v153
	v_mul_f32_e32 v24, 0xbfb8aa3b, v24
	v_exp_f32_e32 v24, v24
	v_mul_f32_e32 v157, v74, v157
	v_mul_f32_e32 v74, v74, v153
	v_mul_f32_e32 v74, 0x3fb8aa3b, v74
	v_exp_f32_e32 v74, v74
	v_mul_f32_e32 v157, 0x3fb8aa3b, v157
	v_exp_f32_e32 v157, v157
	v_add_f32_e32 v25, 1.0, v25
	v_fma_f32 v153, -v74, v74, 1.0
	v_max_f32_e32 v153, 0, v153
	v_fma_f32 v159, -v157, v157, 1.0
	v_rcp_f32_e32 v25, v25
	v_sqrt_f32_e32 v153, v153
	v_add_f32_e32 v24, 1.0, v24
	v_max_f32_e32 v159, 0, v159
	v_rcp_f32_e32 v24, v24
	v_sqrt_f32_e32 v159, v159
	s_waitcnt lgkmcnt(0)
	v_lshlrev_b32_e32 v152, 16, v152
	v_mul_f32_e32 v25, v25, v153
	v_mul_f32_e32 v25, v25, v152
	v_lshlrev_b32_e32 v158, 16, v158
	v_mul_f32_e32 v24, v24, v159
	v_mul_f32_e32 v25, v157, v25
	v_mul_f32_e32 v74, v157, v74
	v_fmac_f32_e32 v25, v24, v158
	v_mul_f32_e32 v24, v32, v74
	v_mul_f32_e32 v32, v32, v25
	v_fmac_f32_e32 v32, v23, v22
	v_mul_f32_e32 v74, v31, v24
	v_mfma_f32_16x16x32_bf16 v[22:25], v[34:37], v[6:9], 0
	v_lshlrev_b32_e32 v21, 16, v21
	v_mul_f32_e32 v6, v31, v32
	v_fmac_f32_e32 v6, v33, v21
	v_mfma_f32_16x16x32_bf16 v[32:35], v[34:37], v[14:17], 0
	ds_bpermute_b32 v7, v68, v6
	ds_bpermute_b32 v14, v68, v6 offset:64
	ds_bpermute_b32 v16, v68, v6 offset:128
	v_mfma_f32_16x16x32_bf16 v[22:25], v[38:41], v[2:5], v[22:25]
	ds_bpermute_b32 v77, v68, v79 offset:128
	ds_bpermute_b32 v79, v68, v79 offset:192
	ds_bpermute_b32 v80, v68, v83
	v_mfma_f32_16x16x32_bf16 v[32:35], v[38:41], v[10:13], v[32:35]
	ds_bpermute_b32 v12, v68, v6 offset:192
	s_nop 2
	v_add_f32_e32 v2, v151, v22
	v_mul_f32_e32 v2, 0xbfb8aa3b, v2
	v_exp_f32_e32 v2, v2
	ds_read_u16 v10, v70 offset:560
	v_add_f32_e32 v4, v150, v32
	v_mul_f32_e32 v4, 0xbfb8aa3b, v4
	v_exp_f32_e32 v4, v4
	v_add_f32_e32 v2, 1.0, v2
	v_rcp_f32_e32 v2, v2
	v_add_f32_e32 v22, v151, v25
	v_add_f32_e32 v4, 1.0, v4
	v_rcp_f32_e32 v8, v4
	v_add_f32_e32 v4, v151, v23
	v_mul_f32_e32 v4, 0xbfb8aa3b, v4
	v_mul_f32_e32 v2, v72, v2
	v_exp_f32_e32 v4, v4
	v_mul_f32_e32 v2, 0x3fb8aa3b, v2
	v_exp_f32_e32 v2, v2
	ds_read_u16 v25, v70 offset:1616
	v_add_f32_e32 v4, 1.0, v4
	v_rcp_f32_e32 v4, v4
	v_fma_f32 v6, -v2, v2, 1.0
	v_max_f32_e32 v6, 0, v6
	v_sqrt_f32_e32 v9, v6
	v_add_f32_e32 v6, v150, v33
	v_mul_f32_e32 v6, 0xbfb8aa3b, v6
	v_mul_f32_e32 v4, v72, v4
	v_exp_f32_e32 v6, v6
	v_mul_f32_e32 v4, 0x3fb8aa3b, v4
	v_exp_f32_e32 v4, v4
	v_mul_f32_e32 v8, v8, v9
	v_add_f32_e32 v6, 1.0, v6
	v_rcp_f32_e32 v11, v6
	v_fma_f32 v6, -v4, v4, 1.0
	v_max_f32_e32 v6, 0, v6
	v_sqrt_f32_e32 v13, v6
	s_waitcnt lgkmcnt(1)
	v_lshlrev_b32_e32 v9, 16, v10
	v_mul_f32_e32 v22, 0xbfb8aa3b, v22
	v_exp_f32_e32 v23, v22
	v_mul_f32_e32 v10, v11, v13
	v_add_f32_e32 v11, v151, v24
	v_mul_f32_e32 v11, 0xbfb8aa3b, v11
	v_exp_f32_e32 v11, v11
	v_add_f32_e32 v23, 1.0, v23
	v_rcp_f32_e32 v23, v23
	v_add_f32_e32 v13, v150, v34
	v_add_f32_e32 v11, 1.0, v11
	v_rcp_f32_e32 v11, v11
	v_mul_f32_e32 v23, v72, v23
	v_add_f32_e32 v24, v150, v35
	v_mul_f32_e32 v23, 0x3fb8aa3b, v23
	v_mul_f32_e32 v11, v72, v11
	v_mul_f32_e32 v11, 0x3fb8aa3b, v11
	v_mul_f32_e32 v13, 0xbfb8aa3b, v13
	v_exp_f32_e32 v11, v11
	v_mul_f32_e32 v24, 0xbfb8aa3b, v24
	v_exp_f32_e32 v23, v23
	v_exp_f32_e32 v17, v13
	v_exp_f32_e32 v24, v24
	v_fma_f32 v22, -v11, v11, 1.0
	v_fma_f32 v31, -v23, v23, 1.0
	v_add_f32_e32 v17, 1.0, v17
	v_max_f32_e32 v22, 0, v22
	v_add_f32_e32 v24, 1.0, v24
	v_max_f32_e32 v31, 0, v31
	v_rcp_f32_e32 v17, v17
	v_sqrt_f32_e32 v22, v22
	v_rcp_f32_e32 v24, v24
	v_sqrt_f32_e32 v31, v31
	ds_read_u16 v13, v70 offset:1088
	v_mul_f32_e32 v17, v17, v22
	s_waitcnt lgkmcnt(1)
	v_lshlrev_b32_e32 v22, 16, v25
	v_mul_f32_e32 v24, v24, v31
	v_mul_f32_e32 v22, v24, v22
	s_waitcnt lgkmcnt(0)
	v_lshlrev_b32_e32 v13, 16, v13
	v_mul_f32_e32 v23, v11, v23
	v_mul_f32_e32 v11, v11, v22
	v_fmac_f32_e32 v11, v17, v13
	v_mul_f32_e32 v13, v4, v23
	v_mul_f32_e32 v4, v4, v11
	v_fmac_f32_e32 v4, v10, v9
	v_lshlrev_b32_e32 v137, 16, v137
	v_lshlrev_b32_e32 v6, 16, v89
	v_mul_f32_e32 v23, v2, v4
	v_fmac_f32_e32 v140, v138, v137
	v_mul_f32_e32 v10, v2, v13
	v_fmac_f32_e32 v23, v8, v6
	ds_bpermute_b32 v137, v68, v140
	ds_bpermute_b32 v138, v68, v140 offset:64
	ds_bpermute_b32 v139, v68, v140 offset:128
	ds_bpermute_b32 v140, v68, v140 offset:192
	ds_bpermute_b32 v82, v68, v83 offset:64
	ds_bpermute_b32 v81, v68, v83 offset:128
	ds_bpermute_b32 v83, v68, v83 offset:192
	s_nop 0
	s_nop 0
	s_nop 0
	s_nop 0
	s_nop 0
	s_nop 0
	v_mov_b32_e32 v27, v168
	v_mov_b32_e32 v29, v168
	s_nop 1
	v_permlane16_swap_b32_e32 v27, v29
	s_nop 1
	v_mov_b32_e32 v30, v27
	v_mov_b32_e32 v20, v29
	s_nop 1
	v_permlane32_swap_b32_e32 v27, v30
	v_permlane32_swap_b32_e32 v29, v20
	s_nop 1
	v_mov_b32_e32 v26, v169
	v_mov_b32_e32 v28, v169
	s_nop 1
	v_permlane16_swap_b32_e32 v26, v28
	s_nop 1
	v_mov_b32_e32 v18, v26
	v_mov_b32_e32 v19, v28
	s_nop 1
	v_permlane32_swap_b32_e32 v26, v18
	v_permlane32_swap_b32_e32 v28, v19
	s_nop 1
	s_nop 0
	s_nop 0
	s_nop 0
	v_mov_b32_e32 v21, v74
	v_mov_b32_e32 v15, v74
	s_nop 1
	v_permlane16_swap_b32_e32 v21, v15
	s_nop 1
	v_mov_b32_e32 v3, v21
	v_mov_b32_e32 v5, v15
	s_nop 1
	v_permlane32_swap_b32_e32 v21, v3
	v_permlane32_swap_b32_e32 v15, v5
	s_nop 1
	s_nop 0
	ds_bpermute_b32 v13, v68, v23
	s_nop 0
	ds_bpermute_b32 v4, v68, v23 offset:64
	s_nop 0
	ds_bpermute_b32 v22, v68, v23 offset:128
	v_mov_b32_e32 v2, v10
	v_mov_b32_e32 v17, v10
	s_nop 1
	v_permlane16_swap_b32_e32 v2, v17
	s_nop 1
	v_mov_b32_e32 v9, v2
	v_mov_b32_e32 v11, v17
	s_nop 1
	v_permlane32_swap_b32_e32 v2, v9
	v_permlane32_swap_b32_e32 v17, v11
	s_nop 1
	ds_bpermute_b32 v23, v68, v23 offset:192
	v_cmp_eq_u32_e32 vcc, 0, v43
	s_and_saveexec_b64 s[0:1], vcc
	s_cbranch_execz .LBB0_775
; #define LAS __attribute__((address_space(3)))
; __device__ __forceinline__ unsigned f2bf(float f) { unsigned u = __builtin_bit_cast(unsigned, f); return (u + 0x7fffu + ((u >> 16) & 1u)) >> 16; }
; __device__ __forceinline__ float fgelu(float x) { const float u = 0.7978845608028654f * (x + 0.044715f * x * x * x); return 0.5f * x * (2.0f - 2.0f * frcp(__expf(2.0f * u) + 1.0f)); }
; template <int DIR, int MODE>
; __device__ __forceinline__ void lru_pass(const Args& a, const LAS bf16_t* cxb, LAS bf16_t* gyb, const LAS float* carry, const bf16x8 (&Bw)[2][2][2], const float (&prm)[2][3], int l, int tt, float (&hf)[8][2][4]) {
;     ...
;             const float A4 = DIR ? cum[0] : cum[3], H4 = DIR ? hl[0] : hl[3];
;             float Aq[4], Hq[4];
; #pragma unroll
;             for (int q = 0; q < 4; ++q) { Aq[q] = __shfl(A4, fr + 16 * q); Hq[q] = __shfl(H4, fr + 16 * q); }
;             float hin;
;             if (DIR == 0) { const float s0 = C[nt], s1 = Aq[0] * s0 + Hq[0], s2 = Aq[1] * s1 + Hq[1], s3 = Aq[2] * s2 + Hq[2]; C[nt] = Aq[3] * s3 + Hq[3]; hin = fq == 0 ? s0 : (fq == 1 ? s1 : (fq == 2 ? s2 : s3)); }
;             else { const float s3 = C[nt], s2 = Aq[3] * s3 + Hq[3], s1 = Aq[2] * s2 + Hq[2], s0 = Aq[1] * s1 + Hq[1]; C[nt] = Aq[0] * s0 + Hq[0]; hin = fq == 3 ? s3 : (fq == 2 ? s2 : (fq == 1 ? s1 : s0)); }
;             if (MODE == 0) At[nt] *= (Aq[0] * Aq[1]) * (Aq[2] * Aq[3]);
;             else {
; #pragma unroll
;                 for (int reg = 0; reg < 4; ++reg) {
;                     const float hv = hl[reg] + cum[reg] * hin;
;                     if (DIR == 0) hf[m][nt][reg] = hv;
;                     else { LAS bf16_t* gp = gyb + (m * 16 + 4 * fq + reg) * CXS + cc[nt];
;                         const float g = bf2f(*gp);
;                         *gp = (bf16_t)f2bf((hf[m][nt][reg] + hv) * fgelu(g)); }
;                 }
;             }
;         }
;     }
;     if (MODE == 0 && fq == 0) {
; #pragma unroll
;         for (int nt = 0; nt < 2; ++nt) { f32x2 sm; sm[0] = At[nt]; sm[1] = C[nt]; *(f32x2*)(SUM + ((size_t)(tt * 2 + DIR) * 256 + cc[nt]) * 2) = sm; }
	v_fmac_f32_e32 v92, 0, v58
	v_fmac_f32_e32 v91, v92, v56
	v_fmac_f32_e32 v90, v91, v54
	v_fmac_f32_e32 v88, v90, v52
	v_fmac_f32_e32 v100, v88, v59
	v_fmac_f32_e32 v99, v100, v57
	v_fmac_f32_e32 v98, v99, v55
	v_fmac_f32_e32 v97, v98, v53
	v_fmac_f32_e32 v108, v97, v67
	v_fmac_f32_e32 v107, v108, v65
	v_fmac_f32_e32 v87, 0, v50
	v_fmac_f32_e32 v106, v107, v66
	v_fmac_f32_e32 v86, v87, v48
	v_fmac_f32_e32 v105, v106, v64
	v_fmac_f32_e32 v85, v86, v46
	v_fmac_f32_e32 v123, v105, v124
	v_fmac_f32_e32 v84, v85, v44
	v_fmac_f32_e32 v122, v123, v121
	v_fmac_f32_e32 v96, v84, v51
	v_fmac_f32_e32 v119, v122, v120
	v_fmac_f32_e32 v95, v96, v49
	v_fmac_f32_e32 v117, v119, v118
	v_fmac_f32_e32 v94, v95, v47
	v_fmac_f32_e32 v136, v117, v75
	v_fmac_f32_e32 v93, v94, v45
	v_fmac_f32_e32 v135, v136, v73
	v_fmac_f32_e32 v104, v93, v63
	v_fmac_f32_e32 v133, v135, v134
	v_fmac_f32_e32 v103, v104, v61
	v_fmac_f32_e32 v131, v133, v132
	v_fmac_f32_e32 v102, v103, v62
	s_waitcnt lgkmcnt(4)
	v_fmac_f32_e32 v144, v131, v83
	v_fmac_f32_e32 v101, v102, v60
	v_fmac_f32_e32 v143, v144, v81
	v_fmac_f32_e32 v115, v101, v116
	v_fmac_f32_e32 v142, v143, v82
	v_fmac_f32_e32 v114, v115, v113
	v_fmac_f32_e32 v141, v142, v80
	v_fmac_f32_e32 v111, v114, v112
	s_waitcnt lgkmcnt(4)
	v_fmac_f32_e32 v19, v141, v20
	v_fmac_f32_e32 v109, v111, v110
	v_fmac_f32_e32 v18, v19, v30
	v_fmac_f32_e32 v130, v109, v71
	v_fmac_f32_e32 v28, v18, v29
	v_fmac_f32_e32 v129, v130, v69
	v_pk_mul_f32 v[34:35], v[52:53], v[54:55]
	v_pk_mul_f32 v[36:37], v[56:57], v[58:59]
	v_fmac_f32_e32 v26, v28, v27
	v_fmac_f32_e32 v127, v129, v128
	v_pk_mul_f32 v[32:33], v[64:65], v[66:67]
	v_pk_mul_f32 v[34:35], v[34:35], v[36:37]
	s_waitcnt lgkmcnt(0)
	v_fmac_f32_e32 v23, v26, v11
	v_fmac_f32_e32 v125, v127, v126
	v_pk_mul_f32 v[34:35], v[34:35], v[34:35] op_sel:[0,1] op_sel_hi:[1,0]
	v_pk_mul_f32 v[32:33], v[32:33], v[32:33] op_sel:[0,1] op_sel_hi:[1,0]
	v_fmac_f32_e32 v22, v23, v9
	v_fmac_f32_e32 v140, v125, v79
	v_mul_f32_e32 v8, v27, v29
	v_mul_f32_e32 v10, v30, v20
	v_mov_b32_e32 v35, v132
	v_mov_b32_e32 v33, v134
	v_fmac_f32_e32 v4, v22, v17
	v_pk_mul_f32 v[18:19], v[44:45], v[46:47]
	v_pk_mul_f32 v[22:23], v[48:49], v[50:51]
	v_fmac_f32_e32 v139, v140, v77
	v_pk_mul_f32 v[32:33], v[34:35], v[32:33]
	v_pk_mul_f32 v[34:35], v[8:9], v[10:11]
	v_pk_mul_f32 v[10:11], v[60:61], v[62:63]
	v_pk_mul_f32 v[18:19], v[18:19], v[22:23]
	v_fmac_f32_e32 v138, v139, v78
	v_pk_mul_f32 v[18:19], v[18:19], v[18:19] op_sel:[0,1] op_sel_hi:[1,0]
	v_pk_mul_f32 v[10:11], v[10:11], v[10:11] op_sel:[0,1] op_sel_hi:[1,0]
	v_fmac_f32_e32 v137, v138, v76
	v_mul_f32_e32 v72, v118, v120
	v_mul_f32_e32 v74, v121, v124
	v_mul_f32_e32 v68, v110, v112
	v_mul_f32_e32 v70, v113, v116
	v_mov_b32_e32 v19, v126
	v_mov_b32_e32 v11, v128
	v_fmac_f32_e32 v155, v137, v156
	v_pk_mul_f32 v[36:37], v[72:73], v[74:75]
	v_pk_mul_f32 v[22:23], v[68:69], v[70:71]
	v_pk_mul_f32 v[10:11], v[18:19], v[10:11]
	v_fmac_f32_e32 v154, v155, v149
	v_pk_mul_f32 v[32:33], v[32:33], v[36:37]
	v_pk_mul_f32 v[8:9], v[76:77], v[78:79]
	v_pk_mul_f32 v[10:11], v[10:11], v[22:23]
	v_fmac_f32_e32 v147, v154, v148
	s_lshl_b32 s4, s82, 1
	v_pk_mul_f32 v[32:33], v[32:33], v[32:33] op_sel:[0,1] op_sel_hi:[1,0]
	v_pk_mul_f32 v[10:11], v[10:11], v[10:11] op_sel:[0,1] op_sel_hi:[1,0]
	v_pk_mul_f32 v[8:9], v[8:9], v[8:9] op_sel:[0,1] op_sel_hi:[1,0]
	v_fmac_f32_e32 v145, v147, v146
	s_or_b32 s4, s4, 1
	v_pk_mul_f32 v[24:25], v[80:81], v[82:83]
	v_mov_b32_e32 v33, v2
	v_fmac_f32_e32 v13, v4, v2
	v_mul_f32_e32 v2, v146, v148
	v_mul_f32_e32 v4, v149, v156
	v_mov_b32_e32 v11, v21
	v_mov_b32_e32 v9, v15
	v_fmac_f32_e32 v12, v145, v5
	s_ashr_i32 s5, s4, 31
	v_pk_mul_f32 v[24:25], v[24:25], v[24:25] op_sel:[0,1] op_sel_hi:[1,0]
	v_pk_mul_f32 v[18:19], v[2:3], v[4:5]
	v_pk_mul_f32 v[8:9], v[10:11], v[8:9]
	v_fmac_f32_e32 v16, v12, v3
	s_lshl_b64 s[4:5], s[4:5], 11
	v_readlane_b32 s28, v253, 43
	v_mov_b32_e32 v25, v17
	v_pk_mul_f32 v[8:9], v[8:9], v[18:19]
	v_fmac_f32_e32 v14, v16, v15
	v_readlane_b32 s29, v253, 44
	s_add_u32 s4, s28, s4
	v_pk_mul_f32 v[24:25], v[32:33], v[24:25]
	v_fmac_f32_e32 v7, v14, v21
	s_addc_u32 s5, s29, s5
	v_pk_mul_f32 v[2:3], v[8:9], v[8:9] op_sel:[0,1] op_sel_hi:[1,0]
	v_ashrrev_i32_e32 v43, 31, v42
	v_or_b32_e32 v6, 16, v42
	v_pk_mul_f32 v[24:25], v[24:25], v[34:35]
	v_mov_b32_e32 v3, v7
	v_lshl_add_u64 v[4:5], v[42:43], 3, s[4:5]
	global_store_dwordx2 v[4:5], v[2:3], off
	v_pk_mul_f32 v[2:3], v[24:25], v[24:25] op_sel:[0,1] op_sel_hi:[1,0]
	v_ashrrev_i32_e32 v7, 31, v6
	v_mov_b32_e32 v3, v13
	v_lshl_add_u64 v[4:5], v[6:7], 3, s[4:5]
	global_store_dwordx2 v[4:5], v[2:3], off
